# plus remaining GEMM epilogues' first loads before the alignment barrier; accumulator zeroing removed (K-tile 0 peeled, first MFMA per accumulator takes SrcC = 0)
# speedup vs baseline: 1.0003x; 1.0003x over previous
;     __host__ __device__ bool next(int i, Unit& u) const { const int L = base + i * Gp + cp; if (L >= end) return false; return T.next(L, u); }
;     __host__ __device__ bool next(int i, Unit& u) const { const int L = i * Gp + cp; if (cp < 0 || L >= n) return false; u.kb = L & 3; u.pn = (L >> 2) % nN; u.pm = pm0 + (L >> 2) / nN; return true; }
;     __host__ __device__ bool next(int i, Unit& u) const { const bool ok = T.next(i >> 2, u); u.kb = i & 3; return ok; }
; #define PG8_BAR __builtin_amdgcn_s_barrier()
; template <class Epi, class Sched, bool ALIGN_EPI = false, bool SP2 = false>
; __device__ __forceinline__ void gemm_phase(PG8_LAS unsigned char* lds, const Gemm g, const Sched& S, const Epi& E, const int tid) {
;     ...
;         const bool has_next = S.next(ui + 1, nxt);
;         const char* nA = has_next ? (const char*)g.A + (size_t)nxt.pm * tstep + (size_t)nxt.kb * g.sA : cA; const char* nB = has_next ? (const char*)g.Bt + (size_t)nxt.pn * tstep + (size_t)nxt.kb * g.sB : cB;
;         for (int t = 0; t < nt; t += 2) {
;             const bool last = (t == nt - 2);
;             const char* a1 = cA + (size_t)(t + 1) * kstep;
;             const char* a2 = last ? nA : cA + (size_t)(t + 2) * kstep; const char* b2 = last ? nB : cB + (size_t)(t + 2) * kstep;
;     ...
; #pragma unroll
;         for (int a = 0; a < 2; ++a)
; #pragma unroll
;             for (int b = 0; b < 2; ++b)
; #pragma unroll
;                 for (int m = 0; m < 4; ++m)
; #pragma unroll
;                     for (int n = 0; n < 2; ++n) acc[a][b][m][n] = (f32x4){0.f, 0.f, 0.f, 0.f};
;         cur = nxt; cA = nA; cB = nB; ++ui;
;         if constexpr (ALIGN_EPI) { if (wr == 1) PG8_BAR; }
.LBB0_340:
	s_ashr_i32 s37, s36, 31
	s_lshl_b64 s[38:39], s[36:37], 20
	s_add_u32 s38, s58, s38
	s_addc_u32 s39, s59, s39
	s_and_b64 s[40:41], s[6:7], exec
	s_cselect_b32 s1, s39, s11
	s_cselect_b32 s9, s38, s10
	s_ashr_i32 s35, s34, 31
	s_lshl_b64 s[40:41], s[34:35], 20
	s_add_u32 s40, s60, s40
	s_addc_u32 s41, s61, s41
	s_and_b64 s[42:43], s[6:7], exec
	s_cselect_b32 s35, s41, s13
	s_cselect_b32 s37, s40, s12
	s_add_u32 s10, s10, 0x80080
	s_addc_u32 s11, s11, 0
	s_add_u32 s44, s12, 0x100
	v_mov_b32_e32 v0, 0
	s_addc_u32 s45, s13, 0
	s_mov_b32 s46, -2
	s_cmp_eq_u32 s100, 0
	s_cbranch_scc1 .Lmy_nobar_341
	s_barrier
	s_mov_b32 s100, 0
; #define PG8_STAGE(bufoff, gbase, voff) do { _Pragma("unroll") for (int _i = 0; _i < 2; ++_i) \
;         __builtin_amdgcn_global_load_lds((const unsigned*)((const char*)(gbase) + (voff)[_i]), (PG8_LAS unsigned*)(lds + (bufoff) + ldsw + _i * 8192), 16, 0, 0); } while (0)
; #define PG8_LDA(dst, b, h) do { _Pragma("unroll") for (int m = 0; m < 4; ++m) _Pragma("unroll") for (int k = 0; k < 2; ++k) dst[m][k] = *(const PG8_LAS bf16x8*)(lds + PG8_SA(b, h) + aoff + m * 2048 + k * 1024); } while (0)
; #define PG8_LDB(dst, b, h) do { _Pragma("unroll") for (int n = 0; n < 2; ++n) _Pragma("unroll") for (int k = 0; k < 2; ++k) dst[n][k] = *(const PG8_LAS bf16x8*)(lds + PG8_SB(b, h) + boff + n * 2048 + k * 1024); } while (0)
; #define PG8_MMA(ai, bj, At, Bt) do { __builtin_amdgcn_s_setprio(1); _Pragma("unroll") for (int m = 0; m < 4; ++m) _Pragma("unroll") for (int n = 0; n < 2; ++n) _Pragma("unroll") for (int k = 0; k < 2; ++k) \
;         acc[ai][bj][m][n] = __builtin_amdgcn_mfma_f32_16x16x32_bf16(Bt[n][k], At[m][k], acc[ai][bj][m][n], 0, 0, 0); __builtin_amdgcn_s_setprio(0); } while (0)
; #define PG8_WAIT_V(n) asm volatile("s_waitcnt vmcnt(" #n ")" ::: "memory")
; #define PG8_WAIT_L(n) asm volatile("s_waitcnt lgkmcnt(" #n ")" ::: "memory")
; #define PG8_BAR __builtin_amdgcn_s_barrier()
; template <class Epi, class Sched, bool ALIGN_EPI = false, bool SP2 = false>
; __device__ __forceinline__ void gemm_phase(PG8_LAS unsigned char* lds, const Gemm g, const Sched& S, const Epi& E, const int tid) {
;     ...
;             const char* a1 = cA + (size_t)(t + 1) * kstep;
;             const char* a2 = last ? nA : cA + (size_t)(t + 2) * kstep; const char* b2 = last ? nB : cB + (size_t)(t + 2) * kstep;
;             const char* a3 = a2 + kstep; const char* b3 = b2 + kstep;
;             if (last && has_next) S.a_ready(nxt);
;             if constexpr (SP2) {
;             PG8_LDB(B0, 0, 0); PG8_LDB(B1, 0, 1); PG8_SCHED; PG8_LDA(At, 0, 0); PG8_STAGE(PG8_SA(1, 1), a1 + hstep, voffA);
;             PG8_WAIT_V(8); PG8_WAIT_L(0); PG8_BAR; PG8_MMA(0, 0, At, B0); PG8_MMA(0, 1, At, B1); PG8_BAR; PG8_SCHED;
;             PG8_LDA(At, 0, 1); PG8_STAGE(PG8_SB(0, 0), b2, voffB); PG8_STAGE(PG8_SB(0, 1), b2 + hstep, voffB); PG8_STAGE(PG8_SA(0, 0), a2, voffA);
;             PG8_WAIT_V(8); PG8_WAIT_L(0); PG8_BAR; PG8_MMA(1, 0, At, B0); PG8_MMA(1, 1, At, B1); PG8_BAR; PG8_SCHED;
.Lmy_nobar_341:
	s_add_u32 s12, s10, 0xfff80080
	s_addc_u32 s13, s11, -1
	s_add_i32 s47, 0, 0x10000
	v_add_u32_e32 v28, s47, v197
	s_waitcnt vmcnt(0)
	v_add_u32_e32 v60, s33, v197
	ds_read_b128 v[16:19], v28
	ds_read_b128 v[20:23], v28 offset:1024
	ds_read_b128 v[24:27], v28 offset:2048
	ds_read_b128 v[28:31], v28 offset:3072
	ds_read_b128 v[40:43], v60
	ds_read_b128 v[44:47], v60 offset:1024
	ds_read_b128 v[56:59], v60 offset:2048
	ds_read_b128 v[60:63], v60 offset:3072
	s_cmp_eq_u32 s46, 28
	s_cselect_b32 s43, s1, s13
	s_cselect_b32 s42, s9, s12
	s_cselect_b32 s13, s35, s45
	s_cselect_b32 s12, s37, s44
	v_lshl_add_u64 v[194:195], s[10:11], 0, v[190:191]
	s_add_i32 m0, s63, 0xc000
	ds_read_b128 v[80:83], v240
	ds_read_b128 v[84:87], v240 offset:1024
	ds_read_b128 v[104:107], v240 offset:2048
	ds_read_b128 v[108:111], v240 offset:3072
	ds_read_b128 v[198:201], v240 offset:4096
	ds_read_b128 v[202:205], v240 offset:5120
	ds_read_b128 v[214:217], v240 offset:6144
	ds_read_b128 v[218:221], v240 offset:7168
	global_load_lds_dwordx4 v[194:195], off
	v_lshl_add_u64 v[194:195], s[10:11], 0, v[192:193]
	s_add_i32 m0, s63, 0xe000
	s_nop 0
	global_load_lds_dwordx4 v[194:195], off
	s_waitcnt vmcnt(8)
	s_waitcnt lgkmcnt(0)
	s_barrier
	s_setprio 1
	s_waitcnt lgkmcnt(0)
	v_mfma_f32_16x16x32_bf16 v[172:175], v[16:19], v[80:83], 0
	v_mfma_f32_16x16x32_bf16 v[168:171], v[24:27], v[80:83], 0
	v_mfma_f32_16x16x32_bf16 v[156:159], v[16:19], v[104:107], 0
	v_mfma_f32_16x16x32_bf16 v[152:155], v[24:27], v[104:107], 0
	v_mfma_f32_16x16x32_bf16 v[140:143], v[16:19], v[198:201], 0
	v_mfma_f32_16x16x32_bf16 v[136:139], v[24:27], v[198:201], 0
	v_mfma_f32_16x16x32_bf16 v[124:127], v[16:19], v[214:217], 0
	v_mfma_f32_16x16x32_bf16 v[120:123], v[24:27], v[214:217], 0
	v_mfma_f32_16x16x32_bf16 v[172:175], v[20:23], v[84:87], v[172:175]
	v_mfma_f32_16x16x32_bf16 v[168:171], v[28:31], v[84:87], v[168:171]
	v_mfma_f32_16x16x32_bf16 v[156:159], v[20:23], v[108:111], v[156:159]
	v_mfma_f32_16x16x32_bf16 v[152:155], v[28:31], v[108:111], v[152:155]
	v_mfma_f32_16x16x32_bf16 v[140:143], v[20:23], v[202:205], v[140:143]
	v_mfma_f32_16x16x32_bf16 v[136:139], v[28:31], v[202:205], v[136:139]
	v_mfma_f32_16x16x32_bf16 v[124:127], v[20:23], v[218:221], v[124:127]
	v_mfma_f32_16x16x32_bf16 v[120:123], v[28:31], v[218:221], v[120:123]
	s_setprio 0
	s_setprio 1
	v_mfma_f32_16x16x32_bf16 v[164:167], v[40:43], v[80:83], 0
	v_mfma_f32_16x16x32_bf16 v[80:83], v[56:59], v[80:83], 0
	v_mfma_f32_16x16x32_bf16 v[164:167], v[44:47], v[84:87], v[164:167]
	v_mfma_f32_16x16x32_bf16 v[80:83], v[60:63], v[84:87], v[80:83]
	v_mfma_f32_16x16x32_bf16 v[84:87], v[40:43], v[104:107], 0
	v_mfma_f32_16x16x32_bf16 v[104:107], v[56:59], v[104:107], 0
	v_mfma_f32_16x16x32_bf16 v[128:131], v[56:59], v[198:201], 0
	v_mfma_f32_16x16x32_bf16 v[116:119], v[40:43], v[214:217], 0
	v_mfma_f32_16x16x32_bf16 v[112:115], v[56:59], v[214:217], 0
	v_mfma_f32_16x16x32_bf16 v[84:87], v[44:47], v[108:111], v[84:87]
	v_mfma_f32_16x16x32_bf16 v[104:107], v[60:63], v[108:111], v[104:107]
	v_mfma_f32_16x16x32_bf16 v[108:111], v[40:43], v[198:201], 0
	v_mfma_f32_16x16x32_bf16 v[128:131], v[60:63], v[202:205], v[128:131]
	v_mfma_f32_16x16x32_bf16 v[116:119], v[44:47], v[218:221], v[116:119]
	v_mfma_f32_16x16x32_bf16 v[112:115], v[60:63], v[218:221], v[112:115]
	v_mfma_f32_16x16x32_bf16 v[108:111], v[44:47], v[202:205], v[108:111]
	s_setprio 0
	s_barrier
	s_add_i32 s47, s47, s62
	v_lshl_add_u64 v[194:195], s[12:13], 0, v[178:179]
	s_mov_b32 m0, s47
	ds_read_b128 v[132:135], v240 offset:16384
	ds_read_b128 v[144:147], v240 offset:17408
	ds_read_b128 v[148:151], v240 offset:18432
	ds_read_b128 v[160:163], v240 offset:19456
	ds_read_b128 v[198:201], v240 offset:20480
	ds_read_b128 v[202:205], v240 offset:21504
	ds_read_b128 v[214:217], v240 offset:22528
	ds_read_b128 v[218:221], v240 offset:23552
	global_load_lds_dwordx4 v[194:195], off
	s_add_i32 m0, s47, 0x2000
	s_add_u32 s48, s12, 0x80000
	v_lshl_add_u64 v[206:207], s[12:13], 0, v[182:183]
	s_addc_u32 s49, s13, 0
	s_add_i32 s47, s33, s62
	global_load_lds_dwordx4 v[206:207], off
	v_lshl_add_u64 v[210:211], s[48:49], 0, v[178:179]
	s_mov_b32 m0, s47
	v_lshl_add_u64 v[234:235], s[42:43], 0, v[180:181]
	global_load_lds_dwordx4 v[210:211], off
	v_lshl_add_u64 v[210:211], s[48:49], 0, v[182:183]
	s_add_i32 m0, s47, 0x2000
	s_nop 0
	global_load_lds_dwordx4 v[210:211], off
	v_lshl_add_u64 v[210:211], s[42:43], 0, v[176:177]
	s_mov_b32 m0, s63
	s_nop 0
	global_load_lds_dwordx4 v[210:211], off
	s_mov_b32 m0, s64
	s_nop 0
	global_load_lds_dwordx4 v[234:235], off
	s_waitcnt vmcnt(8)
	s_waitcnt lgkmcnt(0)
	s_barrier
	s_setprio 1
	s_waitcnt lgkmcnt(0)
	v_mfma_f32_16x16x32_bf16 v[100:103], v[16:19], v[132:135], 0
	v_mfma_f32_16x16x32_bf16 v[96:99], v[24:27], v[132:135], 0
	v_mfma_f32_16x16x32_bf16 v[76:79], v[16:19], v[148:151], 0
	v_mfma_f32_16x16x32_bf16 v[72:75], v[24:27], v[148:151], 0
	v_mfma_f32_16x16x32_bf16 v[52:55], v[16:19], v[198:201], 0
	v_mfma_f32_16x16x32_bf16 v[48:51], v[24:27], v[198:201], 0
	v_mfma_f32_16x16x32_bf16 v[12:15], v[16:19], v[214:217], 0
	v_mfma_f32_16x16x32_bf16 v[8:11], v[24:27], v[214:217], 0
	v_mfma_f32_16x16x32_bf16 v[100:103], v[20:23], v[144:147], v[100:103]
	v_mfma_f32_16x16x32_bf16 v[96:99], v[28:31], v[144:147], v[96:99]
	v_mfma_f32_16x16x32_bf16 v[76:79], v[20:23], v[160:163], v[76:79]
	v_mfma_f32_16x16x32_bf16 v[72:75], v[28:31], v[160:163], v[72:75]
	v_mfma_f32_16x16x32_bf16 v[52:55], v[20:23], v[202:205], v[52:55]
	v_mfma_f32_16x16x32_bf16 v[48:51], v[28:31], v[202:205], v[48:51]
	v_mfma_f32_16x16x32_bf16 v[12:15], v[20:23], v[218:221], v[12:15]
	v_mfma_f32_16x16x32_bf16 v[8:11], v[28:31], v[218:221], v[8:11]
	s_setprio 0
	s_setprio 1
	v_mfma_f32_16x16x32_bf16 v[36:39], v[40:43], v[198:201], 0
	v_mfma_f32_16x16x32_bf16 v[32:35], v[56:59], v[198:201], 0
	v_mfma_f32_16x16x32_bf16 v[4:7], v[40:43], v[214:217], 0
	v_mfma_f32_16x16x32_bf16 v[0:3], v[56:59], v[214:217], 0
	v_mfma_f32_16x16x32_bf16 v[16:19], v[40:43], v[132:135], 0
	v_mfma_f32_16x16x32_bf16 v[20:23], v[56:59], v[132:135], 0
	v_mfma_f32_16x16x32_bf16 v[24:27], v[40:43], v[148:151], 0
	v_mfma_f32_16x16x32_bf16 v[28:31], v[56:59], v[148:151], 0
	v_mfma_f32_16x16x32_bf16 v[36:39], v[44:47], v[202:205], v[36:39]
	v_mfma_f32_16x16x32_bf16 v[32:35], v[60:63], v[202:205], v[32:35]
	v_mfma_f32_16x16x32_bf16 v[4:7], v[44:47], v[218:221], v[4:7]
	v_mfma_f32_16x16x32_bf16 v[0:3], v[60:63], v[218:221], v[0:3]
	v_mfma_f32_16x16x32_bf16 v[16:19], v[44:47], v[144:147], v[16:19]
	v_mfma_f32_16x16x32_bf16 v[20:23], v[60:63], v[144:147], v[20:23]
	v_mfma_f32_16x16x32_bf16 v[24:27], v[44:47], v[160:163], v[24:27]
	v_mfma_f32_16x16x32_bf16 v[28:31], v[60:63], v[160:163], v[28:31]
	s_setprio 0
	s_barrier
	s_branch .Lmy_mid_341

; #define PG8_STAGE(bufoff, gbase, voff) do { _Pragma("unroll") for (int _i = 0; _i < 2; ++_i) \
;         __builtin_amdgcn_global_load_lds((const unsigned*)((const char*)(gbase) + (voff)[_i]), (PG8_LAS unsigned*)(lds + (bufoff) + ldsw + _i * 8192), 16, 0, 0); } while (0)
; #define PG8_LDA(dst, b, h) do { _Pragma("unroll") for (int m = 0; m < 4; ++m) _Pragma("unroll") for (int k = 0; k < 2; ++k) dst[m][k] = *(const PG8_LAS bf16x8*)(lds + PG8_SA(b, h) + aoff + m * 2048 + k * 1024); } while (0)
; #define PG8_LDB(dst, b, h) do { _Pragma("unroll") for (int n = 0; n < 2; ++n) _Pragma("unroll") for (int k = 0; k < 2; ++k) dst[n][k] = *(const PG8_LAS bf16x8*)(lds + PG8_SB(b, h) + boff + n * 2048 + k * 1024); } while (0)
; #define PG8_MMA(ai, bj, At, Bt) do { __builtin_amdgcn_s_setprio(1); _Pragma("unroll") for (int m = 0; m < 4; ++m) _Pragma("unroll") for (int n = 0; n < 2; ++n) _Pragma("unroll") for (int k = 0; k < 2; ++k) \
;         acc[ai][bj][m][n] = __builtin_amdgcn_mfma_f32_16x16x32_bf16(Bt[n][k], At[m][k], acc[ai][bj][m][n], 0, 0, 0); __builtin_amdgcn_s_setprio(0); } while (0)
; #define PG8_WAIT_V(n) asm volatile("s_waitcnt vmcnt(" #n ")" ::: "memory")
; #define PG8_WAIT_L(n) asm volatile("s_waitcnt lgkmcnt(" #n ")" ::: "memory")
; #define PG8_BAR __builtin_amdgcn_s_barrier()
; #define PG8_SCHED __builtin_amdgcn_sched_barrier(0)
; template <class Epi, class Sched, bool ALIGN_EPI = false, bool SP2 = false>
; __device__ __forceinline__ void gemm_phase(PG8_LAS unsigned char* lds, const Gemm g, const Sched& S, const Epi& E, const int tid) {
;     ...
;             PG8_LDB(B0, 1, 0); PG8_LDB(B1, 1, 1); PG8_SCHED; PG8_LDA(At, 1, 0); PG8_STAGE(PG8_SA(0, 1), a2 + hstep, voffA);
;             PG8_WAIT_V(8); PG8_WAIT_L(0); PG8_BAR; PG8_MMA(0, 0, At, B0); PG8_MMA(0, 1, At, B1); PG8_BAR; PG8_SCHED;
.Lmy_mid_341:
	s_add_i32 s47, 0, 0x18000
	s_add_i32 s48, 0, 0x1c000
	v_add_u32_e32 v60, s47, v197
	v_add_u32_e32 v64, s48, v197
	ds_read_b128 v[40:43], v60
	ds_read_b128 v[44:47], v60 offset:1024
	ds_read_b128 v[56:59], v60 offset:2048
	ds_read_b128 v[60:63], v60 offset:3072
	ds_read_b128 v[198:201], v64
	ds_read_b128 v[202:205], v64 offset:1024
	ds_read_b128 v[214:217], v64 offset:2048
	ds_read_b128 v[218:221], v64 offset:3072
	s_add_u32 s42, s42, 0x80000
	s_addc_u32 s43, s43, 0
	s_mov_b32 m0, s65
	v_lshl_add_u64 v[132:133], s[42:43], 0, v[176:177]
	ds_read_b128 v[64:67], v240 offset:32768
	ds_read_b128 v[68:71], v240 offset:33792
	ds_read_b128 v[88:91], v240 offset:34816
	ds_read_b128 v[92:95], v240 offset:35840
	ds_read_b128 v[222:225], v240 offset:36864
	ds_read_b128 v[226:229], v240 offset:37888
	ds_read_b128 v[230:233], v240 offset:38912
	ds_read_b128 v[242:245], v240 offset:39936
	global_load_lds_dwordx4 v[132:133], off
	v_lshl_add_u64 v[132:133], s[42:43], 0, v[180:181]
	s_mov_b32 m0, s66
	s_nop 0
	global_load_lds_dwordx4 v[132:133], off
	s_waitcnt vmcnt(8)
	s_waitcnt lgkmcnt(0)
	s_barrier
	s_setprio 1
	s_waitcnt lgkmcnt(0)
	v_mfma_f32_16x16x32_bf16 v[132:135], v[40:43], v[64:67], v[172:175]
	v_mfma_f32_16x16x32_bf16 v[172:175], v[44:47], v[68:71], v[132:135]
	v_mfma_f32_16x16x32_bf16 v[132:135], v[56:59], v[64:67], v[168:171]
	v_mfma_f32_16x16x32_bf16 v[168:171], v[60:63], v[68:71], v[132:135]
	v_mfma_f32_16x16x32_bf16 v[132:135], v[40:43], v[88:91], v[156:159]
	v_mfma_f32_16x16x32_bf16 v[156:159], v[44:47], v[92:95], v[132:135]
	v_mfma_f32_16x16x32_bf16 v[132:135], v[56:59], v[88:91], v[152:155]
	v_mfma_f32_16x16x32_bf16 v[152:155], v[60:63], v[92:95], v[132:135]
	v_mfma_f32_16x16x32_bf16 v[132:135], v[40:43], v[222:225], v[140:143]
	v_mfma_f32_16x16x32_bf16 v[140:143], v[44:47], v[226:229], v[132:135]
	v_mfma_f32_16x16x32_bf16 v[132:135], v[56:59], v[222:225], v[136:139]
	v_mfma_f32_16x16x32_bf16 v[124:127], v[40:43], v[230:233], v[124:127]
	v_mfma_f32_16x16x32_bf16 v[120:123], v[56:59], v[230:233], v[120:123]
	v_mfma_f32_16x16x32_bf16 v[136:139], v[60:63], v[226:229], v[132:135]
	v_mfma_f32_16x16x32_bf16 v[124:127], v[44:47], v[242:245], v[124:127]
	v_mfma_f32_16x16x32_bf16 v[120:123], v[60:63], v[242:245], v[120:123]
	s_setprio 0
	s_setprio 1
	v_mfma_f32_16x16x32_bf16 v[132:135], v[198:201], v[64:67], v[164:167]
	v_mfma_f32_16x16x32_bf16 v[64:67], v[214:217], v[64:67], v[80:83]
	v_mfma_f32_16x16x32_bf16 v[160:163], v[218:221], v[68:71], v[64:67]
	v_mfma_f32_16x16x32_bf16 v[64:67], v[198:201], v[88:91], v[84:87]
	v_mfma_f32_16x16x32_bf16 v[148:151], v[202:205], v[92:95], v[64:67]
	v_mfma_f32_16x16x32_bf16 v[64:67], v[214:217], v[88:91], v[104:107]
	v_mfma_f32_16x16x32_bf16 v[144:147], v[218:221], v[92:95], v[64:67]
	v_mfma_f32_16x16x32_bf16 v[64:67], v[198:201], v[222:225], v[108:111]
	v_mfma_f32_16x16x32_bf16 v[164:167], v[202:205], v[68:71], v[132:135]
	v_mfma_f32_16x16x32_bf16 v[132:135], v[202:205], v[226:229], v[64:67]
	v_mfma_f32_16x16x32_bf16 v[64:67], v[214:217], v[222:225], v[128:131]
	v_mfma_f32_16x16x32_bf16 v[128:131], v[218:221], v[226:229], v[64:67]
	v_mfma_f32_16x16x32_bf16 v[64:67], v[198:201], v[230:233], v[116:119]
	v_mfma_f32_16x16x32_bf16 v[116:119], v[202:205], v[242:245], v[64:67]
	v_mfma_f32_16x16x32_bf16 v[64:67], v[214:217], v[230:233], v[112:115]
	v_mfma_f32_16x16x32_bf16 v[112:115], v[218:221], v[242:245], v[64:67]
	s_setprio 0
	s_barrier
; #define PG8_STAGE(bufoff, gbase, voff) do { _Pragma("unroll") for (int _i = 0; _i < 2; ++_i) \
;         __builtin_amdgcn_global_load_lds((const unsigned*)((const char*)(gbase) + (voff)[_i]), (PG8_LAS unsigned*)(lds + (bufoff) + ldsw + _i * 8192), 16, 0, 0); } while (0)
; #define PG8_LDA(dst, b, h) do { _Pragma("unroll") for (int m = 0; m < 4; ++m) _Pragma("unroll") for (int k = 0; k < 2; ++k) dst[m][k] = *(const PG8_LAS bf16x8*)(lds + PG8_SA(b, h) + aoff + m * 2048 + k * 1024); } while (0)
; #define PG8_MMA(ai, bj, At, Bt) do { __builtin_amdgcn_s_setprio(1); _Pragma("unroll") for (int m = 0; m < 4; ++m) _Pragma("unroll") for (int n = 0; n < 2; ++n) _Pragma("unroll") for (int k = 0; k < 2; ++k) \
;         acc[ai][bj][m][n] = __builtin_amdgcn_mfma_f32_16x16x32_bf16(Bt[n][k], At[m][k], acc[ai][bj][m][n], 0, 0, 0); __builtin_amdgcn_s_setprio(0); } while (0)
; #define PG8_WAIT_V(n) asm volatile("s_waitcnt vmcnt(" #n ")" ::: "memory")
; #define PG8_WAIT_L(n) asm volatile("s_waitcnt lgkmcnt(" #n ")" ::: "memory")
; #define PG8_BAR __builtin_amdgcn_s_barrier()
; #define PG8_SCHED __builtin_amdgcn_sched_barrier(0)
; template <class Epi, class Sched, bool ALIGN_EPI = false, bool SP2 = false>
; __device__ __forceinline__ void gemm_phase(PG8_LAS unsigned char* lds, const Gemm g, const Sched& S, const Epi& E, const int tid) {
;     ...
;             PG8_LDA(At, 1, 1); PG8_STAGE(PG8_SB(1, 0), b3, voffB); PG8_STAGE(PG8_SB(1, 1), b3 + hstep, voffB); PG8_STAGE(PG8_SA(1, 0), a3, voffA);
;             PG8_WAIT_V(8); PG8_WAIT_L(0); PG8_BAR; PG8_MMA(1, 0, At, B0); PG8_MMA(1, 1, At, B1); PG8_BAR; PG8_SCHED;
;     ...
;         if constexpr (ALIGN_EPI) { if (wr == 0) PG8_BAR; }
	s_add_i32 s42, s47, s62
	v_lshl_add_u64 v[88:89], v[194:195], 0, s[2:3]
	s_mov_b32 m0, s42
	s_nop 1
	ds_read_b128 v[64:67], v240 offset:49152
	ds_read_b128 v[68:71], v240 offset:50176
	ds_read_b128 v[80:83], v240 offset:51200
	ds_read_b128 v[84:87], v240 offset:52224
	ds_read_b128 v[104:107], v240 offset:53248
	ds_read_b128 v[108:111], v240 offset:54272
	ds_read_b128 v[222:225], v240 offset:55296
	ds_read_b128 v[226:229], v240 offset:56320
	global_load_lds_dwordx4 v[88:89], off
	s_add_i32 m0, s42, 0x2000
	s_add_u32 s12, s12, 0x80080
	v_lshl_add_u64 v[88:89], v[206:207], 0, s[2:3]
	s_addc_u32 s13, s13, 0
	s_add_i32 s42, s48, s62
	global_load_lds_dwordx4 v[88:89], off
	v_lshl_add_u64 v[88:89], s[12:13], 0, v[178:179]
	s_mov_b32 m0, s42
	s_nop 0
	global_load_lds_dwordx4 v[88:89], off
	v_lshl_add_u64 v[88:89], s[12:13], 0, v[182:183]
	s_add_i32 m0, s42, 0x2000
	s_nop 0
	global_load_lds_dwordx4 v[88:89], off
	v_lshl_add_u64 v[88:89], v[210:211], 0, s[2:3]
	s_mov_b32 m0, s70
	s_nop 0
	global_load_lds_dwordx4 v[88:89], off
	v_lshl_add_u64 v[88:89], v[234:235], 0, s[2:3]
	s_mov_b32 m0, s71
	s_nop 0
	global_load_lds_dwordx4 v[88:89], off
	s_waitcnt vmcnt(8)
	s_waitcnt lgkmcnt(0)
	s_barrier
	s_setprio 1
	s_waitcnt lgkmcnt(0)
	v_mfma_f32_16x16x32_bf16 v[88:91], v[40:43], v[64:67], v[100:103]
	v_mfma_f32_16x16x32_bf16 v[100:103], v[44:47], v[68:71], v[88:91]
	v_mfma_f32_16x16x32_bf16 v[88:91], v[56:59], v[64:67], v[96:99]
	v_mfma_f32_16x16x32_bf16 v[76:79], v[40:43], v[80:83], v[76:79]
	v_mfma_f32_16x16x32_bf16 v[72:75], v[56:59], v[80:83], v[72:75]
	v_mfma_f32_16x16x32_bf16 v[52:55], v[40:43], v[104:107], v[52:55]
	v_mfma_f32_16x16x32_bf16 v[48:51], v[56:59], v[104:107], v[48:51]
	v_mfma_f32_16x16x32_bf16 v[12:15], v[40:43], v[222:225], v[12:15]
	v_mfma_f32_16x16x32_bf16 v[8:11], v[56:59], v[222:225], v[8:11]
	v_mfma_f32_16x16x32_bf16 v[96:99], v[60:63], v[68:71], v[88:91]
	v_mfma_f32_16x16x32_bf16 v[76:79], v[44:47], v[84:87], v[76:79]
	v_mfma_f32_16x16x32_bf16 v[72:75], v[60:63], v[84:87], v[72:75]
	v_mfma_f32_16x16x32_bf16 v[52:55], v[44:47], v[108:111], v[52:55]
	v_mfma_f32_16x16x32_bf16 v[48:51], v[60:63], v[108:111], v[48:51]
	v_mfma_f32_16x16x32_bf16 v[12:15], v[44:47], v[226:229], v[12:15]
	v_mfma_f32_16x16x32_bf16 v[8:11], v[60:63], v[226:229], v[8:11]
	s_setprio 0
	s_setprio 1
	v_mfma_f32_16x16x32_bf16 v[16:19], v[198:201], v[64:67], v[16:19]
	v_mfma_f32_16x16x32_bf16 v[92:95], v[202:205], v[68:71], v[16:19]
	v_mfma_f32_16x16x32_bf16 v[16:19], v[214:217], v[64:67], v[20:23]
	v_mfma_f32_16x16x32_bf16 v[88:91], v[218:221], v[68:71], v[16:19]
	v_mfma_f32_16x16x32_bf16 v[16:19], v[198:201], v[80:83], v[24:27]
	v_mfma_f32_16x16x32_bf16 v[68:71], v[202:205], v[84:87], v[16:19]
	v_mfma_f32_16x16x32_bf16 v[16:19], v[214:217], v[80:83], v[28:31]
	v_mfma_f32_16x16x32_bf16 v[64:67], v[218:221], v[84:87], v[16:19]
	v_mfma_f32_16x16x32_bf16 v[16:19], v[198:201], v[104:107], v[36:39]
	v_mfma_f32_16x16x32_bf16 v[36:39], v[202:205], v[108:111], v[16:19]
	v_mfma_f32_16x16x32_bf16 v[16:19], v[214:217], v[104:107], v[32:35]
	v_mfma_f32_16x16x32_bf16 v[4:7], v[198:201], v[222:225], v[4:7]
	v_mfma_f32_16x16x32_bf16 v[0:3], v[214:217], v[222:225], v[0:3]
	v_mfma_f32_16x16x32_bf16 v[32:35], v[218:221], v[108:111], v[16:19]
	v_mfma_f32_16x16x32_bf16 v[4:7], v[202:205], v[226:229], v[4:7]
	v_mfma_f32_16x16x32_bf16 v[0:3], v[218:221], v[226:229], v[0:3]
	s_setprio 0
	s_barrier
	s_add_i32 s46, s46, 2
	s_add_u32 s10, s10, 0x100
	s_addc_u32 s11, s11, 0
	s_add_u32 s44, s44, 0x100
	s_addc_u32 s45, s45, 0
	s_cmp_gt_u32 s46, 29
	s_cbranch_scc0 .LBB0_341
	s_cmpk_lt_i32 s0, 0x80
	s_cselect_b64 s[42:43], -1, 0
	s_cmpk_gt_i32 s0, 0x7f
	s_cselect_b64 s[44:45], -1, 0
	s_mov_b64 s[10:11], 0x3400
	s_and_b64 vcc, exec, s[44:45]
	s_cbranch_vccnz .LBB0_346
	s_ashr_i32 s1, s0, 5
	s_mul_hi_i32 s11, s1, 0xd00
	s_mul_i32 s10, s1, 0xd00

;     __device__ __forceinline__ void operator()(const f32x4 (&acc)[2][2][4][2], const Unit& un, int wr, int wc, int fr, int fq) const {
;         const int pn = un.pn, rbase = un.pm * 256 + wr * 64 + fr, cw = wc * 32 + 8 * fq;
;         const bool lat = un.pm < (NLAT / 256);
;         const float* sw = shw + (size_t)(lat ? (un.pm >> 5) : 4) * INC + pn * 256 + cw;
;         f32x4 s0[2], s1[2]; float rr[2][4];
; #pragma unroll
;         for (int bj = 0; bj < 2; ++bj) { s0[bj] = *(const f32x4*)(sw + bj * 128); s1[bj] = *(const f32x4*)(sw + bj * 128 + 4); }
; #pragma unroll
;         for (int ai = 0; ai < 2; ++ai)
; #pragma unroll
;             for (int m = 0; m < 4; ++m) rr[ai][m] = rs[rbase + ai * 128 + m * 16];
;         const bool ropetile = lat && pn >= 8 && pn <= 10; const int pih_ = cw & 63, half_ = pih_ >> 5, i0_ = (pih_ & 31) >> 1;
; #pragma unroll
;         for (int ai = 0; ai < 2; ++ai) {
;         f32x4 rp[4][2];
;         if (ropetile) {
; #pragma unroll
;             for (int m = 0; m < 4; ++m) { const int t = (rbase + ai * 128 + m * 16) & (SEQ - 1), pos = half_ ? (t & 63) : (t >> 6); const f32x4* rq = (const f32x4*)(rope + pos * 16 + i0_); rp[m][0] = rq[0]; rp[m][1] = rq[1]; } }
; #pragma unroll
;         for (int m = 0; m < 4; ++m)
; #pragma unroll
;         for (int bj = 0; bj < 2; ++bj) {
;             const int row = rbase + ai * 128 + m * 16; const int ct = bj * 128 + cw;
;             const f32x4 v0 = acc[ai][bj][m][0] * rr[ai][m] + s0[bj], v1 = acc[ai][bj][m][1] * rr[ai][m] + s1[bj];
;             if (pn < 4) {
;                 u32x4 w; w.x = pk2(gelu_tanh(v0.x), gelu_tanh(v0.y)); w.y = pk2(gelu_tanh(v0.z), gelu_tanh(v0.w)); w.z = pk2(gelu_tanh(v1.x), gelu_tanh(v1.y)); w.w = pk2(gelu_tanh(v1.z), gelu_tanh(v1.w));
;                 *(u32x4*)(ga + (size_t)row * 1024 + pn * 256 + ct) = w;
;             } else if (pn < 8) {
;                 u32x2 w; w.x = pk2(v0.x * sigmoidf_(v0.y), v0.z * sigmoidf_(v0.w)); w.y = pk2(v1.x * sigmoidf_(v1.y), v1.z * sigmoidf_(v1.w));
;                 *(u32x2*)(yb + (size_t)row * 512 + (((pn - 4) * 256 + ct) >> 1)) = w;
;             } else if (pn < 10 || (pn == 10 && bj == 0)) {
;                 const bool isq = pn < 10; const int cs = isq ? (pn - 8) * 256 + ct : ct;
;                 float x[8] = {v0.x, v0.y, v0.z, v0.w, v1.x, v1.y, v1.z, v1.w};
.LBB0_348:
	s_xor_b64 s[12:13], s[10:11], -1
	s_cmp_gt_i32 s8, 3
	s_cselect_b64 s[52:53], -1, 0
	s_cmp_gt_u32 s8, 9
	s_cselect_b64 s[48:49], -1, 0
	s_cmp_lt_u32 s8, 10
	s_cselect_b64 vcc, -1, 0
	s_cmp_lg_u32 s8, 10
	v_mov_b32_e32 v195, 0x3e38aa3b
	s_mov_b64 s[54:55], -1
	s_cselect_b64 s[46:47], -1, 0
	s_add_i32 s75, s50, 0xfffff500
	s_add_i32 s37, s50, 0xfffff800
	v_cndmask_b32_e32 v196, 1.0, v195, vcc
	s_add_i32 s35, s50, 0xfffffc00
	v_lshlrev_b64 v[224:225], 10, v[198:199]
	s_and_b64 vcc, exec, s[30:31]
	s_cbranch_vccz .LBB0_344
	s_barrier
.LBB0_344:
	s_waitcnt vmcnt(0)
	v_pk_fma_f32 v[228:229], v[174:175], v[226:227], v[46:47] op_sel_hi:[1,0,1]
	v_pk_fma_f32 v[230:231], v[172:173], v[226:227], v[44:45] op_sel_hi:[1,0,1]
	v_pk_fma_f32 v[172:173], v[170:171], v[226:227], v[42:43] op_sel_hi:[1,0,1]
	v_pk_fma_f32 v[174:175], v[168:169], v[226:227], v[40:41] op_sel_hi:[1,0,1]
	s_and_b64 vcc, exec, s[52:53]
	s_cbranch_vccz .LBB0_368
	s_mov_b64 s[8:9], -1
	s_and_b64 vcc, exec, s[12:13]
	s_cbranch_vccz .LBB0_365
	s_andn2_b64 vcc, exec, s[48:49]
	s_cbranch_vccnz .LBB0_354
	s_and_b64 vcc, exec, s[46:47]
	s_cbranch_vccz .LBB0_353
	v_or_b32_e32 v195, s75, v184
	v_lshrrev_b32_e32 v195, 4, v195
	s_mov_b32 s8, 0x8400
	v_mad_u64_u32 v[210:211], s[8:9], v195, s8, v[198:199]
	v_lshlrev_b64 v[210:211], 5, v[210:211]
	v_cvt_pk_bf16_f32 v168, v230, v231
	v_cvt_pk_bf16_f32 v169, v228, v229
	v_cvt_pk_bf16_f32 v170, v174, v175
	v_cvt_pk_bf16_f32 v171, v172, v173
	v_lshl_add_u64 v[210:211], v[186:187], 0, v[210:211]
	global_store_dwordx4 v[210:211], v[168:171], off
	s_mov_b64 s[8:9], 0

;     __host__ __device__ bool next(int i, Unit& u) const { const int L = base + i * Gp + cp; if (L >= end) return false; return T.next(L, u); }
;     __host__ __device__ bool next(int i, Unit& u) const { const int L = i * Gp + cp; if (cp < 0 || L >= n) return false; u.kb = L & 3; u.pn = (L >> 2) % nN; u.pm = pm0 + (L >> 2) / nN; return true; }
;     __host__ __device__ bool next(int i, Unit& u) const { const bool ok = T.next(i >> 2, u); u.kb = i & 3; return ok; }
; #define PG8_BAR __builtin_amdgcn_s_barrier()
; template <class Epi, class Sched, bool ALIGN_EPI = false, bool SP2 = false>
; __device__ __forceinline__ void gemm_phase(PG8_LAS unsigned char* lds, const Gemm g, const Sched& S, const Epi& E, const int tid) {
;     ...
;         const bool has_next = S.next(ui + 1, nxt);
;         const char* nA = has_next ? (const char*)g.A + (size_t)nxt.pm * tstep + (size_t)nxt.kb * g.sA : cA; const char* nB = has_next ? (const char*)g.Bt + (size_t)nxt.pn * tstep + (size_t)nxt.kb * g.sB : cB;
;         for (int t = 0; t < nt; t += 2) {
;             const bool last = (t == nt - 2);
;             const char* a1 = cA + (size_t)(t + 1) * kstep;
;             const char* a2 = last ? nA : cA + (size_t)(t + 2) * kstep; const char* b2 = last ? nB : cB + (size_t)(t + 2) * kstep;
;     ...
; #pragma unroll
;         for (int a = 0; a < 2; ++a)
; #pragma unroll
;             for (int b = 0; b < 2; ++b)
; #pragma unroll
;                 for (int m = 0; m < 4; ++m)
; #pragma unroll
;                     for (int n = 0; n < 2; ++n) acc[a][b][m][n] = (f32x4){0.f, 0.f, 0.f, 0.f};
;         cur = nxt; cA = nA; cB = nB; ++ui;
;         if constexpr (ALIGN_EPI) { if (wr == 1) PG8_BAR; }
.LBB0_767:
	s_ashr_i32 s15, s14, 31
	s_lshl_b64 s[16:17], s[14:15], 20
	s_add_u32 s16, s34, s16
	s_addc_u32 s17, s35, s17
	s_and_b64 s[18:19], s[12:13], exec
	s_cselect_b32 s15, s17, s25
	s_cselect_b32 s21, s16, s24
	s_ashr_i32 s11, s10, 31
	s_lshl_b64 s[18:19], s[10:11], 20
	s_add_u32 s18, s36, s18
	s_addc_u32 s19, s37, s19
	s_and_b64 s[28:29], s[12:13], exec
	s_cselect_b32 s11, s19, s27
	s_cselect_b32 s48, s18, s26
	s_add_u32 s24, s24, 0x80080
	s_addc_u32 s25, s25, 0
	s_add_u32 s49, s26, 0x100
	v_mov_b32_e32 v0, 0
	s_addc_u32 s50, s27, 0
	s_mov_b32 s51, -2
	s_cmp_eq_u32 s100, 0
	s_cbranch_scc1 .Lmy_nobar_768
	s_barrier
	s_mov_b32 s100, 0
; #define PG8_STAGE(bufoff, gbase, voff) do { _Pragma("unroll") for (int _i = 0; _i < 2; ++_i) \
;         __builtin_amdgcn_global_load_lds((const unsigned*)((const char*)(gbase) + (voff)[_i]), (PG8_LAS unsigned*)(lds + (bufoff) + ldsw + _i * 8192), 16, 0, 0); } while (0)
; #define PG8_LDA(dst, b, h) do { _Pragma("unroll") for (int m = 0; m < 4; ++m) _Pragma("unroll") for (int k = 0; k < 2; ++k) dst[m][k] = *(const PG8_LAS bf16x8*)(lds + PG8_SA(b, h) + aoff + m * 2048 + k * 1024); } while (0)
; #define PG8_LDB(dst, b, h) do { _Pragma("unroll") for (int n = 0; n < 2; ++n) _Pragma("unroll") for (int k = 0; k < 2; ++k) dst[n][k] = *(const PG8_LAS bf16x8*)(lds + PG8_SB(b, h) + boff + n * 2048 + k * 1024); } while (0)
; #define PG8_MMA(ai, bj, At, Bt) do { __builtin_amdgcn_s_setprio(1); _Pragma("unroll") for (int m = 0; m < 4; ++m) _Pragma("unroll") for (int n = 0; n < 2; ++n) _Pragma("unroll") for (int k = 0; k < 2; ++k) \
;         acc[ai][bj][m][n] = __builtin_amdgcn_mfma_f32_16x16x32_bf16(Bt[n][k], At[m][k], acc[ai][bj][m][n], 0, 0, 0); __builtin_amdgcn_s_setprio(0); } while (0)
; #define PG8_WAIT_V(n) asm volatile("s_waitcnt vmcnt(" #n ")" ::: "memory")
; #define PG8_WAIT_L(n) asm volatile("s_waitcnt lgkmcnt(" #n ")" ::: "memory")
; #define PG8_BAR __builtin_amdgcn_s_barrier()
; template <class Epi, class Sched, bool ALIGN_EPI = false, bool SP2 = false>
; __device__ __forceinline__ void gemm_phase(PG8_LAS unsigned char* lds, const Gemm g, const Sched& S, const Epi& E, const int tid) {
;     ...
;             const char* a1 = cA + (size_t)(t + 1) * kstep;
;             const char* a2 = last ? nA : cA + (size_t)(t + 2) * kstep; const char* b2 = last ? nB : cB + (size_t)(t + 2) * kstep;
;             const char* a3 = a2 + kstep; const char* b3 = b2 + kstep;
;             if (last && has_next) S.a_ready(nxt);
;             if constexpr (SP2) {
;             PG8_LDB(B0, 0, 0); PG8_LDB(B1, 0, 1); PG8_SCHED; PG8_LDA(At, 0, 0); PG8_STAGE(PG8_SA(1, 1), a1 + hstep, voffA);
;             PG8_WAIT_V(8); PG8_WAIT_L(0); PG8_BAR; PG8_MMA(0, 0, At, B0); PG8_MMA(0, 1, At, B1); PG8_BAR; PG8_SCHED;
;             PG8_LDA(At, 0, 1); PG8_STAGE(PG8_SB(0, 0), b2, voffB); PG8_STAGE(PG8_SB(0, 1), b2 + hstep, voffB); PG8_STAGE(PG8_SA(0, 0), a2, voffA);
;             PG8_WAIT_V(8); PG8_WAIT_L(0); PG8_BAR; PG8_MMA(1, 0, At, B0); PG8_MMA(1, 1, At, B1); PG8_BAR; PG8_SCHED;
.Lmy_nobar_768:
	s_add_u32 s26, s24, 0xfff80080
	s_addc_u32 s27, s25, -1
	s_add_i32 s52, 0, 0x10000
	v_add_u32_e32 v68, s52, v157
	v_add_u32_e32 v154, s33, v157
	ds_read_b128 v[48:51], v68
	ds_read_b128 v[52:55], v68 offset:1024
	ds_read_b128 v[64:67], v68 offset:2048
	ds_read_b128 v[68:71], v68 offset:3072
	ds_read_b128 v[162:165], v154
	ds_read_b128 v[166:169], v154 offset:1024
	ds_read_b128 v[170:173], v154 offset:2048
	ds_read_b128 v[174:177], v154 offset:3072
	s_cmp_eq_u32 s51, 28
	s_cselect_b32 s29, s15, s27
	s_cselect_b32 s28, s21, s26
	s_cselect_b32 s27, s11, s50
	s_cselect_b32 s26, s48, s49
	v_lshl_add_u64 v[206:207], s[24:25], 0, v[150:151]
	s_add_i32 m0, s23, 0xc000
	ds_read_b128 v[178:181], v161
	ds_read_b128 v[182:185], v161 offset:1024
	ds_read_b128 v[186:189], v161 offset:2048
	ds_read_b128 v[190:193], v161 offset:3072
	ds_read_b128 v[194:197], v161 offset:4096
	ds_read_b128 v[198:201], v161 offset:5120
	ds_read_b128 v[202:205], v161 offset:6144
	ds_read_b128 v[214:217], v161 offset:7168
	global_load_lds_dwordx4 v[206:207], off
	v_lshl_add_u64 v[206:207], s[24:25], 0, v[152:153]
	s_add_i32 m0, s23, 0xe000
	s_nop 0
	global_load_lds_dwordx4 v[206:207], off
	s_waitcnt vmcnt(8)
	s_waitcnt lgkmcnt(0)
	s_barrier
	s_setprio 1
	s_waitcnt lgkmcnt(0)
	v_mfma_f32_16x16x32_bf16 v[140:143], v[48:51], v[178:181], 0
	v_mfma_f32_16x16x32_bf16 v[136:139], v[64:67], v[178:181], 0
	v_mfma_f32_16x16x32_bf16 v[124:127], v[48:51], v[186:189], 0
	v_mfma_f32_16x16x32_bf16 v[120:123], v[64:67], v[186:189], 0
	v_mfma_f32_16x16x32_bf16 v[108:111], v[48:51], v[194:197], 0
	v_mfma_f32_16x16x32_bf16 v[104:107], v[64:67], v[194:197], 0
	v_mfma_f32_16x16x32_bf16 v[92:95], v[48:51], v[202:205], 0
	v_mfma_f32_16x16x32_bf16 v[88:91], v[64:67], v[202:205], 0
	v_mfma_f32_16x16x32_bf16 v[140:143], v[52:55], v[182:185], v[140:143]
	v_mfma_f32_16x16x32_bf16 v[136:139], v[68:71], v[182:185], v[136:139]
	v_mfma_f32_16x16x32_bf16 v[124:127], v[52:55], v[190:193], v[124:127]
	v_mfma_f32_16x16x32_bf16 v[120:123], v[68:71], v[190:193], v[120:123]
	v_mfma_f32_16x16x32_bf16 v[108:111], v[52:55], v[198:201], v[108:111]
	v_mfma_f32_16x16x32_bf16 v[104:107], v[68:71], v[198:201], v[104:107]
	v_mfma_f32_16x16x32_bf16 v[92:95], v[52:55], v[214:217], v[92:95]
	v_mfma_f32_16x16x32_bf16 v[88:91], v[68:71], v[214:217], v[88:91]
	s_setprio 0
	s_setprio 1
	v_mfma_f32_16x16x32_bf16 v[132:135], v[162:165], v[178:181], 0
	v_mfma_f32_16x16x32_bf16 v[128:131], v[170:173], v[178:181], 0
	v_mfma_f32_16x16x32_bf16 v[116:119], v[162:165], v[186:189], 0
	v_mfma_f32_16x16x32_bf16 v[112:115], v[170:173], v[186:189], 0
	v_mfma_f32_16x16x32_bf16 v[100:103], v[162:165], v[194:197], 0
	v_mfma_f32_16x16x32_bf16 v[96:99], v[170:173], v[194:197], 0
	v_mfma_f32_16x16x32_bf16 v[84:87], v[162:165], v[202:205], 0
	v_mfma_f32_16x16x32_bf16 v[80:83], v[170:173], v[202:205], 0
	v_mfma_f32_16x16x32_bf16 v[132:135], v[166:169], v[182:185], v[132:135]
	v_mfma_f32_16x16x32_bf16 v[128:131], v[174:177], v[182:185], v[128:131]
	v_mfma_f32_16x16x32_bf16 v[116:119], v[166:169], v[190:193], v[116:119]
	v_mfma_f32_16x16x32_bf16 v[112:115], v[174:177], v[190:193], v[112:115]
	v_mfma_f32_16x16x32_bf16 v[100:103], v[166:169], v[198:201], v[100:103]
	v_mfma_f32_16x16x32_bf16 v[96:99], v[174:177], v[198:201], v[96:99]
	v_mfma_f32_16x16x32_bf16 v[84:87], v[166:169], v[214:217], v[84:87]
	v_mfma_f32_16x16x32_bf16 v[80:83], v[174:177], v[214:217], v[80:83]
	s_setprio 0
	s_barrier
	s_add_i32 s52, s52, s38
	v_lshl_add_u64 v[206:207], s[26:27], 0, v[208:209]
	s_mov_b32 m0, s52
	ds_read_b128 v[178:181], v161 offset:16384
	ds_read_b128 v[182:185], v161 offset:17408
	ds_read_b128 v[186:189], v161 offset:18432
	ds_read_b128 v[190:193], v161 offset:19456
	ds_read_b128 v[194:197], v161 offset:20480
	ds_read_b128 v[198:201], v161 offset:21504
	ds_read_b128 v[202:205], v161 offset:22528
	ds_read_b128 v[214:217], v161 offset:23552
	global_load_lds_dwordx4 v[206:207], off
	s_add_i32 m0, s52, 0x2000
	s_add_u32 s52, s26, 0x80000
	v_lshl_add_u64 v[210:211], s[26:27], 0, v[144:145]
	s_addc_u32 s53, s27, 0
	s_add_i32 s54, s33, s38
	global_load_lds_dwordx4 v[210:211], off
	v_lshl_add_u64 v[218:219], s[52:53], 0, v[208:209]
	s_mov_b32 m0, s54
	v_lshl_add_u64 v[220:221], s[28:29], 0, v[146:147]
	global_load_lds_dwordx4 v[218:219], off
	v_lshl_add_u64 v[218:219], s[52:53], 0, v[144:145]
	s_add_i32 m0, s54, 0x2000
	s_nop 0
	global_load_lds_dwordx4 v[218:219], off
	v_lshl_add_u64 v[218:219], s[28:29], 0, v[148:149]
	s_mov_b32 m0, s23
	s_nop 0
	global_load_lds_dwordx4 v[218:219], off
	s_mov_b32 m0, s39
	s_nop 0
	global_load_lds_dwordx4 v[220:221], off
	s_waitcnt vmcnt(8)
	s_waitcnt lgkmcnt(0)
	s_barrier
	s_setprio 1
	s_waitcnt lgkmcnt(0)
	v_mfma_f32_16x16x32_bf16 v[76:79], v[48:51], v[178:181], 0
	v_mfma_f32_16x16x32_bf16 v[72:75], v[64:67], v[178:181], 0
	v_mfma_f32_16x16x32_bf16 v[44:47], v[48:51], v[186:189], 0
	v_mfma_f32_16x16x32_bf16 v[40:43], v[64:67], v[186:189], 0
	v_mfma_f32_16x16x32_bf16 v[28:31], v[48:51], v[194:197], 0
	v_mfma_f32_16x16x32_bf16 v[24:27], v[64:67], v[194:197], 0
	v_mfma_f32_16x16x32_bf16 v[12:15], v[48:51], v[202:205], 0
	v_mfma_f32_16x16x32_bf16 v[8:11], v[64:67], v[202:205], 0
	v_mfma_f32_16x16x32_bf16 v[76:79], v[52:55], v[182:185], v[76:79]
	v_mfma_f32_16x16x32_bf16 v[72:75], v[68:71], v[182:185], v[72:75]
	v_mfma_f32_16x16x32_bf16 v[44:47], v[52:55], v[190:193], v[44:47]
	v_mfma_f32_16x16x32_bf16 v[40:43], v[68:71], v[190:193], v[40:43]
	v_mfma_f32_16x16x32_bf16 v[28:31], v[52:55], v[198:201], v[28:31]
	v_mfma_f32_16x16x32_bf16 v[24:27], v[68:71], v[198:201], v[24:27]
	v_mfma_f32_16x16x32_bf16 v[12:15], v[52:55], v[214:217], v[12:15]
	v_mfma_f32_16x16x32_bf16 v[8:11], v[68:71], v[214:217], v[8:11]
	s_setprio 0
	s_setprio 1
	v_mfma_f32_16x16x32_bf16 v[36:39], v[162:165], v[186:189], 0
	v_mfma_f32_16x16x32_bf16 v[32:35], v[170:173], v[186:189], 0
	v_mfma_f32_16x16x32_bf16 v[20:23], v[162:165], v[194:197], 0
	v_mfma_f32_16x16x32_bf16 v[16:19], v[170:173], v[194:197], 0
	v_mfma_f32_16x16x32_bf16 v[4:7], v[162:165], v[202:205], 0
	v_mfma_f32_16x16x32_bf16 v[0:3], v[170:173], v[202:205], 0
	v_mfma_f32_16x16x32_bf16 v[48:51], v[162:165], v[178:181], 0
	v_mfma_f32_16x16x32_bf16 v[52:55], v[170:173], v[178:181], 0
	v_mfma_f32_16x16x32_bf16 v[36:39], v[166:169], v[190:193], v[36:39]
	v_mfma_f32_16x16x32_bf16 v[32:35], v[174:177], v[190:193], v[32:35]
	v_mfma_f32_16x16x32_bf16 v[20:23], v[166:169], v[198:201], v[20:23]
	v_mfma_f32_16x16x32_bf16 v[16:19], v[174:177], v[198:201], v[16:19]
	v_mfma_f32_16x16x32_bf16 v[4:7], v[166:169], v[214:217], v[4:7]
	v_mfma_f32_16x16x32_bf16 v[0:3], v[174:177], v[214:217], v[0:3]
	v_mfma_f32_16x16x32_bf16 v[48:51], v[166:169], v[182:185], v[48:51]
	v_mfma_f32_16x16x32_bf16 v[52:55], v[174:177], v[182:185], v[52:55]
	s_setprio 0
	s_barrier
	s_branch .Lmy_mid_768

; #define PG8_STAGE(bufoff, gbase, voff) do { _Pragma("unroll") for (int _i = 0; _i < 2; ++_i) \
;         __builtin_amdgcn_global_load_lds((const unsigned*)((const char*)(gbase) + (voff)[_i]), (PG8_LAS unsigned*)(lds + (bufoff) + ldsw + _i * 8192), 16, 0, 0); } while (0)
; #define PG8_LDA(dst, b, h) do { _Pragma("unroll") for (int m = 0; m < 4; ++m) _Pragma("unroll") for (int k = 0; k < 2; ++k) dst[m][k] = *(const PG8_LAS bf16x8*)(lds + PG8_SA(b, h) + aoff + m * 2048 + k * 1024); } while (0)
; #define PG8_LDB(dst, b, h) do { _Pragma("unroll") for (int n = 0; n < 2; ++n) _Pragma("unroll") for (int k = 0; k < 2; ++k) dst[n][k] = *(const PG8_LAS bf16x8*)(lds + PG8_SB(b, h) + boff + n * 2048 + k * 1024); } while (0)
; #define PG8_MMA(ai, bj, At, Bt) do { __builtin_amdgcn_s_setprio(1); _Pragma("unroll") for (int m = 0; m < 4; ++m) _Pragma("unroll") for (int n = 0; n < 2; ++n) _Pragma("unroll") for (int k = 0; k < 2; ++k) \
;         acc[ai][bj][m][n] = __builtin_amdgcn_mfma_f32_16x16x32_bf16(Bt[n][k], At[m][k], acc[ai][bj][m][n], 0, 0, 0); __builtin_amdgcn_s_setprio(0); } while (0)
; #define PG8_WAIT_V(n) asm volatile("s_waitcnt vmcnt(" #n ")" ::: "memory")
; #define PG8_WAIT_L(n) asm volatile("s_waitcnt lgkmcnt(" #n ")" ::: "memory")
; #define PG8_BAR __builtin_amdgcn_s_barrier()
; #define PG8_SCHED __builtin_amdgcn_sched_barrier(0)
; template <class Epi, class Sched, bool ALIGN_EPI = false, bool SP2 = false>
; __device__ __forceinline__ void gemm_phase(PG8_LAS unsigned char* lds, const Gemm g, const Sched& S, const Epi& E, const int tid) {
;     ...
;             PG8_LDB(B0, 1, 0); PG8_LDB(B1, 1, 1); PG8_SCHED; PG8_LDA(At, 1, 0); PG8_STAGE(PG8_SA(0, 1), a2 + hstep, voffA);
;             PG8_WAIT_V(8); PG8_WAIT_L(0); PG8_BAR; PG8_MMA(0, 0, At, B0); PG8_MMA(0, 1, At, B1); PG8_BAR; PG8_SCHED;
;             PG8_LDA(At, 1, 1); PG8_STAGE(PG8_SB(1, 0), b3, voffB); PG8_STAGE(PG8_SB(1, 1), b3 + hstep, voffB); PG8_STAGE(PG8_SA(1, 0), a3, voffA);
.Lmy_mid_768:
	s_add_i32 s52, 0, 0x18000
	s_add_i32 s53, 0, 0x1c000
	v_add_u32_e32 v68, s52, v157
	v_add_u32_e32 v154, s53, v157
	ds_read_b128 v[56:59], v68
	ds_read_b128 v[60:63], v68 offset:1024
	ds_read_b128 v[64:67], v68 offset:2048
	ds_read_b128 v[68:71], v68 offset:3072
	ds_read_b128 v[162:165], v154
	ds_read_b128 v[166:169], v154 offset:1024
	ds_read_b128 v[170:173], v154 offset:2048
	ds_read_b128 v[174:177], v154 offset:3072
	s_add_u32 s28, s28, 0x80000
	s_addc_u32 s29, s29, 0
	s_mov_b32 m0, s40
	v_lshl_add_u64 v[222:223], s[28:29], 0, v[148:149]
	ds_read_b128 v[178:181], v161 offset:32768
	ds_read_b128 v[182:185], v161 offset:33792
	ds_read_b128 v[186:189], v161 offset:34816
	ds_read_b128 v[190:193], v161 offset:35840
	ds_read_b128 v[194:197], v161 offset:36864
	ds_read_b128 v[198:201], v161 offset:37888
	ds_read_b128 v[202:205], v161 offset:38912
	ds_read_b128 v[214:217], v161 offset:39936
	global_load_lds_dwordx4 v[222:223], off
	v_lshl_add_u64 v[222:223], s[28:29], 0, v[146:147]
	s_mov_b32 m0, s41
	s_nop 0
	global_load_lds_dwordx4 v[222:223], off
	s_waitcnt vmcnt(8)
	s_waitcnt lgkmcnt(0)
	s_barrier
	s_setprio 1
	s_waitcnt lgkmcnt(0)
	v_mfma_f32_16x16x32_bf16 v[140:143], v[56:59], v[178:181], v[140:143]
	v_mfma_f32_16x16x32_bf16 v[136:139], v[64:67], v[178:181], v[136:139]
	v_mfma_f32_16x16x32_bf16 v[124:127], v[56:59], v[186:189], v[124:127]
	v_mfma_f32_16x16x32_bf16 v[120:123], v[64:67], v[186:189], v[120:123]
	v_mfma_f32_16x16x32_bf16 v[108:111], v[56:59], v[194:197], v[108:111]
	v_mfma_f32_16x16x32_bf16 v[104:107], v[64:67], v[194:197], v[104:107]
	v_mfma_f32_16x16x32_bf16 v[92:95], v[56:59], v[202:205], v[92:95]
	v_mfma_f32_16x16x32_bf16 v[88:91], v[64:67], v[202:205], v[88:91]
	v_mfma_f32_16x16x32_bf16 v[140:143], v[60:63], v[182:185], v[140:143]
	v_mfma_f32_16x16x32_bf16 v[136:139], v[68:71], v[182:185], v[136:139]
	v_mfma_f32_16x16x32_bf16 v[124:127], v[60:63], v[190:193], v[124:127]
	v_mfma_f32_16x16x32_bf16 v[120:123], v[68:71], v[190:193], v[120:123]
	v_mfma_f32_16x16x32_bf16 v[108:111], v[60:63], v[198:201], v[108:111]
	v_mfma_f32_16x16x32_bf16 v[104:107], v[68:71], v[198:201], v[104:107]
	v_mfma_f32_16x16x32_bf16 v[92:95], v[60:63], v[214:217], v[92:95]
	v_mfma_f32_16x16x32_bf16 v[88:91], v[68:71], v[214:217], v[88:91]
	s_setprio 0
	s_setprio 1
	v_mfma_f32_16x16x32_bf16 v[132:135], v[162:165], v[178:181], v[132:135]
	v_mfma_f32_16x16x32_bf16 v[128:131], v[170:173], v[178:181], v[128:131]
	v_mfma_f32_16x16x32_bf16 v[116:119], v[162:165], v[186:189], v[116:119]
	v_mfma_f32_16x16x32_bf16 v[112:115], v[170:173], v[186:189], v[112:115]
	v_mfma_f32_16x16x32_bf16 v[100:103], v[162:165], v[194:197], v[100:103]
	v_mfma_f32_16x16x32_bf16 v[96:99], v[170:173], v[194:197], v[96:99]
	v_mfma_f32_16x16x32_bf16 v[84:87], v[162:165], v[202:205], v[84:87]
	v_mfma_f32_16x16x32_bf16 v[80:83], v[170:173], v[202:205], v[80:83]
	v_mfma_f32_16x16x32_bf16 v[132:135], v[166:169], v[182:185], v[132:135]
	v_mfma_f32_16x16x32_bf16 v[128:131], v[174:177], v[182:185], v[128:131]
	v_mfma_f32_16x16x32_bf16 v[116:119], v[166:169], v[190:193], v[116:119]
	v_mfma_f32_16x16x32_bf16 v[112:115], v[174:177], v[190:193], v[112:115]
	v_mfma_f32_16x16x32_bf16 v[100:103], v[166:169], v[198:201], v[100:103]
	v_mfma_f32_16x16x32_bf16 v[96:99], v[174:177], v[198:201], v[96:99]
	v_mfma_f32_16x16x32_bf16 v[84:87], v[166:169], v[214:217], v[84:87]
	v_mfma_f32_16x16x32_bf16 v[80:83], v[174:177], v[214:217], v[80:83]
	s_setprio 0
	s_barrier
	s_add_i32 s28, s52, s38
	v_lshl_add_u64 v[206:207], v[206:207], 0, s[2:3]
	s_mov_b32 m0, s28
	ds_read_b128 v[178:181], v161 offset:49152
	ds_read_b128 v[182:185], v161 offset:50176
	ds_read_b128 v[186:189], v161 offset:51200
	ds_read_b128 v[190:193], v161 offset:52224
	ds_read_b128 v[194:197], v161 offset:53248
	ds_read_b128 v[198:201], v161 offset:54272
	ds_read_b128 v[202:205], v161 offset:55296
	ds_read_b128 v[214:217], v161 offset:56320
	global_load_lds_dwordx4 v[206:207], off
	s_add_i32 m0, s28, 0x2000
	s_add_u32 s26, s26, 0x80080
	v_lshl_add_u64 v[206:207], v[210:211], 0, s[2:3]
	s_addc_u32 s27, s27, 0
	s_add_i32 s28, s53, s38
	global_load_lds_dwordx4 v[206:207], off
	v_lshl_add_u64 v[206:207], s[26:27], 0, v[208:209]
	s_mov_b32 m0, s28
	s_nop 0
	global_load_lds_dwordx4 v[206:207], off
	v_lshl_add_u64 v[206:207], s[26:27], 0, v[144:145]
	s_add_i32 m0, s28, 0x2000
	s_nop 0
	global_load_lds_dwordx4 v[206:207], off
	v_lshl_add_u64 v[206:207], v[218:219], 0, s[2:3]
	s_mov_b32 m0, s45
	s_nop 0
	global_load_lds_dwordx4 v[206:207], off
	v_lshl_add_u64 v[206:207], v[220:221], 0, s[2:3]
	s_mov_b32 m0, s46
	s_nop 0
	global_load_lds_dwordx4 v[206:207], off
	s_waitcnt vmcnt(8)
	s_waitcnt lgkmcnt(0)
	s_barrier
; #define PG8_STAGE(bufoff, gbase, voff) do { _Pragma("unroll") for (int _i = 0; _i < 2; ++_i) \
;         __builtin_amdgcn_global_load_lds((const unsigned*)((const char*)(gbase) + (voff)[_i]), (PG8_LAS unsigned*)(lds + (bufoff) + ldsw + _i * 8192), 16, 0, 0); } while (0)
; #define PG8_LDA(dst, b, h) do { _Pragma("unroll") for (int m = 0; m < 4; ++m) _Pragma("unroll") for (int k = 0; k < 2; ++k) dst[m][k] = *(const PG8_LAS bf16x8*)(lds + PG8_SA(b, h) + aoff + m * 2048 + k * 1024); } while (0)
; #define PG8_MMA(ai, bj, At, Bt) do { __builtin_amdgcn_s_setprio(1); _Pragma("unroll") for (int m = 0; m < 4; ++m) _Pragma("unroll") for (int n = 0; n < 2; ++n) _Pragma("unroll") for (int k = 0; k < 2; ++k) \
;         acc[ai][bj][m][n] = __builtin_amdgcn_mfma_f32_16x16x32_bf16(Bt[n][k], At[m][k], acc[ai][bj][m][n], 0, 0, 0); __builtin_amdgcn_s_setprio(0); } while (0)
; #define PG8_WAIT_V(n) asm volatile("s_waitcnt vmcnt(" #n ")" ::: "memory")
; #define PG8_WAIT_L(n) asm volatile("s_waitcnt lgkmcnt(" #n ")" ::: "memory")
; #define PG8_BAR __builtin_amdgcn_s_barrier()
; #define PG8_SCHED __builtin_amdgcn_sched_barrier(0)
; template <class Epi, class Sched, bool ALIGN_EPI = false, bool SP2 = false>
; __device__ __forceinline__ void gemm_phase(PG8_LAS unsigned char* lds, const Gemm g, const Sched& S, const Epi& E, const int tid) {
;     ...
;             PG8_LDA(At, 1, 1); PG8_STAGE(PG8_SB(1, 0), b3, voffB); PG8_STAGE(PG8_SB(1, 1), b3 + hstep, voffB); PG8_STAGE(PG8_SA(1, 0), a3, voffA);
;             PG8_WAIT_V(8); PG8_WAIT_L(0); PG8_BAR; PG8_MMA(1, 0, At, B0); PG8_MMA(1, 1, At, B1); PG8_BAR; PG8_SCHED;
;     __device__ __forceinline__ void operator()(const f32x4 (&acc)[2][2][4][2], const Unit& un, int wr, int wc, int fr, int fq) const {
;         const int rbase = un.pm * 256 + wr * 64 + fr, cw = un.pn * 256 + wc * 32 + 8 * fq;
;         const int slot = un.pm < (NLAT / 256) ? (un.pm >> 5) : 4; const float* sw = shw + (size_t)slot * DFF;
;         f32x4 s0[2], s1[2]; float rr[2][4];
; #pragma unroll
;         for (int bj = 0; bj < 2; ++bj) { s0[bj] = *(const f32x4*)(sw + cw + bj * 128); s1[bj] = *(const f32x4*)(sw + cw + bj * 128 + 4); }
; #pragma unroll
;         for (int ai = 0; ai < 2; ++ai)
; #pragma unroll
;             for (int m = 0; m < 4; ++m) rr[ai][m] = rs[rbase + ai * 128 + m * 16];
	s_setprio 1
	s_waitcnt lgkmcnt(0)
	v_mfma_f32_16x16x32_bf16 v[76:79], v[56:59], v[178:181], v[76:79]
	v_mfma_f32_16x16x32_bf16 v[72:75], v[64:67], v[178:181], v[72:75]
	v_mfma_f32_16x16x32_bf16 v[44:47], v[56:59], v[186:189], v[44:47]
	v_mfma_f32_16x16x32_bf16 v[40:43], v[64:67], v[186:189], v[40:43]
	v_mfma_f32_16x16x32_bf16 v[28:31], v[56:59], v[194:197], v[28:31]
	v_mfma_f32_16x16x32_bf16 v[24:27], v[64:67], v[194:197], v[24:27]
	v_mfma_f32_16x16x32_bf16 v[12:15], v[56:59], v[202:205], v[12:15]
	v_mfma_f32_16x16x32_bf16 v[8:11], v[64:67], v[202:205], v[8:11]
	v_mfma_f32_16x16x32_bf16 v[76:79], v[60:63], v[182:185], v[76:79]
	v_mfma_f32_16x16x32_bf16 v[72:75], v[68:71], v[182:185], v[72:75]
	v_mfma_f32_16x16x32_bf16 v[44:47], v[60:63], v[190:193], v[44:47]
	v_mfma_f32_16x16x32_bf16 v[40:43], v[68:71], v[190:193], v[40:43]
	v_mfma_f32_16x16x32_bf16 v[28:31], v[60:63], v[198:201], v[28:31]
	v_mfma_f32_16x16x32_bf16 v[24:27], v[68:71], v[198:201], v[24:27]
	v_mfma_f32_16x16x32_bf16 v[12:15], v[60:63], v[214:217], v[12:15]
	v_mfma_f32_16x16x32_bf16 v[8:11], v[68:71], v[214:217], v[8:11]
	s_setprio 0
	s_setprio 1
	v_mfma_f32_16x16x32_bf16 v[48:51], v[162:165], v[178:181], v[48:51]
	v_mfma_f32_16x16x32_bf16 v[60:63], v[166:169], v[182:185], v[48:51]
	v_mfma_f32_16x16x32_bf16 v[48:51], v[170:173], v[178:181], v[52:55]
	v_mfma_f32_16x16x32_bf16 v[36:39], v[162:165], v[186:189], v[36:39]
	v_mfma_f32_16x16x32_bf16 v[32:35], v[170:173], v[186:189], v[32:35]
	v_mfma_f32_16x16x32_bf16 v[20:23], v[162:165], v[194:197], v[20:23]
	v_mfma_f32_16x16x32_bf16 v[16:19], v[170:173], v[194:197], v[16:19]
	v_mfma_f32_16x16x32_bf16 v[4:7], v[162:165], v[202:205], v[4:7]
	v_mfma_f32_16x16x32_bf16 v[0:3], v[170:173], v[202:205], v[0:3]
	v_mfma_f32_16x16x32_bf16 v[56:59], v[174:177], v[182:185], v[48:51]
	v_mfma_f32_16x16x32_bf16 v[36:39], v[166:169], v[190:193], v[36:39]
	v_mfma_f32_16x16x32_bf16 v[32:35], v[174:177], v[190:193], v[32:35]
	v_mfma_f32_16x16x32_bf16 v[20:23], v[166:169], v[198:201], v[20:23]
	v_mfma_f32_16x16x32_bf16 v[16:19], v[174:177], v[198:201], v[16:19]
	v_mfma_f32_16x16x32_bf16 v[4:7], v[166:169], v[214:217], v[4:7]
	v_mfma_f32_16x16x32_bf16 v[0:3], v[174:177], v[214:217], v[0:3]
	s_setprio 0
	s_barrier
	s_add_i32 s51, s51, 2
	s_add_u32 s24, s24, 0x100
	s_addc_u32 s25, s25, 0
	s_add_u32 s49, s49, 0x100
	s_addc_u32 s50, s50, 0
	s_cmp_gt_u32 s51, 29
	s_cbranch_scc0 .LBB0_768
	s_ashr_i32 s24, s20, 5
	s_ashr_i32 s25, s24, 31
	s_lshl_b64 s[24:25], s[24:25], 13
	s_cmpk_lt_i32 s20, 0x80
	s_cselect_b32 s25, s25, 0
	s_cselect_b32 s24, s24, 0x8000
	s_lshl_b64 s[24:25], s[24:25], 2
	v_lshl_or_b32 v176, s22, 8, v159
	s_add_u32 s24, s42, s24
	v_lshl_add_u32 v178, s20, 8, v155
	s_addc_u32 s25, s43, s25
	v_ashrrev_i32_e32 v177, 31, v176
	v_ashrrev_i32_e32 v179, 31, v178
	v_lshl_add_u64 v[52:53], v[176:177], 2, s[24:25]
	v_lshl_add_u64 v[180:181], v[178:179], 2, s[6:7]
	global_load_dwordx4 v[64:67], v[52:53], off offset:16
	global_load_dwordx4 v[68:71], v[52:53], off
	global_load_dwordx4 v[48:51], v[52:53], off offset:528
	s_nop 0
	global_load_dwordx4 v[52:55], v[52:53], off offset:512
	v_or_b32_e32 v172, 16, v178
	global_load_dword v174, v[180:181], off
	v_ashrrev_i32_e32 v173, 31, v172
	v_lshl_add_u64 v[162:163], v[172:173], 2, s[6:7]
	global_load_dword v170, v[162:163], off
	v_or_b32_e32 v168, 32, v178
	v_ashrrev_i32_e32 v169, 31, v168
	v_lshl_add_u64 v[162:163], v[168:169], 2, s[6:7]
	global_load_dword v166, v[162:163], off
	v_or_b32_e32 v164, 48, v178
	v_lshlrev_b64 v[178:179], 14, v[178:179]
	v_ashrrev_i32_e32 v165, 31, v164
	v_lshl_add_u64 v[162:163], v[164:165], 2, s[6:7]
	global_load_dword v162, v[162:163], off
	s_nop 0
	global_load_dword v160, v[180:181], off offset:512
	global_load_dword v158, v[180:181], off offset:576
	global_load_dword v156, v[180:181], off offset:640
	global_load_dword v154, v[180:181], off offset:704
	s_and_b64 vcc, exec, s[8:9]
	s_cbranch_vccz .LBB0_771
	s_barrier

;     __host__ __device__ bool next(int i, Unit& u) const { const int L = base + i * Gp + cp; if (L >= end) return false; return T.next(L, u); }
;     __host__ __device__ bool next(int i, Unit& u) const { const int L = i * Gp + cp; if (cp < 0 || L >= n) return false; u.kb = L & 3; u.pn = (L >> 2) % nN; u.pm = pm0 + (L >> 2) / nN; return true; }
;     __host__ __device__ bool next(int i, Unit& u) const { const bool ok = T.next(i >> 2, u); u.kb = i & 3; return ok; }
; #define PG8_BAR __builtin_amdgcn_s_barrier()
; template <class Epi, class Sched, bool ALIGN_EPI = false, bool SP2 = false>
; __device__ __forceinline__ void gemm_phase(PG8_LAS unsigned char* lds, const Gemm g, const Sched& S, const Epi& E, const int tid) {
;     ...
;         const bool has_next = S.next(ui + 1, nxt);
;         const char* nA = has_next ? (const char*)g.A + (size_t)nxt.pm * tstep + (size_t)nxt.kb * g.sA : cA; const char* nB = has_next ? (const char*)g.Bt + (size_t)nxt.pn * tstep + (size_t)nxt.kb * g.sB : cB;
;         for (int t = 0; t < nt; t += 2) {
;             const bool last = (t == nt - 2);
;             const char* a1 = cA + (size_t)(t + 1) * kstep;
;             const char* a2 = last ? nA : cA + (size_t)(t + 2) * kstep; const char* b2 = last ? nB : cB + (size_t)(t + 2) * kstep;
;     ...
; #pragma unroll
;         for (int a = 0; a < 2; ++a)
; #pragma unroll
;             for (int b = 0; b < 2; ++b)
; #pragma unroll
;                 for (int m = 0; m < 4; ++m)
; #pragma unroll
;                     for (int n = 0; n < 2; ++n) acc[a][b][m][n] = (f32x4){0.f, 0.f, 0.f, 0.f};
;         cur = nxt; cA = nA; cB = nB; ++ui;
;         if constexpr (ALIGN_EPI) { if (wr == 1) PG8_BAR; }
.LBB0_1030:
	s_ashr_i32 s13, s12, 31
	s_lshl_b64 s[14:15], s[12:13], 18
	s_add_u32 s14, s30, s14
	s_addc_u32 s15, s31, s15
	s_and_b64 s[16:17], s[0:1], exec
	s_cselect_b32 s13, s15, s23
	s_cselect_b32 s19, s14, s22
	s_ashr_i32 s11, s10, 31
	s_lshl_b64 s[16:17], s[10:11], 18
	s_add_u32 s16, s34, s16
	s_addc_u32 s17, s35, s17
	s_and_b64 s[26:27], s[0:1], exec
	s_cselect_b32 s11, s17, s25
	s_cselect_b32 s47, s16, s24
	s_add_u32 s22, s22, 0x20080
	s_addc_u32 s23, s23, 0
	s_add_u32 s48, s24, 0x100
	v_mov_b32_e32 v0, 0
	s_addc_u32 s49, s25, 0
	s_mov_b32 s50, -2
	s_cmp_eq_u32 s100, 0
	s_cbranch_scc1 .Lmy_nobar_1031
	s_barrier
	s_mov_b32 s100, 0
; #define PG8_STAGE(bufoff, gbase, voff) do { _Pragma("unroll") for (int _i = 0; _i < 2; ++_i) \
;         __builtin_amdgcn_global_load_lds((const unsigned*)((const char*)(gbase) + (voff)[_i]), (PG8_LAS unsigned*)(lds + (bufoff) + ldsw + _i * 8192), 16, 0, 0); } while (0)
; #define PG8_LDA(dst, b, h) do { _Pragma("unroll") for (int m = 0; m < 4; ++m) _Pragma("unroll") for (int k = 0; k < 2; ++k) dst[m][k] = *(const PG8_LAS bf16x8*)(lds + PG8_SA(b, h) + aoff + m * 2048 + k * 1024); } while (0)
; #define PG8_LDB(dst, b, h) do { _Pragma("unroll") for (int n = 0; n < 2; ++n) _Pragma("unroll") for (int k = 0; k < 2; ++k) dst[n][k] = *(const PG8_LAS bf16x8*)(lds + PG8_SB(b, h) + boff + n * 2048 + k * 1024); } while (0)
; #define PG8_MMA(ai, bj, At, Bt) do { __builtin_amdgcn_s_setprio(1); _Pragma("unroll") for (int m = 0; m < 4; ++m) _Pragma("unroll") for (int n = 0; n < 2; ++n) _Pragma("unroll") for (int k = 0; k < 2; ++k) \
;         acc[ai][bj][m][n] = __builtin_amdgcn_mfma_f32_16x16x32_bf16(Bt[n][k], At[m][k], acc[ai][bj][m][n], 0, 0, 0); __builtin_amdgcn_s_setprio(0); } while (0)
; #define PG8_WAIT_V(n) asm volatile("s_waitcnt vmcnt(" #n ")" ::: "memory")
; #define PG8_WAIT_L(n) asm volatile("s_waitcnt lgkmcnt(" #n ")" ::: "memory")
; #define PG8_BAR __builtin_amdgcn_s_barrier()
; template <class Epi, class Sched, bool ALIGN_EPI = false, bool SP2 = false>
; __device__ __forceinline__ void gemm_phase(PG8_LAS unsigned char* lds, const Gemm g, const Sched& S, const Epi& E, const int tid) {
;     ...
;             const char* a1 = cA + (size_t)(t + 1) * kstep;
;             const char* a2 = last ? nA : cA + (size_t)(t + 2) * kstep; const char* b2 = last ? nB : cB + (size_t)(t + 2) * kstep;
;             const char* a3 = a2 + kstep; const char* b3 = b2 + kstep;
;             if (last && has_next) S.a_ready(nxt);
;             if constexpr (SP2) {
;             PG8_LDB(B0, 0, 0); PG8_LDB(B1, 0, 1); PG8_SCHED; PG8_LDA(At, 0, 0); PG8_STAGE(PG8_SA(1, 1), a1 + hstep, voffA);
;             PG8_WAIT_V(8); PG8_WAIT_L(0); PG8_BAR; PG8_MMA(0, 0, At, B0); PG8_MMA(0, 1, At, B1); PG8_BAR; PG8_SCHED;
;             PG8_LDA(At, 0, 1); PG8_STAGE(PG8_SB(0, 0), b2, voffB); PG8_STAGE(PG8_SB(0, 1), b2 + hstep, voffB); PG8_STAGE(PG8_SA(0, 0), a2, voffA);
;             PG8_WAIT_V(8); PG8_WAIT_L(0); PG8_BAR; PG8_MMA(1, 0, At, B0); PG8_MMA(1, 1, At, B1); PG8_BAR; PG8_SCHED;
.Lmy_nobar_1031:
	s_add_u32 s24, s22, 0xfffe0080
	s_addc_u32 s25, s23, -1
	s_add_i32 s51, 0, 0x10000
	v_add_u32_e32 v138, s51, v141
	ds_read_b128 v[144:147], v138
	ds_read_b128 v[148:151], v138 offset:1024
	ds_read_b128 v[152:155], v138 offset:2048
	ds_read_b128 v[156:159], v138 offset:3072
	v_add_u32_e32 v138, s33, v141
	ds_read_b128 v[160:163], v138
	ds_read_b128 v[164:167], v138 offset:1024
	ds_read_b128 v[168:171], v138 offset:2048
	ds_read_b128 v[172:175], v138 offset:3072
	s_cmp_eq_u32 s50, 4
	s_cselect_b32 s27, s13, s25
	s_cselect_b32 s26, s19, s24
	s_cselect_b32 s25, s11, s49
	s_cselect_b32 s24, s47, s48
	v_lshl_add_u64 v[138:139], s[22:23], 0, v[134:135]
	s_add_i32 m0, s21, 0xc000
	ds_read_b128 v[176:179], v143
	ds_read_b128 v[180:183], v143 offset:1024
	ds_read_b128 v[184:187], v143 offset:2048
	ds_read_b128 v[188:191], v143 offset:3072
	ds_read_b128 v[192:195], v143 offset:4096
	ds_read_b128 v[196:199], v143 offset:5120
	ds_read_b128 v[200:203], v143 offset:6144
	ds_read_b128 v[204:207], v143 offset:7168
	global_load_lds_dwordx4 v[138:139], off
	v_lshl_add_u64 v[138:139], s[22:23], 0, v[136:137]
	s_add_i32 m0, s21, 0xe000
	s_nop 0
	global_load_lds_dwordx4 v[138:139], off
	s_waitcnt vmcnt(8)
	s_waitcnt lgkmcnt(0)
	s_barrier
	s_setprio 1
	s_waitcnt lgkmcnt(0)
	v_mfma_f32_16x16x32_bf16 v[124:127], v[144:147], v[176:179], 0
	v_mfma_f32_16x16x32_bf16 v[120:123], v[152:155], v[176:179], 0
	v_mfma_f32_16x16x32_bf16 v[108:111], v[144:147], v[184:187], 0
	v_mfma_f32_16x16x32_bf16 v[104:107], v[152:155], v[184:187], 0
	v_mfma_f32_16x16x32_bf16 v[92:95], v[144:147], v[192:195], 0
	v_mfma_f32_16x16x32_bf16 v[88:91], v[152:155], v[192:195], 0
	v_mfma_f32_16x16x32_bf16 v[76:79], v[144:147], v[200:203], 0
	v_mfma_f32_16x16x32_bf16 v[72:75], v[152:155], v[200:203], 0
	v_mfma_f32_16x16x32_bf16 v[124:127], v[148:151], v[180:183], v[124:127]
	v_mfma_f32_16x16x32_bf16 v[120:123], v[156:159], v[180:183], v[120:123]
	v_mfma_f32_16x16x32_bf16 v[108:111], v[148:151], v[188:191], v[108:111]
	v_mfma_f32_16x16x32_bf16 v[104:107], v[156:159], v[188:191], v[104:107]
	v_mfma_f32_16x16x32_bf16 v[92:95], v[148:151], v[196:199], v[92:95]
	v_mfma_f32_16x16x32_bf16 v[88:91], v[156:159], v[196:199], v[88:91]
	v_mfma_f32_16x16x32_bf16 v[76:79], v[148:151], v[204:207], v[76:79]
	v_mfma_f32_16x16x32_bf16 v[72:75], v[156:159], v[204:207], v[72:75]
	s_setprio 0
	s_setprio 1
	v_mfma_f32_16x16x32_bf16 v[116:119], v[160:163], v[176:179], 0
	v_mfma_f32_16x16x32_bf16 v[112:115], v[168:171], v[176:179], 0
	v_mfma_f32_16x16x32_bf16 v[100:103], v[160:163], v[184:187], 0
	v_mfma_f32_16x16x32_bf16 v[96:99], v[168:171], v[184:187], 0
	v_mfma_f32_16x16x32_bf16 v[84:87], v[160:163], v[192:195], 0
	v_mfma_f32_16x16x32_bf16 v[80:83], v[168:171], v[192:195], 0
	v_mfma_f32_16x16x32_bf16 v[68:71], v[160:163], v[200:203], 0
	v_mfma_f32_16x16x32_bf16 v[64:67], v[168:171], v[200:203], 0
	v_mfma_f32_16x16x32_bf16 v[116:119], v[164:167], v[180:183], v[116:119]
	v_mfma_f32_16x16x32_bf16 v[112:115], v[172:175], v[180:183], v[112:115]
	v_mfma_f32_16x16x32_bf16 v[100:103], v[164:167], v[188:191], v[100:103]
	v_mfma_f32_16x16x32_bf16 v[96:99], v[172:175], v[188:191], v[96:99]
	v_mfma_f32_16x16x32_bf16 v[84:87], v[164:167], v[196:199], v[84:87]
	v_mfma_f32_16x16x32_bf16 v[80:83], v[172:175], v[196:199], v[80:83]
	v_mfma_f32_16x16x32_bf16 v[68:71], v[164:167], v[204:207], v[68:71]
	v_mfma_f32_16x16x32_bf16 v[64:67], v[172:175], v[204:207], v[64:67]
	s_setprio 0
	s_barrier
	s_add_i32 s51, s51, s36
	v_lshl_add_u64 v[138:139], s[24:25], 0, v[208:209]
	s_mov_b32 m0, s51
	ds_read_b128 v[176:179], v143 offset:16384
	ds_read_b128 v[180:183], v143 offset:17408
	ds_read_b128 v[184:187], v143 offset:18432
	ds_read_b128 v[188:191], v143 offset:19456
	ds_read_b128 v[192:195], v143 offset:20480
	ds_read_b128 v[196:199], v143 offset:21504
	ds_read_b128 v[200:203], v143 offset:22528
	ds_read_b128 v[204:207], v143 offset:23552
	global_load_lds_dwordx4 v[138:139], off
	s_add_i32 m0, s51, 0x2000
	s_add_u32 s52, s24, 0x20000
	v_lshl_add_u64 v[210:211], s[24:25], 0, v[128:129]
	s_addc_u32 s53, s25, 0
	s_add_i32 s51, s33, s36
	global_load_lds_dwordx4 v[210:211], off
	v_lshl_add_u64 v[214:215], s[52:53], 0, v[208:209]
	s_mov_b32 m0, s51
	v_lshl_add_u64 v[216:217], s[26:27], 0, v[130:131]
	global_load_lds_dwordx4 v[214:215], off
	v_lshl_add_u64 v[214:215], s[52:53], 0, v[128:129]
	s_add_i32 m0, s51, 0x2000
	s_nop 0
	global_load_lds_dwordx4 v[214:215], off
	v_lshl_add_u64 v[214:215], s[26:27], 0, v[132:133]
	s_mov_b32 m0, s21
	s_nop 0
	global_load_lds_dwordx4 v[214:215], off
	s_mov_b32 m0, s40
	s_nop 0
	global_load_lds_dwordx4 v[216:217], off
	s_waitcnt vmcnt(8)
	s_waitcnt lgkmcnt(0)
	s_barrier
	s_setprio 1
	s_waitcnt lgkmcnt(0)
	v_mfma_f32_16x16x32_bf16 v[60:63], v[144:147], v[176:179], 0
	v_mfma_f32_16x16x32_bf16 v[56:59], v[152:155], v[176:179], 0
	v_mfma_f32_16x16x32_bf16 v[44:47], v[144:147], v[184:187], 0
	v_mfma_f32_16x16x32_bf16 v[40:43], v[152:155], v[184:187], 0
	v_mfma_f32_16x16x32_bf16 v[28:31], v[144:147], v[192:195], 0
	v_mfma_f32_16x16x32_bf16 v[24:27], v[152:155], v[192:195], 0
	v_mfma_f32_16x16x32_bf16 v[12:15], v[144:147], v[200:203], 0
	v_mfma_f32_16x16x32_bf16 v[8:11], v[152:155], v[200:203], 0
	v_mfma_f32_16x16x32_bf16 v[60:63], v[148:151], v[180:183], v[60:63]
	v_mfma_f32_16x16x32_bf16 v[56:59], v[156:159], v[180:183], v[56:59]
	v_mfma_f32_16x16x32_bf16 v[44:47], v[148:151], v[188:191], v[44:47]
	v_mfma_f32_16x16x32_bf16 v[40:43], v[156:159], v[188:191], v[40:43]
	v_mfma_f32_16x16x32_bf16 v[28:31], v[148:151], v[196:199], v[28:31]
	v_mfma_f32_16x16x32_bf16 v[24:27], v[156:159], v[196:199], v[24:27]
	v_mfma_f32_16x16x32_bf16 v[12:15], v[148:151], v[204:207], v[12:15]
	v_mfma_f32_16x16x32_bf16 v[8:11], v[156:159], v[204:207], v[8:11]
	s_setprio 0
	s_setprio 1
	v_mfma_f32_16x16x32_bf16 v[52:55], v[160:163], v[176:179], 0
	v_mfma_f32_16x16x32_bf16 v[48:51], v[168:171], v[176:179], 0
	v_mfma_f32_16x16x32_bf16 v[36:39], v[160:163], v[184:187], 0
	v_mfma_f32_16x16x32_bf16 v[32:35], v[168:171], v[184:187], 0
	v_mfma_f32_16x16x32_bf16 v[20:23], v[160:163], v[192:195], 0
	v_mfma_f32_16x16x32_bf16 v[16:19], v[168:171], v[192:195], 0
	v_mfma_f32_16x16x32_bf16 v[4:7], v[160:163], v[200:203], 0
	v_mfma_f32_16x16x32_bf16 v[0:3], v[168:171], v[200:203], 0
	v_mfma_f32_16x16x32_bf16 v[52:55], v[164:167], v[180:183], v[52:55]
	v_mfma_f32_16x16x32_bf16 v[48:51], v[172:175], v[180:183], v[48:51]
	v_mfma_f32_16x16x32_bf16 v[36:39], v[164:167], v[188:191], v[36:39]
	v_mfma_f32_16x16x32_bf16 v[32:35], v[172:175], v[188:191], v[32:35]
	v_mfma_f32_16x16x32_bf16 v[20:23], v[164:167], v[196:199], v[20:23]
	v_mfma_f32_16x16x32_bf16 v[16:19], v[172:175], v[196:199], v[16:19]
	v_mfma_f32_16x16x32_bf16 v[4:7], v[164:167], v[204:207], v[4:7]
	v_mfma_f32_16x16x32_bf16 v[0:3], v[172:175], v[204:207], v[0:3]
	s_setprio 0
	s_barrier
	s_branch .Lmy_mid_1031

; #define PG8_STAGE(bufoff, gbase, voff) do { _Pragma("unroll") for (int _i = 0; _i < 2; ++_i) \
;         __builtin_amdgcn_global_load_lds((const unsigned*)((const char*)(gbase) + (voff)[_i]), (PG8_LAS unsigned*)(lds + (bufoff) + ldsw + _i * 8192), 16, 0, 0); } while (0)
; #define PG8_LDA(dst, b, h) do { _Pragma("unroll") for (int m = 0; m < 4; ++m) _Pragma("unroll") for (int k = 0; k < 2; ++k) dst[m][k] = *(const PG8_LAS bf16x8*)(lds + PG8_SA(b, h) + aoff + m * 2048 + k * 1024); } while (0)
; #define PG8_LDB(dst, b, h) do { _Pragma("unroll") for (int n = 0; n < 2; ++n) _Pragma("unroll") for (int k = 0; k < 2; ++k) dst[n][k] = *(const PG8_LAS bf16x8*)(lds + PG8_SB(b, h) + boff + n * 2048 + k * 1024); } while (0)
; #define PG8_MMA(ai, bj, At, Bt) do { __builtin_amdgcn_s_setprio(1); _Pragma("unroll") for (int m = 0; m < 4; ++m) _Pragma("unroll") for (int n = 0; n < 2; ++n) _Pragma("unroll") for (int k = 0; k < 2; ++k) \
;         acc[ai][bj][m][n] = __builtin_amdgcn_mfma_f32_16x16x32_bf16(Bt[n][k], At[m][k], acc[ai][bj][m][n], 0, 0, 0); __builtin_amdgcn_s_setprio(0); } while (0)
; #define PG8_WAIT_V(n) asm volatile("s_waitcnt vmcnt(" #n ")" ::: "memory")
; #define PG8_WAIT_L(n) asm volatile("s_waitcnt lgkmcnt(" #n ")" ::: "memory")
; #define PG8_BAR __builtin_amdgcn_s_barrier()
; #define PG8_SCHED __builtin_amdgcn_sched_barrier(0)
; template <class Epi, class Sched, bool ALIGN_EPI = false, bool SP2 = false>
; __device__ __forceinline__ void gemm_phase(PG8_LAS unsigned char* lds, const Gemm g, const Sched& S, const Epi& E, const int tid) {
;     ...
;             PG8_LDB(B0, 1, 0); PG8_LDB(B1, 1, 1); PG8_SCHED; PG8_LDA(At, 1, 0); PG8_STAGE(PG8_SA(0, 1), a2 + hstep, voffA);
;             PG8_WAIT_V(8); PG8_WAIT_L(0); PG8_BAR; PG8_MMA(0, 0, At, B0); PG8_MMA(0, 1, At, B1); PG8_BAR; PG8_SCHED;
.Lmy_mid_1031:
	s_add_i32 s51, 0, 0x18000
	s_add_i32 s52, 0, 0x1c000
	v_add_u32_e32 v156, s51, v141
	v_add_u32_e32 v172, s52, v141
	ds_read_b128 v[144:147], v156
	ds_read_b128 v[148:151], v156 offset:1024
	ds_read_b128 v[152:155], v156 offset:2048
	ds_read_b128 v[156:159], v156 offset:3072
	ds_read_b128 v[160:163], v172
	ds_read_b128 v[164:167], v172 offset:1024
	ds_read_b128 v[168:171], v172 offset:2048
	ds_read_b128 v[172:175], v172 offset:3072
	s_add_u32 s26, s26, 0x20000
	s_addc_u32 s27, s27, 0
	s_mov_b32 m0, s41
	v_lshl_add_u64 v[218:219], s[26:27], 0, v[132:133]
	ds_read_b128 v[176:179], v143 offset:32768
	ds_read_b128 v[180:183], v143 offset:33792
	ds_read_b128 v[184:187], v143 offset:34816
	ds_read_b128 v[188:191], v143 offset:35840
	ds_read_b128 v[192:195], v143 offset:36864
	ds_read_b128 v[196:199], v143 offset:37888
	ds_read_b128 v[200:203], v143 offset:38912
	ds_read_b128 v[204:207], v143 offset:39936
	global_load_lds_dwordx4 v[218:219], off
	v_lshl_add_u64 v[218:219], s[26:27], 0, v[130:131]
	s_mov_b32 m0, s42
	s_nop 0
	global_load_lds_dwordx4 v[218:219], off
	s_waitcnt vmcnt(8)
	s_waitcnt lgkmcnt(0)
	s_barrier
	s_setprio 1
	s_waitcnt lgkmcnt(0)
	v_mfma_f32_16x16x32_bf16 v[124:127], v[144:147], v[176:179], v[124:127]
	v_mfma_f32_16x16x32_bf16 v[120:123], v[152:155], v[176:179], v[120:123]
	v_mfma_f32_16x16x32_bf16 v[108:111], v[144:147], v[184:187], v[108:111]
	v_mfma_f32_16x16x32_bf16 v[104:107], v[152:155], v[184:187], v[104:107]
	v_mfma_f32_16x16x32_bf16 v[92:95], v[144:147], v[192:195], v[92:95]
	v_mfma_f32_16x16x32_bf16 v[88:91], v[152:155], v[192:195], v[88:91]
	v_mfma_f32_16x16x32_bf16 v[76:79], v[144:147], v[200:203], v[76:79]
	v_mfma_f32_16x16x32_bf16 v[72:75], v[152:155], v[200:203], v[72:75]
	v_mfma_f32_16x16x32_bf16 v[124:127], v[148:151], v[180:183], v[124:127]
	v_mfma_f32_16x16x32_bf16 v[120:123], v[156:159], v[180:183], v[120:123]
	v_mfma_f32_16x16x32_bf16 v[108:111], v[148:151], v[188:191], v[108:111]
	v_mfma_f32_16x16x32_bf16 v[104:107], v[156:159], v[188:191], v[104:107]
	v_mfma_f32_16x16x32_bf16 v[92:95], v[148:151], v[196:199], v[92:95]
	v_mfma_f32_16x16x32_bf16 v[88:91], v[156:159], v[196:199], v[88:91]
	v_mfma_f32_16x16x32_bf16 v[76:79], v[148:151], v[204:207], v[76:79]
	v_mfma_f32_16x16x32_bf16 v[72:75], v[156:159], v[204:207], v[72:75]
	s_setprio 0
	s_setprio 1
	v_mfma_f32_16x16x32_bf16 v[116:119], v[160:163], v[176:179], v[116:119]
	v_mfma_f32_16x16x32_bf16 v[112:115], v[168:171], v[176:179], v[112:115]
	v_mfma_f32_16x16x32_bf16 v[100:103], v[160:163], v[184:187], v[100:103]
	v_mfma_f32_16x16x32_bf16 v[96:99], v[168:171], v[184:187], v[96:99]
	v_mfma_f32_16x16x32_bf16 v[84:87], v[160:163], v[192:195], v[84:87]
	v_mfma_f32_16x16x32_bf16 v[80:83], v[168:171], v[192:195], v[80:83]
	v_mfma_f32_16x16x32_bf16 v[68:71], v[160:163], v[200:203], v[68:71]
	v_mfma_f32_16x16x32_bf16 v[64:67], v[168:171], v[200:203], v[64:67]
	v_mfma_f32_16x16x32_bf16 v[116:119], v[164:167], v[180:183], v[116:119]
	v_mfma_f32_16x16x32_bf16 v[112:115], v[172:175], v[180:183], v[112:115]
	v_mfma_f32_16x16x32_bf16 v[100:103], v[164:167], v[188:191], v[100:103]
	v_mfma_f32_16x16x32_bf16 v[96:99], v[172:175], v[188:191], v[96:99]
	v_mfma_f32_16x16x32_bf16 v[84:87], v[164:167], v[196:199], v[84:87]
	v_mfma_f32_16x16x32_bf16 v[80:83], v[172:175], v[196:199], v[80:83]
	v_mfma_f32_16x16x32_bf16 v[68:71], v[164:167], v[204:207], v[68:71]
	v_mfma_f32_16x16x32_bf16 v[64:67], v[172:175], v[204:207], v[64:67]
	s_setprio 0
	s_barrier
; #define PG8_STAGE(bufoff, gbase, voff) do { _Pragma("unroll") for (int _i = 0; _i < 2; ++_i) \
;         __builtin_amdgcn_global_load_lds((const unsigned*)((const char*)(gbase) + (voff)[_i]), (PG8_LAS unsigned*)(lds + (bufoff) + ldsw + _i * 8192), 16, 0, 0); } while (0)
; #define PG8_LDA(dst, b, h) do { _Pragma("unroll") for (int m = 0; m < 4; ++m) _Pragma("unroll") for (int k = 0; k < 2; ++k) dst[m][k] = *(const PG8_LAS bf16x8*)(lds + PG8_SA(b, h) + aoff + m * 2048 + k * 1024); } while (0)
; #define PG8_MMA(ai, bj, At, Bt) do { __builtin_amdgcn_s_setprio(1); _Pragma("unroll") for (int m = 0; m < 4; ++m) _Pragma("unroll") for (int n = 0; n < 2; ++n) _Pragma("unroll") for (int k = 0; k < 2; ++k) \
;         acc[ai][bj][m][n] = __builtin_amdgcn_mfma_f32_16x16x32_bf16(Bt[n][k], At[m][k], acc[ai][bj][m][n], 0, 0, 0); __builtin_amdgcn_s_setprio(0); } while (0)
; #define PG8_WAIT_V(n) asm volatile("s_waitcnt vmcnt(" #n ")" ::: "memory")
; #define PG8_WAIT_L(n) asm volatile("s_waitcnt lgkmcnt(" #n ")" ::: "memory")
; #define PG8_BAR __builtin_amdgcn_s_barrier()
; #define PG8_SCHED __builtin_amdgcn_sched_barrier(0)
; template <class Epi, class Sched, bool ALIGN_EPI = false, bool SP2 = false>
; __device__ __forceinline__ void gemm_phase(PG8_LAS unsigned char* lds, const Gemm g, const Sched& S, const Epi& E, const int tid) {
;     ...
;             PG8_LDA(At, 1, 1); PG8_STAGE(PG8_SB(1, 0), b3, voffB); PG8_STAGE(PG8_SB(1, 1), b3 + hstep, voffB); PG8_STAGE(PG8_SA(1, 0), a3, voffA);
;             PG8_WAIT_V(8); PG8_WAIT_L(0); PG8_BAR; PG8_MMA(1, 0, At, B0); PG8_MMA(1, 1, At, B1); PG8_BAR; PG8_SCHED;
;     ...
;         if constexpr (ALIGN_EPI) { if (wr == 0) PG8_BAR; }
	s_add_i32 s26, s51, s36
	v_lshl_add_u64 v[138:139], v[138:139], 0, s[2:3]
	s_mov_b32 m0, s26
	ds_read_b128 v[176:179], v143 offset:49152
	ds_read_b128 v[180:183], v143 offset:50176
	ds_read_b128 v[184:187], v143 offset:51200
	ds_read_b128 v[188:191], v143 offset:52224
	ds_read_b128 v[192:195], v143 offset:53248
	ds_read_b128 v[196:199], v143 offset:54272
	ds_read_b128 v[200:203], v143 offset:55296
	ds_read_b128 v[204:207], v143 offset:56320
	global_load_lds_dwordx4 v[138:139], off
	s_add_i32 m0, s26, 0x2000
	s_add_u32 s24, s24, 0x20080
	v_lshl_add_u64 v[138:139], v[210:211], 0, s[2:3]
	s_addc_u32 s25, s25, 0
	s_add_i32 s26, s52, s36
	global_load_lds_dwordx4 v[138:139], off
	v_lshl_add_u64 v[138:139], s[24:25], 0, v[208:209]
	s_mov_b32 m0, s26
	s_nop 0
	global_load_lds_dwordx4 v[138:139], off
	v_lshl_add_u64 v[138:139], s[24:25], 0, v[128:129]
	s_add_i32 m0, s26, 0x2000
	s_nop 0
	global_load_lds_dwordx4 v[138:139], off
	v_lshl_add_u64 v[138:139], v[214:215], 0, s[2:3]
	s_mov_b32 m0, s43
	s_nop 0
	global_load_lds_dwordx4 v[138:139], off
	v_lshl_add_u64 v[138:139], v[216:217], 0, s[2:3]
	s_mov_b32 m0, s44
	s_nop 0
	global_load_lds_dwordx4 v[138:139], off
	s_waitcnt vmcnt(8)
	s_waitcnt lgkmcnt(0)
	s_barrier
	s_setprio 1
	s_waitcnt lgkmcnt(0)
	v_mfma_f32_16x16x32_bf16 v[60:63], v[144:147], v[176:179], v[60:63]
	v_mfma_f32_16x16x32_bf16 v[56:59], v[152:155], v[176:179], v[56:59]
	v_mfma_f32_16x16x32_bf16 v[44:47], v[144:147], v[184:187], v[44:47]
	v_mfma_f32_16x16x32_bf16 v[40:43], v[152:155], v[184:187], v[40:43]
	v_mfma_f32_16x16x32_bf16 v[28:31], v[144:147], v[192:195], v[28:31]
	v_mfma_f32_16x16x32_bf16 v[24:27], v[152:155], v[192:195], v[24:27]
	v_mfma_f32_16x16x32_bf16 v[12:15], v[144:147], v[200:203], v[12:15]
	v_mfma_f32_16x16x32_bf16 v[8:11], v[152:155], v[200:203], v[8:11]
	v_mfma_f32_16x16x32_bf16 v[60:63], v[148:151], v[180:183], v[60:63]
	v_mfma_f32_16x16x32_bf16 v[56:59], v[156:159], v[180:183], v[56:59]
	v_mfma_f32_16x16x32_bf16 v[44:47], v[148:151], v[188:191], v[44:47]
	v_mfma_f32_16x16x32_bf16 v[40:43], v[156:159], v[188:191], v[40:43]
	v_mfma_f32_16x16x32_bf16 v[28:31], v[148:151], v[196:199], v[28:31]
	v_mfma_f32_16x16x32_bf16 v[24:27], v[156:159], v[196:199], v[24:27]
	v_mfma_f32_16x16x32_bf16 v[12:15], v[148:151], v[204:207], v[12:15]
	v_mfma_f32_16x16x32_bf16 v[8:11], v[156:159], v[204:207], v[8:11]
	s_setprio 0
	s_setprio 1
	v_mfma_f32_16x16x32_bf16 v[52:55], v[160:163], v[176:179], v[52:55]
	v_mfma_f32_16x16x32_bf16 v[48:51], v[168:171], v[176:179], v[48:51]
	v_mfma_f32_16x16x32_bf16 v[36:39], v[160:163], v[184:187], v[36:39]
	v_mfma_f32_16x16x32_bf16 v[32:35], v[168:171], v[184:187], v[32:35]
	v_mfma_f32_16x16x32_bf16 v[20:23], v[160:163], v[192:195], v[20:23]
	v_mfma_f32_16x16x32_bf16 v[16:19], v[168:171], v[192:195], v[16:19]
	v_mfma_f32_16x16x32_bf16 v[4:7], v[160:163], v[200:203], v[4:7]
	v_mfma_f32_16x16x32_bf16 v[0:3], v[168:171], v[200:203], v[0:3]
	v_mfma_f32_16x16x32_bf16 v[52:55], v[164:167], v[180:183], v[52:55]
	v_mfma_f32_16x16x32_bf16 v[48:51], v[172:175], v[180:183], v[48:51]
	v_mfma_f32_16x16x32_bf16 v[36:39], v[164:167], v[188:191], v[36:39]
	v_mfma_f32_16x16x32_bf16 v[32:35], v[172:175], v[188:191], v[32:35]
	v_mfma_f32_16x16x32_bf16 v[20:23], v[164:167], v[196:199], v[20:23]
	v_mfma_f32_16x16x32_bf16 v[16:19], v[172:175], v[196:199], v[16:19]
	v_mfma_f32_16x16x32_bf16 v[4:7], v[164:167], v[204:207], v[4:7]
	v_mfma_f32_16x16x32_bf16 v[0:3], v[172:175], v[204:207], v[0:3]
	s_setprio 0
	s_barrier
	s_add_i32 s50, s50, 2
	s_add_u32 s22, s22, 0x100
	s_addc_u32 s23, s23, 0
	s_add_u32 s48, s48, 0x100
	s_addc_u32 s49, s49, 0
	s_cmp_gt_u32 s50, 5
	s_cbranch_scc0 .LBB0_1031
	s_and_b64 vcc, exec, s[8:9]
	s_cbranch_vccz .LBB0_1034
	s_barrier

;     __host__ __device__ bool next(int i, Unit& u) const { const int L = base + i * Gp + cp; if (L >= end) return false; return T.next(L, u); }
;     __host__ __device__ bool next(int i, Unit& u) const { const int L = i * Gp + cp; if (cp < 0 || L >= n) return false; u.kb = L & 3; u.pn = (L >> 2) % nN; u.pm = pm0 + (L >> 2) / nN; return true; }
;     __host__ __device__ bool next(int i, Unit& u) const { const bool ok = T.next(i >> 2, u); u.kb = i & 3; return ok; }
; #define PG8_BAR __builtin_amdgcn_s_barrier()
; template <class Epi, class Sched, bool ALIGN_EPI = false, bool SP2 = false>
; __device__ __forceinline__ void gemm_phase(PG8_LAS unsigned char* lds, const Gemm g, const Sched& S, const Epi& E, const int tid) {
;     ...
;         const bool has_next = S.next(ui + 1, nxt);
;         const char* nA = has_next ? (const char*)g.A + (size_t)nxt.pm * tstep + (size_t)nxt.kb * g.sA : cA; const char* nB = has_next ? (const char*)g.Bt + (size_t)nxt.pn * tstep + (size_t)nxt.kb * g.sB : cB;
;         for (int t = 0; t < nt; t += 2) {
;             const bool last = (t == nt - 2);
;             const char* a1 = cA + (size_t)(t + 1) * kstep;
;             const char* a2 = last ? nA : cA + (size_t)(t + 2) * kstep; const char* b2 = last ? nB : cB + (size_t)(t + 2) * kstep;
;     ...
; #pragma unroll
;         for (int a = 0; a < 2; ++a)
; #pragma unroll
;             for (int b = 0; b < 2; ++b)
; #pragma unroll
;                 for (int m = 0; m < 4; ++m)
; #pragma unroll
;                     for (int n = 0; n < 2; ++n) acc[a][b][m][n] = (f32x4){0.f, 0.f, 0.f, 0.f};
;         cur = nxt; cA = nA; cB = nB; ++ui;
;         if constexpr (ALIGN_EPI) { if (wr == 1) PG8_BAR; }
.LBB0_1046:
	s_ashr_i32 s15, s14, 31
	s_lshl_b64 s[16:17], s[14:15], 20
	s_add_u32 s16, s34, s16
	s_addc_u32 s17, s35, s17
	s_and_b64 s[18:19], s[12:13], exec
	s_cselect_b32 s15, s17, s25
	s_cselect_b32 s21, s16, s24
	s_ashr_i32 s11, s10, 31
	s_lshl_b64 s[18:19], s[10:11], 20
	s_add_u32 s18, s36, s18
	s_addc_u32 s19, s37, s19
	s_and_b64 s[28:29], s[12:13], exec
	s_cselect_b32 s11, s19, s27
	s_cselect_b32 s47, s18, s26
	s_add_u32 s24, s24, 0x80080
	s_addc_u32 s25, s25, 0
	s_add_u32 s48, s26, 0x100
	v_mov_b32_e32 v0, 0
	s_addc_u32 s49, s27, 0
	s_mov_b32 s50, -2
	s_cmp_eq_u32 s100, 0
	s_cbranch_scc1 .Lmy_nobar_1047
	s_barrier
	s_mov_b32 s100, 0
; #define PG8_STAGE(bufoff, gbase, voff) do { _Pragma("unroll") for (int _i = 0; _i < 2; ++_i) \
;         __builtin_amdgcn_global_load_lds((const unsigned*)((const char*)(gbase) + (voff)[_i]), (PG8_LAS unsigned*)(lds + (bufoff) + ldsw + _i * 8192), 16, 0, 0); } while (0)
; #define PG8_LDA(dst, b, h) do { _Pragma("unroll") for (int m = 0; m < 4; ++m) _Pragma("unroll") for (int k = 0; k < 2; ++k) dst[m][k] = *(const PG8_LAS bf16x8*)(lds + PG8_SA(b, h) + aoff + m * 2048 + k * 1024); } while (0)
; #define PG8_LDB(dst, b, h) do { _Pragma("unroll") for (int n = 0; n < 2; ++n) _Pragma("unroll") for (int k = 0; k < 2; ++k) dst[n][k] = *(const PG8_LAS bf16x8*)(lds + PG8_SB(b, h) + boff + n * 2048 + k * 1024); } while (0)
; #define PG8_MMA(ai, bj, At, Bt) do { __builtin_amdgcn_s_setprio(1); _Pragma("unroll") for (int m = 0; m < 4; ++m) _Pragma("unroll") for (int n = 0; n < 2; ++n) _Pragma("unroll") for (int k = 0; k < 2; ++k) \
;         acc[ai][bj][m][n] = __builtin_amdgcn_mfma_f32_16x16x32_bf16(Bt[n][k], At[m][k], acc[ai][bj][m][n], 0, 0, 0); __builtin_amdgcn_s_setprio(0); } while (0)
; #define PG8_WAIT_V(n) asm volatile("s_waitcnt vmcnt(" #n ")" ::: "memory")
; #define PG8_WAIT_L(n) asm volatile("s_waitcnt lgkmcnt(" #n ")" ::: "memory")
; #define PG8_BAR __builtin_amdgcn_s_barrier()
; template <class Epi, class Sched, bool ALIGN_EPI = false, bool SP2 = false>
; __device__ __forceinline__ void gemm_phase(PG8_LAS unsigned char* lds, const Gemm g, const Sched& S, const Epi& E, const int tid) {
;     ...
;             const char* a1 = cA + (size_t)(t + 1) * kstep;
;             const char* a2 = last ? nA : cA + (size_t)(t + 2) * kstep; const char* b2 = last ? nB : cB + (size_t)(t + 2) * kstep;
;             const char* a3 = a2 + kstep; const char* b3 = b2 + kstep;
;             if (last && has_next) S.a_ready(nxt);
;             if constexpr (SP2) {
;             PG8_LDB(B0, 0, 0); PG8_LDB(B1, 0, 1); PG8_SCHED; PG8_LDA(At, 0, 0); PG8_STAGE(PG8_SA(1, 1), a1 + hstep, voffA);
;             PG8_WAIT_V(8); PG8_WAIT_L(0); PG8_BAR; PG8_MMA(0, 0, At, B0); PG8_MMA(0, 1, At, B1); PG8_BAR; PG8_SCHED;
;             PG8_LDA(At, 0, 1); PG8_STAGE(PG8_SB(0, 0), b2, voffB); PG8_STAGE(PG8_SB(0, 1), b2 + hstep, voffB); PG8_STAGE(PG8_SA(0, 0), a2, voffA);
;             PG8_WAIT_V(8); PG8_WAIT_L(0); PG8_BAR; PG8_MMA(1, 0, At, B0); PG8_MMA(1, 1, At, B1); PG8_BAR; PG8_SCHED;
.Lmy_nobar_1047:
	s_add_u32 s26, s24, 0xfff80080
	s_addc_u32 s27, s25, -1
	s_add_i32 s51, 0, 0x10000
	v_add_u32_e32 v68, s51, v157
	v_add_u32_e32 v154, s33, v157
	ds_read_b128 v[48:51], v68
	ds_read_b128 v[52:55], v68 offset:1024
	ds_read_b128 v[64:67], v68 offset:2048
	ds_read_b128 v[68:71], v68 offset:3072
	ds_read_b128 v[162:165], v154
	ds_read_b128 v[166:169], v154 offset:1024
	ds_read_b128 v[170:173], v154 offset:2048
	ds_read_b128 v[174:177], v154 offset:3072
	s_cmp_eq_u32 s50, 28
	s_cselect_b32 s29, s15, s27
	s_cselect_b32 s28, s21, s26
	s_cselect_b32 s27, s11, s49
	s_cselect_b32 s26, s47, s48
	v_lshl_add_u64 v[206:207], s[24:25], 0, v[150:151]
	s_add_i32 m0, s23, 0xc000
	ds_read_b128 v[178:181], v161
	ds_read_b128 v[182:185], v161 offset:1024
	ds_read_b128 v[186:189], v161 offset:2048
	ds_read_b128 v[190:193], v161 offset:3072
	ds_read_b128 v[194:197], v161 offset:4096
	ds_read_b128 v[198:201], v161 offset:5120
	ds_read_b128 v[202:205], v161 offset:6144
	ds_read_b128 v[214:217], v161 offset:7168
	global_load_lds_dwordx4 v[206:207], off
	v_lshl_add_u64 v[206:207], s[24:25], 0, v[152:153]
	s_add_i32 m0, s23, 0xe000
	s_nop 0
	global_load_lds_dwordx4 v[206:207], off
	s_waitcnt vmcnt(8)
	s_waitcnt lgkmcnt(0)
	s_barrier
	s_setprio 1
	s_waitcnt lgkmcnt(0)
	v_mfma_f32_16x16x32_bf16 v[140:143], v[48:51], v[178:181], 0
	v_mfma_f32_16x16x32_bf16 v[136:139], v[64:67], v[178:181], 0
	v_mfma_f32_16x16x32_bf16 v[124:127], v[48:51], v[186:189], 0
	v_mfma_f32_16x16x32_bf16 v[120:123], v[64:67], v[186:189], 0
	v_mfma_f32_16x16x32_bf16 v[108:111], v[48:51], v[194:197], 0
	v_mfma_f32_16x16x32_bf16 v[104:107], v[64:67], v[194:197], 0
	v_mfma_f32_16x16x32_bf16 v[92:95], v[48:51], v[202:205], 0
	v_mfma_f32_16x16x32_bf16 v[88:91], v[64:67], v[202:205], 0
	v_mfma_f32_16x16x32_bf16 v[140:143], v[52:55], v[182:185], v[140:143]
	v_mfma_f32_16x16x32_bf16 v[136:139], v[68:71], v[182:185], v[136:139]
	v_mfma_f32_16x16x32_bf16 v[124:127], v[52:55], v[190:193], v[124:127]
	v_mfma_f32_16x16x32_bf16 v[120:123], v[68:71], v[190:193], v[120:123]
	v_mfma_f32_16x16x32_bf16 v[108:111], v[52:55], v[198:201], v[108:111]
	v_mfma_f32_16x16x32_bf16 v[104:107], v[68:71], v[198:201], v[104:107]
	v_mfma_f32_16x16x32_bf16 v[92:95], v[52:55], v[214:217], v[92:95]
	v_mfma_f32_16x16x32_bf16 v[88:91], v[68:71], v[214:217], v[88:91]
	s_setprio 0
	s_setprio 1
	v_mfma_f32_16x16x32_bf16 v[132:135], v[162:165], v[178:181], 0
	v_mfma_f32_16x16x32_bf16 v[128:131], v[170:173], v[178:181], 0
	v_mfma_f32_16x16x32_bf16 v[116:119], v[162:165], v[186:189], 0
	v_mfma_f32_16x16x32_bf16 v[112:115], v[170:173], v[186:189], 0
	v_mfma_f32_16x16x32_bf16 v[100:103], v[162:165], v[194:197], 0
	v_mfma_f32_16x16x32_bf16 v[96:99], v[170:173], v[194:197], 0
	v_mfma_f32_16x16x32_bf16 v[84:87], v[162:165], v[202:205], 0
	v_mfma_f32_16x16x32_bf16 v[80:83], v[170:173], v[202:205], 0
	v_mfma_f32_16x16x32_bf16 v[132:135], v[166:169], v[182:185], v[132:135]
	v_mfma_f32_16x16x32_bf16 v[128:131], v[174:177], v[182:185], v[128:131]
	v_mfma_f32_16x16x32_bf16 v[116:119], v[166:169], v[190:193], v[116:119]
	v_mfma_f32_16x16x32_bf16 v[112:115], v[174:177], v[190:193], v[112:115]
	v_mfma_f32_16x16x32_bf16 v[100:103], v[166:169], v[198:201], v[100:103]
	v_mfma_f32_16x16x32_bf16 v[96:99], v[174:177], v[198:201], v[96:99]
	v_mfma_f32_16x16x32_bf16 v[84:87], v[166:169], v[214:217], v[84:87]
	v_mfma_f32_16x16x32_bf16 v[80:83], v[174:177], v[214:217], v[80:83]
	s_setprio 0
	s_barrier
	s_add_i32 s51, s51, s38
	v_lshl_add_u64 v[206:207], s[26:27], 0, v[208:209]
	s_mov_b32 m0, s51
	ds_read_b128 v[178:181], v161 offset:16384
	ds_read_b128 v[182:185], v161 offset:17408
	ds_read_b128 v[186:189], v161 offset:18432
	ds_read_b128 v[190:193], v161 offset:19456
	ds_read_b128 v[194:197], v161 offset:20480
	ds_read_b128 v[198:201], v161 offset:21504
	ds_read_b128 v[202:205], v161 offset:22528
	ds_read_b128 v[214:217], v161 offset:23552
	global_load_lds_dwordx4 v[206:207], off
	s_add_i32 m0, s51, 0x2000
	s_add_u32 s52, s26, 0x80000
	v_lshl_add_u64 v[210:211], s[26:27], 0, v[144:145]
	s_addc_u32 s53, s27, 0
	s_add_i32 s51, s33, s38
	global_load_lds_dwordx4 v[210:211], off
	v_lshl_add_u64 v[218:219], s[52:53], 0, v[208:209]
	s_mov_b32 m0, s51
	v_lshl_add_u64 v[220:221], s[28:29], 0, v[146:147]
	global_load_lds_dwordx4 v[218:219], off
	v_lshl_add_u64 v[218:219], s[52:53], 0, v[144:145]
	s_add_i32 m0, s51, 0x2000
	s_nop 0
	global_load_lds_dwordx4 v[218:219], off
	v_lshl_add_u64 v[218:219], s[28:29], 0, v[148:149]
	s_mov_b32 m0, s23
	s_nop 0
	global_load_lds_dwordx4 v[218:219], off
	s_mov_b32 m0, s39
	s_nop 0
	global_load_lds_dwordx4 v[220:221], off
	s_waitcnt vmcnt(8)
	s_waitcnt lgkmcnt(0)
	s_barrier
	s_setprio 1
	s_waitcnt lgkmcnt(0)
	v_mfma_f32_16x16x32_bf16 v[76:79], v[48:51], v[178:181], 0
	v_mfma_f32_16x16x32_bf16 v[72:75], v[64:67], v[178:181], 0
	v_mfma_f32_16x16x32_bf16 v[44:47], v[48:51], v[186:189], 0
	v_mfma_f32_16x16x32_bf16 v[40:43], v[64:67], v[186:189], 0
	v_mfma_f32_16x16x32_bf16 v[28:31], v[48:51], v[194:197], 0
	v_mfma_f32_16x16x32_bf16 v[24:27], v[64:67], v[194:197], 0
	v_mfma_f32_16x16x32_bf16 v[12:15], v[48:51], v[202:205], 0
	v_mfma_f32_16x16x32_bf16 v[8:11], v[64:67], v[202:205], 0
	v_mfma_f32_16x16x32_bf16 v[76:79], v[52:55], v[182:185], v[76:79]
	v_mfma_f32_16x16x32_bf16 v[72:75], v[68:71], v[182:185], v[72:75]
	v_mfma_f32_16x16x32_bf16 v[44:47], v[52:55], v[190:193], v[44:47]
	v_mfma_f32_16x16x32_bf16 v[40:43], v[68:71], v[190:193], v[40:43]
	v_mfma_f32_16x16x32_bf16 v[28:31], v[52:55], v[198:201], v[28:31]
	v_mfma_f32_16x16x32_bf16 v[24:27], v[68:71], v[198:201], v[24:27]
	v_mfma_f32_16x16x32_bf16 v[12:15], v[52:55], v[214:217], v[12:15]
	v_mfma_f32_16x16x32_bf16 v[8:11], v[68:71], v[214:217], v[8:11]
	s_setprio 0
	s_setprio 1
	v_mfma_f32_16x16x32_bf16 v[36:39], v[162:165], v[186:189], 0
	v_mfma_f32_16x16x32_bf16 v[32:35], v[170:173], v[186:189], 0
	v_mfma_f32_16x16x32_bf16 v[20:23], v[162:165], v[194:197], 0
	v_mfma_f32_16x16x32_bf16 v[16:19], v[170:173], v[194:197], 0
	v_mfma_f32_16x16x32_bf16 v[4:7], v[162:165], v[202:205], 0
	v_mfma_f32_16x16x32_bf16 v[0:3], v[170:173], v[202:205], 0
	v_mfma_f32_16x16x32_bf16 v[48:51], v[162:165], v[178:181], 0
	v_mfma_f32_16x16x32_bf16 v[52:55], v[170:173], v[178:181], 0
	v_mfma_f32_16x16x32_bf16 v[36:39], v[166:169], v[190:193], v[36:39]
	v_mfma_f32_16x16x32_bf16 v[32:35], v[174:177], v[190:193], v[32:35]
	v_mfma_f32_16x16x32_bf16 v[20:23], v[166:169], v[198:201], v[20:23]
	v_mfma_f32_16x16x32_bf16 v[16:19], v[174:177], v[198:201], v[16:19]
	v_mfma_f32_16x16x32_bf16 v[4:7], v[166:169], v[214:217], v[4:7]
	v_mfma_f32_16x16x32_bf16 v[0:3], v[174:177], v[214:217], v[0:3]
	v_mfma_f32_16x16x32_bf16 v[48:51], v[166:169], v[182:185], v[48:51]
	v_mfma_f32_16x16x32_bf16 v[52:55], v[174:177], v[182:185], v[52:55]
	s_setprio 0
	s_barrier
	s_branch .Lmy_mid_1047

; #define PG8_STAGE(bufoff, gbase, voff) do { _Pragma("unroll") for (int _i = 0; _i < 2; ++_i) \
;         __builtin_amdgcn_global_load_lds((const unsigned*)((const char*)(gbase) + (voff)[_i]), (PG8_LAS unsigned*)(lds + (bufoff) + ldsw + _i * 8192), 16, 0, 0); } while (0)
; #define PG8_LDA(dst, b, h) do { _Pragma("unroll") for (int m = 0; m < 4; ++m) _Pragma("unroll") for (int k = 0; k < 2; ++k) dst[m][k] = *(const PG8_LAS bf16x8*)(lds + PG8_SA(b, h) + aoff + m * 2048 + k * 1024); } while (0)
; #define PG8_LDB(dst, b, h) do { _Pragma("unroll") for (int n = 0; n < 2; ++n) _Pragma("unroll") for (int k = 0; k < 2; ++k) dst[n][k] = *(const PG8_LAS bf16x8*)(lds + PG8_SB(b, h) + boff + n * 2048 + k * 1024); } while (0)
; #define PG8_MMA(ai, bj, At, Bt) do { __builtin_amdgcn_s_setprio(1); _Pragma("unroll") for (int m = 0; m < 4; ++m) _Pragma("unroll") for (int n = 0; n < 2; ++n) _Pragma("unroll") for (int k = 0; k < 2; ++k) \
;         acc[ai][bj][m][n] = __builtin_amdgcn_mfma_f32_16x16x32_bf16(Bt[n][k], At[m][k], acc[ai][bj][m][n], 0, 0, 0); __builtin_amdgcn_s_setprio(0); } while (0)
; #define PG8_WAIT_V(n) asm volatile("s_waitcnt vmcnt(" #n ")" ::: "memory")
; #define PG8_WAIT_L(n) asm volatile("s_waitcnt lgkmcnt(" #n ")" ::: "memory")
; #define PG8_BAR __builtin_amdgcn_s_barrier()
; #define PG8_SCHED __builtin_amdgcn_sched_barrier(0)
; template <class Epi, class Sched, bool ALIGN_EPI = false, bool SP2 = false>
; __device__ __forceinline__ void gemm_phase(PG8_LAS unsigned char* lds, const Gemm g, const Sched& S, const Epi& E, const int tid) {
;     ...
;             PG8_LDB(B0, 1, 0); PG8_LDB(B1, 1, 1); PG8_SCHED; PG8_LDA(At, 1, 0); PG8_STAGE(PG8_SA(0, 1), a2 + hstep, voffA);
;             PG8_WAIT_V(8); PG8_WAIT_L(0); PG8_BAR; PG8_MMA(0, 0, At, B0); PG8_MMA(0, 1, At, B1); PG8_BAR; PG8_SCHED;
;             PG8_LDA(At, 1, 1); PG8_STAGE(PG8_SB(1, 0), b3, voffB); PG8_STAGE(PG8_SB(1, 1), b3 + hstep, voffB); PG8_STAGE(PG8_SA(1, 0), a3, voffA);
.Lmy_mid_1047:
	s_add_i32 s51, 0, 0x18000
	s_add_i32 s52, 0, 0x1c000
	v_add_u32_e32 v68, s51, v157
	v_add_u32_e32 v154, s52, v157
	ds_read_b128 v[56:59], v68
	ds_read_b128 v[60:63], v68 offset:1024
	ds_read_b128 v[64:67], v68 offset:2048
	ds_read_b128 v[68:71], v68 offset:3072
	ds_read_b128 v[162:165], v154
	ds_read_b128 v[166:169], v154 offset:1024
	ds_read_b128 v[170:173], v154 offset:2048
	ds_read_b128 v[174:177], v154 offset:3072
	s_add_u32 s28, s28, 0x80000
	s_addc_u32 s29, s29, 0
	s_mov_b32 m0, s40
	v_lshl_add_u64 v[222:223], s[28:29], 0, v[148:149]
	ds_read_b128 v[178:181], v161 offset:32768
	ds_read_b128 v[182:185], v161 offset:33792
	ds_read_b128 v[186:189], v161 offset:34816
	ds_read_b128 v[190:193], v161 offset:35840
	ds_read_b128 v[194:197], v161 offset:36864
	ds_read_b128 v[198:201], v161 offset:37888
	ds_read_b128 v[202:205], v161 offset:38912
	ds_read_b128 v[214:217], v161 offset:39936
	global_load_lds_dwordx4 v[222:223], off
	v_lshl_add_u64 v[222:223], s[28:29], 0, v[146:147]
	s_mov_b32 m0, s41
	s_nop 0
	global_load_lds_dwordx4 v[222:223], off
	s_waitcnt vmcnt(8)
	s_waitcnt lgkmcnt(0)
	s_barrier
	s_setprio 1
	s_waitcnt lgkmcnt(0)
	v_mfma_f32_16x16x32_bf16 v[140:143], v[56:59], v[178:181], v[140:143]
	v_mfma_f32_16x16x32_bf16 v[136:139], v[64:67], v[178:181], v[136:139]
	v_mfma_f32_16x16x32_bf16 v[124:127], v[56:59], v[186:189], v[124:127]
	v_mfma_f32_16x16x32_bf16 v[120:123], v[64:67], v[186:189], v[120:123]
	v_mfma_f32_16x16x32_bf16 v[108:111], v[56:59], v[194:197], v[108:111]
	v_mfma_f32_16x16x32_bf16 v[104:107], v[64:67], v[194:197], v[104:107]
	v_mfma_f32_16x16x32_bf16 v[92:95], v[56:59], v[202:205], v[92:95]
	v_mfma_f32_16x16x32_bf16 v[88:91], v[64:67], v[202:205], v[88:91]
	v_mfma_f32_16x16x32_bf16 v[140:143], v[60:63], v[182:185], v[140:143]
	v_mfma_f32_16x16x32_bf16 v[136:139], v[68:71], v[182:185], v[136:139]
	v_mfma_f32_16x16x32_bf16 v[124:127], v[60:63], v[190:193], v[124:127]
	v_mfma_f32_16x16x32_bf16 v[120:123], v[68:71], v[190:193], v[120:123]
	v_mfma_f32_16x16x32_bf16 v[108:111], v[60:63], v[198:201], v[108:111]
	v_mfma_f32_16x16x32_bf16 v[104:107], v[68:71], v[198:201], v[104:107]
	v_mfma_f32_16x16x32_bf16 v[92:95], v[60:63], v[214:217], v[92:95]
	v_mfma_f32_16x16x32_bf16 v[88:91], v[68:71], v[214:217], v[88:91]
	s_setprio 0
	s_setprio 1
	v_mfma_f32_16x16x32_bf16 v[132:135], v[162:165], v[178:181], v[132:135]
	v_mfma_f32_16x16x32_bf16 v[128:131], v[170:173], v[178:181], v[128:131]
	v_mfma_f32_16x16x32_bf16 v[116:119], v[162:165], v[186:189], v[116:119]
	v_mfma_f32_16x16x32_bf16 v[112:115], v[170:173], v[186:189], v[112:115]
	v_mfma_f32_16x16x32_bf16 v[100:103], v[162:165], v[194:197], v[100:103]
	v_mfma_f32_16x16x32_bf16 v[96:99], v[170:173], v[194:197], v[96:99]
	v_mfma_f32_16x16x32_bf16 v[84:87], v[162:165], v[202:205], v[84:87]
	v_mfma_f32_16x16x32_bf16 v[80:83], v[170:173], v[202:205], v[80:83]
	v_mfma_f32_16x16x32_bf16 v[132:135], v[166:169], v[182:185], v[132:135]
	v_mfma_f32_16x16x32_bf16 v[128:131], v[174:177], v[182:185], v[128:131]
	v_mfma_f32_16x16x32_bf16 v[116:119], v[166:169], v[190:193], v[116:119]
	v_mfma_f32_16x16x32_bf16 v[112:115], v[174:177], v[190:193], v[112:115]
	v_mfma_f32_16x16x32_bf16 v[100:103], v[166:169], v[198:201], v[100:103]
	v_mfma_f32_16x16x32_bf16 v[96:99], v[174:177], v[198:201], v[96:99]
	v_mfma_f32_16x16x32_bf16 v[84:87], v[166:169], v[214:217], v[84:87]
	v_mfma_f32_16x16x32_bf16 v[80:83], v[174:177], v[214:217], v[80:83]
	s_setprio 0
	s_barrier
	s_add_i32 s28, s51, s38
	v_lshl_add_u64 v[206:207], v[206:207], 0, s[2:3]
	s_mov_b32 m0, s28
	ds_read_b128 v[178:181], v161 offset:49152
	ds_read_b128 v[182:185], v161 offset:50176
	ds_read_b128 v[186:189], v161 offset:51200
	ds_read_b128 v[190:193], v161 offset:52224
	ds_read_b128 v[194:197], v161 offset:53248
	ds_read_b128 v[198:201], v161 offset:54272
	ds_read_b128 v[202:205], v161 offset:55296
	ds_read_b128 v[214:217], v161 offset:56320
	global_load_lds_dwordx4 v[206:207], off
	s_add_i32 m0, s28, 0x2000
	s_add_u32 s26, s26, 0x80080
	v_lshl_add_u64 v[206:207], v[210:211], 0, s[2:3]
	s_addc_u32 s27, s27, 0
	s_add_i32 s28, s52, s38
	global_load_lds_dwordx4 v[206:207], off
	v_lshl_add_u64 v[206:207], s[26:27], 0, v[208:209]
	s_mov_b32 m0, s28
	s_nop 0
	global_load_lds_dwordx4 v[206:207], off
	v_lshl_add_u64 v[206:207], s[26:27], 0, v[144:145]
	s_add_i32 m0, s28, 0x2000
	s_nop 0
	global_load_lds_dwordx4 v[206:207], off
	v_lshl_add_u64 v[206:207], v[218:219], 0, s[2:3]
	s_mov_b32 m0, s44
	s_nop 0
	global_load_lds_dwordx4 v[206:207], off
	v_lshl_add_u64 v[206:207], v[220:221], 0, s[2:3]
	s_mov_b32 m0, s45
	s_nop 0
	global_load_lds_dwordx4 v[206:207], off
	s_waitcnt vmcnt(8)
	s_waitcnt lgkmcnt(0)
	s_barrier
; #define PG8_STAGE(bufoff, gbase, voff) do { _Pragma("unroll") for (int _i = 0; _i < 2; ++_i) \
;         __builtin_amdgcn_global_load_lds((const unsigned*)((const char*)(gbase) + (voff)[_i]), (PG8_LAS unsigned*)(lds + (bufoff) + ldsw + _i * 8192), 16, 0, 0); } while (0)
; #define PG8_LDA(dst, b, h) do { _Pragma("unroll") for (int m = 0; m < 4; ++m) _Pragma("unroll") for (int k = 0; k < 2; ++k) dst[m][k] = *(const PG8_LAS bf16x8*)(lds + PG8_SA(b, h) + aoff + m * 2048 + k * 1024); } while (0)
; #define PG8_MMA(ai, bj, At, Bt) do { __builtin_amdgcn_s_setprio(1); _Pragma("unroll") for (int m = 0; m < 4; ++m) _Pragma("unroll") for (int n = 0; n < 2; ++n) _Pragma("unroll") for (int k = 0; k < 2; ++k) \
;         acc[ai][bj][m][n] = __builtin_amdgcn_mfma_f32_16x16x32_bf16(Bt[n][k], At[m][k], acc[ai][bj][m][n], 0, 0, 0); __builtin_amdgcn_s_setprio(0); } while (0)
; #define PG8_WAIT_V(n) asm volatile("s_waitcnt vmcnt(" #n ")" ::: "memory")
; #define PG8_WAIT_L(n) asm volatile("s_waitcnt lgkmcnt(" #n ")" ::: "memory")
; #define PG8_BAR __builtin_amdgcn_s_barrier()
; #define PG8_SCHED __builtin_amdgcn_sched_barrier(0)
; template <class Epi, class Sched, bool ALIGN_EPI = false, bool SP2 = false>
; __device__ __forceinline__ void gemm_phase(PG8_LAS unsigned char* lds, const Gemm g, const Sched& S, const Epi& E, const int tid) {
;     ...
;             PG8_LDA(At, 1, 1); PG8_STAGE(PG8_SB(1, 0), b3, voffB); PG8_STAGE(PG8_SB(1, 1), b3 + hstep, voffB); PG8_STAGE(PG8_SA(1, 0), a3, voffA);
;             PG8_WAIT_V(8); PG8_WAIT_L(0); PG8_BAR; PG8_MMA(1, 0, At, B0); PG8_MMA(1, 1, At, B1); PG8_BAR; PG8_SCHED;
;     __device__ __forceinline__ void operator()(const f32x4 (&acc)[2][2][4][2], const Unit& un, int wr, int wc, int fr, int fq) const {
;         const int rbase = un.pm * 256 + wr * 64 + fr, cw = un.pn * 256 + wc * 32 + 8 * fq;
;         const int slot = un.pm < (NLAT / 256) ? (un.pm >> 5) : 4; const float* sw = shw + (size_t)slot * DFF;
;         f32x4 s0[2], s1[2]; float rr[2][4];
; #pragma unroll
;         for (int bj = 0; bj < 2; ++bj) { s0[bj] = *(const f32x4*)(sw + cw + bj * 128); s1[bj] = *(const f32x4*)(sw + cw + bj * 128 + 4); }
; #pragma unroll
;         for (int ai = 0; ai < 2; ++ai)
; #pragma unroll
;             for (int m = 0; m < 4; ++m) rr[ai][m] = rs[rbase + ai * 128 + m * 16];
	s_setprio 1
	s_waitcnt lgkmcnt(0)
	v_mfma_f32_16x16x32_bf16 v[76:79], v[56:59], v[178:181], v[76:79]
	v_mfma_f32_16x16x32_bf16 v[72:75], v[64:67], v[178:181], v[72:75]
	v_mfma_f32_16x16x32_bf16 v[44:47], v[56:59], v[186:189], v[44:47]
	v_mfma_f32_16x16x32_bf16 v[40:43], v[64:67], v[186:189], v[40:43]
	v_mfma_f32_16x16x32_bf16 v[28:31], v[56:59], v[194:197], v[28:31]
	v_mfma_f32_16x16x32_bf16 v[24:27], v[64:67], v[194:197], v[24:27]
	v_mfma_f32_16x16x32_bf16 v[12:15], v[56:59], v[202:205], v[12:15]
	v_mfma_f32_16x16x32_bf16 v[8:11], v[64:67], v[202:205], v[8:11]
	v_mfma_f32_16x16x32_bf16 v[76:79], v[60:63], v[182:185], v[76:79]
	v_mfma_f32_16x16x32_bf16 v[72:75], v[68:71], v[182:185], v[72:75]
	v_mfma_f32_16x16x32_bf16 v[44:47], v[60:63], v[190:193], v[44:47]
	v_mfma_f32_16x16x32_bf16 v[40:43], v[68:71], v[190:193], v[40:43]
	v_mfma_f32_16x16x32_bf16 v[28:31], v[60:63], v[198:201], v[28:31]
	v_mfma_f32_16x16x32_bf16 v[24:27], v[68:71], v[198:201], v[24:27]
	v_mfma_f32_16x16x32_bf16 v[12:15], v[60:63], v[214:217], v[12:15]
	v_mfma_f32_16x16x32_bf16 v[8:11], v[68:71], v[214:217], v[8:11]
	s_setprio 0
	s_setprio 1
	v_mfma_f32_16x16x32_bf16 v[48:51], v[162:165], v[178:181], v[48:51]
	v_mfma_f32_16x16x32_bf16 v[60:63], v[166:169], v[182:185], v[48:51]
	v_mfma_f32_16x16x32_bf16 v[48:51], v[170:173], v[178:181], v[52:55]
	v_mfma_f32_16x16x32_bf16 v[36:39], v[162:165], v[186:189], v[36:39]
	v_mfma_f32_16x16x32_bf16 v[32:35], v[170:173], v[186:189], v[32:35]
	v_mfma_f32_16x16x32_bf16 v[20:23], v[162:165], v[194:197], v[20:23]
	v_mfma_f32_16x16x32_bf16 v[16:19], v[170:173], v[194:197], v[16:19]
	v_mfma_f32_16x16x32_bf16 v[4:7], v[162:165], v[202:205], v[4:7]
	v_mfma_f32_16x16x32_bf16 v[0:3], v[170:173], v[202:205], v[0:3]
	v_mfma_f32_16x16x32_bf16 v[56:59], v[174:177], v[182:185], v[48:51]
	v_mfma_f32_16x16x32_bf16 v[36:39], v[166:169], v[190:193], v[36:39]
	v_mfma_f32_16x16x32_bf16 v[32:35], v[174:177], v[190:193], v[32:35]
	v_mfma_f32_16x16x32_bf16 v[20:23], v[166:169], v[198:201], v[20:23]
	v_mfma_f32_16x16x32_bf16 v[16:19], v[174:177], v[198:201], v[16:19]
	v_mfma_f32_16x16x32_bf16 v[4:7], v[166:169], v[214:217], v[4:7]
	v_mfma_f32_16x16x32_bf16 v[0:3], v[174:177], v[214:217], v[0:3]
	s_setprio 0
	s_barrier
	s_add_i32 s50, s50, 2
	s_add_u32 s24, s24, 0x100
	s_addc_u32 s25, s25, 0
	s_add_u32 s48, s48, 0x100
	s_addc_u32 s49, s49, 0
	s_cmp_gt_u32 s50, 29
	s_cbranch_scc0 .LBB0_1047
	s_ashr_i32 s24, s20, 5
	s_ashr_i32 s25, s24, 31
	s_lshl_b64 s[24:25], s[24:25], 13
	s_cmpk_lt_i32 s20, 0x80
	s_cselect_b32 s25, s25, 0
	s_cselect_b32 s24, s24, 0x8000
	s_lshl_b64 s[24:25], s[24:25], 2
	v_lshl_or_b32 v176, s22, 8, v159
	s_add_u32 s24, s42, s24
	v_lshl_add_u32 v178, s20, 8, v155
	s_addc_u32 s25, s43, s25
	v_ashrrev_i32_e32 v177, 31, v176
	v_ashrrev_i32_e32 v179, 31, v178
	v_lshl_add_u64 v[52:53], v[176:177], 2, s[24:25]
	v_lshl_add_u64 v[180:181], v[178:179], 2, s[6:7]
	global_load_dwordx4 v[64:67], v[52:53], off offset:16
	global_load_dwordx4 v[68:71], v[52:53], off
	global_load_dwordx4 v[48:51], v[52:53], off offset:528
	s_nop 0
	global_load_dwordx4 v[52:55], v[52:53], off offset:512
	v_or_b32_e32 v172, 16, v178
	global_load_dword v174, v[180:181], off
	v_ashrrev_i32_e32 v173, 31, v172
	v_lshl_add_u64 v[162:163], v[172:173], 2, s[6:7]
	global_load_dword v170, v[162:163], off
	v_or_b32_e32 v168, 32, v178
	v_ashrrev_i32_e32 v169, 31, v168
	v_lshl_add_u64 v[162:163], v[168:169], 2, s[6:7]
	global_load_dword v166, v[162:163], off
	v_or_b32_e32 v164, 48, v178
	v_lshlrev_b64 v[178:179], 14, v[178:179]
	v_ashrrev_i32_e32 v165, 31, v164
	v_lshl_add_u64 v[162:163], v[164:165], 2, s[6:7]
	global_load_dword v162, v[162:163], off
	s_nop 0
	global_load_dword v160, v[180:181], off offset:512
	global_load_dword v158, v[180:181], off offset:576
	global_load_dword v156, v[180:181], off offset:640
	global_load_dword v154, v[180:181], off offset:704
	s_and_b64 vcc, exec, s[8:9]
	s_cbranch_vccz .LBB0_1050
	s_barrier

;     __host__ __device__ bool next(int i, Unit& u) const { const int L = base + i * Gp + cp; if (L >= end) return false; return T.next(L, u); }
;     __host__ __device__ bool next(int i, Unit& u) const { const int L = i * Gp + cp; if (cp < 0 || L >= n) return false; u.kb = L & 3; u.pn = (L >> 2) % nN; u.pm = pm0 + (L >> 2) / nN; return true; }
;     __host__ __device__ bool next(int i, Unit& u) const { const bool ok = T.next(i >> 2, u); u.kb = i & 3; return ok; }
; #define PG8_BAR __builtin_amdgcn_s_barrier()
; template <class Epi, class Sched, bool ALIGN_EPI = false, bool SP2 = false>
; __device__ __forceinline__ void gemm_phase(PG8_LAS unsigned char* lds, const Gemm g, const Sched& S, const Epi& E, const int tid) {
;     ...
;         const bool has_next = S.next(ui + 1, nxt);
;         const char* nA = has_next ? (const char*)g.A + (size_t)nxt.pm * tstep + (size_t)nxt.kb * g.sA : cA; const char* nB = has_next ? (const char*)g.Bt + (size_t)nxt.pn * tstep + (size_t)nxt.kb * g.sB : cB;
;         for (int t = 0; t < nt; t += 2) {
;             const bool last = (t == nt - 2);
;             const char* a1 = cA + (size_t)(t + 1) * kstep;
;             const char* a2 = last ? nA : cA + (size_t)(t + 2) * kstep; const char* b2 = last ? nB : cB + (size_t)(t + 2) * kstep;
;     ...
; #pragma unroll
;         for (int a = 0; a < 2; ++a)
; #pragma unroll
;             for (int b = 0; b < 2; ++b)
; #pragma unroll
;                 for (int m = 0; m < 4; ++m)
; #pragma unroll
;                     for (int n = 0; n < 2; ++n) acc[a][b][m][n] = (f32x4){0.f, 0.f, 0.f, 0.f};
;         cur = nxt; cA = nA; cB = nB; ++ui;
;         if constexpr (ALIGN_EPI) { if (wr == 1) PG8_BAR; }
.LBB0_1127:
	s_ashr_i32 s13, s12, 31
	s_lshl_b64 s[18:19], s[12:13], 18
	s_add_u32 s13, s34, s18
	s_addc_u32 s15, s35, s19
	s_lshl_b32 s18, s47, 21
	s_add_u32 s18, s13, s18
	s_addc_u32 s19, s15, 0
	s_and_b64 s[4:5], s[4:5], exec
	s_cselect_b32 s13, s19, s25
	s_cselect_b32 s15, s18, s24
	s_add_u32 s4, s26, 0x20080
	s_addc_u32 s5, s27, 0
	s_add_u32 s21, s24, 0x100
	v_mov_b32_e32 v0, 0
	s_addc_u32 s23, s25, 0
	s_mov_b32 s49, -2
	s_cmp_eq_u32 s100, 0
	s_cbranch_scc1 .Lmy_nobar_1128
	s_barrier
	s_mov_b32 s100, 0
; #define PG8_STAGE(bufoff, gbase, voff) do { _Pragma("unroll") for (int _i = 0; _i < 2; ++_i) \
;         __builtin_amdgcn_global_load_lds((const unsigned*)((const char*)(gbase) + (voff)[_i]), (PG8_LAS unsigned*)(lds + (bufoff) + ldsw + _i * 8192), 16, 0, 0); } while (0)
; #define PG8_LDA(dst, b, h) do { _Pragma("unroll") for (int m = 0; m < 4; ++m) _Pragma("unroll") for (int k = 0; k < 2; ++k) dst[m][k] = *(const PG8_LAS bf16x8*)(lds + PG8_SA(b, h) + aoff + m * 2048 + k * 1024); } while (0)
; #define PG8_LDB(dst, b, h) do { _Pragma("unroll") for (int n = 0; n < 2; ++n) _Pragma("unroll") for (int k = 0; k < 2; ++k) dst[n][k] = *(const PG8_LAS bf16x8*)(lds + PG8_SB(b, h) + boff + n * 2048 + k * 1024); } while (0)
; #define PG8_MMA(ai, bj, At, Bt) do { __builtin_amdgcn_s_setprio(1); _Pragma("unroll") for (int m = 0; m < 4; ++m) _Pragma("unroll") for (int n = 0; n < 2; ++n) _Pragma("unroll") for (int k = 0; k < 2; ++k) \
;         acc[ai][bj][m][n] = __builtin_amdgcn_mfma_f32_16x16x32_bf16(Bt[n][k], At[m][k], acc[ai][bj][m][n], 0, 0, 0); __builtin_amdgcn_s_setprio(0); } while (0)
; #define PG8_WAIT_V(n) asm volatile("s_waitcnt vmcnt(" #n ")" ::: "memory")
; #define PG8_WAIT_L(n) asm volatile("s_waitcnt lgkmcnt(" #n ")" ::: "memory")
; #define PG8_BAR __builtin_amdgcn_s_barrier()
; template <class Epi, class Sched, bool ALIGN_EPI = false, bool SP2 = false>
; __device__ __forceinline__ void gemm_phase(PG8_LAS unsigned char* lds, const Gemm g, const Sched& S, const Epi& E, const int tid) {
;     ...
;             const char* a1 = cA + (size_t)(t + 1) * kstep;
;             const char* a2 = last ? nA : cA + (size_t)(t + 2) * kstep; const char* b2 = last ? nB : cB + (size_t)(t + 2) * kstep;
;             const char* a3 = a2 + kstep; const char* b3 = b2 + kstep;
;             if (last && has_next) S.a_ready(nxt);
;             if constexpr (SP2) {
;             PG8_LDB(B0, 0, 0); PG8_LDB(B1, 0, 1); PG8_SCHED; PG8_LDA(At, 0, 0); PG8_STAGE(PG8_SA(1, 1), a1 + hstep, voffA);
;             PG8_WAIT_V(8); PG8_WAIT_L(0); PG8_BAR; PG8_MMA(0, 0, At, B0); PG8_MMA(0, 1, At, B1); PG8_BAR; PG8_SCHED;
;             PG8_LDA(At, 0, 1); PG8_STAGE(PG8_SB(0, 0), b2, voffB); PG8_STAGE(PG8_SB(0, 1), b2 + hstep, voffB); PG8_STAGE(PG8_SA(0, 0), a2, voffA);
;             PG8_WAIT_V(8); PG8_WAIT_L(0); PG8_BAR; PG8_MMA(1, 0, At, B0); PG8_MMA(1, 1, At, B1); PG8_BAR; PG8_SCHED;
.Lmy_nobar_1128:
	s_add_u32 s24, s4, 0xfffe0080
	s_addc_u32 s25, s5, -1
	s_add_i32 s50, 0, 0x10000
	v_add_u32_e32 v140, s50, v211
	v_add_u32_e32 v156, s33, v211
	ds_read_b128 v[128:131], v140
	ds_read_b128 v[132:135], v140 offset:1024
	ds_read_b128 v[136:139], v140 offset:2048
	ds_read_b128 v[140:143], v140 offset:3072
	ds_read_b128 v[144:147], v156
	ds_read_b128 v[148:151], v156 offset:1024
	ds_read_b128 v[152:155], v156 offset:2048
	ds_read_b128 v[156:159], v156 offset:3072
	s_cmp_eq_u32 s49, 4
	s_cselect_b32 s27, s17, s25
	s_cselect_b32 s26, s16, s24
	s_cselect_b32 s25, s13, s23
	s_cselect_b32 s24, s15, s21
	v_lshl_add_u64 v[192:193], s[4:5], 0, v[200:201]
	s_add_i32 m0, s37, 0xc000
	ds_read_b128 v[160:163], v225
	ds_read_b128 v[164:167], v225 offset:1024
	ds_read_b128 v[168:171], v225 offset:2048
	ds_read_b128 v[172:175], v225 offset:3072
	ds_read_b128 v[176:179], v225 offset:4096
	ds_read_b128 v[180:183], v225 offset:5120
	ds_read_b128 v[184:187], v225 offset:6144
	ds_read_b128 v[188:191], v225 offset:7168
	global_load_lds_dwordx4 v[192:193], off
	v_lshl_add_u64 v[192:193], s[4:5], 0, v[202:203]
	s_add_i32 m0, s37, 0xe000
	s_nop 0
	global_load_lds_dwordx4 v[192:193], off
	s_waitcnt vmcnt(8)
	s_waitcnt lgkmcnt(0)
	s_barrier
	s_setprio 1
	s_waitcnt lgkmcnt(0)
	v_mfma_f32_16x16x32_bf16 v[124:127], v[128:131], v[160:163], 0
	v_mfma_f32_16x16x32_bf16 v[120:123], v[136:139], v[160:163], 0
	v_mfma_f32_16x16x32_bf16 v[108:111], v[128:131], v[168:171], 0
	v_mfma_f32_16x16x32_bf16 v[104:107], v[136:139], v[168:171], 0
	v_mfma_f32_16x16x32_bf16 v[100:103], v[128:131], v[176:179], 0
	v_mfma_f32_16x16x32_bf16 v[96:99], v[136:139], v[176:179], 0
	v_mfma_f32_16x16x32_bf16 v[92:95], v[128:131], v[184:187], 0
	v_mfma_f32_16x16x32_bf16 v[88:91], v[136:139], v[184:187], 0
	v_mfma_f32_16x16x32_bf16 v[124:127], v[132:135], v[164:167], v[124:127]
	v_mfma_f32_16x16x32_bf16 v[120:123], v[140:143], v[164:167], v[120:123]
	v_mfma_f32_16x16x32_bf16 v[108:111], v[132:135], v[172:175], v[108:111]
	v_mfma_f32_16x16x32_bf16 v[104:107], v[140:143], v[172:175], v[104:107]
	v_mfma_f32_16x16x32_bf16 v[100:103], v[132:135], v[180:183], v[100:103]
	v_mfma_f32_16x16x32_bf16 v[96:99], v[140:143], v[180:183], v[96:99]
	v_mfma_f32_16x16x32_bf16 v[92:95], v[132:135], v[188:191], v[92:95]
	v_mfma_f32_16x16x32_bf16 v[88:91], v[140:143], v[188:191], v[88:91]
	s_setprio 0
	s_setprio 1
	v_mfma_f32_16x16x32_bf16 v[116:119], v[144:147], v[160:163], 0
	v_mfma_f32_16x16x32_bf16 v[112:115], v[152:155], v[160:163], 0
	v_mfma_f32_16x16x32_bf16 v[84:87], v[144:147], v[168:171], 0
	v_mfma_f32_16x16x32_bf16 v[80:83], v[152:155], v[168:171], 0
	v_mfma_f32_16x16x32_bf16 v[76:79], v[144:147], v[176:179], 0
	v_mfma_f32_16x16x32_bf16 v[72:75], v[152:155], v[176:179], 0
	v_mfma_f32_16x16x32_bf16 v[68:71], v[144:147], v[184:187], 0
	v_mfma_f32_16x16x32_bf16 v[64:67], v[152:155], v[184:187], 0
	v_mfma_f32_16x16x32_bf16 v[116:119], v[148:151], v[164:167], v[116:119]
	v_mfma_f32_16x16x32_bf16 v[112:115], v[156:159], v[164:167], v[112:115]
	v_mfma_f32_16x16x32_bf16 v[84:87], v[148:151], v[172:175], v[84:87]
	v_mfma_f32_16x16x32_bf16 v[80:83], v[156:159], v[172:175], v[80:83]
	v_mfma_f32_16x16x32_bf16 v[76:79], v[148:151], v[180:183], v[76:79]
	v_mfma_f32_16x16x32_bf16 v[72:75], v[156:159], v[180:183], v[72:75]
	v_mfma_f32_16x16x32_bf16 v[68:71], v[148:151], v[188:191], v[68:71]
	v_mfma_f32_16x16x32_bf16 v[64:67], v[156:159], v[188:191], v[64:67]
	s_setprio 0
	s_barrier
	s_add_i32 s50, s50, s36
	v_lshl_add_u64 v[192:193], s[24:25], 0, v[208:209]
	s_mov_b32 m0, s50
	ds_read_b128 v[160:163], v225 offset:16384
	ds_read_b128 v[164:167], v225 offset:17408
	ds_read_b128 v[168:171], v225 offset:18432
	ds_read_b128 v[172:175], v225 offset:19456
	ds_read_b128 v[176:179], v225 offset:20480
	ds_read_b128 v[180:183], v225 offset:21504
	ds_read_b128 v[184:187], v225 offset:22528
	ds_read_b128 v[188:191], v225 offset:23552
	global_load_lds_dwordx4 v[192:193], off
	s_add_i32 m0, s50, 0x2000
	s_add_u32 s50, s24, 0x20000
	v_lshl_add_u64 v[204:205], s[24:25], 0, v[198:199]
	s_addc_u32 s51, s25, 0
	s_add_i32 s52, s33, s36
	global_load_lds_dwordx4 v[204:205], off
	v_lshl_add_u64 v[206:207], s[50:51], 0, v[208:209]
	s_mov_b32 m0, s52
	v_lshl_add_u64 v[214:215], s[26:27], 0, v[196:197]
	global_load_lds_dwordx4 v[206:207], off
	v_lshl_add_u64 v[206:207], s[50:51], 0, v[198:199]
	s_add_i32 m0, s52, 0x2000
	s_nop 0
	global_load_lds_dwordx4 v[206:207], off
	v_lshl_add_u64 v[206:207], s[26:27], 0, v[194:195]
	s_mov_b32 m0, s37
	s_nop 0
	global_load_lds_dwordx4 v[206:207], off
	s_mov_b32 m0, s38
	s_nop 0
	global_load_lds_dwordx4 v[214:215], off
	s_waitcnt vmcnt(8)
	s_waitcnt lgkmcnt(0)
	s_barrier
	s_setprio 1
	s_waitcnt lgkmcnt(0)
	v_mfma_f32_16x16x32_bf16 v[60:63], v[128:131], v[160:163], 0
	v_mfma_f32_16x16x32_bf16 v[56:59], v[136:139], v[160:163], 0
	v_mfma_f32_16x16x32_bf16 v[44:47], v[128:131], v[168:171], 0
	v_mfma_f32_16x16x32_bf16 v[40:43], v[136:139], v[168:171], 0
	v_mfma_f32_16x16x32_bf16 v[28:31], v[128:131], v[176:179], 0
	v_mfma_f32_16x16x32_bf16 v[24:27], v[136:139], v[176:179], 0
	v_mfma_f32_16x16x32_bf16 v[12:15], v[128:131], v[184:187], 0
	v_mfma_f32_16x16x32_bf16 v[8:11], v[136:139], v[184:187], 0
	v_mfma_f32_16x16x32_bf16 v[60:63], v[132:135], v[164:167], v[60:63]
	v_mfma_f32_16x16x32_bf16 v[56:59], v[140:143], v[164:167], v[56:59]
	v_mfma_f32_16x16x32_bf16 v[44:47], v[132:135], v[172:175], v[44:47]
	v_mfma_f32_16x16x32_bf16 v[40:43], v[140:143], v[172:175], v[40:43]
	v_mfma_f32_16x16x32_bf16 v[28:31], v[132:135], v[180:183], v[28:31]
	v_mfma_f32_16x16x32_bf16 v[24:27], v[140:143], v[180:183], v[24:27]
	v_mfma_f32_16x16x32_bf16 v[12:15], v[132:135], v[188:191], v[12:15]
	v_mfma_f32_16x16x32_bf16 v[8:11], v[140:143], v[188:191], v[8:11]
	s_setprio 0
	s_setprio 1
	v_mfma_f32_16x16x32_bf16 v[52:55], v[144:147], v[160:163], 0
	v_mfma_f32_16x16x32_bf16 v[48:51], v[152:155], v[160:163], 0
	v_mfma_f32_16x16x32_bf16 v[36:39], v[144:147], v[168:171], 0
	v_mfma_f32_16x16x32_bf16 v[32:35], v[152:155], v[168:171], 0
	v_mfma_f32_16x16x32_bf16 v[20:23], v[144:147], v[176:179], 0
	v_mfma_f32_16x16x32_bf16 v[16:19], v[152:155], v[176:179], 0
	v_mfma_f32_16x16x32_bf16 v[4:7], v[144:147], v[184:187], 0
	v_mfma_f32_16x16x32_bf16 v[0:3], v[152:155], v[184:187], 0
	v_mfma_f32_16x16x32_bf16 v[52:55], v[148:151], v[164:167], v[52:55]
	v_mfma_f32_16x16x32_bf16 v[48:51], v[156:159], v[164:167], v[48:51]
	v_mfma_f32_16x16x32_bf16 v[36:39], v[148:151], v[172:175], v[36:39]
	v_mfma_f32_16x16x32_bf16 v[32:35], v[156:159], v[172:175], v[32:35]
	v_mfma_f32_16x16x32_bf16 v[20:23], v[148:151], v[180:183], v[20:23]
	v_mfma_f32_16x16x32_bf16 v[16:19], v[156:159], v[180:183], v[16:19]
	v_mfma_f32_16x16x32_bf16 v[4:7], v[148:151], v[188:191], v[4:7]
	v_mfma_f32_16x16x32_bf16 v[0:3], v[156:159], v[188:191], v[0:3]
	s_setprio 0
	s_barrier
	s_branch .Lmy_mid_1128

; #define PG8_STAGE(bufoff, gbase, voff) do { _Pragma("unroll") for (int _i = 0; _i < 2; ++_i) \
;         __builtin_amdgcn_global_load_lds((const unsigned*)((const char*)(gbase) + (voff)[_i]), (PG8_LAS unsigned*)(lds + (bufoff) + ldsw + _i * 8192), 16, 0, 0); } while (0)
; #define PG8_LDA(dst, b, h) do { _Pragma("unroll") for (int m = 0; m < 4; ++m) _Pragma("unroll") for (int k = 0; k < 2; ++k) dst[m][k] = *(const PG8_LAS bf16x8*)(lds + PG8_SA(b, h) + aoff + m * 2048 + k * 1024); } while (0)
; #define PG8_LDB(dst, b, h) do { _Pragma("unroll") for (int n = 0; n < 2; ++n) _Pragma("unroll") for (int k = 0; k < 2; ++k) dst[n][k] = *(const PG8_LAS bf16x8*)(lds + PG8_SB(b, h) + boff + n * 2048 + k * 1024); } while (0)
; #define PG8_MMA(ai, bj, At, Bt) do { __builtin_amdgcn_s_setprio(1); _Pragma("unroll") for (int m = 0; m < 4; ++m) _Pragma("unroll") for (int n = 0; n < 2; ++n) _Pragma("unroll") for (int k = 0; k < 2; ++k) \
;         acc[ai][bj][m][n] = __builtin_amdgcn_mfma_f32_16x16x32_bf16(Bt[n][k], At[m][k], acc[ai][bj][m][n], 0, 0, 0); __builtin_amdgcn_s_setprio(0); } while (0)
; #define PG8_WAIT_V(n) asm volatile("s_waitcnt vmcnt(" #n ")" ::: "memory")
; #define PG8_WAIT_L(n) asm volatile("s_waitcnt lgkmcnt(" #n ")" ::: "memory")
; #define PG8_BAR __builtin_amdgcn_s_barrier()
; #define PG8_SCHED __builtin_amdgcn_sched_barrier(0)
; template <class Epi, class Sched, bool ALIGN_EPI = false, bool SP2 = false>
; __device__ __forceinline__ void gemm_phase(PG8_LAS unsigned char* lds, const Gemm g, const Sched& S, const Epi& E, const int tid) {
;     ...
;             PG8_LDB(B0, 1, 0); PG8_LDB(B1, 1, 1); PG8_SCHED; PG8_LDA(At, 1, 0); PG8_STAGE(PG8_SA(0, 1), a2 + hstep, voffA);
;             PG8_WAIT_V(8); PG8_WAIT_L(0); PG8_BAR; PG8_MMA(0, 0, At, B0); PG8_MMA(0, 1, At, B1); PG8_BAR; PG8_SCHED;
.Lmy_mid_1128:
	s_add_i32 s50, 0, 0x18000
	s_add_i32 s51, 0, 0x1c000
	v_add_u32_e32 v140, s50, v211
	v_add_u32_e32 v156, s51, v211
	ds_read_b128 v[128:131], v140
	ds_read_b128 v[132:135], v140 offset:1024
	ds_read_b128 v[136:139], v140 offset:2048
	ds_read_b128 v[140:143], v140 offset:3072
	ds_read_b128 v[144:147], v156
	ds_read_b128 v[148:151], v156 offset:1024
	ds_read_b128 v[152:155], v156 offset:2048
	ds_read_b128 v[156:159], v156 offset:3072
	s_add_u32 s26, s26, 0x20000
	s_addc_u32 s27, s27, 0
	s_mov_b32 m0, s39
	v_lshl_add_u64 v[216:217], s[26:27], 0, v[194:195]
	ds_read_b128 v[160:163], v225 offset:32768
	ds_read_b128 v[164:167], v225 offset:33792
	ds_read_b128 v[168:171], v225 offset:34816
	ds_read_b128 v[172:175], v225 offset:35840
	ds_read_b128 v[176:179], v225 offset:36864
	ds_read_b128 v[180:183], v225 offset:37888
	ds_read_b128 v[184:187], v225 offset:38912
	ds_read_b128 v[188:191], v225 offset:39936
	global_load_lds_dwordx4 v[216:217], off
	v_lshl_add_u64 v[216:217], s[26:27], 0, v[196:197]
	s_mov_b32 m0, s40
	s_nop 0
	global_load_lds_dwordx4 v[216:217], off
	s_waitcnt vmcnt(8)
	s_waitcnt lgkmcnt(0)
	s_barrier
	s_setprio 1
	s_waitcnt lgkmcnt(0)
	v_mfma_f32_16x16x32_bf16 v[124:127], v[128:131], v[160:163], v[124:127]
	v_mfma_f32_16x16x32_bf16 v[120:123], v[136:139], v[160:163], v[120:123]
	v_mfma_f32_16x16x32_bf16 v[108:111], v[128:131], v[168:171], v[108:111]
	v_mfma_f32_16x16x32_bf16 v[104:107], v[136:139], v[168:171], v[104:107]
	v_mfma_f32_16x16x32_bf16 v[100:103], v[128:131], v[176:179], v[100:103]
	v_mfma_f32_16x16x32_bf16 v[96:99], v[136:139], v[176:179], v[96:99]
	v_mfma_f32_16x16x32_bf16 v[92:95], v[128:131], v[184:187], v[92:95]
	v_mfma_f32_16x16x32_bf16 v[88:91], v[136:139], v[184:187], v[88:91]
	v_mfma_f32_16x16x32_bf16 v[124:127], v[132:135], v[164:167], v[124:127]
	v_mfma_f32_16x16x32_bf16 v[120:123], v[140:143], v[164:167], v[120:123]
	v_mfma_f32_16x16x32_bf16 v[108:111], v[132:135], v[172:175], v[108:111]
	v_mfma_f32_16x16x32_bf16 v[104:107], v[140:143], v[172:175], v[104:107]
	v_mfma_f32_16x16x32_bf16 v[100:103], v[132:135], v[180:183], v[100:103]
	v_mfma_f32_16x16x32_bf16 v[96:99], v[140:143], v[180:183], v[96:99]
	v_mfma_f32_16x16x32_bf16 v[92:95], v[132:135], v[188:191], v[92:95]
	v_mfma_f32_16x16x32_bf16 v[88:91], v[140:143], v[188:191], v[88:91]
	s_setprio 0
	s_setprio 1
	v_mfma_f32_16x16x32_bf16 v[116:119], v[144:147], v[160:163], v[116:119]
	v_mfma_f32_16x16x32_bf16 v[112:115], v[152:155], v[160:163], v[112:115]
	v_mfma_f32_16x16x32_bf16 v[84:87], v[144:147], v[168:171], v[84:87]
	v_mfma_f32_16x16x32_bf16 v[80:83], v[152:155], v[168:171], v[80:83]
	v_mfma_f32_16x16x32_bf16 v[76:79], v[144:147], v[176:179], v[76:79]
	v_mfma_f32_16x16x32_bf16 v[72:75], v[152:155], v[176:179], v[72:75]
	v_mfma_f32_16x16x32_bf16 v[68:71], v[144:147], v[184:187], v[68:71]
	v_mfma_f32_16x16x32_bf16 v[64:67], v[152:155], v[184:187], v[64:67]
	v_mfma_f32_16x16x32_bf16 v[116:119], v[148:151], v[164:167], v[116:119]
	v_mfma_f32_16x16x32_bf16 v[112:115], v[156:159], v[164:167], v[112:115]
	v_mfma_f32_16x16x32_bf16 v[84:87], v[148:151], v[172:175], v[84:87]
	v_mfma_f32_16x16x32_bf16 v[80:83], v[156:159], v[172:175], v[80:83]
	v_mfma_f32_16x16x32_bf16 v[76:79], v[148:151], v[180:183], v[76:79]
	v_mfma_f32_16x16x32_bf16 v[72:75], v[156:159], v[180:183], v[72:75]
	v_mfma_f32_16x16x32_bf16 v[68:71], v[148:151], v[188:191], v[68:71]
	v_mfma_f32_16x16x32_bf16 v[64:67], v[156:159], v[188:191], v[64:67]
	s_setprio 0
	s_barrier
; #define PG8_STAGE(bufoff, gbase, voff) do { _Pragma("unroll") for (int _i = 0; _i < 2; ++_i) \
;         __builtin_amdgcn_global_load_lds((const unsigned*)((const char*)(gbase) + (voff)[_i]), (PG8_LAS unsigned*)(lds + (bufoff) + ldsw + _i * 8192), 16, 0, 0); } while (0)
; #define PG8_LDA(dst, b, h) do { _Pragma("unroll") for (int m = 0; m < 4; ++m) _Pragma("unroll") for (int k = 0; k < 2; ++k) dst[m][k] = *(const PG8_LAS bf16x8*)(lds + PG8_SA(b, h) + aoff + m * 2048 + k * 1024); } while (0)
; #define PG8_MMA(ai, bj, At, Bt) do { __builtin_amdgcn_s_setprio(1); _Pragma("unroll") for (int m = 0; m < 4; ++m) _Pragma("unroll") for (int n = 0; n < 2; ++n) _Pragma("unroll") for (int k = 0; k < 2; ++k) \
;         acc[ai][bj][m][n] = __builtin_amdgcn_mfma_f32_16x16x32_bf16(Bt[n][k], At[m][k], acc[ai][bj][m][n], 0, 0, 0); __builtin_amdgcn_s_setprio(0); } while (0)
; #define PG8_WAIT_V(n) asm volatile("s_waitcnt vmcnt(" #n ")" ::: "memory")
; #define PG8_WAIT_L(n) asm volatile("s_waitcnt lgkmcnt(" #n ")" ::: "memory")
; #define PG8_BAR __builtin_amdgcn_s_barrier()
; #define PG8_SCHED __builtin_amdgcn_sched_barrier(0)
; template <class Epi, class Sched, bool ALIGN_EPI = false, bool SP2 = false>
; __device__ __forceinline__ void gemm_phase(PG8_LAS unsigned char* lds, const Gemm g, const Sched& S, const Epi& E, const int tid) {
;     ...
;             PG8_LDA(At, 1, 1); PG8_STAGE(PG8_SB(1, 0), b3, voffB); PG8_STAGE(PG8_SB(1, 1), b3 + hstep, voffB); PG8_STAGE(PG8_SA(1, 0), a3, voffA);
;             PG8_WAIT_V(8); PG8_WAIT_L(0); PG8_BAR; PG8_MMA(1, 0, At, B0); PG8_MMA(1, 1, At, B1); PG8_BAR; PG8_SCHED;
;     __device__ __forceinline__ void operator()(const f32x4 (&acc)[2][2][4][2], const Unit& un, int wr, int wc, int fr, int fq) const {
;         const int rbase = un.pm * 256 + wr * 64 + fr, cw = un.pn * 256 + wc * 32 + 8 * fq, kb = un.kb;
; #pragma unroll
;         for (int ai = 0; ai < 2; ++ai) {
;             u32x4 ga_[4][2], pa_[4][2];
; #pragma unroll
;             for (int m = 0; m < 4; ++m)
; #pragma unroll
;                 for (int bj = 0; bj < 2; ++bj) { const int row = rbase + ai * 128 + m * 16, col = cw + bj * 128; ga_[m][bj] = *(const u32x4*)(gate + (size_t)row * DFF + kb * D + col);
;                     pa_[m][bj] = kb > 0 ? *(const u32x4*)(mg + (size_t)row * D + col) : (u32x4){0u, 0u, 0u, 0u}; }
	s_add_i32 s26, s50, s36
	v_lshl_add_u64 v[192:193], v[192:193], 0, s[2:3]
	s_mov_b32 m0, s26
	ds_read_b128 v[160:163], v225 offset:49152
	ds_read_b128 v[164:167], v225 offset:50176
	ds_read_b128 v[168:171], v225 offset:51200
	ds_read_b128 v[172:175], v225 offset:52224
	ds_read_b128 v[176:179], v225 offset:53248
	ds_read_b128 v[180:183], v225 offset:54272
	ds_read_b128 v[184:187], v225 offset:55296
	ds_read_b128 v[188:191], v225 offset:56320
	global_load_lds_dwordx4 v[192:193], off
	s_add_i32 m0, s26, 0x2000
	s_add_u32 s24, s24, 0x20080
	v_lshl_add_u64 v[192:193], v[204:205], 0, s[2:3]
	s_addc_u32 s25, s25, 0
	s_add_i32 s26, s51, s36
	global_load_lds_dwordx4 v[192:193], off
	v_lshl_add_u64 v[192:193], s[24:25], 0, v[208:209]
	s_mov_b32 m0, s26
	s_nop 0
	global_load_lds_dwordx4 v[192:193], off
	v_lshl_add_u64 v[192:193], s[24:25], 0, v[198:199]
	s_add_i32 m0, s26, 0x2000
	s_nop 0
	global_load_lds_dwordx4 v[192:193], off
	v_lshl_add_u64 v[192:193], v[206:207], 0, s[2:3]
	s_mov_b32 m0, s43
	s_nop 0
	global_load_lds_dwordx4 v[192:193], off
	v_lshl_add_u64 v[192:193], v[214:215], 0, s[2:3]
	s_mov_b32 m0, s44
	s_nop 0
	global_load_lds_dwordx4 v[192:193], off
	s_waitcnt vmcnt(8)
	s_waitcnt lgkmcnt(0)
	s_barrier
	s_setprio 1
	s_waitcnt lgkmcnt(0)
	v_mfma_f32_16x16x32_bf16 v[60:63], v[128:131], v[160:163], v[60:63]
	v_mfma_f32_16x16x32_bf16 v[56:59], v[136:139], v[160:163], v[56:59]
	v_mfma_f32_16x16x32_bf16 v[44:47], v[128:131], v[168:171], v[44:47]
	v_mfma_f32_16x16x32_bf16 v[40:43], v[136:139], v[168:171], v[40:43]
	v_mfma_f32_16x16x32_bf16 v[28:31], v[128:131], v[176:179], v[28:31]
	v_mfma_f32_16x16x32_bf16 v[24:27], v[136:139], v[176:179], v[24:27]
	v_mfma_f32_16x16x32_bf16 v[12:15], v[128:131], v[184:187], v[12:15]
	v_mfma_f32_16x16x32_bf16 v[8:11], v[136:139], v[184:187], v[8:11]
	v_mfma_f32_16x16x32_bf16 v[60:63], v[132:135], v[164:167], v[60:63]
	v_mfma_f32_16x16x32_bf16 v[56:59], v[140:143], v[164:167], v[56:59]
	v_mfma_f32_16x16x32_bf16 v[44:47], v[132:135], v[172:175], v[44:47]
	v_mfma_f32_16x16x32_bf16 v[40:43], v[140:143], v[172:175], v[40:43]
	v_mfma_f32_16x16x32_bf16 v[28:31], v[132:135], v[180:183], v[28:31]
	v_mfma_f32_16x16x32_bf16 v[24:27], v[140:143], v[180:183], v[24:27]
	v_mfma_f32_16x16x32_bf16 v[12:15], v[132:135], v[188:191], v[12:15]
	v_mfma_f32_16x16x32_bf16 v[8:11], v[140:143], v[188:191], v[8:11]
	s_setprio 0
	s_setprio 1
	v_mfma_f32_16x16x32_bf16 v[52:55], v[144:147], v[160:163], v[52:55]
	v_mfma_f32_16x16x32_bf16 v[48:51], v[152:155], v[160:163], v[48:51]
	v_mfma_f32_16x16x32_bf16 v[36:39], v[144:147], v[168:171], v[36:39]
	v_mfma_f32_16x16x32_bf16 v[32:35], v[152:155], v[168:171], v[32:35]
	v_mfma_f32_16x16x32_bf16 v[20:23], v[144:147], v[176:179], v[20:23]
	v_mfma_f32_16x16x32_bf16 v[16:19], v[152:155], v[176:179], v[16:19]
	v_mfma_f32_16x16x32_bf16 v[4:7], v[144:147], v[184:187], v[4:7]
	v_mfma_f32_16x16x32_bf16 v[0:3], v[152:155], v[184:187], v[0:3]
	v_mfma_f32_16x16x32_bf16 v[52:55], v[148:151], v[164:167], v[52:55]
	v_mfma_f32_16x16x32_bf16 v[48:51], v[156:159], v[164:167], v[48:51]
	v_mfma_f32_16x16x32_bf16 v[36:39], v[148:151], v[172:175], v[36:39]
	v_mfma_f32_16x16x32_bf16 v[32:35], v[156:159], v[172:175], v[32:35]
	v_mfma_f32_16x16x32_bf16 v[20:23], v[148:151], v[180:183], v[20:23]
	v_mfma_f32_16x16x32_bf16 v[16:19], v[156:159], v[180:183], v[16:19]
	v_mfma_f32_16x16x32_bf16 v[4:7], v[148:151], v[188:191], v[4:7]
	v_mfma_f32_16x16x32_bf16 v[0:3], v[156:159], v[188:191], v[0:3]
	s_setprio 0
	s_barrier
	s_add_i32 s49, s49, 2
	s_add_u32 s4, s4, 0x100
	s_addc_u32 s5, s5, 0
	s_add_u32 s21, s21, 0x100
	s_addc_u32 s23, s23, 0
	s_cmp_gt_u32 s49, 5
	s_cbranch_scc0 .LBB0_1128
	s_cmp_lg_u32 s48, 0
	v_lshl_add_u32 v206, s20, 8, v210
	v_lshl_or_b32 v204, s22, 8, v224
	s_cselect_b64 s[22:23], -1, 0
	s_lshl_b32 s4, s48, 12
	s_add_u32 s20, s41, s4
	v_ashrrev_i32_e32 v207, 31, v206
	s_addc_u32 s21, s42, 0
	v_lshlrev_b64 v[128:129], 14, v[206:207]
	v_lshl_add_u64 v[128:129], s[20:21], 0, v[128:129]
	v_ashrrev_i32_e32 v205, 31, v204
	v_lshl_add_u64 v[130:131], v[204:205], 1, v[128:129]
	global_load_dwordx4 v[186:189], v[130:131], off
	v_lshlrev_b64 v[128:129], 12, v[206:207]
	v_lshl_add_u64 v[220:221], s[8:9], 0, v[128:129]
	s_cmp_eq_u32 s48, 0
	v_lshl_add_u64 v[128:129], v[204:205], 1, v[220:221]
	s_cbranch_scc1 .LBB0_1133
	global_load_dwordx4 v[190:193], v[128:129], off
	s_branch .LBB0_1134

; #define PG8_BAR __builtin_amdgcn_s_barrier()
; template <class Epi, class Sched, bool ALIGN_EPI = false, bool SP2 = false>
; __device__ __forceinline__ void gemm_phase(PG8_LAS unsigned char* lds, const Gemm g, const Sched& S, const Epi& E, const int tid) {
;     ...
;         if constexpr (ALIGN_EPI) { if (wr == 0) PG8_BAR; }
.LBB0_1148:
	s_and_b64 vcc, exec, s[10:11]
	s_cbranch_vccz .LBB0_1131
	s_barrier

;     __host__ __device__ bool next(int i, Unit& u) const { const int L = base + i * Gp + cp; if (L >= end) return false; return T.next(L, u); }
;     __host__ __device__ bool next(int i, Unit& u) const { const int L = i * Gp + cp; if (cp < 0 || L >= n) return false; u.kb = L & 3; u.pn = (L >> 2) % nN; u.pm = pm0 + (L >> 2) / nN; return true; }
;     __host__ __device__ bool next(int i, Unit& u) const { const bool ok = T.next(i >> 2, u); u.kb = i & 3; return ok; }
; #define PG8_BAR __builtin_amdgcn_s_barrier()
; template <class Epi, class Sched, bool ALIGN_EPI = false, bool SP2 = false>
; __device__ __forceinline__ void gemm_phase(PG8_LAS unsigned char* lds, const Gemm g, const Sched& S, const Epi& E, const int tid) {
;     ...
;         const bool has_next = S.next(ui + 1, nxt);
;         const char* nA = has_next ? (const char*)g.A + (size_t)nxt.pm * tstep + (size_t)nxt.kb * g.sA : cA; const char* nB = has_next ? (const char*)g.Bt + (size_t)nxt.pn * tstep + (size_t)nxt.kb * g.sB : cB;
;         for (int t = 0; t < nt; t += 2) {
;             const bool last = (t == nt - 2);
;             const char* a1 = cA + (size_t)(t + 1) * kstep;
;             const char* a2 = last ? nA : cA + (size_t)(t + 2) * kstep; const char* b2 = last ? nB : cB + (size_t)(t + 2) * kstep;
;     ...
; #pragma unroll
;         for (int a = 0; a < 2; ++a)
; #pragma unroll
;             for (int b = 0; b < 2; ++b)
; #pragma unroll
;                 for (int m = 0; m < 4; ++m)
; #pragma unroll
;                     for (int n = 0; n < 2; ++n) acc[a][b][m][n] = (f32x4){0.f, 0.f, 0.f, 0.f};
;         cur = nxt; cA = nA; cB = nB; ++ui;
;         if constexpr (ALIGN_EPI) { if (wr == 1) PG8_BAR; }
.LBB0_1315:
	s_ashr_i32 s31, s30, 31
	s_lshl_b64 s[34:35], s[30:31], 20
	s_add_u32 s34, s50, s34
	s_addc_u32 s35, s51, s35
	s_and_b64 s[36:37], s[0:1], exec
	s_cselect_b32 s31, s35, s43
	s_cselect_b32 s39, s34, s42
	s_ashr_i32 s29, s28, 31
	s_lshl_b64 s[36:37], s[28:29], 20
	s_add_u32 s36, s52, s36
	s_addc_u32 s37, s53, s37
	s_and_b64 s[46:47], s[0:1], exec
	s_cselect_b32 s29, s37, s45
	s_cselect_b32 s41, s36, s44
	s_add_u32 s42, s42, 0x80080
	s_addc_u32 s43, s43, 0
	s_add_u32 s71, s44, 0x100
	v_mov_b32_e32 v0, 0
	s_addc_u32 s72, s45, 0
	s_mov_b32 s73, -2
	s_cmp_eq_u32 s100, 0
	s_cbranch_scc1 .Lmy_nobar_1316
	s_barrier
	s_mov_b32 s100, 0
; #define PG8_STAGE(bufoff, gbase, voff) do { _Pragma("unroll") for (int _i = 0; _i < 2; ++_i) \
;         __builtin_amdgcn_global_load_lds((const unsigned*)((const char*)(gbase) + (voff)[_i]), (PG8_LAS unsigned*)(lds + (bufoff) + ldsw + _i * 8192), 16, 0, 0); } while (0)
; #define PG8_LDA(dst, b, h) do { _Pragma("unroll") for (int m = 0; m < 4; ++m) _Pragma("unroll") for (int k = 0; k < 2; ++k) dst[m][k] = *(const PG8_LAS bf16x8*)(lds + PG8_SA(b, h) + aoff + m * 2048 + k * 1024); } while (0)
; #define PG8_LDB(dst, b, h) do { _Pragma("unroll") for (int n = 0; n < 2; ++n) _Pragma("unroll") for (int k = 0; k < 2; ++k) dst[n][k] = *(const PG8_LAS bf16x8*)(lds + PG8_SB(b, h) + boff + n * 2048 + k * 1024); } while (0)
; #define PG8_MMA(ai, bj, At, Bt) do { __builtin_amdgcn_s_setprio(1); _Pragma("unroll") for (int m = 0; m < 4; ++m) _Pragma("unroll") for (int n = 0; n < 2; ++n) _Pragma("unroll") for (int k = 0; k < 2; ++k) \
;         acc[ai][bj][m][n] = __builtin_amdgcn_mfma_f32_16x16x32_bf16(Bt[n][k], At[m][k], acc[ai][bj][m][n], 0, 0, 0); __builtin_amdgcn_s_setprio(0); } while (0)
; #define PG8_WAIT_V(n) asm volatile("s_waitcnt vmcnt(" #n ")" ::: "memory")
; #define PG8_WAIT_L(n) asm volatile("s_waitcnt lgkmcnt(" #n ")" ::: "memory")
; #define PG8_BAR __builtin_amdgcn_s_barrier()
; template <class Epi, class Sched, bool ALIGN_EPI = false, bool SP2 = false>
; __device__ __forceinline__ void gemm_phase(PG8_LAS unsigned char* lds, const Gemm g, const Sched& S, const Epi& E, const int tid) {
;     ...
;             const char* a1 = cA + (size_t)(t + 1) * kstep;
;             const char* a2 = last ? nA : cA + (size_t)(t + 2) * kstep; const char* b2 = last ? nB : cB + (size_t)(t + 2) * kstep;
;             const char* a3 = a2 + kstep; const char* b3 = b2 + kstep;
;             if (last && has_next) S.a_ready(nxt);
;             if constexpr (SP2) {
;             PG8_LDB(B0, 0, 0); PG8_LDB(B1, 0, 1); PG8_SCHED; PG8_LDA(At, 0, 0); PG8_STAGE(PG8_SA(1, 1), a1 + hstep, voffA);
;             PG8_WAIT_V(8); PG8_WAIT_L(0); PG8_BAR; PG8_MMA(0, 0, At, B0); PG8_MMA(0, 1, At, B1); PG8_BAR; PG8_SCHED;
;             PG8_LDA(At, 0, 1); PG8_STAGE(PG8_SB(0, 0), b2, voffB); PG8_STAGE(PG8_SB(0, 1), b2 + hstep, voffB); PG8_STAGE(PG8_SA(0, 0), a2, voffA);
;             PG8_WAIT_V(8); PG8_WAIT_L(0); PG8_BAR; PG8_MMA(1, 0, At, B0); PG8_MMA(1, 1, At, B1); PG8_BAR; PG8_SCHED;
.Lmy_nobar_1316:
	s_add_u32 s44, s42, 0xfff80080
	s_addc_u32 s45, s43, -1
	s_add_i32 s74, 0, 0x10000
	v_add_u32_e32 v132, s74, v252
	v_add_u32_e32 v156, s33, v252
	ds_read_b128 v[116:119], v132
	ds_read_b128 v[124:127], v132 offset:1024
	ds_read_b128 v[128:131], v132 offset:2048
	ds_read_b128 v[132:135], v132 offset:3072
	ds_read_b128 v[144:147], v156
	ds_read_b128 v[148:151], v156 offset:1024
	ds_read_b128 v[152:155], v156 offset:2048
	ds_read_b128 v[156:159], v156 offset:3072
	s_cmp_eq_u32 s73, 28
	s_cselect_b32 s47, s31, s45
	s_cselect_b32 s46, s39, s44
	s_cselect_b32 s45, s29, s72
	s_cselect_b32 s44, s41, s71
	v_lshl_add_u64 v[192:193], s[42:43], 0, v[220:221]
	s_add_i32 m0, s55, 0xc000
	ds_read_b128 v[160:163], v210
	ds_read_b128 v[164:167], v210 offset:1024
	ds_read_b128 v[168:171], v210 offset:2048
	ds_read_b128 v[172:175], v210 offset:3072
	ds_read_b128 v[176:179], v210 offset:4096
	ds_read_b128 v[180:183], v210 offset:5120
	ds_read_b128 v[184:187], v210 offset:6144
	ds_read_b128 v[188:191], v210 offset:7168
	global_load_lds_dwordx4 v[192:193], off
	v_lshl_add_u64 v[192:193], s[42:43], 0, v[222:223]
	s_add_i32 m0, s55, 0xe000
	s_nop 0
	global_load_lds_dwordx4 v[192:193], off
	s_waitcnt vmcnt(8)
	s_waitcnt lgkmcnt(0)
	s_barrier
	s_setprio 1
	s_waitcnt lgkmcnt(0)
	v_mfma_f32_16x16x32_bf16 v[140:143], v[116:119], v[160:163], 0
	v_mfma_f32_16x16x32_bf16 v[136:139], v[128:131], v[160:163], 0
	v_mfma_f32_16x16x32_bf16 v[108:111], v[116:119], v[168:171], 0
	v_mfma_f32_16x16x32_bf16 v[104:107], v[128:131], v[168:171], 0
	v_mfma_f32_16x16x32_bf16 v[92:95], v[116:119], v[176:179], 0
	v_mfma_f32_16x16x32_bf16 v[88:91], v[128:131], v[176:179], 0
	v_mfma_f32_16x16x32_bf16 v[76:79], v[116:119], v[184:187], 0
	v_mfma_f32_16x16x32_bf16 v[72:75], v[128:131], v[184:187], 0
	v_mfma_f32_16x16x32_bf16 v[140:143], v[124:127], v[164:167], v[140:143]
	v_mfma_f32_16x16x32_bf16 v[136:139], v[132:135], v[164:167], v[136:139]
	v_mfma_f32_16x16x32_bf16 v[108:111], v[124:127], v[172:175], v[108:111]
	v_mfma_f32_16x16x32_bf16 v[104:107], v[132:135], v[172:175], v[104:107]
	v_mfma_f32_16x16x32_bf16 v[92:95], v[124:127], v[180:183], v[92:95]
	v_mfma_f32_16x16x32_bf16 v[88:91], v[132:135], v[180:183], v[88:91]
	v_mfma_f32_16x16x32_bf16 v[76:79], v[124:127], v[188:191], v[76:79]
	v_mfma_f32_16x16x32_bf16 v[72:75], v[132:135], v[188:191], v[72:75]
	s_setprio 0
	s_setprio 1
	v_mfma_f32_16x16x32_bf16 v[120:123], v[144:147], v[160:163], 0
	v_mfma_f32_16x16x32_bf16 v[112:115], v[152:155], v[160:163], 0
	v_mfma_f32_16x16x32_bf16 v[100:103], v[144:147], v[168:171], 0
	v_mfma_f32_16x16x32_bf16 v[96:99], v[152:155], v[168:171], 0
	v_mfma_f32_16x16x32_bf16 v[84:87], v[144:147], v[176:179], 0
	v_mfma_f32_16x16x32_bf16 v[80:83], v[152:155], v[176:179], 0
	v_mfma_f32_16x16x32_bf16 v[68:71], v[144:147], v[184:187], 0
	v_mfma_f32_16x16x32_bf16 v[64:67], v[152:155], v[184:187], 0
	v_mfma_f32_16x16x32_bf16 v[120:123], v[148:151], v[164:167], v[120:123]
	v_mfma_f32_16x16x32_bf16 v[112:115], v[156:159], v[164:167], v[112:115]
	v_mfma_f32_16x16x32_bf16 v[100:103], v[148:151], v[172:175], v[100:103]
	v_mfma_f32_16x16x32_bf16 v[96:99], v[156:159], v[172:175], v[96:99]
	v_mfma_f32_16x16x32_bf16 v[84:87], v[148:151], v[180:183], v[84:87]
	v_mfma_f32_16x16x32_bf16 v[80:83], v[156:159], v[180:183], v[80:83]
	v_mfma_f32_16x16x32_bf16 v[68:71], v[148:151], v[188:191], v[68:71]
	v_mfma_f32_16x16x32_bf16 v[64:67], v[156:159], v[188:191], v[64:67]
	s_setprio 0
	s_barrier
	s_add_i32 s74, s74, s54
	v_lshl_add_u64 v[192:193], s[44:45], 0, v[208:209]
	s_mov_b32 m0, s74
	ds_read_b128 v[160:163], v210 offset:16384
	ds_read_b128 v[164:167], v210 offset:17408
	ds_read_b128 v[168:171], v210 offset:18432
	ds_read_b128 v[172:175], v210 offset:19456
	ds_read_b128 v[176:179], v210 offset:20480
	ds_read_b128 v[180:183], v210 offset:21504
	ds_read_b128 v[184:187], v210 offset:22528
	ds_read_b128 v[188:191], v210 offset:23552
	global_load_lds_dwordx4 v[192:193], off
	s_add_i32 m0, s74, 0x2000
	s_add_u32 s74, s44, 0x80000
	v_lshl_add_u64 v[194:195], s[44:45], 0, v[218:219]
	s_addc_u32 s75, s45, 0
	s_add_i32 s76, s33, s54
	global_load_lds_dwordx4 v[194:195], off
	v_lshl_add_u64 v[196:197], s[74:75], 0, v[208:209]
	s_mov_b32 m0, s76
	v_lshl_add_u64 v[198:199], s[46:47], 0, v[216:217]
	global_load_lds_dwordx4 v[196:197], off
	v_lshl_add_u64 v[196:197], s[74:75], 0, v[218:219]
	s_add_i32 m0, s76, 0x2000
	s_nop 0
	global_load_lds_dwordx4 v[196:197], off
	v_lshl_add_u64 v[196:197], s[46:47], 0, v[214:215]
	s_mov_b32 m0, s55
	s_nop 0
	global_load_lds_dwordx4 v[196:197], off
	s_mov_b32 m0, s56
	s_nop 0
	global_load_lds_dwordx4 v[198:199], off
	s_waitcnt vmcnt(8)
	s_waitcnt lgkmcnt(0)
	s_barrier
	s_setprio 1
	s_waitcnt lgkmcnt(0)
	v_mfma_f32_16x16x32_bf16 v[60:63], v[116:119], v[160:163], 0
	v_mfma_f32_16x16x32_bf16 v[56:59], v[128:131], v[160:163], 0
	v_mfma_f32_16x16x32_bf16 v[44:47], v[116:119], v[168:171], 0
	v_mfma_f32_16x16x32_bf16 v[40:43], v[128:131], v[168:171], 0
	v_mfma_f32_16x16x32_bf16 v[28:31], v[116:119], v[176:179], 0
	v_mfma_f32_16x16x32_bf16 v[24:27], v[128:131], v[176:179], 0
	v_mfma_f32_16x16x32_bf16 v[12:15], v[116:119], v[184:187], 0
	v_mfma_f32_16x16x32_bf16 v[8:11], v[128:131], v[184:187], 0
	v_mfma_f32_16x16x32_bf16 v[60:63], v[124:127], v[164:167], v[60:63]
	v_mfma_f32_16x16x32_bf16 v[56:59], v[132:135], v[164:167], v[56:59]
	v_mfma_f32_16x16x32_bf16 v[44:47], v[124:127], v[172:175], v[44:47]
	v_mfma_f32_16x16x32_bf16 v[40:43], v[132:135], v[172:175], v[40:43]
	v_mfma_f32_16x16x32_bf16 v[28:31], v[124:127], v[180:183], v[28:31]
	v_mfma_f32_16x16x32_bf16 v[24:27], v[132:135], v[180:183], v[24:27]
	v_mfma_f32_16x16x32_bf16 v[12:15], v[124:127], v[188:191], v[12:15]
	v_mfma_f32_16x16x32_bf16 v[8:11], v[132:135], v[188:191], v[8:11]
	s_setprio 0
	s_setprio 1
	v_mfma_f32_16x16x32_bf16 v[52:55], v[144:147], v[160:163], 0
	v_mfma_f32_16x16x32_bf16 v[48:51], v[152:155], v[160:163], 0
	v_mfma_f32_16x16x32_bf16 v[36:39], v[144:147], v[168:171], 0
	v_mfma_f32_16x16x32_bf16 v[32:35], v[152:155], v[168:171], 0
	v_mfma_f32_16x16x32_bf16 v[20:23], v[144:147], v[176:179], 0
	v_mfma_f32_16x16x32_bf16 v[16:19], v[152:155], v[176:179], 0
	v_mfma_f32_16x16x32_bf16 v[4:7], v[144:147], v[184:187], 0
	v_mfma_f32_16x16x32_bf16 v[0:3], v[152:155], v[184:187], 0
	v_mfma_f32_16x16x32_bf16 v[52:55], v[148:151], v[164:167], v[52:55]
	v_mfma_f32_16x16x32_bf16 v[48:51], v[156:159], v[164:167], v[48:51]
	v_mfma_f32_16x16x32_bf16 v[36:39], v[148:151], v[172:175], v[36:39]
	v_mfma_f32_16x16x32_bf16 v[32:35], v[156:159], v[172:175], v[32:35]
	v_mfma_f32_16x16x32_bf16 v[20:23], v[148:151], v[180:183], v[20:23]
	v_mfma_f32_16x16x32_bf16 v[16:19], v[156:159], v[180:183], v[16:19]
	v_mfma_f32_16x16x32_bf16 v[4:7], v[148:151], v[188:191], v[4:7]
	v_mfma_f32_16x16x32_bf16 v[0:3], v[156:159], v[188:191], v[0:3]
	s_setprio 0
	s_barrier
	s_branch .Lmy_mid_1316

; #define PG8_STAGE(bufoff, gbase, voff) do { _Pragma("unroll") for (int _i = 0; _i < 2; ++_i) \
;         __builtin_amdgcn_global_load_lds((const unsigned*)((const char*)(gbase) + (voff)[_i]), (PG8_LAS unsigned*)(lds + (bufoff) + ldsw + _i * 8192), 16, 0, 0); } while (0)
; #define PG8_LDA(dst, b, h) do { _Pragma("unroll") for (int m = 0; m < 4; ++m) _Pragma("unroll") for (int k = 0; k < 2; ++k) dst[m][k] = *(const PG8_LAS bf16x8*)(lds + PG8_SA(b, h) + aoff + m * 2048 + k * 1024); } while (0)
; #define PG8_LDB(dst, b, h) do { _Pragma("unroll") for (int n = 0; n < 2; ++n) _Pragma("unroll") for (int k = 0; k < 2; ++k) dst[n][k] = *(const PG8_LAS bf16x8*)(lds + PG8_SB(b, h) + boff + n * 2048 + k * 1024); } while (0)
; #define PG8_MMA(ai, bj, At, Bt) do { __builtin_amdgcn_s_setprio(1); _Pragma("unroll") for (int m = 0; m < 4; ++m) _Pragma("unroll") for (int n = 0; n < 2; ++n) _Pragma("unroll") for (int k = 0; k < 2; ++k) \
;         acc[ai][bj][m][n] = __builtin_amdgcn_mfma_f32_16x16x32_bf16(Bt[n][k], At[m][k], acc[ai][bj][m][n], 0, 0, 0); __builtin_amdgcn_s_setprio(0); } while (0)
; #define PG8_WAIT_V(n) asm volatile("s_waitcnt vmcnt(" #n ")" ::: "memory")
; #define PG8_WAIT_L(n) asm volatile("s_waitcnt lgkmcnt(" #n ")" ::: "memory")
; #define PG8_BAR __builtin_amdgcn_s_barrier()
; #define PG8_SCHED __builtin_amdgcn_sched_barrier(0)
; template <class Epi, class Sched, bool ALIGN_EPI = false, bool SP2 = false>
; __device__ __forceinline__ void gemm_phase(PG8_LAS unsigned char* lds, const Gemm g, const Sched& S, const Epi& E, const int tid) {
;     ...
;             PG8_LDB(B0, 1, 0); PG8_LDB(B1, 1, 1); PG8_SCHED; PG8_LDA(At, 1, 0); PG8_STAGE(PG8_SA(0, 1), a2 + hstep, voffA);
;             PG8_WAIT_V(8); PG8_WAIT_L(0); PG8_BAR; PG8_MMA(0, 0, At, B0); PG8_MMA(0, 1, At, B1); PG8_BAR; PG8_SCHED;
.Lmy_mid_1316:
	s_add_i32 s74, 0, 0x18000
	s_add_i32 s75, 0, 0x1c000
	v_add_u32_e32 v132, s74, v252
	v_add_u32_e32 v156, s75, v252
	ds_read_b128 v[116:119], v132
	ds_read_b128 v[124:127], v132 offset:1024
	ds_read_b128 v[128:131], v132 offset:2048
	ds_read_b128 v[132:135], v132 offset:3072
	ds_read_b128 v[144:147], v156
	ds_read_b128 v[148:151], v156 offset:1024
	ds_read_b128 v[152:155], v156 offset:2048
	ds_read_b128 v[156:159], v156 offset:3072
	s_add_u32 s46, s46, 0x80000
	s_addc_u32 s47, s47, 0
	s_mov_b32 m0, s57
	v_lshl_add_u64 v[200:201], s[46:47], 0, v[214:215]
	ds_read_b128 v[160:163], v210 offset:32768
	ds_read_b128 v[164:167], v210 offset:33792
	ds_read_b128 v[168:171], v210 offset:34816
	ds_read_b128 v[172:175], v210 offset:35840
	ds_read_b128 v[176:179], v210 offset:36864
	ds_read_b128 v[180:183], v210 offset:37888
	ds_read_b128 v[184:187], v210 offset:38912
	ds_read_b128 v[188:191], v210 offset:39936
	global_load_lds_dwordx4 v[200:201], off
	v_lshl_add_u64 v[200:201], s[46:47], 0, v[216:217]
	s_mov_b32 m0, s58
	s_nop 0
	global_load_lds_dwordx4 v[200:201], off
	s_waitcnt vmcnt(8)
	s_waitcnt lgkmcnt(0)
	s_barrier
	s_setprio 1
	s_waitcnt lgkmcnt(0)
	v_mfma_f32_16x16x32_bf16 v[140:143], v[116:119], v[160:163], v[140:143]
	v_mfma_f32_16x16x32_bf16 v[136:139], v[128:131], v[160:163], v[136:139]
	v_mfma_f32_16x16x32_bf16 v[108:111], v[116:119], v[168:171], v[108:111]
	v_mfma_f32_16x16x32_bf16 v[104:107], v[128:131], v[168:171], v[104:107]
	v_mfma_f32_16x16x32_bf16 v[92:95], v[116:119], v[176:179], v[92:95]
	v_mfma_f32_16x16x32_bf16 v[88:91], v[128:131], v[176:179], v[88:91]
	v_mfma_f32_16x16x32_bf16 v[76:79], v[116:119], v[184:187], v[76:79]
	v_mfma_f32_16x16x32_bf16 v[72:75], v[128:131], v[184:187], v[72:75]
	v_mfma_f32_16x16x32_bf16 v[140:143], v[124:127], v[164:167], v[140:143]
	v_mfma_f32_16x16x32_bf16 v[136:139], v[132:135], v[164:167], v[136:139]
	v_mfma_f32_16x16x32_bf16 v[108:111], v[124:127], v[172:175], v[108:111]
	v_mfma_f32_16x16x32_bf16 v[104:107], v[132:135], v[172:175], v[104:107]
	v_mfma_f32_16x16x32_bf16 v[92:95], v[124:127], v[180:183], v[92:95]
	v_mfma_f32_16x16x32_bf16 v[88:91], v[132:135], v[180:183], v[88:91]
	v_mfma_f32_16x16x32_bf16 v[76:79], v[124:127], v[188:191], v[76:79]
	v_mfma_f32_16x16x32_bf16 v[72:75], v[132:135], v[188:191], v[72:75]
	s_setprio 0
	s_setprio 1
	v_mfma_f32_16x16x32_bf16 v[120:123], v[144:147], v[160:163], v[120:123]
	v_mfma_f32_16x16x32_bf16 v[112:115], v[152:155], v[160:163], v[112:115]
	v_mfma_f32_16x16x32_bf16 v[100:103], v[144:147], v[168:171], v[100:103]
	v_mfma_f32_16x16x32_bf16 v[96:99], v[152:155], v[168:171], v[96:99]
	v_mfma_f32_16x16x32_bf16 v[84:87], v[144:147], v[176:179], v[84:87]
	v_mfma_f32_16x16x32_bf16 v[80:83], v[152:155], v[176:179], v[80:83]
	v_mfma_f32_16x16x32_bf16 v[68:71], v[144:147], v[184:187], v[68:71]
	v_mfma_f32_16x16x32_bf16 v[64:67], v[152:155], v[184:187], v[64:67]
	v_mfma_f32_16x16x32_bf16 v[120:123], v[148:151], v[164:167], v[120:123]
	v_mfma_f32_16x16x32_bf16 v[112:115], v[156:159], v[164:167], v[112:115]
	v_mfma_f32_16x16x32_bf16 v[100:103], v[148:151], v[172:175], v[100:103]
	v_mfma_f32_16x16x32_bf16 v[96:99], v[156:159], v[172:175], v[96:99]
	v_mfma_f32_16x16x32_bf16 v[84:87], v[148:151], v[180:183], v[84:87]
	v_mfma_f32_16x16x32_bf16 v[80:83], v[156:159], v[180:183], v[80:83]
	v_mfma_f32_16x16x32_bf16 v[68:71], v[148:151], v[188:191], v[68:71]
	v_mfma_f32_16x16x32_bf16 v[64:67], v[156:159], v[188:191], v[64:67]
	s_setprio 0
	s_barrier
; #define PG8_STAGE(bufoff, gbase, voff) do { _Pragma("unroll") for (int _i = 0; _i < 2; ++_i) \
;         __builtin_amdgcn_global_load_lds((const unsigned*)((const char*)(gbase) + (voff)[_i]), (PG8_LAS unsigned*)(lds + (bufoff) + ldsw + _i * 8192), 16, 0, 0); } while (0)
; #define PG8_LDA(dst, b, h) do { _Pragma("unroll") for (int m = 0; m < 4; ++m) _Pragma("unroll") for (int k = 0; k < 2; ++k) dst[m][k] = *(const PG8_LAS bf16x8*)(lds + PG8_SA(b, h) + aoff + m * 2048 + k * 1024); } while (0)
; #define PG8_WAIT_V(n) asm volatile("s_waitcnt vmcnt(" #n ")" ::: "memory")
; #define PG8_WAIT_L(n) asm volatile("s_waitcnt lgkmcnt(" #n ")" ::: "memory")
; #define PG8_BAR __builtin_amdgcn_s_barrier()
; template <class Epi, class Sched, bool ALIGN_EPI = false, bool SP2 = false>
; __device__ __forceinline__ void gemm_phase(PG8_LAS unsigned char* lds, const Gemm g, const Sched& S, const Epi& E, const int tid) {
;     ...
;             PG8_LDA(At, 1, 1); PG8_STAGE(PG8_SB(1, 0), b3, voffB); PG8_STAGE(PG8_SB(1, 1), b3 + hstep, voffB); PG8_STAGE(PG8_SA(1, 0), a3, voffA);
;             PG8_WAIT_V(8); PG8_WAIT_L(0); PG8_BAR; PG8_MMA(1, 0, At, B0); PG8_MMA(1, 1, At, B1); PG8_BAR; PG8_SCHED;
;     __device__ __forceinline__ void operator()(const f32x4 (&acc)[2][2][4][2], const Unit& un, int wr, int wc, int fr_, int fq_) const {
;         const int ln_ = lane_fresh(), fr = ln_ & 15, fq = ln_ >> 4; (void)fr_; (void)fq_;
;         const int rbase = un.pm * 256 + wr * 64 + fr, cw = un.pn * 256 + wc * 32 + 8 * fq;
;         const bool lat = un.pm < (NLAT / 256);
;         const int slot = lat ? (un.pm >> 5) : 4;
;         const float* src = lat ? srcl : srcc; float* dst = lat ? dstl : dstc; const int radj = lat ? 0 : NLAT;
;         const float* gp = modg + (size_t)slot * 12288; const float* sp2 = sc2 + (size_t)slot * 12288;
;         float ssq[2][4];
; #pragma unroll
;         for (int ai = 0; ai < 2; ++ai)
; #pragma unroll
;             for (int m = 0; m < 4; ++m) ssq[ai][m] = 0.f;
;         f32x4 g0[2], g1[2], y0s[2], y1s[2];
; #pragma unroll
;         for (int bj = 0; bj < 2; ++bj) { const int col = cw + bj * 128; g0[bj] = *(const f32x4*)(gp + col); g1[bj] = *(const f32x4*)(gp + col + 4);
;             y0s[bj] = *(const f32x4*)(ng2 + col) * (*(const f32x4*)(sp2 + col) + 1.f); y1s[bj] = *(const f32x4*)(ng2 + col + 4) * (*(const f32x4*)(sp2 + col + 4) + 1.f); }
	s_add_i32 s46, s74, s54
	v_lshl_add_u64 v[192:193], v[192:193], 0, s[2:3]
	s_mov_b32 m0, s46
	ds_read_b128 v[160:163], v210 offset:49152
	ds_read_b128 v[164:167], v210 offset:50176
	ds_read_b128 v[168:171], v210 offset:51200
	ds_read_b128 v[172:175], v210 offset:52224
	ds_read_b128 v[176:179], v210 offset:53248
	ds_read_b128 v[180:183], v210 offset:54272
	ds_read_b128 v[184:187], v210 offset:55296
	ds_read_b128 v[188:191], v210 offset:56320
	global_load_lds_dwordx4 v[192:193], off
	s_add_i32 m0, s46, 0x2000
	s_add_u32 s44, s44, 0x80080
	v_lshl_add_u64 v[192:193], v[194:195], 0, s[2:3]
	s_addc_u32 s45, s45, 0
	s_add_i32 s46, s75, s54
	global_load_lds_dwordx4 v[192:193], off
	v_lshl_add_u64 v[192:193], s[44:45], 0, v[208:209]
	s_mov_b32 m0, s46
	s_nop 0
	global_load_lds_dwordx4 v[192:193], off
	v_lshl_add_u64 v[192:193], s[44:45], 0, v[218:219]
	s_add_i32 m0, s46, 0x2000
	s_nop 0
	global_load_lds_dwordx4 v[192:193], off
	v_lshl_add_u64 v[192:193], v[196:197], 0, s[2:3]
	s_mov_b32 m0, s66
	s_nop 0
	global_load_lds_dwordx4 v[192:193], off
	v_lshl_add_u64 v[192:193], v[198:199], 0, s[2:3]
	s_mov_b32 m0, s67
	s_nop 0
	global_load_lds_dwordx4 v[192:193], off
	s_waitcnt vmcnt(8)
	s_waitcnt lgkmcnt(0)
	s_barrier
	s_setprio 1
	s_waitcnt lgkmcnt(0)
	v_mfma_f32_16x16x32_bf16 v[60:63], v[116:119], v[160:163], v[60:63]
	v_mfma_f32_16x16x32_bf16 v[56:59], v[128:131], v[160:163], v[56:59]
	v_mfma_f32_16x16x32_bf16 v[44:47], v[116:119], v[168:171], v[44:47]
	v_mfma_f32_16x16x32_bf16 v[40:43], v[128:131], v[168:171], v[40:43]
	v_mfma_f32_16x16x32_bf16 v[28:31], v[116:119], v[176:179], v[28:31]
	v_mfma_f32_16x16x32_bf16 v[24:27], v[128:131], v[176:179], v[24:27]
	v_mfma_f32_16x16x32_bf16 v[12:15], v[116:119], v[184:187], v[12:15]
	v_mfma_f32_16x16x32_bf16 v[8:11], v[128:131], v[184:187], v[8:11]
	v_mfma_f32_16x16x32_bf16 v[60:63], v[124:127], v[164:167], v[60:63]
	v_mfma_f32_16x16x32_bf16 v[56:59], v[132:135], v[164:167], v[56:59]
	v_mfma_f32_16x16x32_bf16 v[44:47], v[124:127], v[172:175], v[44:47]
	v_mfma_f32_16x16x32_bf16 v[40:43], v[132:135], v[172:175], v[40:43]
	v_mfma_f32_16x16x32_bf16 v[28:31], v[124:127], v[180:183], v[28:31]
	v_mfma_f32_16x16x32_bf16 v[24:27], v[132:135], v[180:183], v[24:27]
	v_mfma_f32_16x16x32_bf16 v[12:15], v[124:127], v[188:191], v[12:15]
	v_mfma_f32_16x16x32_bf16 v[8:11], v[132:135], v[188:191], v[8:11]
	s_setprio 0
	s_setprio 1
	v_mfma_f32_16x16x32_bf16 v[52:55], v[144:147], v[160:163], v[52:55]
	v_mfma_f32_16x16x32_bf16 v[48:51], v[152:155], v[160:163], v[48:51]
	v_mfma_f32_16x16x32_bf16 v[36:39], v[144:147], v[168:171], v[36:39]
	v_mfma_f32_16x16x32_bf16 v[32:35], v[152:155], v[168:171], v[32:35]
	v_mfma_f32_16x16x32_bf16 v[20:23], v[144:147], v[176:179], v[20:23]
	v_mfma_f32_16x16x32_bf16 v[16:19], v[152:155], v[176:179], v[16:19]
	v_mfma_f32_16x16x32_bf16 v[4:7], v[144:147], v[184:187], v[4:7]
	v_mfma_f32_16x16x32_bf16 v[0:3], v[152:155], v[184:187], v[0:3]
	v_mfma_f32_16x16x32_bf16 v[52:55], v[148:151], v[164:167], v[52:55]
	v_mfma_f32_16x16x32_bf16 v[48:51], v[156:159], v[164:167], v[48:51]
	v_mfma_f32_16x16x32_bf16 v[36:39], v[148:151], v[172:175], v[36:39]
	v_mfma_f32_16x16x32_bf16 v[32:35], v[156:159], v[172:175], v[32:35]
	v_mfma_f32_16x16x32_bf16 v[20:23], v[148:151], v[180:183], v[20:23]
	v_mfma_f32_16x16x32_bf16 v[16:19], v[156:159], v[180:183], v[16:19]
	v_mfma_f32_16x16x32_bf16 v[4:7], v[148:151], v[188:191], v[4:7]
	v_mfma_f32_16x16x32_bf16 v[0:3], v[156:159], v[188:191], v[0:3]
	s_setprio 0
	s_barrier
	s_add_i32 s73, s73, 2
	s_add_u32 s42, s42, 0x100
	s_addc_u32 s43, s43, 0
	s_add_u32 s71, s71, 0x100
	s_addc_u32 s72, s72, 0
	s_cmp_gt_u32 s73, 29
	s_cbranch_scc0 .LBB0_1316
	s_cmpk_gt_i32 s40, 0x7f
	s_mov_b32 s71, 0x280000
	s_mov_b32 s72, 0x2c0000
	v_mbcnt_lo_u32_b32 v211, -1, 0
	v_mbcnt_hi_u32_b32 v211, -1, v211
	s_cbranch_scc1 .LBB0_1321
	s_ashr_i32 s29, s40, 5
	s_mul_hi_i32 s47, s29, 0x3000
	s_mul_i32 s46, s29, 0x3000
	s_mov_b32 s29, 0
	s_mov_b64 s[42:43], s[14:15]
	s_mov_b64 s[44:45], s[10:11]
	s_branch .LBB0_1322

;     __device__ __forceinline__ void operator()(const f32x4 (&acc)[2][2][4][2], const Unit& un, int wr, int wc, int fr_, int fq_) const {
;         const int ln_ = lane_fresh(), fr = ln_ & 15, fq = ln_ >> 4; (void)fr_; (void)fq_;
;         const int rbase = un.pm * 256 + wr * 64 + fr, cw = un.pn * 256 + wc * 32 + 8 * fq;
;         const bool lat = un.pm < (NLAT / 256);
;         const int slot = lat ? (un.pm >> 5) : 4;
;         const float* src = lat ? srcl : srcc; float* dst = lat ? dstl : dstc; const int radj = lat ? 0 : NLAT;
;         const float* gp = modg + (size_t)slot * 12288; const float* sp2 = sc2 + (size_t)slot * 12288;
;         float ssq[2][4];
; #pragma unroll
;         for (int ai = 0; ai < 2; ++ai)
; #pragma unroll
;             for (int m = 0; m < 4; ++m) ssq[ai][m] = 0.f;
;         f32x4 g0[2], g1[2], y0s[2], y1s[2];
; #pragma unroll
;         for (int bj = 0; bj < 2; ++bj) { const int col = cw + bj * 128; g0[bj] = *(const f32x4*)(gp + col); g1[bj] = *(const f32x4*)(gp + col + 4);
;             y0s[bj] = *(const f32x4*)(ng2 + col) * (*(const f32x4*)(sp2 + col) + 1.f); y1s[bj] = *(const f32x4*)(ng2 + col + 4) * (*(const f32x4*)(sp2 + col + 4) + 1.f); }
; #pragma unroll
;         for (int ai = 0; ai < 2; ++ai) {
;             f32x4 xa[4][2][2];
; #pragma unroll
;             for (int m = 0; m < 4; ++m)
; #pragma unroll
;                 for (int bj = 0; bj < 2; ++bj) { const float* sp = src + (size_t)(rbase + ai * 128 + m * 16 - radj) * D + cw + bj * 128; xa[m][bj][0] = *(const f32x4*)sp; xa[m][bj][1] = *(const f32x4*)(sp + 4); }
; #pragma unroll
;             for (int m = 0; m < 4; ++m)
; #pragma unroll
;                 for (int bj = 0; bj < 2; ++bj) { const int row = rbase + ai * 128 + m * 16, col = cw + bj * 128; const f32x4 v0 = acc[ai][bj][m][0], v1 = acc[ai][bj][m][1];
;                     float* dp = dst + (size_t)(row - radj) * D + col;
;                     const f32x4 x0 = xa[m][bj][0] + g0[bj] * v0, x1 = xa[m][bj][1] + g1[bj] * v1;
;                     *(f32x4*)dp = x0; *(f32x4*)(dp + 4) = x1;
;                     ssq[ai][m] += (x0.x * x0.x + x0.y * x0.y) + (x0.z * x0.z + x0.w * x0.w) + (x1.x * x1.x + x1.y * x1.y) + (x1.z * x1.z + x1.w * x1.w);
;                     const f32x4 y0 = x0 * y0s[bj], y1 = x1 * y1s[bj];
.LBB0_1322:
	s_lshl_b32 s31, s40, 8
	s_add_i32 s31, s31, s64
	v_and_or_b32 v224, v211, 15, s31
	s_lshl_b32 s31, s38, 8
	s_or_b32 s31, s31, s65
	v_ashrrev_i32_e32 v116, 1, v211
	s_lshl_b64 s[40:41], s[46:47], 2
	v_and_b32_e32 v116, -8, v116
	s_add_u32 s46, s59, s40
	v_add_u32_e32 v248, s31, v116
	s_addc_u32 s47, s60, s41
	s_add_u32 s40, s61, s40
	v_ashrrev_i32_e32 v249, 31, v248
	s_addc_u32 s41, s62, s41
	v_lshlrev_b64 v[242:243], 2, v[248:249]
	v_lshl_add_u64 v[152:153], s[46:47], 0, v[242:243]
	v_lshl_add_u64 v[154:155], s[22:23], 0, v[242:243]
	v_lshl_add_u64 v[156:157], s[40:41], 0, v[242:243]
	global_load_dwordx4 v[128:131], v[152:153], off offset:16
	global_load_dwordx4 v[132:135], v[152:153], off
	global_load_dwordx4 v[116:119], v[154:155], off offset:16
	global_load_dwordx4 v[124:127], v[154:155], off
	global_load_dwordx4 v[144:147], v[156:157], off offset:16
	global_load_dwordx4 v[148:151], v[156:157], off
	s_and_b64 vcc, exec, s[26:27]
	s_cbranch_vccz .LBB0_1319
	s_barrier
.LBB0_1319:
	v_subrev_u32_e32 v246, s29, v224
	v_ashrrev_i32_e32 v247, 31, v246
	v_lshl_add_u64 v[244:245], s[44:45], 0, v[242:243]
	v_lshlrev_b64 v[250:251], 13, v[246:247]
	v_ashrrev_i32_e32 v225, 31, v224
	v_lshlrev_b64 v[212:213], 12, v[224:225]
	s_ashr_i32 s39, s38, 31
	v_cmp_gt_u32_e32 vcc, 16, v211
	s_lshl_b64 s[38:39], s[38:39], 4
	s_waitcnt vmcnt(0)
	v_pk_add_f32 v[150:151], v[150:151], 1.0 op_sel_hi:[1,0]
	v_pk_add_f32 v[148:149], v[148:149], 1.0 op_sel_hi:[1,0]
	v_pk_mul_f32 v[234:235], v[126:127], v[150:151]
	v_pk_mul_f32 v[236:237], v[124:125], v[148:149]
	v_pk_add_f32 v[124:125], v[146:147], 1.0 op_sel_hi:[1,0]
	v_pk_add_f32 v[126:127], v[144:145], 1.0 op_sel_hi:[1,0]
	v_pk_mul_f32 v[238:239], v[118:119], v[124:125]
	v_pk_mul_f32 v[240:241], v[116:117], v[126:127]
	global_load_dwordx4 v[116:119], v[152:153], off offset:528
	global_load_dwordx4 v[124:127], v[152:153], off offset:512
	global_load_dwordx4 v[144:147], v[154:155], off offset:528
	global_load_dwordx4 v[148:151], v[154:155], off offset:512
	s_nop 0
	global_load_dwordx4 v[152:155], v[156:157], off offset:528
	s_nop 0
	global_load_dwordx4 v[156:159], v[156:157], off offset:512
	s_waitcnt vmcnt(0)
	v_pk_add_f32 v[158:159], v[158:159], 1.0 op_sel_hi:[1,0]
	s_nop 0
	v_pk_mul_f32 v[226:227], v[150:151], v[158:159]
	v_pk_add_f32 v[150:151], v[152:153], 1.0 op_sel_hi:[1,0]
	v_pk_add_f32 v[156:157], v[156:157], 1.0 op_sel_hi:[1,0]
	v_pk_mul_f32 v[232:233], v[144:145], v[150:151]
	v_lshl_add_u64 v[144:145], v[244:245], 0, v[250:251]
	global_load_dwordx4 v[200:203], v[144:145], off offset:16
	global_load_dwordx4 v[204:207], v[144:145], off
	global_load_dwordx4 v[192:195], v[144:145], off offset:528
	global_load_dwordx4 v[196:199], v[144:145], off offset:512
	v_or_b32_e32 v144, 16, v246
	v_ashrrev_i32_e32 v145, 31, v144
	v_lshlrev_b64 v[144:145], 13, v[144:145]
	v_lshl_add_u64 v[144:145], v[244:245], 0, v[144:145]
	global_load_dwordx4 v[184:187], v[144:145], off offset:16
	global_load_dwordx4 v[188:191], v[144:145], off
	global_load_dwordx4 v[176:179], v[144:145], off offset:528
	global_load_dwordx4 v[180:183], v[144:145], off offset:512
	v_or_b32_e32 v144, 32, v246
	v_ashrrev_i32_e32 v145, 31, v144
	v_lshlrev_b64 v[144:145], 13, v[144:145]
	v_lshl_add_u64 v[144:145], v[244:245], 0, v[144:145]
	global_load_dwordx4 v[168:171], v[144:145], off offset:16
	global_load_dwordx4 v[172:175], v[144:145], off
	global_load_dwordx4 v[160:163], v[144:145], off offset:528
	global_load_dwordx4 v[164:167], v[144:145], off offset:512
	v_or_b32_e32 v144, 48, v246
	v_ashrrev_i32_e32 v145, 31, v144
	v_pk_mul_f32 v[228:229], v[148:149], v[156:157]
	v_pk_add_f32 v[148:149], v[154:155], 1.0 op_sel_hi:[1,0]
	v_lshlrev_b64 v[144:145], 13, v[144:145]
	v_pk_mul_f32 v[230:231], v[146:147], v[148:149]
	v_lshl_add_u64 v[148:149], v[244:245], 0, v[144:145]
	global_load_dwordx4 v[152:155], v[148:149], off offset:16
	global_load_dwordx4 v[156:159], v[148:149], off
	global_load_dwordx4 v[144:147], v[148:149], off offset:528
	s_nop 0
	global_load_dwordx4 v[148:151], v[148:149], off offset:512
	v_lshl_add_u64 v[250:251], s[42:43], 0, v[250:251]
	v_lshl_add_u64 v[250:251], v[250:251], 0, v[242:243]
	s_waitcnt vmcnt(15)
	v_pk_fma_f32 v[136:137], v[136:137], v[128:129], v[200:201]
	s_waitcnt vmcnt(14)
	v_pk_fma_f32 v[142:143], v[142:143], v[134:135], v[206:207]
	v_pk_fma_f32 v[140:141], v[140:141], v[132:133], v[204:205]
	v_mul_f32_e32 v201, v143, v143
	v_mul_f32_e32 v200, v141, v141
	v_fmac_f32_e32 v200, v140, v140
	v_fmac_f32_e32 v201, v142, v142
	v_add_f32_e32 v200, v200, v201
	v_mul_f32_e32 v201, v137, v137
	v_pk_fma_f32 v[138:139], v[138:139], v[130:131], v[202:203]
	v_fmac_f32_e32 v201, v136, v136
	v_add_f32_e32 v200, v200, v201
	v_mul_f32_e32 v201, v139, v139
	v_fmac_f32_e32 v201, v138, v138
	global_store_dwordx4 v[250:251], v[140:143], off
	global_store_dwordx4 v[250:251], v[136:139], off offset:16
	v_add_f32_e32 v202, v201, v200
	v_pk_mul_f32 v[140:141], v[236:237], v[140:141]
	v_pk_mul_f32 v[200:201], v[238:239], v[138:139]
	v_pk_mul_f32 v[138:139], v[240:241], v[136:137]
	v_pk_mul_f32 v[142:143], v[234:235], v[142:143]
	v_cvt_pk_bf16_f32 v136, v140, v141
	v_cvt_pk_bf16_f32 v138, v138, v139
	v_cvt_pk_bf16_f32 v139, v200, v201
	v_lshl_add_u64 v[140:141], s[20:21], 0, v[212:213]
	v_lshlrev_b64 v[200:201], 1, v[248:249]
	v_cvt_pk_bf16_f32 v137, v142, v143
	v_lshl_add_u64 v[140:141], v[140:141], 0, v[200:201]
	s_waitcnt vmcnt(14)
; __device__ __forceinline__ unsigned pk2(float lo, float hi) { const f32x2 v = {lo, hi}; return __builtin_bit_cast(unsigned, __builtin_convertvector(v, bf16x2_t)); }
;     __device__ __forceinline__ void operator()(const f32x4 (&acc)[2][2][4][2], const Unit& un, int wr, int wc, int fr_, int fq_) const {
;     ...
; #pragma unroll
;             for (int m = 0; m < 4; ++m)
; #pragma unroll
;                 for (int bj = 0; bj < 2; ++bj) { const int row = rbase + ai * 128 + m * 16, col = cw + bj * 128; const f32x4 v0 = acc[ai][bj][m][0], v1 = acc[ai][bj][m][1];
;                     float* dp = dst + (size_t)(row - radj) * D + col;
;                     const f32x4 x0 = xa[m][bj][0] + g0[bj] * v0, x1 = xa[m][bj][1] + g1[bj] * v1;
;                     *(f32x4*)dp = x0; *(f32x4*)(dp + 4) = x1;
;                     ssq[ai][m] += (x0.x * x0.x + x0.y * x0.y) + (x0.z * x0.z + x0.w * x0.w) + (x1.x * x1.x + x1.y * x1.y) + (x1.z * x1.z + x1.w * x1.w);
;                     const f32x4 y0 = x0 * y0s[bj], y1 = x1 * y1s[bj];
;                     u32x4 w; w.x = pk2(y0.x, y0.y); w.y = pk2(y0.z, y0.w); w.z = pk2(y1.x, y1.y); w.w = pk2(y1.z, y1.w); *(u32x4*)(xg + (size_t)row * D + col) = w; } }
	v_pk_fma_f32 v[122:123], v[122:123], v[126:127], v[198:199]
	v_pk_fma_f32 v[120:121], v[120:121], v[124:125], v[196:197]
	global_store_dwordx4 v[140:141], v[136:139], off
	v_pk_fma_f32 v[112:113], v[112:113], v[116:117], v[192:193]
	v_pk_fma_f32 v[114:115], v[114:115], v[118:119], v[194:195]
	v_mul_f32_e32 v136, v121, v121
	v_mul_f32_e32 v137, v123, v123
	v_fmac_f32_e32 v136, v120, v120
	v_fmac_f32_e32 v137, v122, v122
	v_add_f32_e32 v136, v136, v137
	v_mul_f32_e32 v137, v113, v113
	v_fmac_f32_e32 v137, v112, v112
	v_add_f32_e32 v136, v136, v137
	v_mul_f32_e32 v137, v115, v115
	v_fmac_f32_e32 v137, v114, v114
	v_add_f32_e32 v136, v137, v136
	global_store_dwordx4 v[250:251], v[120:123], off offset:512
	global_store_dwordx4 v[250:251], v[112:115], off offset:528
	v_add_f32_e32 v194, v202, v136
	v_pk_mul_f32 v[122:123], v[226:227], v[122:123]
	v_pk_mul_f32 v[120:121], v[228:229], v[120:121]
	v_pk_mul_f32 v[136:137], v[230:231], v[114:115]
	v_pk_mul_f32 v[114:115], v[232:233], v[112:113]
	v_cvt_pk_bf16_f32 v112, v120, v121
	v_cvt_pk_bf16_f32 v113, v122, v123
	v_cvt_pk_bf16_f32 v114, v114, v115
	v_cvt_pk_bf16_f32 v115, v136, v137
	v_or_b32_e32 v192, 16, v224
	global_store_dwordx4 v[140:141], v[112:115], off offset:256
	v_ashrrev_i32_e32 v193, 31, v192
	v_lshlrev_b64 v[120:121], 12, v[192:193]
	v_subrev_u32_e32 v112, s29, v192
	v_ashrrev_i32_e32 v113, 31, v112
	v_lshlrev_b64 v[112:113], 13, v[112:113]
	v_lshl_add_u64 v[112:113], s[42:43], 0, v[112:113]
	s_waitcnt vmcnt(16)
	v_pk_fma_f32 v[110:111], v[110:111], v[134:135], v[190:191]
	v_pk_fma_f32 v[108:109], v[108:109], v[132:133], v[188:189]
	v_pk_fma_f32 v[106:107], v[106:107], v[130:131], v[186:187]
	v_pk_fma_f32 v[104:105], v[104:105], v[128:129], v[184:185]
	v_lshl_add_u64 v[122:123], v[112:113], 0, v[242:243]
	v_pk_mul_f32 v[114:115], v[234:235], v[110:111]
	v_pk_mul_f32 v[112:113], v[236:237], v[108:109]
	v_pk_mul_f32 v[136:137], v[238:239], v[106:107]
	v_pk_mul_f32 v[138:139], v[240:241], v[104:105]
	v_lshl_add_u64 v[120:121], s[20:21], 0, v[120:121]
	v_cvt_pk_bf16_f32 v112, v112, v113
	v_cvt_pk_bf16_f32 v113, v114, v115
	v_cvt_pk_bf16_f32 v114, v138, v139
	v_cvt_pk_bf16_f32 v115, v136, v137
	v_lshl_add_u64 v[120:121], v[120:121], 0, v[200:201]
	s_waitcnt vmcnt(14)
	v_pk_fma_f32 v[102:103], v[102:103], v[126:127], v[182:183]
	v_pk_fma_f32 v[100:101], v[100:101], v[124:125], v[180:181]
	v_pk_fma_f32 v[98:99], v[98:99], v[118:119], v[178:179]
	v_pk_fma_f32 v[96:97], v[96:97], v[116:117], v[176:177]
	global_store_dwordx4 v[122:123], v[108:111], off
	global_store_dwordx4 v[122:123], v[104:107], off offset:16
	global_store_dwordx4 v[120:121], v[112:115], off
	global_store_dwordx4 v[122:123], v[100:103], off offset:512
	global_store_dwordx4 v[122:123], v[96:99], off offset:528
	v_pk_mul_f32 v[114:115], v[226:227], v[102:103]
	v_pk_mul_f32 v[112:113], v[228:229], v[100:101]
	v_pk_mul_f32 v[122:123], v[230:231], v[98:99]
	v_pk_mul_f32 v[136:137], v[232:233], v[96:97]
	v_cvt_pk_bf16_f32 v112, v112, v113
	v_cvt_pk_bf16_f32 v113, v114, v115
	v_cvt_pk_bf16_f32 v114, v136, v137
	v_cvt_pk_bf16_f32 v115, v122, v123
	v_or_b32_e32 v176, 32, v224
	global_store_dwordx4 v[120:121], v[112:115], off offset:256
	v_ashrrev_i32_e32 v177, 31, v176
	v_lshlrev_b64 v[120:121], 12, v[176:177]
	v_subrev_u32_e32 v112, s29, v176
	v_ashrrev_i32_e32 v113, 31, v112
	v_lshlrev_b64 v[112:113], 13, v[112:113]
	v_lshl_add_u64 v[112:113], s[42:43], 0, v[112:113]
	s_waitcnt vmcnt(18)
	v_pk_fma_f32 v[94:95], v[94:95], v[134:135], v[174:175]
	v_pk_fma_f32 v[92:93], v[92:93], v[132:133], v[172:173]
	v_pk_fma_f32 v[90:91], v[90:91], v[130:131], v[170:171]
	v_pk_fma_f32 v[88:89], v[88:89], v[128:129], v[168:169]
	v_lshl_add_u64 v[122:123], v[112:113], 0, v[242:243]
	v_pk_mul_f32 v[114:115], v[234:235], v[94:95]
	v_pk_mul_f32 v[112:113], v[236:237], v[92:93]
	v_pk_mul_f32 v[136:137], v[238:239], v[90:91]
	v_pk_mul_f32 v[138:139], v[240:241], v[88:89]
	v_lshl_add_u64 v[120:121], s[20:21], 0, v[120:121]
	v_cvt_pk_bf16_f32 v112, v112, v113
	v_cvt_pk_bf16_f32 v113, v114, v115
	v_cvt_pk_bf16_f32 v114, v138, v139
	v_cvt_pk_bf16_f32 v115, v136, v137
	v_lshl_add_u64 v[120:121], v[120:121], 0, v[200:201]
	s_waitcnt vmcnt(16)
	v_pk_fma_f32 v[86:87], v[86:87], v[126:127], v[166:167]
	v_pk_fma_f32 v[84:85], v[84:85], v[124:125], v[164:165]
	v_pk_fma_f32 v[82:83], v[82:83], v[118:119], v[162:163]
	v_pk_fma_f32 v[80:81], v[80:81], v[116:117], v[160:161]
	global_store_dwordx4 v[122:123], v[92:95], off
	global_store_dwordx4 v[122:123], v[88:91], off offset:16
	global_store_dwordx4 v[120:121], v[112:115], off
	global_store_dwordx4 v[122:123], v[84:87], off offset:512
	global_store_dwordx4 v[122:123], v[80:83], off offset:528
	v_pk_mul_f32 v[114:115], v[226:227], v[86:87]
	v_pk_mul_f32 v[112:113], v[228:229], v[84:85]
	v_pk_mul_f32 v[122:123], v[230:231], v[82:83]
	v_pk_mul_f32 v[136:137], v[232:233], v[80:81]
	v_cvt_pk_bf16_f32 v112, v112, v113
	v_cvt_pk_bf16_f32 v113, v114, v115
	v_cvt_pk_bf16_f32 v114, v136, v137
	v_cvt_pk_bf16_f32 v115, v122, v123
	v_or_b32_e32 v160, 48, v224
	global_store_dwordx4 v[120:121], v[112:115], off offset:256
	v_ashrrev_i32_e32 v161, 31, v160
	v_lshlrev_b64 v[120:121], 12, v[160:161]
	v_subrev_u32_e32 v112, s29, v160
	v_ashrrev_i32_e32 v113, 31, v112
	v_lshlrev_b64 v[112:113], 13, v[112:113]
	v_lshl_add_u64 v[112:113], s[42:43], 0, v[112:113]
	s_waitcnt vmcnt(20)
; __device__ __forceinline__ unsigned pk2(float lo, float hi) { const f32x2 v = {lo, hi}; return __builtin_bit_cast(unsigned, __builtin_convertvector(v, bf16x2_t)); }
;     __device__ __forceinline__ void operator()(const f32x4 (&acc)[2][2][4][2], const Unit& un, int wr, int wc, int fr_, int fq_) const {
;     ...
;         for (int ai = 0; ai < 2; ++ai) {
;             f32x4 xa[4][2][2];
; #pragma unroll
;             for (int m = 0; m < 4; ++m)
; #pragma unroll
;                 for (int bj = 0; bj < 2; ++bj) { const float* sp = src + (size_t)(rbase + ai * 128 + m * 16 - radj) * D + cw + bj * 128; xa[m][bj][0] = *(const f32x4*)sp; xa[m][bj][1] = *(const f32x4*)(sp + 4); }
; #pragma unroll
;             for (int m = 0; m < 4; ++m)
; #pragma unroll
;                 for (int bj = 0; bj < 2; ++bj) { const int row = rbase + ai * 128 + m * 16, col = cw + bj * 128; const f32x4 v0 = acc[ai][bj][m][0], v1 = acc[ai][bj][m][1];
;                     float* dp = dst + (size_t)(row - radj) * D + col;
;                     const f32x4 x0 = xa[m][bj][0] + g0[bj] * v0, x1 = xa[m][bj][1] + g1[bj] * v1;
;                     *(f32x4*)dp = x0; *(f32x4*)(dp + 4) = x1;
;                     ssq[ai][m] += (x0.x * x0.x + x0.y * x0.y) + (x0.z * x0.z + x0.w * x0.w) + (x1.x * x1.x + x1.y * x1.y) + (x1.z * x1.z + x1.w * x1.w);
;                     const f32x4 y0 = x0 * y0s[bj], y1 = x1 * y1s[bj];
;                     u32x4 w; w.x = pk2(y0.x, y0.y); w.y = pk2(y0.z, y0.w); w.z = pk2(y1.x, y1.y); w.w = pk2(y1.z, y1.w); *(u32x4*)(xg + (size_t)row * D + col) = w; } }
	v_pk_fma_f32 v[78:79], v[78:79], v[134:135], v[158:159]
	v_pk_fma_f32 v[76:77], v[76:77], v[132:133], v[156:157]
	v_pk_fma_f32 v[74:75], v[74:75], v[130:131], v[154:155]
	v_pk_fma_f32 v[72:73], v[72:73], v[128:129], v[152:153]
	v_lshl_add_u64 v[122:123], v[112:113], 0, v[242:243]
	v_pk_mul_f32 v[114:115], v[234:235], v[78:79]
	v_pk_mul_f32 v[112:113], v[236:237], v[76:77]
	v_pk_mul_f32 v[136:137], v[238:239], v[74:75]
	v_pk_mul_f32 v[138:139], v[240:241], v[72:73]
	v_lshl_add_u64 v[120:121], s[20:21], 0, v[120:121]
	v_cvt_pk_bf16_f32 v112, v112, v113
	v_cvt_pk_bf16_f32 v113, v114, v115
	v_cvt_pk_bf16_f32 v114, v138, v139
	v_cvt_pk_bf16_f32 v115, v136, v137
	v_lshl_add_u64 v[120:121], v[120:121], 0, v[200:201]
	s_waitcnt vmcnt(18)
	v_pk_fma_f32 v[70:71], v[70:71], v[126:127], v[150:151]
	v_pk_fma_f32 v[68:69], v[68:69], v[124:125], v[148:149]
	v_pk_fma_f32 v[66:67], v[66:67], v[118:119], v[146:147]
	v_pk_fma_f32 v[64:65], v[64:65], v[116:117], v[144:145]
	global_store_dwordx4 v[122:123], v[76:79], off
	global_store_dwordx4 v[122:123], v[72:75], off offset:16
	global_store_dwordx4 v[120:121], v[112:115], off
	global_store_dwordx4 v[122:123], v[68:71], off offset:512
	global_store_dwordx4 v[122:123], v[64:67], off offset:528
	v_pk_mul_f32 v[114:115], v[226:227], v[70:71]
	v_pk_mul_f32 v[112:113], v[228:229], v[68:69]
	v_pk_mul_f32 v[122:123], v[230:231], v[66:67]
	v_pk_mul_f32 v[136:137], v[232:233], v[64:65]
	v_cvt_pk_bf16_f32 v112, v112, v113
	v_cvt_pk_bf16_f32 v113, v114, v115
	v_cvt_pk_bf16_f32 v114, v136, v137
	v_cvt_pk_bf16_f32 v115, v122, v123
	global_store_dwordx4 v[120:121], v[112:115], off offset:256
	v_add_u32_e32 v144, 0x80, v224
	v_subrev_u32_e32 v158, s29, v144
	v_add_u32_e32 v112, 0x80, v246
	v_ashrrev_i32_e32 v113, 31, v112
	v_lshlrev_b64 v[112:113], 13, v[112:113]
	v_lshl_add_u64 v[112:113], v[244:245], 0, v[112:113]
	global_load_dwordx4 v[146:149], v[112:113], off offset:16
	global_load_dwordx4 v[150:153], v[112:113], off
	global_load_dwordx4 v[154:157], v[112:113], off offset:528
	global_load_dwordx4 v[162:165], v[112:113], off offset:512
	v_add_u32_e32 v112, 0x90, v246
	v_ashrrev_i32_e32 v113, 31, v112
	v_lshlrev_b64 v[112:113], 13, v[112:113]
	v_lshl_add_u64 v[112:113], v[244:245], 0, v[112:113]
	global_load_dwordx4 v[166:169], v[112:113], off offset:16
	global_load_dwordx4 v[170:173], v[112:113], off
	global_load_dwordx4 v[178:181], v[112:113], off offset:528
	global_load_dwordx4 v[182:185], v[112:113], off offset:512
	v_add_u32_e32 v112, 0xa0, v246
	v_ashrrev_i32_e32 v113, 31, v112
	v_lshlrev_b64 v[112:113], 13, v[112:113]
	v_lshl_add_u64 v[112:113], v[244:245], 0, v[112:113]
	global_load_dwordx4 v[186:189], v[112:113], off offset:16
	global_load_dwordx4 v[196:199], v[112:113], off
	global_load_dwordx4 v[202:205], v[112:113], off offset:528
	global_load_dwordx4 v[248:251], v[112:113], off offset:512
	v_add_u32_e32 v112, 0xb0, v246
	v_ashrrev_i32_e32 v113, 31, v112
	v_lshlrev_b64 v[112:113], 13, v[112:113]
	v_lshl_add_u64 v[120:121], v[244:245], 0, v[112:113]
	global_load_dwordx4 v[136:139], v[120:121], off offset:16
	global_load_dwordx4 v[140:143], v[120:121], off
	global_load_dwordx4 v[112:115], v[120:121], off offset:528
	s_nop 0
	global_load_dwordx4 v[120:123], v[120:121], off offset:512
	v_ashrrev_i32_e32 v159, 31, v158
	v_ashrrev_i32_e32 v145, 31, v144
	v_lshlrev_b64 v[158:159], 13, v[158:159]
	v_lshlrev_b64 v[174:175], 12, v[144:145]
	v_lshl_add_u64 v[158:159], s[42:43], 0, v[158:159]
	v_lshl_add_u64 v[158:159], v[158:159], 0, v[242:243]
	s_waitcnt vmcnt(15)
	v_pk_fma_f32 v[58:59], v[58:59], v[130:131], v[148:149]
	s_waitcnt vmcnt(14)
	v_pk_fma_f32 v[62:63], v[62:63], v[134:135], v[152:153]
	v_pk_fma_f32 v[60:61], v[60:61], v[132:133], v[150:151]
	v_pk_fma_f32 v[56:57], v[56:57], v[128:129], v[146:147]
	v_pk_mul_f32 v[148:149], v[234:235], v[62:63]
	v_pk_mul_f32 v[146:147], v[236:237], v[60:61]
	v_pk_mul_f32 v[150:151], v[238:239], v[58:59]
	v_pk_mul_f32 v[152:153], v[240:241], v[56:57]
	v_cvt_pk_bf16_f32 v146, v146, v147
	v_cvt_pk_bf16_f32 v147, v148, v149
	v_cvt_pk_bf16_f32 v149, v150, v151
	v_lshl_add_u64 v[150:151], s[20:21], 0, v[174:175]
	v_cvt_pk_bf16_f32 v148, v152, v153
	v_lshl_add_u64 v[150:151], v[150:151], 0, v[200:201]
	s_waitcnt vmcnt(12)
	v_pk_fma_f32 v[54:55], v[54:55], v[126:127], v[164:165]
	v_pk_fma_f32 v[52:53], v[52:53], v[124:125], v[162:163]
	v_pk_fma_f32 v[50:51], v[50:51], v[118:119], v[156:157]
	v_pk_fma_f32 v[48:49], v[48:49], v[116:117], v[154:155]
	global_store_dwordx4 v[158:159], v[60:63], off
	global_store_dwordx4 v[158:159], v[56:59], off offset:16
	global_store_dwordx4 v[150:151], v[146:149], off
	v_pk_mul_f32 v[152:153], v[230:231], v[50:51]
	v_pk_mul_f32 v[154:155], v[232:233], v[48:49]
	v_pk_mul_f32 v[148:149], v[226:227], v[54:55]
	v_pk_mul_f32 v[146:147], v[228:229], v[52:53]
	global_store_dwordx4 v[158:159], v[52:55], off offset:512
	global_store_dwordx4 v[158:159], v[48:51], off offset:528
	v_cvt_pk_bf16_f32 v146, v146, v147
	v_cvt_pk_bf16_f32 v147, v148, v149
	v_cvt_pk_bf16_f32 v148, v154, v155
	v_cvt_pk_bf16_f32 v149, v152, v153
	global_store_dwordx4 v[150:151], v[146:149], off offset:256
	s_waitcnt vmcnt(16)
; __device__ __forceinline__ unsigned pk2(float lo, float hi) { const f32x2 v = {lo, hi}; return __builtin_bit_cast(unsigned, __builtin_convertvector(v, bf16x2_t)); }
;     __device__ __forceinline__ void operator()(const f32x4 (&acc)[2][2][4][2], const Unit& un, int wr, int wc, int fr_, int fq_) const {
;     ...
; #pragma unroll
;             for (int m = 0; m < 4; ++m)
; #pragma unroll
;                 for (int bj = 0; bj < 2; ++bj) { const int row = rbase + ai * 128 + m * 16, col = cw + bj * 128; const f32x4 v0 = acc[ai][bj][m][0], v1 = acc[ai][bj][m][1];
;                     float* dp = dst + (size_t)(row - radj) * D + col;
;                     const f32x4 x0 = xa[m][bj][0] + g0[bj] * v0, x1 = xa[m][bj][1] + g1[bj] * v1;
;                     *(f32x4*)dp = x0; *(f32x4*)(dp + 4) = x1;
;                     ssq[ai][m] += (x0.x * x0.x + x0.y * x0.y) + (x0.z * x0.z + x0.w * x0.w) + (x1.x * x1.x + x1.y * x1.y) + (x1.z * x1.z + x1.w * x1.w);
;                     const f32x4 y0 = x0 * y0s[bj], y1 = x1 * y1s[bj];
;                     u32x4 w; w.x = pk2(y0.x, y0.y); w.y = pk2(y0.z, y0.w); w.z = pk2(y1.x, y1.y); w.w = pk2(y1.z, y1.w); *(u32x4*)(xg + (size_t)row * D + col) = w; } }
; #pragma unroll
;         for (int ai = 0; ai < 2; ++ai)
; #pragma unroll
;             for (int m = 0; m < 4; ++m) { float s = ssq[ai][m]; s += shx<16>(s); s += shx<32>(s);
;                 if (fq == 0) ps[((size_t)(rbase + ai * 128 + m * 16) * 8 + un.pn) * 4 + wc] = s; }
	v_pk_fma_f32 v[46:47], v[46:47], v[134:135], v[172:173]
	v_pk_fma_f32 v[44:45], v[44:45], v[132:133], v[170:171]
	v_add_u32_e32 v146, 0x90, v224
	v_subrev_u32_e32 v148, s29, v146
	v_ashrrev_i32_e32 v149, 31, v148
	v_lshlrev_b64 v[148:149], 13, v[148:149]
	v_ashrrev_i32_e32 v147, 31, v146
	v_lshl_add_u64 v[148:149], s[42:43], 0, v[148:149]
	v_lshlrev_b64 v[152:153], 12, v[146:147]
	v_pk_fma_f32 v[42:43], v[42:43], v[130:131], v[168:169]
	v_pk_fma_f32 v[40:41], v[40:41], v[128:129], v[166:167]
	v_lshl_add_u64 v[154:155], v[148:149], 0, v[242:243]
	v_pk_mul_f32 v[150:151], v[234:235], v[46:47]
	v_pk_mul_f32 v[148:149], v[236:237], v[44:45]
	v_pk_mul_f32 v[156:157], v[238:239], v[42:43]
	v_pk_mul_f32 v[158:159], v[240:241], v[40:41]
	v_lshl_add_u64 v[152:153], s[20:21], 0, v[152:153]
	v_cvt_pk_bf16_f32 v148, v148, v149
	v_cvt_pk_bf16_f32 v149, v150, v151
	v_cvt_pk_bf16_f32 v150, v158, v159
	v_cvt_pk_bf16_f32 v151, v156, v157
	v_lshl_add_u64 v[152:153], v[152:153], 0, v[200:201]
	s_waitcnt vmcnt(14)
	v_pk_fma_f32 v[38:39], v[38:39], v[126:127], v[184:185]
	v_pk_fma_f32 v[36:37], v[36:37], v[124:125], v[182:183]
	v_pk_fma_f32 v[34:35], v[34:35], v[118:119], v[180:181]
	v_pk_fma_f32 v[32:33], v[32:33], v[116:117], v[178:179]
	global_store_dwordx4 v[154:155], v[44:47], off
	global_store_dwordx4 v[154:155], v[40:43], off offset:16
	global_store_dwordx4 v[152:153], v[148:151], off
	global_store_dwordx4 v[154:155], v[36:39], off offset:512
	global_store_dwordx4 v[154:155], v[32:35], off offset:528
	v_pk_mul_f32 v[150:151], v[226:227], v[38:39]
	v_pk_mul_f32 v[148:149], v[228:229], v[36:37]
	v_pk_mul_f32 v[154:155], v[230:231], v[34:35]
	v_pk_mul_f32 v[156:157], v[232:233], v[32:33]
	v_cvt_pk_bf16_f32 v148, v148, v149
	v_cvt_pk_bf16_f32 v149, v150, v151
	v_cvt_pk_bf16_f32 v150, v156, v157
	v_cvt_pk_bf16_f32 v151, v154, v155
	global_store_dwordx4 v[152:153], v[148:151], off offset:256
	s_waitcnt vmcnt(18)
	v_pk_fma_f32 v[30:31], v[30:31], v[134:135], v[198:199]
	v_pk_fma_f32 v[28:29], v[28:29], v[132:133], v[196:197]
	v_add_u32_e32 v148, 0xa0, v224
	v_subrev_u32_e32 v150, s29, v148
	v_ashrrev_i32_e32 v151, 31, v150
	v_lshlrev_b64 v[150:151], 13, v[150:151]
	v_ashrrev_i32_e32 v149, 31, v148
	v_lshl_add_u64 v[150:151], s[42:43], 0, v[150:151]
	v_lshlrev_b64 v[154:155], 12, v[148:149]
	v_pk_fma_f32 v[26:27], v[26:27], v[130:131], v[188:189]
	v_pk_fma_f32 v[24:25], v[24:25], v[128:129], v[186:187]
	v_lshl_add_u64 v[156:157], v[150:151], 0, v[242:243]
	v_pk_mul_f32 v[152:153], v[234:235], v[30:31]
	v_pk_mul_f32 v[150:151], v[236:237], v[28:29]
	v_pk_mul_f32 v[158:159], v[238:239], v[26:27]
	v_pk_mul_f32 v[162:163], v[240:241], v[24:25]
	v_lshl_add_u64 v[154:155], s[20:21], 0, v[154:155]
	v_cvt_pk_bf16_f32 v150, v150, v151
	v_cvt_pk_bf16_f32 v151, v152, v153
	v_cvt_pk_bf16_f32 v152, v162, v163
	v_cvt_pk_bf16_f32 v153, v158, v159
	v_lshl_add_u64 v[154:155], v[154:155], 0, v[200:201]
	s_waitcnt vmcnt(16)
	v_pk_fma_f32 v[22:23], v[22:23], v[126:127], v[250:251]
	v_pk_fma_f32 v[20:21], v[20:21], v[124:125], v[248:249]
	v_pk_fma_f32 v[18:19], v[18:19], v[118:119], v[204:205]
	v_pk_fma_f32 v[16:17], v[16:17], v[116:117], v[202:203]
	global_store_dwordx4 v[156:157], v[28:31], off
	global_store_dwordx4 v[156:157], v[24:27], off offset:16
	global_store_dwordx4 v[154:155], v[150:153], off
	global_store_dwordx4 v[156:157], v[20:23], off offset:512
	global_store_dwordx4 v[156:157], v[16:19], off offset:528
	v_pk_mul_f32 v[152:153], v[226:227], v[22:23]
	v_pk_mul_f32 v[150:151], v[228:229], v[20:21]
	v_pk_mul_f32 v[156:157], v[230:231], v[18:19]
	v_pk_mul_f32 v[158:159], v[232:233], v[16:17]
	v_cvt_pk_bf16_f32 v150, v150, v151
	v_cvt_pk_bf16_f32 v151, v152, v153
	v_cvt_pk_bf16_f32 v152, v158, v159
	v_cvt_pk_bf16_f32 v153, v156, v157
	global_store_dwordx4 v[154:155], v[150:153], off offset:256
	s_waitcnt vmcnt(20)
	v_pk_fma_f32 v[14:15], v[14:15], v[134:135], v[142:143]
	v_pk_fma_f32 v[12:13], v[12:13], v[132:133], v[140:141]
	v_add_u32_e32 v150, 0xb0, v224
	v_subrev_u32_e32 v152, s29, v150
	v_ashrrev_i32_e32 v153, 31, v152
	v_ashrrev_i32_e32 v151, 31, v150
	v_pk_fma_f32 v[10:11], v[10:11], v[130:131], v[138:139]
	v_lshlrev_b64 v[152:153], 13, v[152:153]
	v_lshlrev_b64 v[154:155], 12, v[150:151]
	v_pk_fma_f32 v[8:9], v[8:9], v[128:129], v[136:137]
	v_pk_mul_f32 v[130:131], v[234:235], v[14:15]
	v_pk_mul_f32 v[128:129], v[236:237], v[12:13]
	v_pk_mul_f32 v[132:133], v[238:239], v[10:11]
	s_waitcnt vmcnt(18)
	v_pk_fma_f32 v[6:7], v[6:7], v[126:127], v[122:123]
	v_pk_fma_f32 v[4:5], v[4:5], v[124:125], v[120:121]
	v_pk_fma_f32 v[2:3], v[2:3], v[118:119], v[114:115]
	v_pk_fma_f32 v[0:1], v[0:1], v[116:117], v[112:113]
	v_lshl_add_u64 v[152:153], s[42:43], 0, v[152:153]
	v_pk_mul_f32 v[134:135], v[240:241], v[8:9]
	v_cvt_pk_bf16_f32 v128, v128, v129
	v_cvt_pk_bf16_f32 v129, v130, v131
	v_cvt_pk_bf16_f32 v131, v132, v133
	v_lshl_add_u64 v[132:133], s[20:21], 0, v[154:155]
	v_pk_mul_f32 v[114:115], v[226:227], v[6:7]
	v_pk_mul_f32 v[112:113], v[228:229], v[4:5]
	v_pk_mul_f32 v[116:117], v[230:231], v[2:3]
	v_pk_mul_f32 v[118:119], v[232:233], v[0:1]
	v_lshl_add_u64 v[152:153], v[152:153], 0, v[242:243]
	v_cvt_pk_bf16_f32 v130, v134, v135
	v_lshl_add_u64 v[132:133], v[132:133], 0, v[200:201]
	v_cvt_pk_bf16_f32 v112, v112, v113
	v_cvt_pk_bf16_f32 v113, v114, v115
	v_cvt_pk_bf16_f32 v114, v118, v119
	v_cvt_pk_bf16_f32 v115, v116, v117
	global_store_dwordx4 v[152:153], v[12:15], off
	global_store_dwordx4 v[152:153], v[8:11], off offset:16
	global_store_dwordx4 v[132:133], v[128:131], off
	global_store_dwordx4 v[152:153], v[4:7], off offset:512
	global_store_dwordx4 v[152:153], v[0:3], off offset:528
	global_store_dwordx4 v[132:133], v[112:115], off offset:256
	ds_swizzle_b32 v112, v194 offset:swizzle(SWAP,16)
	s_nop 0
	v_mbcnt_lo_u32_b32 v113, -1, 0
	v_mbcnt_hi_u32_b32 v113, -1, v113
	s_waitcnt lgkmcnt(0)
	v_add_f32_e32 v112, v194, v112
	v_lshlrev_b32_e32 v113, 2, v113
	v_xor_b32_e32 v113, 0x80, v113
	ds_bpermute_b32 v113, v113, v112
	s_and_saveexec_b64 s[40:41], vcc
	s_mov_b32 s74, 0x240000
	s_cbranch_execz .LBB0_1324
	v_lshlrev_b64 v[114:115], 7, v[224:225]
	v_lshl_add_u64 v[114:115], s[24:25], 0, v[114:115]
	v_lshl_add_u64 v[114:115], v[114:115], 0, s[38:39]
	s_mov_b32 s43, s91
	s_lshl_b32 s42, s63, 2
	v_lshl_add_u64 v[114:115], v[114:115], 0, s[42:43]
	s_waitcnt lgkmcnt(0)
	v_add_f32_e32 v112, v112, v113
	global_store_dword v[114:115], v112, off

;     __host__ __device__ bool next(int i, Unit& u) const { const int L = base + i * Gp + cp; if (L >= end) return false; return T.next(L, u); }
;     __host__ __device__ bool next(int i, Unit& u) const { const int L = i * Gp + cp; if (cp < 0 || L >= n) return false; u.kb = L & 3; u.pn = (L >> 2) % nN; u.pm = pm0 + (L >> 2) / nN; return true; }
;     __host__ __device__ bool next(int i, Unit& u) const { const bool ok = T.next(i >> 2, u); u.kb = i & 3; return ok; }
; #define PG8_BAR __builtin_amdgcn_s_barrier()
; template <class Epi, class Sched, bool ALIGN_EPI = false, bool SP2 = false>
; __device__ __forceinline__ void gemm_phase(PG8_LAS unsigned char* lds, const Gemm g, const Sched& S, const Epi& E, const int tid) {
;     ...
;         const bool has_next = S.next(ui + 1, nxt);
;         const char* nA = has_next ? (const char*)g.A + (size_t)nxt.pm * tstep + (size_t)nxt.kb * g.sA : cA; const char* nB = has_next ? (const char*)g.Bt + (size_t)nxt.pn * tstep + (size_t)nxt.kb * g.sB : cB;
;     ...
; #pragma unroll
;         for (int a = 0; a < 2; ++a)
; #pragma unroll
;             for (int b = 0; b < 2; ++b)
; #pragma unroll
;                 for (int m = 0; m < 4; ++m)
; #pragma unroll
;                     for (int n = 0; n < 2; ++n) acc[a][b][m][n] = (f32x4){0.f, 0.f, 0.f, 0.f};
;         cur = nxt; cA = nA; cB = nB; ++ui;
;         if constexpr (ALIGN_EPI) { if (wr == 1) PG8_BAR; }
.LBB0_1478:
	s_ashr_i32 s19, s18, 31
	s_lshl_b64 s[20:21], s[18:19], 20
	s_add_u32 s20, s38, s20
	s_addc_u32 s21, s39, s21
	s_and_b64 s[22:23], s[0:1], exec
	s_cselect_b32 s19, s21, s29
	s_cselect_b32 s25, s20, s28
	s_ashr_i32 s17, s16, 31
	s_lshl_b64 s[22:23], s[16:17], 20
	s_add_u32 s22, s40, s22
	s_addc_u32 s23, s41, s23
	s_and_b64 s[34:35], s[0:1], exec
	s_cselect_b32 s17, s23, s31
	s_cselect_b32 s53, s22, s30
	s_add_u32 s28, s28, 0x80080
	s_addc_u32 s29, s29, 0
	s_add_u32 s54, s30, 0x100
	v_mov_b32_e32 v0, 0
	s_addc_u32 s55, s31, 0
	s_mov_b32 s56, -2
	s_cmp_eq_u32 s100, 0
	s_cbranch_scc1 .Lmy_nobar_1479
	s_barrier
	s_mov_b32 s100, 0
; #define PG8_STAGE(bufoff, gbase, voff) do { _Pragma("unroll") for (int _i = 0; _i < 2; ++_i) \
;         __builtin_amdgcn_global_load_lds((const unsigned*)((const char*)(gbase) + (voff)[_i]), (PG8_LAS unsigned*)(lds + (bufoff) + ldsw + _i * 8192), 16, 0, 0); } while (0)
; #define PG8_LDA(dst, b, h) do { _Pragma("unroll") for (int m = 0; m < 4; ++m) _Pragma("unroll") for (int k = 0; k < 2; ++k) dst[m][k] = *(const PG8_LAS bf16x8*)(lds + PG8_SA(b, h) + aoff + m * 2048 + k * 1024); } while (0)
; #define PG8_LDB(dst, b, h) do { _Pragma("unroll") for (int n = 0; n < 2; ++n) _Pragma("unroll") for (int k = 0; k < 2; ++k) dst[n][k] = *(const PG8_LAS bf16x8*)(lds + PG8_SB(b, h) + boff + n * 2048 + k * 1024); } while (0)
; #define PG8_MMA(ai, bj, At, Bt) do { __builtin_amdgcn_s_setprio(1); _Pragma("unroll") for (int m = 0; m < 4; ++m) _Pragma("unroll") for (int n = 0; n < 2; ++n) _Pragma("unroll") for (int k = 0; k < 2; ++k) \
;         acc[ai][bj][m][n] = __builtin_amdgcn_mfma_f32_16x16x32_bf16(Bt[n][k], At[m][k], acc[ai][bj][m][n], 0, 0, 0); __builtin_amdgcn_s_setprio(0); } while (0)
; #define PG8_WAIT_V(n) asm volatile("s_waitcnt vmcnt(" #n ")" ::: "memory")
; #define PG8_WAIT_L(n) asm volatile("s_waitcnt lgkmcnt(" #n ")" ::: "memory")
; #define PG8_BAR __builtin_amdgcn_s_barrier()
; #define PG8_SCHED __builtin_amdgcn_sched_barrier(0)
; template <class Epi, class Sched, bool ALIGN_EPI = false, bool SP2 = false>
; __device__ __forceinline__ void gemm_phase(PG8_LAS unsigned char* lds, const Gemm g, const Sched& S, const Epi& E, const int tid) {
;     ...
;             if constexpr (SP2) {
;             PG8_LDB(B0, 0, 0); PG8_LDB(B1, 0, 1); PG8_SCHED; PG8_LDA(At, 0, 0); PG8_STAGE(PG8_SA(1, 1), a1 + hstep, voffA);
;             PG8_WAIT_V(8); PG8_WAIT_L(0); PG8_BAR; PG8_MMA(0, 0, At, B0); PG8_MMA(0, 1, At, B1); PG8_BAR; PG8_SCHED;
;             PG8_LDA(At, 0, 1); PG8_STAGE(PG8_SB(0, 0), b2, voffB); PG8_STAGE(PG8_SB(0, 1), b2 + hstep, voffB); PG8_STAGE(PG8_SA(0, 0), a2, voffA);
;             PG8_WAIT_V(8); PG8_WAIT_L(0); PG8_BAR; PG8_MMA(1, 0, At, B0); PG8_MMA(1, 1, At, B1); PG8_BAR; PG8_SCHED;
.Lmy_nobar_1479:
	s_add_u32 s30, s28, 0xfff80080
	s_addc_u32 s31, s29, -1
	s_add_i32 s57, 0, 0x10000
	v_add_u32_e32 v124, s57, v157
	v_add_u32_e32 v154, s33, v157
	ds_read_b128 v[112:115], v124
	ds_read_b128 v[116:119], v124 offset:1024
	ds_read_b128 v[120:123], v124 offset:2048
	ds_read_b128 v[124:127], v124 offset:3072
	ds_read_b128 v[162:165], v154
	ds_read_b128 v[166:169], v154 offset:1024
	ds_read_b128 v[170:173], v154 offset:2048
	ds_read_b128 v[174:177], v154 offset:3072
	s_cmp_eq_u32 s56, 28
	s_cselect_b32 s35, s19, s31
	s_cselect_b32 s34, s25, s30
	s_cselect_b32 s31, s17, s55
	s_cselect_b32 s30, s53, s54
	v_lshl_add_u64 v[206:207], s[28:29], 0, v[150:151]
	s_add_i32 m0, s27, 0xc000
	ds_read_b128 v[178:181], v161
	ds_read_b128 v[182:185], v161 offset:1024
	ds_read_b128 v[186:189], v161 offset:2048
	ds_read_b128 v[190:193], v161 offset:3072
	ds_read_b128 v[194:197], v161 offset:4096
	ds_read_b128 v[198:201], v161 offset:5120
	ds_read_b128 v[202:205], v161 offset:6144
	ds_read_b128 v[214:217], v161 offset:7168
	global_load_lds_dwordx4 v[206:207], off
	v_lshl_add_u64 v[206:207], s[28:29], 0, v[152:153]
	s_add_i32 m0, s27, 0xe000
	s_nop 0
	global_load_lds_dwordx4 v[206:207], off
	s_waitcnt vmcnt(8)
	s_waitcnt lgkmcnt(0)
	s_barrier
	s_setprio 1
	s_waitcnt lgkmcnt(0)
	v_mfma_f32_16x16x32_bf16 v[140:143], v[112:115], v[178:181], 0
	v_mfma_f32_16x16x32_bf16 v[136:139], v[120:123], v[178:181], 0
	v_mfma_f32_16x16x32_bf16 v[108:111], v[112:115], v[186:189], 0
	v_mfma_f32_16x16x32_bf16 v[104:107], v[120:123], v[186:189], 0
	v_mfma_f32_16x16x32_bf16 v[92:95], v[112:115], v[194:197], 0
	v_mfma_f32_16x16x32_bf16 v[88:91], v[120:123], v[194:197], 0
	v_mfma_f32_16x16x32_bf16 v[76:79], v[112:115], v[202:205], 0
	v_mfma_f32_16x16x32_bf16 v[72:75], v[120:123], v[202:205], 0
	v_mfma_f32_16x16x32_bf16 v[140:143], v[116:119], v[182:185], v[140:143]
	v_mfma_f32_16x16x32_bf16 v[136:139], v[124:127], v[182:185], v[136:139]
	v_mfma_f32_16x16x32_bf16 v[108:111], v[116:119], v[190:193], v[108:111]
	v_mfma_f32_16x16x32_bf16 v[104:107], v[124:127], v[190:193], v[104:107]
	v_mfma_f32_16x16x32_bf16 v[92:95], v[116:119], v[198:201], v[92:95]
	v_mfma_f32_16x16x32_bf16 v[88:91], v[124:127], v[198:201], v[88:91]
	v_mfma_f32_16x16x32_bf16 v[76:79], v[116:119], v[214:217], v[76:79]
	v_mfma_f32_16x16x32_bf16 v[72:75], v[124:127], v[214:217], v[72:75]
	s_setprio 0
	s_setprio 1
	v_mfma_f32_16x16x32_bf16 v[132:135], v[162:165], v[178:181], 0
	v_mfma_f32_16x16x32_bf16 v[128:131], v[170:173], v[178:181], 0
	v_mfma_f32_16x16x32_bf16 v[100:103], v[162:165], v[186:189], 0
	v_mfma_f32_16x16x32_bf16 v[96:99], v[170:173], v[186:189], 0
	v_mfma_f32_16x16x32_bf16 v[84:87], v[162:165], v[194:197], 0
	v_mfma_f32_16x16x32_bf16 v[80:83], v[170:173], v[194:197], 0
	v_mfma_f32_16x16x32_bf16 v[68:71], v[162:165], v[202:205], 0
	v_mfma_f32_16x16x32_bf16 v[64:67], v[170:173], v[202:205], 0
	v_mfma_f32_16x16x32_bf16 v[132:135], v[166:169], v[182:185], v[132:135]
	v_mfma_f32_16x16x32_bf16 v[128:131], v[174:177], v[182:185], v[128:131]
	v_mfma_f32_16x16x32_bf16 v[100:103], v[166:169], v[190:193], v[100:103]
	v_mfma_f32_16x16x32_bf16 v[96:99], v[174:177], v[190:193], v[96:99]
	v_mfma_f32_16x16x32_bf16 v[84:87], v[166:169], v[198:201], v[84:87]
	v_mfma_f32_16x16x32_bf16 v[80:83], v[174:177], v[198:201], v[80:83]
	v_mfma_f32_16x16x32_bf16 v[68:71], v[166:169], v[214:217], v[68:71]
	v_mfma_f32_16x16x32_bf16 v[64:67], v[174:177], v[214:217], v[64:67]
	s_setprio 0
	s_barrier
	s_add_i32 s57, s57, s42
	v_lshl_add_u64 v[206:207], s[30:31], 0, v[208:209]
	s_mov_b32 m0, s57
	ds_read_b128 v[178:181], v161 offset:16384
	ds_read_b128 v[182:185], v161 offset:17408
	ds_read_b128 v[186:189], v161 offset:18432
	ds_read_b128 v[190:193], v161 offset:19456
	ds_read_b128 v[194:197], v161 offset:20480
	ds_read_b128 v[198:201], v161 offset:21504
	ds_read_b128 v[202:205], v161 offset:22528
	ds_read_b128 v[214:217], v161 offset:23552
	global_load_lds_dwordx4 v[206:207], off
	s_add_i32 m0, s57, 0x2000
	s_add_u32 s58, s30, 0x80000
	v_lshl_add_u64 v[210:211], s[30:31], 0, v[144:145]
	s_addc_u32 s59, s31, 0
	s_add_i32 s57, s33, s42
	global_load_lds_dwordx4 v[210:211], off
	v_lshl_add_u64 v[212:213], s[58:59], 0, v[208:209]
	s_mov_b32 m0, s57
	v_lshl_add_u64 v[218:219], s[34:35], 0, v[146:147]
	global_load_lds_dwordx4 v[212:213], off
	v_lshl_add_u64 v[212:213], s[58:59], 0, v[144:145]
	s_add_i32 m0, s57, 0x2000
	s_nop 0
	global_load_lds_dwordx4 v[212:213], off
	v_lshl_add_u64 v[212:213], s[34:35], 0, v[148:149]
	s_mov_b32 m0, s27
	s_nop 0
	global_load_lds_dwordx4 v[212:213], off
	s_mov_b32 m0, s44
	s_nop 0
	global_load_lds_dwordx4 v[218:219], off
	s_waitcnt vmcnt(8)
	s_waitcnt lgkmcnt(0)
	s_barrier
	s_setprio 1
	s_waitcnt lgkmcnt(0)
	v_mfma_f32_16x16x32_bf16 v[60:63], v[112:115], v[178:181], 0
	v_mfma_f32_16x16x32_bf16 v[56:59], v[120:123], v[178:181], 0
	v_mfma_f32_16x16x32_bf16 v[44:47], v[112:115], v[186:189], 0
	v_mfma_f32_16x16x32_bf16 v[40:43], v[120:123], v[186:189], 0
	v_mfma_f32_16x16x32_bf16 v[28:31], v[112:115], v[194:197], 0
	v_mfma_f32_16x16x32_bf16 v[24:27], v[120:123], v[194:197], 0
	v_mfma_f32_16x16x32_bf16 v[12:15], v[112:115], v[202:205], 0
	v_mfma_f32_16x16x32_bf16 v[8:11], v[120:123], v[202:205], 0
	v_mfma_f32_16x16x32_bf16 v[60:63], v[116:119], v[182:185], v[60:63]
	v_mfma_f32_16x16x32_bf16 v[56:59], v[124:127], v[182:185], v[56:59]
	v_mfma_f32_16x16x32_bf16 v[44:47], v[116:119], v[190:193], v[44:47]
	v_mfma_f32_16x16x32_bf16 v[40:43], v[124:127], v[190:193], v[40:43]
	v_mfma_f32_16x16x32_bf16 v[28:31], v[116:119], v[198:201], v[28:31]
	v_mfma_f32_16x16x32_bf16 v[24:27], v[124:127], v[198:201], v[24:27]
	v_mfma_f32_16x16x32_bf16 v[12:15], v[116:119], v[214:217], v[12:15]
	v_mfma_f32_16x16x32_bf16 v[8:11], v[124:127], v[214:217], v[8:11]
	s_setprio 0
	s_setprio 1
	v_mfma_f32_16x16x32_bf16 v[52:55], v[162:165], v[178:181], 0
	v_mfma_f32_16x16x32_bf16 v[48:51], v[170:173], v[178:181], 0
	v_mfma_f32_16x16x32_bf16 v[36:39], v[162:165], v[186:189], 0
	v_mfma_f32_16x16x32_bf16 v[32:35], v[170:173], v[186:189], 0
	v_mfma_f32_16x16x32_bf16 v[20:23], v[162:165], v[194:197], 0
	v_mfma_f32_16x16x32_bf16 v[16:19], v[170:173], v[194:197], 0
	v_mfma_f32_16x16x32_bf16 v[4:7], v[162:165], v[202:205], 0
	v_mfma_f32_16x16x32_bf16 v[0:3], v[170:173], v[202:205], 0
	v_mfma_f32_16x16x32_bf16 v[52:55], v[166:169], v[182:185], v[52:55]
	v_mfma_f32_16x16x32_bf16 v[48:51], v[174:177], v[182:185], v[48:51]
	v_mfma_f32_16x16x32_bf16 v[36:39], v[166:169], v[190:193], v[36:39]
	v_mfma_f32_16x16x32_bf16 v[32:35], v[174:177], v[190:193], v[32:35]
	v_mfma_f32_16x16x32_bf16 v[20:23], v[166:169], v[198:201], v[20:23]
	v_mfma_f32_16x16x32_bf16 v[16:19], v[174:177], v[198:201], v[16:19]
	v_mfma_f32_16x16x32_bf16 v[4:7], v[166:169], v[214:217], v[4:7]
	v_mfma_f32_16x16x32_bf16 v[0:3], v[174:177], v[214:217], v[0:3]
	s_setprio 0
	s_barrier
	s_branch .Lmy_mid_1479

; #define PG8_STAGE(bufoff, gbase, voff) do { _Pragma("unroll") for (int _i = 0; _i < 2; ++_i) \
;         __builtin_amdgcn_global_load_lds((const unsigned*)((const char*)(gbase) + (voff)[_i]), (PG8_LAS unsigned*)(lds + (bufoff) + ldsw + _i * 8192), 16, 0, 0); } while (0)
; #define PG8_LDA(dst, b, h) do { _Pragma("unroll") for (int m = 0; m < 4; ++m) _Pragma("unroll") for (int k = 0; k < 2; ++k) dst[m][k] = *(const PG8_LAS bf16x8*)(lds + PG8_SA(b, h) + aoff + m * 2048 + k * 1024); } while (0)
; #define PG8_LDB(dst, b, h) do { _Pragma("unroll") for (int n = 0; n < 2; ++n) _Pragma("unroll") for (int k = 0; k < 2; ++k) dst[n][k] = *(const PG8_LAS bf16x8*)(lds + PG8_SB(b, h) + boff + n * 2048 + k * 1024); } while (0)
; #define PG8_MMA(ai, bj, At, Bt) do { __builtin_amdgcn_s_setprio(1); _Pragma("unroll") for (int m = 0; m < 4; ++m) _Pragma("unroll") for (int n = 0; n < 2; ++n) _Pragma("unroll") for (int k = 0; k < 2; ++k) \
;         acc[ai][bj][m][n] = __builtin_amdgcn_mfma_f32_16x16x32_bf16(Bt[n][k], At[m][k], acc[ai][bj][m][n], 0, 0, 0); __builtin_amdgcn_s_setprio(0); } while (0)
; #define PG8_WAIT_V(n) asm volatile("s_waitcnt vmcnt(" #n ")" ::: "memory")
; #define PG8_WAIT_L(n) asm volatile("s_waitcnt lgkmcnt(" #n ")" ::: "memory")
; #define PG8_BAR __builtin_amdgcn_s_barrier()
; #define PG8_SCHED __builtin_amdgcn_sched_barrier(0)
; template <class Epi, class Sched, bool ALIGN_EPI = false, bool SP2 = false>
; __device__ __forceinline__ void gemm_phase(PG8_LAS unsigned char* lds, const Gemm g, const Sched& S, const Epi& E, const int tid) {
;     ...
;             PG8_LDB(B0, 1, 0); PG8_LDB(B1, 1, 1); PG8_SCHED; PG8_LDA(At, 1, 0); PG8_STAGE(PG8_SA(0, 1), a2 + hstep, voffA);
;             PG8_WAIT_V(8); PG8_WAIT_L(0); PG8_BAR; PG8_MMA(0, 0, At, B0); PG8_MMA(0, 1, At, B1); PG8_BAR; PG8_SCHED;
;             PG8_LDA(At, 1, 1); PG8_STAGE(PG8_SB(1, 0), b3, voffB); PG8_STAGE(PG8_SB(1, 1), b3 + hstep, voffB); PG8_STAGE(PG8_SA(1, 0), a3, voffA);
.Lmy_mid_1479:
	s_add_i32 s57, 0, 0x18000
	s_add_i32 s58, 0, 0x1c000
	v_add_u32_e32 v124, s57, v157
	v_add_u32_e32 v154, s58, v157
	ds_read_b128 v[112:115], v124
	ds_read_b128 v[116:119], v124 offset:1024
	ds_read_b128 v[120:123], v124 offset:2048
	ds_read_b128 v[124:127], v124 offset:3072
	ds_read_b128 v[162:165], v154
	ds_read_b128 v[166:169], v154 offset:1024
	ds_read_b128 v[170:173], v154 offset:2048
	ds_read_b128 v[174:177], v154 offset:3072
	s_add_u32 s34, s34, 0x80000
	s_addc_u32 s35, s35, 0
	s_mov_b32 m0, s45
	v_lshl_add_u64 v[220:221], s[34:35], 0, v[148:149]
	ds_read_b128 v[178:181], v161 offset:32768
	ds_read_b128 v[182:185], v161 offset:33792
	ds_read_b128 v[186:189], v161 offset:34816
	ds_read_b128 v[190:193], v161 offset:35840
	ds_read_b128 v[194:197], v161 offset:36864
	ds_read_b128 v[198:201], v161 offset:37888
	ds_read_b128 v[202:205], v161 offset:38912
	ds_read_b128 v[214:217], v161 offset:39936
	global_load_lds_dwordx4 v[220:221], off
	v_lshl_add_u64 v[220:221], s[34:35], 0, v[146:147]
	s_mov_b32 m0, s46
	s_nop 0
	global_load_lds_dwordx4 v[220:221], off
	s_waitcnt vmcnt(8)
	s_waitcnt lgkmcnt(0)
	s_barrier
	s_setprio 1
	s_waitcnt lgkmcnt(0)
	v_mfma_f32_16x16x32_bf16 v[140:143], v[112:115], v[178:181], v[140:143]
	v_mfma_f32_16x16x32_bf16 v[136:139], v[120:123], v[178:181], v[136:139]
	v_mfma_f32_16x16x32_bf16 v[108:111], v[112:115], v[186:189], v[108:111]
	v_mfma_f32_16x16x32_bf16 v[104:107], v[120:123], v[186:189], v[104:107]
	v_mfma_f32_16x16x32_bf16 v[92:95], v[112:115], v[194:197], v[92:95]
	v_mfma_f32_16x16x32_bf16 v[88:91], v[120:123], v[194:197], v[88:91]
	v_mfma_f32_16x16x32_bf16 v[76:79], v[112:115], v[202:205], v[76:79]
	v_mfma_f32_16x16x32_bf16 v[72:75], v[120:123], v[202:205], v[72:75]
	v_mfma_f32_16x16x32_bf16 v[140:143], v[116:119], v[182:185], v[140:143]
	v_mfma_f32_16x16x32_bf16 v[136:139], v[124:127], v[182:185], v[136:139]
	v_mfma_f32_16x16x32_bf16 v[108:111], v[116:119], v[190:193], v[108:111]
	v_mfma_f32_16x16x32_bf16 v[104:107], v[124:127], v[190:193], v[104:107]
	v_mfma_f32_16x16x32_bf16 v[92:95], v[116:119], v[198:201], v[92:95]
	v_mfma_f32_16x16x32_bf16 v[88:91], v[124:127], v[198:201], v[88:91]
	v_mfma_f32_16x16x32_bf16 v[76:79], v[116:119], v[214:217], v[76:79]
	v_mfma_f32_16x16x32_bf16 v[72:75], v[124:127], v[214:217], v[72:75]
	s_setprio 0
	s_setprio 1
	v_mfma_f32_16x16x32_bf16 v[132:135], v[162:165], v[178:181], v[132:135]
	v_mfma_f32_16x16x32_bf16 v[128:131], v[170:173], v[178:181], v[128:131]
	v_mfma_f32_16x16x32_bf16 v[100:103], v[162:165], v[186:189], v[100:103]
	v_mfma_f32_16x16x32_bf16 v[96:99], v[170:173], v[186:189], v[96:99]
	v_mfma_f32_16x16x32_bf16 v[84:87], v[162:165], v[194:197], v[84:87]
	v_mfma_f32_16x16x32_bf16 v[80:83], v[170:173], v[194:197], v[80:83]
	v_mfma_f32_16x16x32_bf16 v[68:71], v[162:165], v[202:205], v[68:71]
	v_mfma_f32_16x16x32_bf16 v[64:67], v[170:173], v[202:205], v[64:67]
	v_mfma_f32_16x16x32_bf16 v[132:135], v[166:169], v[182:185], v[132:135]
	v_mfma_f32_16x16x32_bf16 v[128:131], v[174:177], v[182:185], v[128:131]
	v_mfma_f32_16x16x32_bf16 v[100:103], v[166:169], v[190:193], v[100:103]
	v_mfma_f32_16x16x32_bf16 v[96:99], v[174:177], v[190:193], v[96:99]
	v_mfma_f32_16x16x32_bf16 v[84:87], v[166:169], v[198:201], v[84:87]
	v_mfma_f32_16x16x32_bf16 v[80:83], v[174:177], v[198:201], v[80:83]
	v_mfma_f32_16x16x32_bf16 v[68:71], v[166:169], v[214:217], v[68:71]
	v_mfma_f32_16x16x32_bf16 v[64:67], v[174:177], v[214:217], v[64:67]
	s_setprio 0
	s_barrier
	s_add_i32 s34, s57, s42
	v_lshl_add_u64 v[206:207], v[206:207], 0, s[2:3]
	s_mov_b32 m0, s34
	ds_read_b128 v[178:181], v161 offset:49152
	ds_read_b128 v[182:185], v161 offset:50176
	ds_read_b128 v[186:189], v161 offset:51200
	ds_read_b128 v[190:193], v161 offset:52224
	ds_read_b128 v[194:197], v161 offset:53248
	ds_read_b128 v[198:201], v161 offset:54272
	ds_read_b128 v[202:205], v161 offset:55296
	ds_read_b128 v[214:217], v161 offset:56320
	global_load_lds_dwordx4 v[206:207], off
	s_add_i32 m0, s34, 0x2000
	s_add_u32 s30, s30, 0x80080
	v_lshl_add_u64 v[206:207], v[210:211], 0, s[2:3]
	s_addc_u32 s31, s31, 0
	s_add_i32 s34, s58, s42
	global_load_lds_dwordx4 v[206:207], off
	v_lshl_add_u64 v[206:207], s[30:31], 0, v[208:209]
	s_mov_b32 m0, s34
	s_nop 0
	global_load_lds_dwordx4 v[206:207], off
	v_lshl_add_u64 v[206:207], s[30:31], 0, v[144:145]
	s_add_i32 m0, s34, 0x2000
	s_nop 0
	global_load_lds_dwordx4 v[206:207], off
	v_lshl_add_u64 v[206:207], v[212:213], 0, s[2:3]
	s_mov_b32 m0, s49
	s_nop 0
	global_load_lds_dwordx4 v[206:207], off
	v_lshl_add_u64 v[206:207], v[218:219], 0, s[2:3]
	s_mov_b32 m0, s50
	s_nop 0
	global_load_lds_dwordx4 v[206:207], off
	s_waitcnt vmcnt(8)
	s_waitcnt lgkmcnt(0)
	s_barrier
; template <class Epi, class Sched, bool ALIGN_EPI = false, bool SP2 = false>
; __device__ __forceinline__ void gemm_phase(PG8_LAS unsigned char* lds, const Gemm g, const Sched& S, const Epi& E, const int tid) {
;     ...
;             PG8_WAIT_V(8); PG8_WAIT_L(0); PG8_BAR; PG8_MMA(1, 0, At, B0); PG8_MMA(1, 1, At, B1); PG8_BAR; PG8_SCHED;
;             } else {
;             PG8_LDB(B0, 0, 0); PG8_SCHED; PG8_LDA(At, 0, 0); PG8_STAGE(PG8_SA(1, 1), a1 + hstep, voffA);
;             PG8_WAIT_L(8); PG8_BAR; PG8_WAIT_L(0); PG8_MMA(0, 0, At, B0); PG8_BAR; PG8_SCHED;
;             PG8_LDB(B1, 0, 1); PG8_STAGE(PG8_SB(0, 0), b2, voffB);
;             PG8_BAR; PG8_WAIT_L(0); PG8_MMA(0, 1, At, B1); PG8_BAR;
;             PG8_LDA(At, 0, 1); PG8_STAGE(PG8_SA(0, 0), a2, voffA);
;             PG8_BAR; PG8_WAIT_L(0); PG8_MMA(1, 0, At, B0); PG8_BAR; PG8_SCHED;
;             PG8_STAGE(PG8_SB(0, 1), b2 + hstep, voffB);
;             PG8_WAIT_V(6); PG8_BAR; PG8_MMA(1, 1, At, B1); PG8_BAR;
;             PG8_LDB(B0, 1, 0); PG8_SCHED; PG8_LDA(At, 1, 0); PG8_STAGE(PG8_SA(0, 1), a2 + hstep, voffA);
;             PG8_WAIT_L(8); PG8_BAR; PG8_WAIT_L(0); PG8_MMA(0, 0, At, B0); PG8_BAR; PG8_SCHED;
;             PG8_LDB(B1, 1, 1); PG8_STAGE(PG8_SB(1, 0), b3, voffB);
;             PG8_BAR; PG8_WAIT_L(0); PG8_MMA(0, 1, At, B1); PG8_BAR;
;             PG8_LDA(At, 1, 1); PG8_STAGE(PG8_SA(1, 0), a3, voffA);
;             PG8_BAR; PG8_WAIT_L(0); PG8_MMA(1, 0, At, B0); PG8_BAR; PG8_SCHED;
;             PG8_STAGE(PG8_SB(1, 1), b3 + hstep, voffB);
;             PG8_WAIT_V(6); PG8_BAR; PG8_MMA(1, 1, At, B1); PG8_BAR;
;             }
;         }
;         if constexpr (ALIGN_EPI) { if (wr == 0) PG8_BAR; }
;     __device__ __forceinline__ void operator()(const f32x4 (&acc)[2][2][4][2], const Unit& un, int wr, int wc, int fr, int fq) const {
;         const int rbase = un.pm * 256 + wr * 64 + fr, cw = un.pn * 256 + wc * 32 + 8 * fq;
;         const int slot = un.pm < (NLAT / 256) ? (un.pm >> 5) : 4; const float* sw = shw + (size_t)slot * DFF;
;         f32x4 s0[2], s1[2]; float rr[2][4];
; #pragma unroll
;         for (int bj = 0; bj < 2; ++bj) { s0[bj] = *(const f32x4*)(sw + cw + bj * 128); s1[bj] = *(const f32x4*)(sw + cw + bj * 128 + 4); }
; #pragma unroll
;         for (int ai = 0; ai < 2; ++ai)
; #pragma unroll
;             for (int m = 0; m < 4; ++m) rr[ai][m] = rs[rbase + ai * 128 + m * 16];
	s_setprio 1
	s_waitcnt lgkmcnt(0)
	v_mfma_f32_16x16x32_bf16 v[60:63], v[112:115], v[178:181], v[60:63]
	v_mfma_f32_16x16x32_bf16 v[56:59], v[120:123], v[178:181], v[56:59]
	v_mfma_f32_16x16x32_bf16 v[44:47], v[112:115], v[186:189], v[44:47]
	v_mfma_f32_16x16x32_bf16 v[40:43], v[120:123], v[186:189], v[40:43]
	v_mfma_f32_16x16x32_bf16 v[28:31], v[112:115], v[194:197], v[28:31]
	v_mfma_f32_16x16x32_bf16 v[24:27], v[120:123], v[194:197], v[24:27]
	v_mfma_f32_16x16x32_bf16 v[12:15], v[112:115], v[202:205], v[12:15]
	v_mfma_f32_16x16x32_bf16 v[8:11], v[120:123], v[202:205], v[8:11]
	v_mfma_f32_16x16x32_bf16 v[60:63], v[116:119], v[182:185], v[60:63]
	v_mfma_f32_16x16x32_bf16 v[56:59], v[124:127], v[182:185], v[56:59]
	v_mfma_f32_16x16x32_bf16 v[44:47], v[116:119], v[190:193], v[44:47]
	v_mfma_f32_16x16x32_bf16 v[40:43], v[124:127], v[190:193], v[40:43]
	v_mfma_f32_16x16x32_bf16 v[28:31], v[116:119], v[198:201], v[28:31]
	v_mfma_f32_16x16x32_bf16 v[24:27], v[124:127], v[198:201], v[24:27]
	v_mfma_f32_16x16x32_bf16 v[12:15], v[116:119], v[214:217], v[12:15]
	v_mfma_f32_16x16x32_bf16 v[8:11], v[124:127], v[214:217], v[8:11]
	s_setprio 0
	s_setprio 1
	v_mfma_f32_16x16x32_bf16 v[52:55], v[162:165], v[178:181], v[52:55]
	v_mfma_f32_16x16x32_bf16 v[48:51], v[170:173], v[178:181], v[48:51]
	v_mfma_f32_16x16x32_bf16 v[36:39], v[162:165], v[186:189], v[36:39]
	v_mfma_f32_16x16x32_bf16 v[32:35], v[170:173], v[186:189], v[32:35]
	v_mfma_f32_16x16x32_bf16 v[20:23], v[162:165], v[194:197], v[20:23]
	v_mfma_f32_16x16x32_bf16 v[16:19], v[170:173], v[194:197], v[16:19]
	v_mfma_f32_16x16x32_bf16 v[4:7], v[162:165], v[202:205], v[4:7]
	v_mfma_f32_16x16x32_bf16 v[0:3], v[170:173], v[202:205], v[0:3]
	v_mfma_f32_16x16x32_bf16 v[52:55], v[166:169], v[182:185], v[52:55]
	v_mfma_f32_16x16x32_bf16 v[48:51], v[174:177], v[182:185], v[48:51]
	v_mfma_f32_16x16x32_bf16 v[36:39], v[166:169], v[190:193], v[36:39]
	v_mfma_f32_16x16x32_bf16 v[32:35], v[174:177], v[190:193], v[32:35]
	v_mfma_f32_16x16x32_bf16 v[20:23], v[166:169], v[198:201], v[20:23]
	v_mfma_f32_16x16x32_bf16 v[16:19], v[174:177], v[198:201], v[16:19]
	v_mfma_f32_16x16x32_bf16 v[4:7], v[166:169], v[214:217], v[4:7]
	v_mfma_f32_16x16x32_bf16 v[0:3], v[174:177], v[214:217], v[0:3]
	s_setprio 0
	s_barrier
	s_add_i32 s56, s56, 2
	s_add_u32 s28, s28, 0x100
	s_addc_u32 s29, s29, 0
	s_add_u32 s54, s54, 0x100
	s_addc_u32 s55, s55, 0
	s_cmp_gt_u32 s56, 29
	s_cbranch_scc0 .LBB0_1479
	s_ashr_i32 s28, s24, 5
	s_ashr_i32 s29, s28, 31
	s_lshl_b64 s[28:29], s[28:29], 13
	s_cmpk_lt_i32 s24, 0x80
	s_cselect_b32 s29, s29, 0
	s_cselect_b32 s28, s28, 0x8000
	s_lshl_b64 s[28:29], s[28:29], 2
	v_lshl_or_b32 v174, s26, 8, v159
	s_add_u32 s28, s47, s28
	v_lshl_add_u32 v176, s24, 8, v155
	s_addc_u32 s29, s48, s29
	v_ashrrev_i32_e32 v175, 31, v174
	v_ashrrev_i32_e32 v177, 31, v176
	v_lshl_add_u64 v[116:117], v[174:175], 2, s[28:29]
	v_lshl_add_u64 v[178:179], v[176:177], 2, s[12:13]
	global_load_dwordx4 v[120:123], v[116:117], off offset:16
	global_load_dwordx4 v[124:127], v[116:117], off
	global_load_dwordx4 v[112:115], v[116:117], off offset:528
	s_nop 0
	global_load_dwordx4 v[116:119], v[116:117], off offset:512
	v_or_b32_e32 v172, 16, v176
	global_load_dword v180, v[178:179], off
	v_ashrrev_i32_e32 v173, 31, v172
	v_lshl_add_u64 v[162:163], v[172:173], 2, s[12:13]
	global_load_dword v170, v[162:163], off
	v_or_b32_e32 v168, 32, v176
	v_ashrrev_i32_e32 v169, 31, v168
	v_lshl_add_u64 v[162:163], v[168:169], 2, s[12:13]
	global_load_dword v166, v[162:163], off
	v_or_b32_e32 v164, 48, v176
	v_ashrrev_i32_e32 v165, 31, v164
	v_lshl_add_u64 v[162:163], v[164:165], 2, s[12:13]
	global_load_dword v162, v[162:163], off
	s_nop 0
	global_load_dword v160, v[178:179], off offset:512
	global_load_dword v158, v[178:179], off offset:576
	global_load_dword v156, v[178:179], off offset:640
	global_load_dword v154, v[178:179], off offset:704
	s_and_b64 vcc, exec, s[14:15]
	s_cbranch_vccz .LBB0_1482
	s_barrier

;     __host__ __device__ bool next(int i, Unit& u) const { const int L = base + i * Gp + cp; if (L >= end) return false; return T.next(L, u); }
;     __host__ __device__ bool next(int i, Unit& u) const { const int L = i * Gp + cp; if (cp < 0 || L >= n) return false; u.kb = L & 3; u.pn = (L >> 2) % nN; u.pm = pm0 + (L >> 2) / nN; return true; }
;     __host__ __device__ bool next(int i, Unit& u) const { const bool ok = T.next(i >> 2, u); u.kb = i & 3; return ok; }
; #define PG8_BAR __builtin_amdgcn_s_barrier()
; template <class Epi, class Sched, bool ALIGN_EPI = false, bool SP2 = false>
; __device__ __forceinline__ void gemm_phase(PG8_LAS unsigned char* lds, const Gemm g, const Sched& S, const Epi& E, const int tid) {
;     ...
;         const bool has_next = S.next(ui + 1, nxt);
;         const char* nA = has_next ? (const char*)g.A + (size_t)nxt.pm * tstep + (size_t)nxt.kb * g.sA : cA; const char* nB = has_next ? (const char*)g.Bt + (size_t)nxt.pn * tstep + (size_t)nxt.kb * g.sB : cB;
;     ...
; #pragma unroll
;         for (int a = 0; a < 2; ++a)
; #pragma unroll
;             for (int b = 0; b < 2; ++b)
; #pragma unroll
;                 for (int m = 0; m < 4; ++m)
; #pragma unroll
;                     for (int n = 0; n < 2; ++n) acc[a][b][m][n] = (f32x4){0.f, 0.f, 0.f, 0.f};
;         cur = nxt; cA = nA; cB = nB; ++ui;
;         if constexpr (ALIGN_EPI) { if (wr == 1) PG8_BAR; }
.LBB0_1558:
	s_ashr_i32 s31, s30, 31
	s_lshl_b64 s[34:35], s[30:31], 22
	s_add_u32 s34, s50, s34
	s_addc_u32 s35, s51, s35
	s_and_b64 s[36:37], s[0:1], exec
	s_cselect_b32 s31, s35, s43
	s_cselect_b32 s39, s34, s42
	s_ashr_i32 s29, s28, 31
	s_lshl_b64 s[36:37], s[28:29], 22
	s_add_u32 s36, s52, s36
	s_addc_u32 s37, s53, s37
	s_and_b64 s[46:47], s[0:1], exec
	s_cselect_b32 s29, s37, s45
	s_cselect_b32 s41, s36, s44
	s_add_u32 s42, s42, 0x200080
	s_addc_u32 s43, s43, 0
	s_add_u32 s71, s44, 0x100
	v_mov_b32_e32 v0, 0
	s_addc_u32 s72, s45, 0
	s_mov_b32 s73, -2
	s_cmp_eq_u32 s100, 0
	s_cbranch_scc1 .Lmy_nobar_1559
	s_barrier
	s_mov_b32 s100, 0
; #define PG8_STAGE(bufoff, gbase, voff) do { _Pragma("unroll") for (int _i = 0; _i < 2; ++_i) \
;         __builtin_amdgcn_global_load_lds((const unsigned*)((const char*)(gbase) + (voff)[_i]), (PG8_LAS unsigned*)(lds + (bufoff) + ldsw + _i * 8192), 16, 0, 0); } while (0)
; #define PG8_LDA(dst, b, h) do { _Pragma("unroll") for (int m = 0; m < 4; ++m) _Pragma("unroll") for (int k = 0; k < 2; ++k) dst[m][k] = *(const PG8_LAS bf16x8*)(lds + PG8_SA(b, h) + aoff + m * 2048 + k * 1024); } while (0)
; #define PG8_LDB(dst, b, h) do { _Pragma("unroll") for (int n = 0; n < 2; ++n) _Pragma("unroll") for (int k = 0; k < 2; ++k) dst[n][k] = *(const PG8_LAS bf16x8*)(lds + PG8_SB(b, h) + boff + n * 2048 + k * 1024); } while (0)
; #define PG8_MMA(ai, bj, At, Bt) do { __builtin_amdgcn_s_setprio(1); _Pragma("unroll") for (int m = 0; m < 4; ++m) _Pragma("unroll") for (int n = 0; n < 2; ++n) _Pragma("unroll") for (int k = 0; k < 2; ++k) \
;         acc[ai][bj][m][n] = __builtin_amdgcn_mfma_f32_16x16x32_bf16(Bt[n][k], At[m][k], acc[ai][bj][m][n], 0, 0, 0); __builtin_amdgcn_s_setprio(0); } while (0)
; #define PG8_WAIT_V(n) asm volatile("s_waitcnt vmcnt(" #n ")" ::: "memory")
; #define PG8_WAIT_L(n) asm volatile("s_waitcnt lgkmcnt(" #n ")" ::: "memory")
; #define PG8_BAR __builtin_amdgcn_s_barrier()
; #define PG8_SCHED __builtin_amdgcn_sched_barrier(0)
; template <class Epi, class Sched, bool ALIGN_EPI = false, bool SP2 = false>
; __device__ __forceinline__ void gemm_phase(PG8_LAS unsigned char* lds, const Gemm g, const Sched& S, const Epi& E, const int tid) {
;     ...
;             if constexpr (SP2) {
;             PG8_LDB(B0, 0, 0); PG8_LDB(B1, 0, 1); PG8_SCHED; PG8_LDA(At, 0, 0); PG8_STAGE(PG8_SA(1, 1), a1 + hstep, voffA);
;             PG8_WAIT_V(8); PG8_WAIT_L(0); PG8_BAR; PG8_MMA(0, 0, At, B0); PG8_MMA(0, 1, At, B1); PG8_BAR; PG8_SCHED;
;             PG8_LDA(At, 0, 1); PG8_STAGE(PG8_SB(0, 0), b2, voffB); PG8_STAGE(PG8_SB(0, 1), b2 + hstep, voffB); PG8_STAGE(PG8_SA(0, 0), a2, voffA);
;             PG8_WAIT_V(8); PG8_WAIT_L(0); PG8_BAR; PG8_MMA(1, 0, At, B0); PG8_MMA(1, 1, At, B1); PG8_BAR; PG8_SCHED;
.Lmy_nobar_1559:
	s_add_u32 s44, s42, 0xffe00080
	s_addc_u32 s45, s43, -1
	s_add_i32 s74, 0, 0x10000
	v_add_u32_e32 v132, s74, v252
	v_add_u32_e32 v156, s33, v252
	ds_read_b128 v[116:119], v132
	ds_read_b128 v[124:127], v132 offset:1024
	ds_read_b128 v[128:131], v132 offset:2048
	ds_read_b128 v[132:135], v132 offset:3072
	ds_read_b128 v[144:147], v156
	ds_read_b128 v[148:151], v156 offset:1024
	ds_read_b128 v[152:155], v156 offset:2048
	ds_read_b128 v[156:159], v156 offset:3072
	s_cmpk_eq_i32 s73, 0x7c
	s_cselect_b32 s47, s31, s45
	s_cselect_b32 s46, s39, s44
	s_cselect_b32 s45, s29, s72
	s_cselect_b32 s44, s41, s71
	v_lshl_add_u64 v[192:193], s[42:43], 0, v[220:221]
	s_add_i32 m0, s55, 0xc000
	ds_read_b128 v[160:163], v210
	ds_read_b128 v[164:167], v210 offset:1024
	ds_read_b128 v[168:171], v210 offset:2048
	ds_read_b128 v[172:175], v210 offset:3072
	ds_read_b128 v[176:179], v210 offset:4096
	ds_read_b128 v[180:183], v210 offset:5120
	ds_read_b128 v[184:187], v210 offset:6144
	ds_read_b128 v[188:191], v210 offset:7168
	global_load_lds_dwordx4 v[192:193], off
	v_lshl_add_u64 v[192:193], s[42:43], 0, v[222:223]
	s_add_i32 m0, s55, 0xe000
	s_nop 0
	global_load_lds_dwordx4 v[192:193], off
	s_waitcnt vmcnt(8)
	s_waitcnt lgkmcnt(0)
	s_barrier
	s_setprio 1
	s_waitcnt lgkmcnt(0)
	v_mfma_f32_16x16x32_bf16 v[140:143], v[116:119], v[160:163], 0
	v_mfma_f32_16x16x32_bf16 v[136:139], v[128:131], v[160:163], 0
	v_mfma_f32_16x16x32_bf16 v[108:111], v[116:119], v[168:171], 0
	v_mfma_f32_16x16x32_bf16 v[104:107], v[128:131], v[168:171], 0
	v_mfma_f32_16x16x32_bf16 v[92:95], v[116:119], v[176:179], 0
	v_mfma_f32_16x16x32_bf16 v[88:91], v[128:131], v[176:179], 0
	v_mfma_f32_16x16x32_bf16 v[76:79], v[116:119], v[184:187], 0
	v_mfma_f32_16x16x32_bf16 v[72:75], v[128:131], v[184:187], 0
	v_mfma_f32_16x16x32_bf16 v[140:143], v[124:127], v[164:167], v[140:143]
	v_mfma_f32_16x16x32_bf16 v[136:139], v[132:135], v[164:167], v[136:139]
	v_mfma_f32_16x16x32_bf16 v[108:111], v[124:127], v[172:175], v[108:111]
	v_mfma_f32_16x16x32_bf16 v[104:107], v[132:135], v[172:175], v[104:107]
	v_mfma_f32_16x16x32_bf16 v[92:95], v[124:127], v[180:183], v[92:95]
	v_mfma_f32_16x16x32_bf16 v[88:91], v[132:135], v[180:183], v[88:91]
	v_mfma_f32_16x16x32_bf16 v[76:79], v[124:127], v[188:191], v[76:79]
	v_mfma_f32_16x16x32_bf16 v[72:75], v[132:135], v[188:191], v[72:75]
	s_setprio 0
	s_setprio 1
	v_mfma_f32_16x16x32_bf16 v[120:123], v[144:147], v[160:163], 0
	v_mfma_f32_16x16x32_bf16 v[112:115], v[152:155], v[160:163], 0
	v_mfma_f32_16x16x32_bf16 v[100:103], v[144:147], v[168:171], 0
	v_mfma_f32_16x16x32_bf16 v[96:99], v[152:155], v[168:171], 0
	v_mfma_f32_16x16x32_bf16 v[84:87], v[144:147], v[176:179], 0
	v_mfma_f32_16x16x32_bf16 v[80:83], v[152:155], v[176:179], 0
	v_mfma_f32_16x16x32_bf16 v[68:71], v[144:147], v[184:187], 0
	v_mfma_f32_16x16x32_bf16 v[64:67], v[152:155], v[184:187], 0
	v_mfma_f32_16x16x32_bf16 v[120:123], v[148:151], v[164:167], v[120:123]
	v_mfma_f32_16x16x32_bf16 v[112:115], v[156:159], v[164:167], v[112:115]
	v_mfma_f32_16x16x32_bf16 v[100:103], v[148:151], v[172:175], v[100:103]
	v_mfma_f32_16x16x32_bf16 v[96:99], v[156:159], v[172:175], v[96:99]
	v_mfma_f32_16x16x32_bf16 v[84:87], v[148:151], v[180:183], v[84:87]
	v_mfma_f32_16x16x32_bf16 v[80:83], v[156:159], v[180:183], v[80:83]
	v_mfma_f32_16x16x32_bf16 v[68:71], v[148:151], v[188:191], v[68:71]
	v_mfma_f32_16x16x32_bf16 v[64:67], v[156:159], v[188:191], v[64:67]
	s_setprio 0
	s_barrier
	s_add_i32 s74, s74, s54
	v_lshl_add_u64 v[192:193], s[44:45], 0, v[208:209]
	s_mov_b32 m0, s74
	ds_read_b128 v[160:163], v210 offset:16384
	ds_read_b128 v[164:167], v210 offset:17408
	ds_read_b128 v[168:171], v210 offset:18432
	ds_read_b128 v[172:175], v210 offset:19456
	ds_read_b128 v[176:179], v210 offset:20480
	ds_read_b128 v[180:183], v210 offset:21504
	ds_read_b128 v[184:187], v210 offset:22528
	ds_read_b128 v[188:191], v210 offset:23552
	global_load_lds_dwordx4 v[192:193], off
	s_add_i32 m0, s74, 0x2000
	s_add_u32 s74, s44, 0x200000
	v_lshl_add_u64 v[194:195], s[44:45], 0, v[218:219]
	s_addc_u32 s75, s45, 0
	s_add_i32 s76, s33, s54
	global_load_lds_dwordx4 v[194:195], off
	v_lshl_add_u64 v[196:197], s[74:75], 0, v[208:209]
	s_mov_b32 m0, s76
	v_lshl_add_u64 v[198:199], s[46:47], 0, v[216:217]
	global_load_lds_dwordx4 v[196:197], off
	v_lshl_add_u64 v[196:197], s[74:75], 0, v[218:219]
	s_add_i32 m0, s76, 0x2000
	s_nop 0
	global_load_lds_dwordx4 v[196:197], off
	v_lshl_add_u64 v[196:197], s[46:47], 0, v[214:215]
	s_mov_b32 m0, s55
	s_nop 0
	global_load_lds_dwordx4 v[196:197], off
	s_mov_b32 m0, s56
	s_nop 0
	global_load_lds_dwordx4 v[198:199], off
	s_waitcnt vmcnt(8)
	s_waitcnt lgkmcnt(0)
	s_barrier
	s_setprio 1
	s_waitcnt lgkmcnt(0)
	v_mfma_f32_16x16x32_bf16 v[60:63], v[116:119], v[160:163], 0
	v_mfma_f32_16x16x32_bf16 v[56:59], v[128:131], v[160:163], 0
	v_mfma_f32_16x16x32_bf16 v[44:47], v[116:119], v[168:171], 0
	v_mfma_f32_16x16x32_bf16 v[40:43], v[128:131], v[168:171], 0
	v_mfma_f32_16x16x32_bf16 v[28:31], v[116:119], v[176:179], 0
	v_mfma_f32_16x16x32_bf16 v[24:27], v[128:131], v[176:179], 0
	v_mfma_f32_16x16x32_bf16 v[12:15], v[116:119], v[184:187], 0
	v_mfma_f32_16x16x32_bf16 v[8:11], v[128:131], v[184:187], 0
	v_mfma_f32_16x16x32_bf16 v[60:63], v[124:127], v[164:167], v[60:63]
	v_mfma_f32_16x16x32_bf16 v[56:59], v[132:135], v[164:167], v[56:59]
	v_mfma_f32_16x16x32_bf16 v[44:47], v[124:127], v[172:175], v[44:47]
	v_mfma_f32_16x16x32_bf16 v[40:43], v[132:135], v[172:175], v[40:43]
	v_mfma_f32_16x16x32_bf16 v[28:31], v[124:127], v[180:183], v[28:31]
	v_mfma_f32_16x16x32_bf16 v[24:27], v[132:135], v[180:183], v[24:27]
	v_mfma_f32_16x16x32_bf16 v[12:15], v[124:127], v[188:191], v[12:15]
	v_mfma_f32_16x16x32_bf16 v[8:11], v[132:135], v[188:191], v[8:11]
	s_setprio 0
	s_setprio 1
	v_mfma_f32_16x16x32_bf16 v[52:55], v[144:147], v[160:163], 0
	v_mfma_f32_16x16x32_bf16 v[48:51], v[152:155], v[160:163], 0
	v_mfma_f32_16x16x32_bf16 v[36:39], v[144:147], v[168:171], 0
	v_mfma_f32_16x16x32_bf16 v[32:35], v[152:155], v[168:171], 0
	v_mfma_f32_16x16x32_bf16 v[20:23], v[144:147], v[176:179], 0
	v_mfma_f32_16x16x32_bf16 v[16:19], v[152:155], v[176:179], 0
	v_mfma_f32_16x16x32_bf16 v[4:7], v[144:147], v[184:187], 0
	v_mfma_f32_16x16x32_bf16 v[0:3], v[152:155], v[184:187], 0
	v_mfma_f32_16x16x32_bf16 v[52:55], v[148:151], v[164:167], v[52:55]
	v_mfma_f32_16x16x32_bf16 v[48:51], v[156:159], v[164:167], v[48:51]
	v_mfma_f32_16x16x32_bf16 v[36:39], v[148:151], v[172:175], v[36:39]
	v_mfma_f32_16x16x32_bf16 v[32:35], v[156:159], v[172:175], v[32:35]
	v_mfma_f32_16x16x32_bf16 v[20:23], v[148:151], v[180:183], v[20:23]
	v_mfma_f32_16x16x32_bf16 v[16:19], v[156:159], v[180:183], v[16:19]
	v_mfma_f32_16x16x32_bf16 v[4:7], v[148:151], v[188:191], v[4:7]
	v_mfma_f32_16x16x32_bf16 v[0:3], v[156:159], v[188:191], v[0:3]
	s_setprio 0
	s_barrier
	s_branch .Lmy_mid_1559

; #define PG8_STAGE(bufoff, gbase, voff) do { _Pragma("unroll") for (int _i = 0; _i < 2; ++_i) \
;         __builtin_amdgcn_global_load_lds((const unsigned*)((const char*)(gbase) + (voff)[_i]), (PG8_LAS unsigned*)(lds + (bufoff) + ldsw + _i * 8192), 16, 0, 0); } while (0)
; #define PG8_LDA(dst, b, h) do { _Pragma("unroll") for (int m = 0; m < 4; ++m) _Pragma("unroll") for (int k = 0; k < 2; ++k) dst[m][k] = *(const PG8_LAS bf16x8*)(lds + PG8_SA(b, h) + aoff + m * 2048 + k * 1024); } while (0)
; #define PG8_LDB(dst, b, h) do { _Pragma("unroll") for (int n = 0; n < 2; ++n) _Pragma("unroll") for (int k = 0; k < 2; ++k) dst[n][k] = *(const PG8_LAS bf16x8*)(lds + PG8_SB(b, h) + boff + n * 2048 + k * 1024); } while (0)
; #define PG8_MMA(ai, bj, At, Bt) do { __builtin_amdgcn_s_setprio(1); _Pragma("unroll") for (int m = 0; m < 4; ++m) _Pragma("unroll") for (int n = 0; n < 2; ++n) _Pragma("unroll") for (int k = 0; k < 2; ++k) \
;         acc[ai][bj][m][n] = __builtin_amdgcn_mfma_f32_16x16x32_bf16(Bt[n][k], At[m][k], acc[ai][bj][m][n], 0, 0, 0); __builtin_amdgcn_s_setprio(0); } while (0)
; #define PG8_WAIT_V(n) asm volatile("s_waitcnt vmcnt(" #n ")" ::: "memory")
; #define PG8_WAIT_L(n) asm volatile("s_waitcnt lgkmcnt(" #n ")" ::: "memory")
; #define PG8_BAR __builtin_amdgcn_s_barrier()
; #define PG8_SCHED __builtin_amdgcn_sched_barrier(0)
; template <class Epi, class Sched, bool ALIGN_EPI = false, bool SP2 = false>
; __device__ __forceinline__ void gemm_phase(PG8_LAS unsigned char* lds, const Gemm g, const Sched& S, const Epi& E, const int tid) {
;     ...
;             PG8_LDB(B0, 1, 0); PG8_LDB(B1, 1, 1); PG8_SCHED; PG8_LDA(At, 1, 0); PG8_STAGE(PG8_SA(0, 1), a2 + hstep, voffA);
;             PG8_WAIT_V(8); PG8_WAIT_L(0); PG8_BAR; PG8_MMA(0, 0, At, B0); PG8_MMA(0, 1, At, B1); PG8_BAR; PG8_SCHED;
.Lmy_mid_1559:
	s_add_i32 s74, 0, 0x18000
	s_add_i32 s75, 0, 0x1c000
	v_add_u32_e32 v132, s74, v252
	v_add_u32_e32 v156, s75, v252
	ds_read_b128 v[116:119], v132
	ds_read_b128 v[124:127], v132 offset:1024
	ds_read_b128 v[128:131], v132 offset:2048
	ds_read_b128 v[132:135], v132 offset:3072
	ds_read_b128 v[144:147], v156
	ds_read_b128 v[148:151], v156 offset:1024
	ds_read_b128 v[152:155], v156 offset:2048
	ds_read_b128 v[156:159], v156 offset:3072
	s_add_u32 s46, s46, 0x200000
	s_addc_u32 s47, s47, 0
	s_mov_b32 m0, s57
	v_lshl_add_u64 v[200:201], s[46:47], 0, v[214:215]
	ds_read_b128 v[160:163], v210 offset:32768
	ds_read_b128 v[164:167], v210 offset:33792
	ds_read_b128 v[168:171], v210 offset:34816
	ds_read_b128 v[172:175], v210 offset:35840
	ds_read_b128 v[176:179], v210 offset:36864
	ds_read_b128 v[180:183], v210 offset:37888
	ds_read_b128 v[184:187], v210 offset:38912
	ds_read_b128 v[188:191], v210 offset:39936
	global_load_lds_dwordx4 v[200:201], off
	v_lshl_add_u64 v[200:201], s[46:47], 0, v[216:217]
	s_mov_b32 m0, s58
	s_nop 0
	global_load_lds_dwordx4 v[200:201], off
	s_waitcnt vmcnt(8)
	s_waitcnt lgkmcnt(0)
	s_barrier
	s_setprio 1
	s_waitcnt lgkmcnt(0)
	v_mfma_f32_16x16x32_bf16 v[140:143], v[116:119], v[160:163], v[140:143]
	v_mfma_f32_16x16x32_bf16 v[136:139], v[128:131], v[160:163], v[136:139]
	v_mfma_f32_16x16x32_bf16 v[108:111], v[116:119], v[168:171], v[108:111]
	v_mfma_f32_16x16x32_bf16 v[104:107], v[128:131], v[168:171], v[104:107]
	v_mfma_f32_16x16x32_bf16 v[92:95], v[116:119], v[176:179], v[92:95]
	v_mfma_f32_16x16x32_bf16 v[88:91], v[128:131], v[176:179], v[88:91]
	v_mfma_f32_16x16x32_bf16 v[76:79], v[116:119], v[184:187], v[76:79]
	v_mfma_f32_16x16x32_bf16 v[72:75], v[128:131], v[184:187], v[72:75]
	v_mfma_f32_16x16x32_bf16 v[140:143], v[124:127], v[164:167], v[140:143]
	v_mfma_f32_16x16x32_bf16 v[136:139], v[132:135], v[164:167], v[136:139]
	v_mfma_f32_16x16x32_bf16 v[108:111], v[124:127], v[172:175], v[108:111]
	v_mfma_f32_16x16x32_bf16 v[104:107], v[132:135], v[172:175], v[104:107]
	v_mfma_f32_16x16x32_bf16 v[92:95], v[124:127], v[180:183], v[92:95]
	v_mfma_f32_16x16x32_bf16 v[88:91], v[132:135], v[180:183], v[88:91]
	v_mfma_f32_16x16x32_bf16 v[76:79], v[124:127], v[188:191], v[76:79]
	v_mfma_f32_16x16x32_bf16 v[72:75], v[132:135], v[188:191], v[72:75]
	s_setprio 0
	s_setprio 1
	v_mfma_f32_16x16x32_bf16 v[120:123], v[144:147], v[160:163], v[120:123]
	v_mfma_f32_16x16x32_bf16 v[112:115], v[152:155], v[160:163], v[112:115]
	v_mfma_f32_16x16x32_bf16 v[100:103], v[144:147], v[168:171], v[100:103]
	v_mfma_f32_16x16x32_bf16 v[96:99], v[152:155], v[168:171], v[96:99]
	v_mfma_f32_16x16x32_bf16 v[84:87], v[144:147], v[176:179], v[84:87]
	v_mfma_f32_16x16x32_bf16 v[80:83], v[152:155], v[176:179], v[80:83]
	v_mfma_f32_16x16x32_bf16 v[68:71], v[144:147], v[184:187], v[68:71]
	v_mfma_f32_16x16x32_bf16 v[64:67], v[152:155], v[184:187], v[64:67]
	v_mfma_f32_16x16x32_bf16 v[120:123], v[148:151], v[164:167], v[120:123]
	v_mfma_f32_16x16x32_bf16 v[112:115], v[156:159], v[164:167], v[112:115]
	v_mfma_f32_16x16x32_bf16 v[100:103], v[148:151], v[172:175], v[100:103]
	v_mfma_f32_16x16x32_bf16 v[96:99], v[156:159], v[172:175], v[96:99]
	v_mfma_f32_16x16x32_bf16 v[84:87], v[148:151], v[180:183], v[84:87]
	v_mfma_f32_16x16x32_bf16 v[80:83], v[156:159], v[180:183], v[80:83]
	v_mfma_f32_16x16x32_bf16 v[68:71], v[148:151], v[188:191], v[68:71]
	v_mfma_f32_16x16x32_bf16 v[64:67], v[156:159], v[188:191], v[64:67]
	s_setprio 0
	s_barrier
; #define PG8_WAIT_V(n) asm volatile("s_waitcnt vmcnt(" #n ")" ::: "memory")
; template <class Epi, class Sched, bool ALIGN_EPI = false, bool SP2 = false>
; __device__ __forceinline__ void gemm_phase(PG8_LAS unsigned char* lds, const Gemm g, const Sched& S, const Epi& E, const int tid) {
;     ...
;             PG8_LDA(At, 1, 1); PG8_STAGE(PG8_SB(1, 0), b3, voffB); PG8_STAGE(PG8_SB(1, 1), b3 + hstep, voffB); PG8_STAGE(PG8_SA(1, 0), a3, voffA);
;             PG8_WAIT_V(8); PG8_WAIT_L(0); PG8_BAR; PG8_MMA(1, 0, At, B0); PG8_MMA(1, 1, At, B1); PG8_BAR; PG8_SCHED;
;             } else {
;             PG8_LDB(B0, 0, 0); PG8_SCHED; PG8_LDA(At, 0, 0); PG8_STAGE(PG8_SA(1, 1), a1 + hstep, voffA);
;             PG8_WAIT_L(8); PG8_BAR; PG8_WAIT_L(0); PG8_MMA(0, 0, At, B0); PG8_BAR; PG8_SCHED;
;             PG8_LDB(B1, 0, 1); PG8_STAGE(PG8_SB(0, 0), b2, voffB);
;             PG8_BAR; PG8_WAIT_L(0); PG8_MMA(0, 1, At, B1); PG8_BAR;
;             PG8_LDA(At, 0, 1); PG8_STAGE(PG8_SA(0, 0), a2, voffA);
;             PG8_BAR; PG8_WAIT_L(0); PG8_MMA(1, 0, At, B0); PG8_BAR; PG8_SCHED;
;             PG8_STAGE(PG8_SB(0, 1), b2 + hstep, voffB);
;             PG8_WAIT_V(6); PG8_BAR; PG8_MMA(1, 1, At, B1); PG8_BAR;
;             PG8_LDB(B0, 1, 0); PG8_SCHED; PG8_LDA(At, 1, 0); PG8_STAGE(PG8_SA(0, 1), a2 + hstep, voffA);
;             PG8_WAIT_L(8); PG8_BAR; PG8_WAIT_L(0); PG8_MMA(0, 0, At, B0); PG8_BAR; PG8_SCHED;
;             PG8_LDB(B1, 1, 1); PG8_STAGE(PG8_SB(1, 0), b3, voffB);
;             PG8_BAR; PG8_WAIT_L(0); PG8_MMA(0, 1, At, B1); PG8_BAR;
;             PG8_LDA(At, 1, 1); PG8_STAGE(PG8_SA(1, 0), a3, voffA);
;             PG8_BAR; PG8_WAIT_L(0); PG8_MMA(1, 0, At, B0); PG8_BAR; PG8_SCHED;
;             PG8_STAGE(PG8_SB(1, 1), b3 + hstep, voffB);
;             PG8_WAIT_V(6); PG8_BAR; PG8_MMA(1, 1, At, B1); PG8_BAR;
;             }
;         }
;         if constexpr (ALIGN_EPI) { if (wr == 0) PG8_BAR; }
;     __device__ __forceinline__ void operator()(const f32x4 (&acc)[2][2][4][2], const Unit& un, int wr, int wc, int fr_, int fq_) const {
;     ...
;         const bool lat = un.pm < (NLAT / 256);
;         const int slot = lat ? (un.pm >> 5) : 4;
;         const float* src = lat ? srcl : srcc; float* dst = lat ? dstl : dstc; const int radj = lat ? 0 : NLAT;
;         const float* gp = modg + (size_t)slot * 12288; const float* sp2 = sc2 + (size_t)slot * 12288;
	s_add_i32 s46, s74, s54
	v_lshl_add_u64 v[192:193], v[192:193], 0, s[2:3]
	s_mov_b32 m0, s46
	ds_read_b128 v[160:163], v210 offset:49152
	ds_read_b128 v[164:167], v210 offset:50176
	ds_read_b128 v[168:171], v210 offset:51200
	ds_read_b128 v[172:175], v210 offset:52224
	ds_read_b128 v[176:179], v210 offset:53248
	ds_read_b128 v[180:183], v210 offset:54272
	ds_read_b128 v[184:187], v210 offset:55296
	ds_read_b128 v[188:191], v210 offset:56320
	global_load_lds_dwordx4 v[192:193], off
	s_add_i32 m0, s46, 0x2000
	s_add_u32 s44, s44, 0x200080
	v_lshl_add_u64 v[192:193], v[194:195], 0, s[2:3]
	s_addc_u32 s45, s45, 0
	s_add_i32 s46, s75, s54
	global_load_lds_dwordx4 v[192:193], off
	v_lshl_add_u64 v[192:193], s[44:45], 0, v[208:209]
	s_mov_b32 m0, s46
	s_nop 0
	global_load_lds_dwordx4 v[192:193], off
	v_lshl_add_u64 v[192:193], s[44:45], 0, v[218:219]
	s_add_i32 m0, s46, 0x2000
	s_nop 0
	global_load_lds_dwordx4 v[192:193], off
	v_lshl_add_u64 v[192:193], v[196:197], 0, s[2:3]
	s_mov_b32 m0, s66
	s_nop 0
	global_load_lds_dwordx4 v[192:193], off
	v_lshl_add_u64 v[192:193], v[198:199], 0, s[2:3]
	s_mov_b32 m0, s67
	s_nop 0
	global_load_lds_dwordx4 v[192:193], off
	s_waitcnt vmcnt(8)
	s_waitcnt lgkmcnt(0)
	s_barrier
	s_setprio 1
	s_waitcnt lgkmcnt(0)
	v_mfma_f32_16x16x32_bf16 v[60:63], v[116:119], v[160:163], v[60:63]
	v_mfma_f32_16x16x32_bf16 v[56:59], v[128:131], v[160:163], v[56:59]
	v_mfma_f32_16x16x32_bf16 v[44:47], v[116:119], v[168:171], v[44:47]
	v_mfma_f32_16x16x32_bf16 v[40:43], v[128:131], v[168:171], v[40:43]
	v_mfma_f32_16x16x32_bf16 v[28:31], v[116:119], v[176:179], v[28:31]
	v_mfma_f32_16x16x32_bf16 v[24:27], v[128:131], v[176:179], v[24:27]
	v_mfma_f32_16x16x32_bf16 v[12:15], v[116:119], v[184:187], v[12:15]
	v_mfma_f32_16x16x32_bf16 v[8:11], v[128:131], v[184:187], v[8:11]
	v_mfma_f32_16x16x32_bf16 v[60:63], v[124:127], v[164:167], v[60:63]
	v_mfma_f32_16x16x32_bf16 v[56:59], v[132:135], v[164:167], v[56:59]
	v_mfma_f32_16x16x32_bf16 v[44:47], v[124:127], v[172:175], v[44:47]
	v_mfma_f32_16x16x32_bf16 v[40:43], v[132:135], v[172:175], v[40:43]
	v_mfma_f32_16x16x32_bf16 v[28:31], v[124:127], v[180:183], v[28:31]
	v_mfma_f32_16x16x32_bf16 v[24:27], v[132:135], v[180:183], v[24:27]
	v_mfma_f32_16x16x32_bf16 v[12:15], v[124:127], v[188:191], v[12:15]
	v_mfma_f32_16x16x32_bf16 v[8:11], v[132:135], v[188:191], v[8:11]
	s_setprio 0
	s_setprio 1
	v_mfma_f32_16x16x32_bf16 v[52:55], v[144:147], v[160:163], v[52:55]
	v_mfma_f32_16x16x32_bf16 v[48:51], v[152:155], v[160:163], v[48:51]
	v_mfma_f32_16x16x32_bf16 v[36:39], v[144:147], v[168:171], v[36:39]
	v_mfma_f32_16x16x32_bf16 v[32:35], v[152:155], v[168:171], v[32:35]
	v_mfma_f32_16x16x32_bf16 v[20:23], v[144:147], v[176:179], v[20:23]
	v_mfma_f32_16x16x32_bf16 v[16:19], v[152:155], v[176:179], v[16:19]
	v_mfma_f32_16x16x32_bf16 v[4:7], v[144:147], v[184:187], v[4:7]
	v_mfma_f32_16x16x32_bf16 v[0:3], v[152:155], v[184:187], v[0:3]
	v_mfma_f32_16x16x32_bf16 v[52:55], v[148:151], v[164:167], v[52:55]
	v_mfma_f32_16x16x32_bf16 v[48:51], v[156:159], v[164:167], v[48:51]
	v_mfma_f32_16x16x32_bf16 v[36:39], v[148:151], v[172:175], v[36:39]
	v_mfma_f32_16x16x32_bf16 v[32:35], v[156:159], v[172:175], v[32:35]
	v_mfma_f32_16x16x32_bf16 v[20:23], v[148:151], v[180:183], v[20:23]
	v_mfma_f32_16x16x32_bf16 v[16:19], v[156:159], v[180:183], v[16:19]
	v_mfma_f32_16x16x32_bf16 v[4:7], v[148:151], v[188:191], v[4:7]
	v_mfma_f32_16x16x32_bf16 v[0:3], v[156:159], v[188:191], v[0:3]
	s_setprio 0
	s_barrier
	s_add_i32 s73, s73, 2
	s_add_u32 s42, s42, 0x100
	s_addc_u32 s43, s43, 0
	s_add_u32 s71, s71, 0x100
	s_addc_u32 s72, s72, 0
	s_cmpk_gt_u32 s73, 0x7d
	s_cbranch_scc0 .LBB0_1559
	s_cmpk_gt_i32 s40, 0x7f
	s_mov_b32 s71, 0x280000
	s_mov_b32 s72, 0x2c0000
	v_mbcnt_lo_u32_b32 v211, -1, 0
	v_mbcnt_hi_u32_b32 v211, -1, v211
	s_cbranch_scc1 .LBB0_1564
	s_ashr_i32 s29, s40, 5
	s_mul_hi_i32 s47, s29, 0x3000
	s_mul_i32 s46, s29, 0x3000
	s_mov_b32 s29, 0
	s_mov_b64 s[42:43], s[14:15]
	s_mov_b64 s[44:45], s[12:13]
	s_branch .LBB0_1565

;     __device__ __forceinline__ void operator()(const f32x4 (&acc)[2][2][4][2], const Unit& un, int wr, int wc, int fr_, int fq_) const {
;     ...
;         const int rbase = un.pm * 256 + wr * 64 + fr, cw = un.pn * 256 + wc * 32 + 8 * fq;
;         const bool lat = un.pm < (NLAT / 256);
;         const int slot = lat ? (un.pm >> 5) : 4;
;         const float* src = lat ? srcl : srcc; float* dst = lat ? dstl : dstc; const int radj = lat ? 0 : NLAT;
;         const float* gp = modg + (size_t)slot * 12288; const float* sp2 = sc2 + (size_t)slot * 12288;
;         float ssq[2][4];
; #pragma unroll
;         for (int ai = 0; ai < 2; ++ai)
; #pragma unroll
;             for (int m = 0; m < 4; ++m) ssq[ai][m] = 0.f;
;         f32x4 g0[2], g1[2], y0s[2], y1s[2];
; #pragma unroll
;         for (int bj = 0; bj < 2; ++bj) { const int col = cw + bj * 128; g0[bj] = *(const f32x4*)(gp + col); g1[bj] = *(const f32x4*)(gp + col + 4);
;             y0s[bj] = *(const f32x4*)(ng2 + col) * (*(const f32x4*)(sp2 + col) + 1.f); y1s[bj] = *(const f32x4*)(ng2 + col + 4) * (*(const f32x4*)(sp2 + col + 4) + 1.f); }
; #pragma unroll
;         for (int ai = 0; ai < 2; ++ai) {
;             f32x4 xa[4][2][2];
; #pragma unroll
;             for (int m = 0; m < 4; ++m)
; #pragma unroll
;                 for (int bj = 0; bj < 2; ++bj) { const float* sp = src + (size_t)(rbase + ai * 128 + m * 16 - radj) * D + cw + bj * 128; xa[m][bj][0] = *(const f32x4*)sp; xa[m][bj][1] = *(const f32x4*)(sp + 4); }
; #pragma unroll
;             for (int m = 0; m < 4; ++m)
; #pragma unroll
;                 for (int bj = 0; bj < 2; ++bj) { const int row = rbase + ai * 128 + m * 16, col = cw + bj * 128; const f32x4 v0 = acc[ai][bj][m][0], v1 = acc[ai][bj][m][1];
;                     float* dp = dst + (size_t)(row - radj) * D + col;
;                     const f32x4 x0 = xa[m][bj][0] + g0[bj] * v0, x1 = xa[m][bj][1] + g1[bj] * v1;
;                     *(f32x4*)dp = x0; *(f32x4*)(dp + 4) = x1;
;                     ssq[ai][m] += (x0.x * x0.x + x0.y * x0.y) + (x0.z * x0.z + x0.w * x0.w) + (x1.x * x1.x + x1.y * x1.y) + (x1.z * x1.z + x1.w * x1.w);
;                     const f32x4 y0 = x0 * y0s[bj], y1 = x1 * y1s[bj];
;                     u32x4 w; w.x = pk2(y0.x, y0.y); w.y = pk2(y0.z, y0.w); w.z = pk2(y1.x, y1.y); w.w = pk2(y1.z, y1.w); *(u32x4*)(xg + (size_t)row * D + col) = w; } }
.LBB0_1562:
	v_subrev_u32_e32 v246, s29, v224
	v_ashrrev_i32_e32 v247, 31, v246
	v_lshl_add_u64 v[244:245], s[44:45], 0, v[242:243]
	v_lshlrev_b64 v[212:213], 13, v[246:247]
	v_ashrrev_i32_e32 v225, 31, v224
	v_lshlrev_b64 v[250:251], 12, v[224:225]
	s_ashr_i32 s39, s38, 31
	v_cmp_gt_u32_e32 vcc, 16, v211
	s_lshl_b64 s[38:39], s[38:39], 4
	s_waitcnt vmcnt(0)
	v_pk_add_f32 v[150:151], v[150:151], 1.0 op_sel_hi:[1,0]
	v_pk_add_f32 v[148:149], v[148:149], 1.0 op_sel_hi:[1,0]
	v_pk_mul_f32 v[234:235], v[126:127], v[150:151]
	v_pk_mul_f32 v[236:237], v[124:125], v[148:149]
	v_pk_add_f32 v[124:125], v[146:147], 1.0 op_sel_hi:[1,0]
	v_pk_add_f32 v[126:127], v[144:145], 1.0 op_sel_hi:[1,0]
	v_pk_mul_f32 v[238:239], v[118:119], v[124:125]
	v_pk_mul_f32 v[240:241], v[116:117], v[126:127]
	global_load_dwordx4 v[116:119], v[152:153], off offset:528
	global_load_dwordx4 v[124:127], v[152:153], off offset:512
	global_load_dwordx4 v[144:147], v[154:155], off offset:528
	global_load_dwordx4 v[148:151], v[154:155], off offset:512
	s_nop 0
	global_load_dwordx4 v[152:155], v[156:157], off offset:528
	s_nop 0
	global_load_dwordx4 v[156:159], v[156:157], off offset:512
	s_waitcnt vmcnt(0)
	v_pk_add_f32 v[158:159], v[158:159], 1.0 op_sel_hi:[1,0]
	s_nop 0
	v_pk_mul_f32 v[226:227], v[150:151], v[158:159]
	v_pk_add_f32 v[150:151], v[152:153], 1.0 op_sel_hi:[1,0]
	v_pk_add_f32 v[156:157], v[156:157], 1.0 op_sel_hi:[1,0]
	v_pk_mul_f32 v[232:233], v[144:145], v[150:151]
	v_lshl_add_u64 v[144:145], v[244:245], 0, v[212:213]
	global_load_dwordx4 v[200:203], v[144:145], off offset:16
	global_load_dwordx4 v[204:207], v[144:145], off
	global_load_dwordx4 v[192:195], v[144:145], off offset:528
	global_load_dwordx4 v[196:199], v[144:145], off offset:512
	v_or_b32_e32 v144, 16, v246
	v_ashrrev_i32_e32 v145, 31, v144
	v_lshlrev_b64 v[144:145], 13, v[144:145]
	v_lshl_add_u64 v[144:145], v[244:245], 0, v[144:145]
	global_load_dwordx4 v[184:187], v[144:145], off offset:16
	global_load_dwordx4 v[188:191], v[144:145], off
	global_load_dwordx4 v[176:179], v[144:145], off offset:528
	global_load_dwordx4 v[180:183], v[144:145], off offset:512
	v_or_b32_e32 v144, 32, v246
	v_ashrrev_i32_e32 v145, 31, v144
	v_lshlrev_b64 v[144:145], 13, v[144:145]
	v_lshl_add_u64 v[144:145], v[244:245], 0, v[144:145]
	global_load_dwordx4 v[168:171], v[144:145], off offset:16
	global_load_dwordx4 v[172:175], v[144:145], off
	global_load_dwordx4 v[160:163], v[144:145], off offset:528
	global_load_dwordx4 v[164:167], v[144:145], off offset:512
	v_or_b32_e32 v144, 48, v246
	v_ashrrev_i32_e32 v145, 31, v144
	v_pk_mul_f32 v[228:229], v[148:149], v[156:157]
	v_pk_add_f32 v[148:149], v[154:155], 1.0 op_sel_hi:[1,0]
	v_lshlrev_b64 v[144:145], 13, v[144:145]
	v_pk_mul_f32 v[230:231], v[146:147], v[148:149]
	v_lshl_add_u64 v[148:149], v[244:245], 0, v[144:145]
	global_load_dwordx4 v[152:155], v[148:149], off offset:16
	global_load_dwordx4 v[156:159], v[148:149], off
	global_load_dwordx4 v[144:147], v[148:149], off offset:528
	s_nop 0
	global_load_dwordx4 v[148:151], v[148:149], off offset:512
	v_lshl_add_u64 v[212:213], s[42:43], 0, v[212:213]
	v_lshl_add_u64 v[212:213], v[212:213], 0, v[242:243]
	s_waitcnt vmcnt(15)
	v_pk_fma_f32 v[136:137], v[136:137], v[128:129], v[200:201]
	s_waitcnt vmcnt(14)
	v_pk_fma_f32 v[142:143], v[142:143], v[134:135], v[206:207]
	v_pk_fma_f32 v[140:141], v[140:141], v[132:133], v[204:205]
	v_mul_f32_e32 v201, v143, v143
	v_mul_f32_e32 v200, v141, v141
	v_fmac_f32_e32 v200, v140, v140
	v_fmac_f32_e32 v201, v142, v142
	v_add_f32_e32 v200, v200, v201
	v_mul_f32_e32 v201, v137, v137
	v_pk_fma_f32 v[138:139], v[138:139], v[130:131], v[202:203]
	v_fmac_f32_e32 v201, v136, v136
	v_add_f32_e32 v200, v200, v201
	v_mul_f32_e32 v201, v139, v139
	v_fmac_f32_e32 v201, v138, v138
	global_store_dwordx4 v[212:213], v[140:143], off
	global_store_dwordx4 v[212:213], v[136:139], off offset:16
	v_add_f32_e32 v202, v201, v200
	v_pk_mul_f32 v[140:141], v[236:237], v[140:141]
	v_pk_mul_f32 v[200:201], v[238:239], v[138:139]
	v_pk_mul_f32 v[138:139], v[240:241], v[136:137]
	v_pk_mul_f32 v[142:143], v[234:235], v[142:143]
	v_cvt_pk_bf16_f32 v136, v140, v141
	v_cvt_pk_bf16_f32 v138, v138, v139
	v_cvt_pk_bf16_f32 v139, v200, v201
	v_lshl_add_u64 v[140:141], s[20:21], 0, v[250:251]
	v_lshlrev_b64 v[200:201], 1, v[248:249]
	v_cvt_pk_bf16_f32 v137, v142, v143
	v_lshl_add_u64 v[140:141], v[140:141], 0, v[200:201]
	s_waitcnt vmcnt(14)
	v_pk_fma_f32 v[122:123], v[122:123], v[126:127], v[198:199]
	v_pk_fma_f32 v[120:121], v[120:121], v[124:125], v[196:197]
	global_store_dwordx4 v[140:141], v[136:139], off
	v_pk_fma_f32 v[112:113], v[112:113], v[116:117], v[192:193]
	v_pk_fma_f32 v[114:115], v[114:115], v[118:119], v[194:195]
	v_mul_f32_e32 v136, v121, v121
	v_mul_f32_e32 v137, v123, v123
	v_fmac_f32_e32 v136, v120, v120
	v_fmac_f32_e32 v137, v122, v122
	v_add_f32_e32 v136, v136, v137
	v_mul_f32_e32 v137, v113, v113
	v_fmac_f32_e32 v137, v112, v112
	v_add_f32_e32 v136, v136, v137
	v_mul_f32_e32 v137, v115, v115
	v_fmac_f32_e32 v137, v114, v114
	v_add_f32_e32 v136, v137, v136
	global_store_dwordx4 v[212:213], v[120:123], off offset:512
	global_store_dwordx4 v[212:213], v[112:115], off offset:528
	v_add_f32_e32 v194, v202, v136
	v_pk_mul_f32 v[122:123], v[226:227], v[122:123]
	v_pk_mul_f32 v[120:121], v[228:229], v[120:121]
	v_pk_mul_f32 v[136:137], v[230:231], v[114:115]
	v_pk_mul_f32 v[114:115], v[232:233], v[112:113]
	v_cvt_pk_bf16_f32 v112, v120, v121
	v_cvt_pk_bf16_f32 v113, v122, v123
	v_cvt_pk_bf16_f32 v114, v114, v115
	v_cvt_pk_bf16_f32 v115, v136, v137
	v_or_b32_e32 v192, 16, v224
	global_store_dwordx4 v[140:141], v[112:115], off offset:256
	v_ashrrev_i32_e32 v193, 31, v192
	v_lshlrev_b64 v[120:121], 12, v[192:193]
	v_subrev_u32_e32 v112, s29, v192
	v_ashrrev_i32_e32 v113, 31, v112
	v_lshlrev_b64 v[112:113], 13, v[112:113]
	v_lshl_add_u64 v[112:113], s[42:43], 0, v[112:113]
	s_waitcnt vmcnt(16)
; __device__ __forceinline__ unsigned pk2(float lo, float hi) { const f32x2 v = {lo, hi}; return __builtin_bit_cast(unsigned, __builtin_convertvector(v, bf16x2_t)); }
;     __device__ __forceinline__ void operator()(const f32x4 (&acc)[2][2][4][2], const Unit& un, int wr, int wc, int fr_, int fq_) const {
;     ...
; #pragma unroll
;             for (int m = 0; m < 4; ++m)
; #pragma unroll
;                 for (int bj = 0; bj < 2; ++bj) { const int row = rbase + ai * 128 + m * 16, col = cw + bj * 128; const f32x4 v0 = acc[ai][bj][m][0], v1 = acc[ai][bj][m][1];
;                     float* dp = dst + (size_t)(row - radj) * D + col;
;                     const f32x4 x0 = xa[m][bj][0] + g0[bj] * v0, x1 = xa[m][bj][1] + g1[bj] * v1;
;                     *(f32x4*)dp = x0; *(f32x4*)(dp + 4) = x1;
;                     ssq[ai][m] += (x0.x * x0.x + x0.y * x0.y) + (x0.z * x0.z + x0.w * x0.w) + (x1.x * x1.x + x1.y * x1.y) + (x1.z * x1.z + x1.w * x1.w);
;                     const f32x4 y0 = x0 * y0s[bj], y1 = x1 * y1s[bj];
;                     u32x4 w; w.x = pk2(y0.x, y0.y); w.y = pk2(y0.z, y0.w); w.z = pk2(y1.x, y1.y); w.w = pk2(y1.z, y1.w); *(u32x4*)(xg + (size_t)row * D + col) = w; } }
	v_pk_fma_f32 v[110:111], v[110:111], v[134:135], v[190:191]
	v_pk_fma_f32 v[108:109], v[108:109], v[132:133], v[188:189]
	v_pk_fma_f32 v[106:107], v[106:107], v[130:131], v[186:187]
	v_pk_fma_f32 v[104:105], v[104:105], v[128:129], v[184:185]
	v_lshl_add_u64 v[122:123], v[112:113], 0, v[242:243]
	v_pk_mul_f32 v[114:115], v[234:235], v[110:111]
	v_pk_mul_f32 v[112:113], v[236:237], v[108:109]
	v_pk_mul_f32 v[136:137], v[238:239], v[106:107]
	v_pk_mul_f32 v[138:139], v[240:241], v[104:105]
	v_lshl_add_u64 v[120:121], s[20:21], 0, v[120:121]
	v_cvt_pk_bf16_f32 v112, v112, v113
	v_cvt_pk_bf16_f32 v113, v114, v115
	v_cvt_pk_bf16_f32 v114, v138, v139
	v_cvt_pk_bf16_f32 v115, v136, v137
	v_lshl_add_u64 v[120:121], v[120:121], 0, v[200:201]
	s_waitcnt vmcnt(14)
	v_pk_fma_f32 v[102:103], v[102:103], v[126:127], v[182:183]
	v_pk_fma_f32 v[100:101], v[100:101], v[124:125], v[180:181]
	v_pk_fma_f32 v[98:99], v[98:99], v[118:119], v[178:179]
	v_pk_fma_f32 v[96:97], v[96:97], v[116:117], v[176:177]
	global_store_dwordx4 v[122:123], v[108:111], off
	global_store_dwordx4 v[122:123], v[104:107], off offset:16
	global_store_dwordx4 v[120:121], v[112:115], off
	global_store_dwordx4 v[122:123], v[100:103], off offset:512
	global_store_dwordx4 v[122:123], v[96:99], off offset:528
	v_pk_mul_f32 v[114:115], v[226:227], v[102:103]
	v_pk_mul_f32 v[112:113], v[228:229], v[100:101]
	v_pk_mul_f32 v[122:123], v[230:231], v[98:99]
	v_pk_mul_f32 v[136:137], v[232:233], v[96:97]
	v_cvt_pk_bf16_f32 v112, v112, v113
	v_cvt_pk_bf16_f32 v113, v114, v115
	v_cvt_pk_bf16_f32 v114, v136, v137
	v_cvt_pk_bf16_f32 v115, v122, v123
	v_or_b32_e32 v176, 32, v224
	global_store_dwordx4 v[120:121], v[112:115], off offset:256
	v_ashrrev_i32_e32 v177, 31, v176
	v_lshlrev_b64 v[120:121], 12, v[176:177]
	v_subrev_u32_e32 v112, s29, v176
	v_ashrrev_i32_e32 v113, 31, v112
	v_lshlrev_b64 v[112:113], 13, v[112:113]
	v_lshl_add_u64 v[112:113], s[42:43], 0, v[112:113]
	s_waitcnt vmcnt(18)
	v_pk_fma_f32 v[94:95], v[94:95], v[134:135], v[174:175]
	v_pk_fma_f32 v[92:93], v[92:93], v[132:133], v[172:173]
	v_pk_fma_f32 v[90:91], v[90:91], v[130:131], v[170:171]
	v_pk_fma_f32 v[88:89], v[88:89], v[128:129], v[168:169]
	v_lshl_add_u64 v[122:123], v[112:113], 0, v[242:243]
	v_pk_mul_f32 v[114:115], v[234:235], v[94:95]
	v_pk_mul_f32 v[112:113], v[236:237], v[92:93]
	v_pk_mul_f32 v[136:137], v[238:239], v[90:91]
	v_pk_mul_f32 v[138:139], v[240:241], v[88:89]
	v_lshl_add_u64 v[120:121], s[20:21], 0, v[120:121]
	v_cvt_pk_bf16_f32 v112, v112, v113
	v_cvt_pk_bf16_f32 v113, v114, v115
	v_cvt_pk_bf16_f32 v114, v138, v139
	v_cvt_pk_bf16_f32 v115, v136, v137
	v_lshl_add_u64 v[120:121], v[120:121], 0, v[200:201]
	s_waitcnt vmcnt(16)
	v_pk_fma_f32 v[86:87], v[86:87], v[126:127], v[166:167]
	v_pk_fma_f32 v[84:85], v[84:85], v[124:125], v[164:165]
	v_pk_fma_f32 v[82:83], v[82:83], v[118:119], v[162:163]
	v_pk_fma_f32 v[80:81], v[80:81], v[116:117], v[160:161]
	global_store_dwordx4 v[122:123], v[92:95], off
	global_store_dwordx4 v[122:123], v[88:91], off offset:16
	global_store_dwordx4 v[120:121], v[112:115], off
	global_store_dwordx4 v[122:123], v[84:87], off offset:512
	global_store_dwordx4 v[122:123], v[80:83], off offset:528
	v_pk_mul_f32 v[114:115], v[226:227], v[86:87]
	v_pk_mul_f32 v[112:113], v[228:229], v[84:85]
	v_pk_mul_f32 v[122:123], v[230:231], v[82:83]
	v_pk_mul_f32 v[136:137], v[232:233], v[80:81]
	v_cvt_pk_bf16_f32 v112, v112, v113
	v_cvt_pk_bf16_f32 v113, v114, v115
	v_cvt_pk_bf16_f32 v114, v136, v137
	v_cvt_pk_bf16_f32 v115, v122, v123
	v_or_b32_e32 v160, 48, v224
	global_store_dwordx4 v[120:121], v[112:115], off offset:256
	v_ashrrev_i32_e32 v161, 31, v160
	v_lshlrev_b64 v[120:121], 12, v[160:161]
	v_subrev_u32_e32 v112, s29, v160
	v_ashrrev_i32_e32 v113, 31, v112
	v_lshlrev_b64 v[112:113], 13, v[112:113]
	v_lshl_add_u64 v[112:113], s[42:43], 0, v[112:113]
	s_waitcnt vmcnt(20)
	v_pk_fma_f32 v[78:79], v[78:79], v[134:135], v[158:159]
	v_pk_fma_f32 v[76:77], v[76:77], v[132:133], v[156:157]
	v_pk_fma_f32 v[74:75], v[74:75], v[130:131], v[154:155]
	v_pk_fma_f32 v[72:73], v[72:73], v[128:129], v[152:153]
	v_lshl_add_u64 v[122:123], v[112:113], 0, v[242:243]
	v_pk_mul_f32 v[114:115], v[234:235], v[78:79]
	v_pk_mul_f32 v[112:113], v[236:237], v[76:77]
	v_pk_mul_f32 v[136:137], v[238:239], v[74:75]
	v_pk_mul_f32 v[138:139], v[240:241], v[72:73]
	v_lshl_add_u64 v[120:121], s[20:21], 0, v[120:121]
	v_cvt_pk_bf16_f32 v112, v112, v113
	v_cvt_pk_bf16_f32 v113, v114, v115
	v_cvt_pk_bf16_f32 v114, v138, v139
	v_cvt_pk_bf16_f32 v115, v136, v137
	v_lshl_add_u64 v[120:121], v[120:121], 0, v[200:201]
	s_waitcnt vmcnt(18)
; __device__ __forceinline__ unsigned pk2(float lo, float hi) { const f32x2 v = {lo, hi}; return __builtin_bit_cast(unsigned, __builtin_convertvector(v, bf16x2_t)); }
;     __device__ __forceinline__ void operator()(const f32x4 (&acc)[2][2][4][2], const Unit& un, int wr, int wc, int fr_, int fq_) const {
;     ...
;         for (int ai = 0; ai < 2; ++ai) {
;             f32x4 xa[4][2][2];
; #pragma unroll
;             for (int m = 0; m < 4; ++m)
; #pragma unroll
;                 for (int bj = 0; bj < 2; ++bj) { const float* sp = src + (size_t)(rbase + ai * 128 + m * 16 - radj) * D + cw + bj * 128; xa[m][bj][0] = *(const f32x4*)sp; xa[m][bj][1] = *(const f32x4*)(sp + 4); }
; #pragma unroll
;             for (int m = 0; m < 4; ++m)
; #pragma unroll
;                 for (int bj = 0; bj < 2; ++bj) { const int row = rbase + ai * 128 + m * 16, col = cw + bj * 128; const f32x4 v0 = acc[ai][bj][m][0], v1 = acc[ai][bj][m][1];
;                     float* dp = dst + (size_t)(row - radj) * D + col;
;                     const f32x4 x0 = xa[m][bj][0] + g0[bj] * v0, x1 = xa[m][bj][1] + g1[bj] * v1;
;                     *(f32x4*)dp = x0; *(f32x4*)(dp + 4) = x1;
;                     ssq[ai][m] += (x0.x * x0.x + x0.y * x0.y) + (x0.z * x0.z + x0.w * x0.w) + (x1.x * x1.x + x1.y * x1.y) + (x1.z * x1.z + x1.w * x1.w);
;                     const f32x4 y0 = x0 * y0s[bj], y1 = x1 * y1s[bj];
;                     u32x4 w; w.x = pk2(y0.x, y0.y); w.y = pk2(y0.z, y0.w); w.z = pk2(y1.x, y1.y); w.w = pk2(y1.z, y1.w); *(u32x4*)(xg + (size_t)row * D + col) = w; } }
	v_pk_fma_f32 v[70:71], v[70:71], v[126:127], v[150:151]
	v_pk_fma_f32 v[68:69], v[68:69], v[124:125], v[148:149]
	v_pk_fma_f32 v[66:67], v[66:67], v[118:119], v[146:147]
	v_pk_fma_f32 v[64:65], v[64:65], v[116:117], v[144:145]
	global_store_dwordx4 v[122:123], v[76:79], off
	global_store_dwordx4 v[122:123], v[72:75], off offset:16
	global_store_dwordx4 v[120:121], v[112:115], off
	global_store_dwordx4 v[122:123], v[68:71], off offset:512
	global_store_dwordx4 v[122:123], v[64:67], off offset:528
	v_pk_mul_f32 v[114:115], v[226:227], v[70:71]
	v_pk_mul_f32 v[112:113], v[228:229], v[68:69]
	v_pk_mul_f32 v[122:123], v[230:231], v[66:67]
	v_pk_mul_f32 v[136:137], v[232:233], v[64:65]
	v_cvt_pk_bf16_f32 v112, v112, v113
	v_cvt_pk_bf16_f32 v113, v114, v115
	v_cvt_pk_bf16_f32 v114, v136, v137
	v_cvt_pk_bf16_f32 v115, v122, v123
	global_store_dwordx4 v[120:121], v[112:115], off offset:256
	v_add_u32_e32 v144, 0x80, v224
	v_subrev_u32_e32 v158, s29, v144
	v_add_u32_e32 v112, 0x80, v246
	v_ashrrev_i32_e32 v113, 31, v112
	v_lshlrev_b64 v[112:113], 13, v[112:113]
	v_lshl_add_u64 v[112:113], v[244:245], 0, v[112:113]
	global_load_dwordx4 v[146:149], v[112:113], off offset:16
	global_load_dwordx4 v[150:153], v[112:113], off
	global_load_dwordx4 v[154:157], v[112:113], off offset:528
	global_load_dwordx4 v[162:165], v[112:113], off offset:512
	v_add_u32_e32 v112, 0x90, v246
	v_ashrrev_i32_e32 v113, 31, v112
	v_lshlrev_b64 v[112:113], 13, v[112:113]
	v_lshl_add_u64 v[112:113], v[244:245], 0, v[112:113]
	global_load_dwordx4 v[166:169], v[112:113], off offset:16
	global_load_dwordx4 v[170:173], v[112:113], off
	global_load_dwordx4 v[178:181], v[112:113], off offset:528
	global_load_dwordx4 v[182:185], v[112:113], off offset:512
	v_add_u32_e32 v112, 0xa0, v246
	v_ashrrev_i32_e32 v113, 31, v112
	v_lshlrev_b64 v[112:113], 13, v[112:113]
	v_lshl_add_u64 v[112:113], v[244:245], 0, v[112:113]
	global_load_dwordx4 v[186:189], v[112:113], off offset:16
	global_load_dwordx4 v[196:199], v[112:113], off
	global_load_dwordx4 v[202:205], v[112:113], off offset:528
	global_load_dwordx4 v[248:251], v[112:113], off offset:512
	v_add_u32_e32 v112, 0xb0, v246
	v_ashrrev_i32_e32 v113, 31, v112
	v_lshlrev_b64 v[112:113], 13, v[112:113]
	v_lshl_add_u64 v[120:121], v[244:245], 0, v[112:113]
	global_load_dwordx4 v[136:139], v[120:121], off offset:16
	global_load_dwordx4 v[140:143], v[120:121], off
	global_load_dwordx4 v[112:115], v[120:121], off offset:528
	s_nop 0
	global_load_dwordx4 v[120:123], v[120:121], off offset:512
	v_ashrrev_i32_e32 v159, 31, v158
	v_ashrrev_i32_e32 v145, 31, v144
	v_lshlrev_b64 v[158:159], 13, v[158:159]
	v_lshlrev_b64 v[174:175], 12, v[144:145]
	v_lshl_add_u64 v[158:159], s[42:43], 0, v[158:159]
	v_lshl_add_u64 v[158:159], v[158:159], 0, v[242:243]
	s_waitcnt vmcnt(15)
	v_pk_fma_f32 v[58:59], v[58:59], v[130:131], v[148:149]
	s_waitcnt vmcnt(14)
	v_pk_fma_f32 v[62:63], v[62:63], v[134:135], v[152:153]
	v_pk_fma_f32 v[60:61], v[60:61], v[132:133], v[150:151]
	v_pk_fma_f32 v[56:57], v[56:57], v[128:129], v[146:147]
	v_pk_mul_f32 v[148:149], v[234:235], v[62:63]
	v_pk_mul_f32 v[146:147], v[236:237], v[60:61]
	v_pk_mul_f32 v[150:151], v[238:239], v[58:59]
	v_pk_mul_f32 v[152:153], v[240:241], v[56:57]
	v_cvt_pk_bf16_f32 v146, v146, v147
	v_cvt_pk_bf16_f32 v147, v148, v149
	v_cvt_pk_bf16_f32 v149, v150, v151
	v_lshl_add_u64 v[150:151], s[20:21], 0, v[174:175]
	v_cvt_pk_bf16_f32 v148, v152, v153
	v_lshl_add_u64 v[150:151], v[150:151], 0, v[200:201]
	s_waitcnt vmcnt(12)
	v_pk_fma_f32 v[54:55], v[54:55], v[126:127], v[164:165]
	v_pk_fma_f32 v[52:53], v[52:53], v[124:125], v[162:163]
	v_pk_fma_f32 v[50:51], v[50:51], v[118:119], v[156:157]
	v_pk_fma_f32 v[48:49], v[48:49], v[116:117], v[154:155]
	global_store_dwordx4 v[158:159], v[60:63], off
	global_store_dwordx4 v[158:159], v[56:59], off offset:16
	global_store_dwordx4 v[150:151], v[146:149], off
	v_pk_mul_f32 v[152:153], v[230:231], v[50:51]
	v_pk_mul_f32 v[154:155], v[232:233], v[48:49]
	v_pk_mul_f32 v[148:149], v[226:227], v[54:55]
	v_pk_mul_f32 v[146:147], v[228:229], v[52:53]
	global_store_dwordx4 v[158:159], v[52:55], off offset:512
	global_store_dwordx4 v[158:159], v[48:51], off offset:528
	v_cvt_pk_bf16_f32 v146, v146, v147
	v_cvt_pk_bf16_f32 v147, v148, v149
	v_cvt_pk_bf16_f32 v148, v154, v155
	v_cvt_pk_bf16_f32 v149, v152, v153
	global_store_dwordx4 v[150:151], v[146:149], off offset:256
	s_waitcnt vmcnt(16)
	v_pk_fma_f32 v[46:47], v[46:47], v[134:135], v[172:173]
	v_pk_fma_f32 v[44:45], v[44:45], v[132:133], v[170:171]
	v_add_u32_e32 v146, 0x90, v224
	v_subrev_u32_e32 v148, s29, v146
	v_ashrrev_i32_e32 v149, 31, v148
	v_lshlrev_b64 v[148:149], 13, v[148:149]
	v_ashrrev_i32_e32 v147, 31, v146
	v_lshl_add_u64 v[148:149], s[42:43], 0, v[148:149]
	v_lshlrev_b64 v[152:153], 12, v[146:147]
	v_pk_fma_f32 v[42:43], v[42:43], v[130:131], v[168:169]
	v_pk_fma_f32 v[40:41], v[40:41], v[128:129], v[166:167]
	v_lshl_add_u64 v[154:155], v[148:149], 0, v[242:243]
	v_pk_mul_f32 v[150:151], v[234:235], v[46:47]
	v_pk_mul_f32 v[148:149], v[236:237], v[44:45]
	v_pk_mul_f32 v[156:157], v[238:239], v[42:43]
	v_pk_mul_f32 v[158:159], v[240:241], v[40:41]
	v_lshl_add_u64 v[152:153], s[20:21], 0, v[152:153]
	v_cvt_pk_bf16_f32 v148, v148, v149
	v_cvt_pk_bf16_f32 v149, v150, v151
	v_cvt_pk_bf16_f32 v150, v158, v159
	v_cvt_pk_bf16_f32 v151, v156, v157
	v_lshl_add_u64 v[152:153], v[152:153], 0, v[200:201]
	s_waitcnt vmcnt(14)
; __device__ __forceinline__ unsigned pk2(float lo, float hi) { const f32x2 v = {lo, hi}; return __builtin_bit_cast(unsigned, __builtin_convertvector(v, bf16x2_t)); }
;     __device__ __forceinline__ void operator()(const f32x4 (&acc)[2][2][4][2], const Unit& un, int wr, int wc, int fr_, int fq_) const {
;     ...
; #pragma unroll
;             for (int m = 0; m < 4; ++m)
; #pragma unroll
;                 for (int bj = 0; bj < 2; ++bj) { const int row = rbase + ai * 128 + m * 16, col = cw + bj * 128; const f32x4 v0 = acc[ai][bj][m][0], v1 = acc[ai][bj][m][1];
;                     float* dp = dst + (size_t)(row - radj) * D + col;
;                     const f32x4 x0 = xa[m][bj][0] + g0[bj] * v0, x1 = xa[m][bj][1] + g1[bj] * v1;
;                     *(f32x4*)dp = x0; *(f32x4*)(dp + 4) = x1;
;                     ssq[ai][m] += (x0.x * x0.x + x0.y * x0.y) + (x0.z * x0.z + x0.w * x0.w) + (x1.x * x1.x + x1.y * x1.y) + (x1.z * x1.z + x1.w * x1.w);
;                     const f32x4 y0 = x0 * y0s[bj], y1 = x1 * y1s[bj];
;                     u32x4 w; w.x = pk2(y0.x, y0.y); w.y = pk2(y0.z, y0.w); w.z = pk2(y1.x, y1.y); w.w = pk2(y1.z, y1.w); *(u32x4*)(xg + (size_t)row * D + col) = w; } }
; #pragma unroll
;         for (int ai = 0; ai < 2; ++ai)
; #pragma unroll
;             for (int m = 0; m < 4; ++m) { float s = ssq[ai][m]; s += shx<16>(s); s += shx<32>(s);
;                 if (fq == 0) ps[((size_t)(rbase + ai * 128 + m * 16) * 8 + un.pn) * 4 + wc] = s; }
	v_pk_fma_f32 v[38:39], v[38:39], v[126:127], v[184:185]
	v_pk_fma_f32 v[36:37], v[36:37], v[124:125], v[182:183]
	v_pk_fma_f32 v[34:35], v[34:35], v[118:119], v[180:181]
	v_pk_fma_f32 v[32:33], v[32:33], v[116:117], v[178:179]
	global_store_dwordx4 v[154:155], v[44:47], off
	global_store_dwordx4 v[154:155], v[40:43], off offset:16
	global_store_dwordx4 v[152:153], v[148:151], off
	global_store_dwordx4 v[154:155], v[36:39], off offset:512
	global_store_dwordx4 v[154:155], v[32:35], off offset:528
	v_pk_mul_f32 v[150:151], v[226:227], v[38:39]
	v_pk_mul_f32 v[148:149], v[228:229], v[36:37]
	v_pk_mul_f32 v[154:155], v[230:231], v[34:35]
	v_pk_mul_f32 v[156:157], v[232:233], v[32:33]
	v_cvt_pk_bf16_f32 v148, v148, v149
	v_cvt_pk_bf16_f32 v149, v150, v151
	v_cvt_pk_bf16_f32 v150, v156, v157
	v_cvt_pk_bf16_f32 v151, v154, v155
	global_store_dwordx4 v[152:153], v[148:151], off offset:256
	s_waitcnt vmcnt(18)
	v_pk_fma_f32 v[30:31], v[30:31], v[134:135], v[198:199]
	v_pk_fma_f32 v[28:29], v[28:29], v[132:133], v[196:197]
	v_add_u32_e32 v148, 0xa0, v224
	v_subrev_u32_e32 v150, s29, v148
	v_ashrrev_i32_e32 v151, 31, v150
	v_lshlrev_b64 v[150:151], 13, v[150:151]
	v_ashrrev_i32_e32 v149, 31, v148
	v_lshl_add_u64 v[150:151], s[42:43], 0, v[150:151]
	v_lshlrev_b64 v[154:155], 12, v[148:149]
	v_pk_fma_f32 v[26:27], v[26:27], v[130:131], v[188:189]
	v_pk_fma_f32 v[24:25], v[24:25], v[128:129], v[186:187]
	v_lshl_add_u64 v[156:157], v[150:151], 0, v[242:243]
	v_pk_mul_f32 v[152:153], v[234:235], v[30:31]
	v_pk_mul_f32 v[150:151], v[236:237], v[28:29]
	v_pk_mul_f32 v[158:159], v[238:239], v[26:27]
	v_pk_mul_f32 v[162:163], v[240:241], v[24:25]
	v_lshl_add_u64 v[154:155], s[20:21], 0, v[154:155]
	v_cvt_pk_bf16_f32 v150, v150, v151
	v_cvt_pk_bf16_f32 v151, v152, v153
	v_cvt_pk_bf16_f32 v152, v162, v163
	v_cvt_pk_bf16_f32 v153, v158, v159
	v_lshl_add_u64 v[154:155], v[154:155], 0, v[200:201]
	s_waitcnt vmcnt(16)
	v_pk_fma_f32 v[22:23], v[22:23], v[126:127], v[250:251]
	v_pk_fma_f32 v[20:21], v[20:21], v[124:125], v[248:249]
	v_pk_fma_f32 v[18:19], v[18:19], v[118:119], v[204:205]
	v_pk_fma_f32 v[16:17], v[16:17], v[116:117], v[202:203]
	global_store_dwordx4 v[156:157], v[28:31], off
	global_store_dwordx4 v[156:157], v[24:27], off offset:16
	global_store_dwordx4 v[154:155], v[150:153], off
	global_store_dwordx4 v[156:157], v[20:23], off offset:512
	global_store_dwordx4 v[156:157], v[16:19], off offset:528
	v_pk_mul_f32 v[152:153], v[226:227], v[22:23]
	v_pk_mul_f32 v[150:151], v[228:229], v[20:21]
	v_pk_mul_f32 v[156:157], v[230:231], v[18:19]
	v_pk_mul_f32 v[158:159], v[232:233], v[16:17]
	v_cvt_pk_bf16_f32 v150, v150, v151
	v_cvt_pk_bf16_f32 v151, v152, v153
	v_cvt_pk_bf16_f32 v152, v158, v159
	v_cvt_pk_bf16_f32 v153, v156, v157
	global_store_dwordx4 v[154:155], v[150:153], off offset:256
	s_waitcnt vmcnt(20)
	v_pk_fma_f32 v[14:15], v[14:15], v[134:135], v[142:143]
	v_pk_fma_f32 v[12:13], v[12:13], v[132:133], v[140:141]
	v_add_u32_e32 v150, 0xb0, v224
	v_subrev_u32_e32 v152, s29, v150
	v_ashrrev_i32_e32 v153, 31, v152
	v_ashrrev_i32_e32 v151, 31, v150
	v_pk_fma_f32 v[10:11], v[10:11], v[130:131], v[138:139]
	v_lshlrev_b64 v[152:153], 13, v[152:153]
	v_lshlrev_b64 v[154:155], 12, v[150:151]
	v_pk_fma_f32 v[8:9], v[8:9], v[128:129], v[136:137]
	v_pk_mul_f32 v[130:131], v[234:235], v[14:15]
	v_pk_mul_f32 v[128:129], v[236:237], v[12:13]
	v_pk_mul_f32 v[132:133], v[238:239], v[10:11]
	s_waitcnt vmcnt(18)
	v_pk_fma_f32 v[6:7], v[6:7], v[126:127], v[122:123]
	v_pk_fma_f32 v[4:5], v[4:5], v[124:125], v[120:121]
	v_pk_fma_f32 v[2:3], v[2:3], v[118:119], v[114:115]
	v_pk_fma_f32 v[0:1], v[0:1], v[116:117], v[112:113]
	v_lshl_add_u64 v[152:153], s[42:43], 0, v[152:153]
	v_pk_mul_f32 v[134:135], v[240:241], v[8:9]
	v_cvt_pk_bf16_f32 v128, v128, v129
	v_cvt_pk_bf16_f32 v129, v130, v131
	v_cvt_pk_bf16_f32 v131, v132, v133
	v_lshl_add_u64 v[132:133], s[20:21], 0, v[154:155]
	v_pk_mul_f32 v[114:115], v[226:227], v[6:7]
	v_pk_mul_f32 v[112:113], v[228:229], v[4:5]
	v_pk_mul_f32 v[116:117], v[230:231], v[2:3]
	v_pk_mul_f32 v[118:119], v[232:233], v[0:1]
	v_lshl_add_u64 v[152:153], v[152:153], 0, v[242:243]
	v_cvt_pk_bf16_f32 v130, v134, v135
	v_lshl_add_u64 v[132:133], v[132:133], 0, v[200:201]
	v_cvt_pk_bf16_f32 v112, v112, v113
	v_cvt_pk_bf16_f32 v113, v114, v115
	v_cvt_pk_bf16_f32 v114, v118, v119
	v_cvt_pk_bf16_f32 v115, v116, v117
	global_store_dwordx4 v[152:153], v[12:15], off
	global_store_dwordx4 v[152:153], v[8:11], off offset:16
	global_store_dwordx4 v[132:133], v[128:131], off
	global_store_dwordx4 v[152:153], v[4:7], off offset:512
	global_store_dwordx4 v[152:153], v[0:3], off offset:528
	global_store_dwordx4 v[132:133], v[112:115], off offset:256
	ds_swizzle_b32 v112, v194 offset:swizzle(SWAP,16)
	s_nop 0
	v_mbcnt_lo_u32_b32 v113, -1, 0
	v_mbcnt_hi_u32_b32 v113, -1, v113
	s_waitcnt lgkmcnt(0)
	v_add_f32_e32 v112, v194, v112
	v_lshlrev_b32_e32 v113, 2, v113
	v_xor_b32_e32 v113, 0x80, v113
	ds_bpermute_b32 v113, v113, v112
	s_and_saveexec_b64 s[40:41], vcc
	s_mov_b32 s74, 0x240000
	s_cbranch_execz .LBB0_1567
	v_lshlrev_b64 v[114:115], 7, v[224:225]
	v_lshl_add_u64 v[114:115], s[24:25], 0, v[114:115]
	v_lshl_add_u64 v[114:115], v[114:115], 0, s[38:39]
	s_mov_b32 s43, s91
	s_lshl_b32 s42, s63, 2
	v_lshl_add_u64 v[114:115], v[114:115], 0, s[42:43]
	s_waitcnt lgkmcnt(0)
	v_add_f32_e32 v112, v112, v113
	global_store_dword v[114:115], v112, off

;     __host__ __device__ bool next(int i, Unit& u) const { const int L = base + i * Gp + cp; if (L >= end) return false; return T.next(L, u); }
;     __host__ __device__ bool next(int i, Unit& u) const { const int L = i * Gp + cp; if (cp < 0 || L >= n) return false; u.kb = L & 3; u.pn = (L >> 2) % nN; u.pm = pm0 + (L >> 2) / nN; return true; }
;     __host__ __device__ bool next(int i, Unit& u) const { const bool ok = T.next(i >> 2, u); u.kb = i & 3; return ok; }
; #define PG8_BAR __builtin_amdgcn_s_barrier()
; template <class Epi, class Sched, bool ALIGN_EPI = false, bool SP2 = false>
; __device__ __forceinline__ void gemm_phase(PG8_LAS unsigned char* lds, const Gemm g, const Sched& S, const Epi& E, const int tid) {
;     ...
;         const bool has_next = S.next(ui + 1, nxt);
;         const char* nA = has_next ? (const char*)g.A + (size_t)nxt.pm * tstep + (size_t)nxt.kb * g.sA : cA; const char* nB = has_next ? (const char*)g.Bt + (size_t)nxt.pn * tstep + (size_t)nxt.kb * g.sB : cB;
;     ...
; #pragma unroll
;         for (int a = 0; a < 2; ++a)
; #pragma unroll
;             for (int b = 0; b < 2; ++b)
; #pragma unroll
;                 for (int m = 0; m < 4; ++m)
; #pragma unroll
;                     for (int n = 0; n < 2; ++n) acc[a][b][m][n] = (f32x4){0.f, 0.f, 0.f, 0.f};
;         cur = nxt; cA = nA; cB = nB; ++ui;
;         if constexpr (ALIGN_EPI) { if (wr == 1) PG8_BAR; }
.LBB0_1603:
	s_ashr_i32 s23, s22, 31
	s_lshl_b64 s[24:25], s[22:23], 22
	s_add_u32 s24, s41, s24
	s_addc_u32 s25, s42, s25
	s_and_b64 s[26:27], s[0:1], exec
	s_cselect_b32 s23, s25, s31
	s_cselect_b32 s56, s24, s30
	s_ashr_i32 s21, s20, 31
	s_lshl_b64 s[26:27], s[20:21], 22
	s_add_u32 s26, s43, s26
	s_addc_u32 s27, s44, s27
	s_and_b64 s[36:37], s[0:1], exec
	s_cselect_b32 s21, s27, s35
	s_cselect_b32 s57, s26, s34
	s_add_u32 s30, s30, 0x200080
	s_addc_u32 s31, s31, 0
	s_add_u32 s58, s34, 0x100
	v_mov_b32_e32 v0, 0
	s_mov_b32 s73, s59
	s_addc_u32 s59, s35, 0
	s_mov_b32 s60, -2
	s_cmp_eq_u32 s100, 0
	s_cbranch_scc1 .Lmy_nobar_1604
	s_barrier
	s_mov_b32 s100, 0
; #define PG8_STAGE(bufoff, gbase, voff) do { _Pragma("unroll") for (int _i = 0; _i < 2; ++_i) \
;         __builtin_amdgcn_global_load_lds((const unsigned*)((const char*)(gbase) + (voff)[_i]), (PG8_LAS unsigned*)(lds + (bufoff) + ldsw + _i * 8192), 16, 0, 0); } while (0)
; #define PG8_LDA(dst, b, h) do { _Pragma("unroll") for (int m = 0; m < 4; ++m) _Pragma("unroll") for (int k = 0; k < 2; ++k) dst[m][k] = *(const PG8_LAS bf16x8*)(lds + PG8_SA(b, h) + aoff + m * 2048 + k * 1024); } while (0)
; #define PG8_LDB(dst, b, h) do { _Pragma("unroll") for (int n = 0; n < 2; ++n) _Pragma("unroll") for (int k = 0; k < 2; ++k) dst[n][k] = *(const PG8_LAS bf16x8*)(lds + PG8_SB(b, h) + boff + n * 2048 + k * 1024); } while (0)
; #define PG8_MMA(ai, bj, At, Bt) do { __builtin_amdgcn_s_setprio(1); _Pragma("unroll") for (int m = 0; m < 4; ++m) _Pragma("unroll") for (int n = 0; n < 2; ++n) _Pragma("unroll") for (int k = 0; k < 2; ++k) \
;         acc[ai][bj][m][n] = __builtin_amdgcn_mfma_f32_16x16x32_bf16(Bt[n][k], At[m][k], acc[ai][bj][m][n], 0, 0, 0); __builtin_amdgcn_s_setprio(0); } while (0)
; #define PG8_WAIT_V(n) asm volatile("s_waitcnt vmcnt(" #n ")" ::: "memory")
; #define PG8_WAIT_L(n) asm volatile("s_waitcnt lgkmcnt(" #n ")" ::: "memory")
; #define PG8_BAR __builtin_amdgcn_s_barrier()
; #define PG8_SCHED __builtin_amdgcn_sched_barrier(0)
; template <class Epi, class Sched, bool ALIGN_EPI = false, bool SP2 = false>
; __device__ __forceinline__ void gemm_phase(PG8_LAS unsigned char* lds, const Gemm g, const Sched& S, const Epi& E, const int tid) {
;     ...
;             if constexpr (SP2) {
;             PG8_LDB(B0, 0, 0); PG8_LDB(B1, 0, 1); PG8_SCHED; PG8_LDA(At, 0, 0); PG8_STAGE(PG8_SA(1, 1), a1 + hstep, voffA);
;             PG8_WAIT_V(8); PG8_WAIT_L(0); PG8_BAR; PG8_MMA(0, 0, At, B0); PG8_MMA(0, 1, At, B1); PG8_BAR; PG8_SCHED;
;             PG8_LDA(At, 0, 1); PG8_STAGE(PG8_SB(0, 0), b2, voffB); PG8_STAGE(PG8_SB(0, 1), b2 + hstep, voffB); PG8_STAGE(PG8_SA(0, 0), a2, voffA);
;             PG8_WAIT_V(8); PG8_WAIT_L(0); PG8_BAR; PG8_MMA(1, 0, At, B0); PG8_MMA(1, 1, At, B1); PG8_BAR; PG8_SCHED;
.Lmy_nobar_1604:
	s_add_u32 s34, s30, 0xffe00080
	s_addc_u32 s35, s31, -1
	s_add_i32 s61, 0, 0x10000
	v_add_u32_e32 v140, s61, v161
	v_add_u32_e32 v158, s33, v161
	ds_read_b128 v[128:131], v140
	ds_read_b128 v[132:135], v140 offset:1024
	ds_read_b128 v[136:139], v140 offset:2048
	ds_read_b128 v[140:143], v140 offset:3072
	ds_read_b128 v[154:157], v158
	ds_read_b128 v[164:167], v158 offset:1024
	ds_read_b128 v[168:171], v158 offset:2048
	ds_read_b128 v[172:175], v158 offset:3072
	s_cmpk_eq_i32 s60, 0x7c
	s_cselect_b32 s37, s23, s35
	s_cselect_b32 s36, s56, s34
	s_cselect_b32 s35, s21, s59
	s_cselect_b32 s34, s57, s58
	v_lshl_add_u64 v[158:159], s[30:31], 0, v[150:151]
	s_add_i32 m0, s29, 0xc000
	ds_read_b128 v[176:179], v163
	ds_read_b128 v[180:183], v163 offset:1024
	ds_read_b128 v[184:187], v163 offset:2048
	ds_read_b128 v[188:191], v163 offset:3072
	ds_read_b128 v[192:195], v163 offset:4096
	ds_read_b128 v[196:199], v163 offset:5120
	ds_read_b128 v[200:203], v163 offset:6144
	ds_read_b128 v[204:207], v163 offset:7168
	global_load_lds_dwordx4 v[158:159], off
	v_lshl_add_u64 v[158:159], s[30:31], 0, v[152:153]
	s_add_i32 m0, s29, 0xe000
	s_nop 0
	global_load_lds_dwordx4 v[158:159], off
	s_waitcnt vmcnt(8)
	s_waitcnt lgkmcnt(0)
	s_barrier
	s_setprio 1
	s_waitcnt lgkmcnt(0)
	v_mfma_f32_16x16x32_bf16 v[124:127], v[128:131], v[176:179], 0
	v_mfma_f32_16x16x32_bf16 v[120:123], v[136:139], v[176:179], 0
	v_mfma_f32_16x16x32_bf16 v[116:119], v[128:131], v[184:187], 0
	v_mfma_f32_16x16x32_bf16 v[112:115], v[136:139], v[184:187], 0
	v_mfma_f32_16x16x32_bf16 v[108:111], v[128:131], v[192:195], 0
	v_mfma_f32_16x16x32_bf16 v[100:103], v[136:139], v[192:195], 0
	v_mfma_f32_16x16x32_bf16 v[92:95], v[128:131], v[200:203], 0
	v_mfma_f32_16x16x32_bf16 v[72:75], v[136:139], v[200:203], 0
	v_mfma_f32_16x16x32_bf16 v[124:127], v[132:135], v[180:183], v[124:127]
	v_mfma_f32_16x16x32_bf16 v[120:123], v[140:143], v[180:183], v[120:123]
	v_mfma_f32_16x16x32_bf16 v[116:119], v[132:135], v[188:191], v[116:119]
	v_mfma_f32_16x16x32_bf16 v[112:115], v[140:143], v[188:191], v[112:115]
	v_mfma_f32_16x16x32_bf16 v[108:111], v[132:135], v[196:199], v[108:111]
	v_mfma_f32_16x16x32_bf16 v[100:103], v[140:143], v[196:199], v[100:103]
	v_mfma_f32_16x16x32_bf16 v[92:95], v[132:135], v[204:207], v[92:95]
	v_mfma_f32_16x16x32_bf16 v[72:75], v[140:143], v[204:207], v[72:75]
	s_setprio 0
	s_setprio 1
	v_mfma_f32_16x16x32_bf16 v[104:107], v[154:157], v[176:179], 0
	v_mfma_f32_16x16x32_bf16 v[96:99], v[168:171], v[176:179], 0
	v_mfma_f32_16x16x32_bf16 v[88:91], v[154:157], v[184:187], 0
	v_mfma_f32_16x16x32_bf16 v[84:87], v[168:171], v[184:187], 0
	v_mfma_f32_16x16x32_bf16 v[80:83], v[154:157], v[192:195], 0
	v_mfma_f32_16x16x32_bf16 v[76:79], v[168:171], v[192:195], 0
	v_mfma_f32_16x16x32_bf16 v[68:71], v[154:157], v[200:203], 0
	v_mfma_f32_16x16x32_bf16 v[64:67], v[168:171], v[200:203], 0
	v_mfma_f32_16x16x32_bf16 v[104:107], v[164:167], v[180:183], v[104:107]
	v_mfma_f32_16x16x32_bf16 v[96:99], v[172:175], v[180:183], v[96:99]
	v_mfma_f32_16x16x32_bf16 v[88:91], v[164:167], v[188:191], v[88:91]
	v_mfma_f32_16x16x32_bf16 v[84:87], v[172:175], v[188:191], v[84:87]
	v_mfma_f32_16x16x32_bf16 v[80:83], v[164:167], v[196:199], v[80:83]
	v_mfma_f32_16x16x32_bf16 v[76:79], v[172:175], v[196:199], v[76:79]
	v_mfma_f32_16x16x32_bf16 v[68:71], v[164:167], v[204:207], v[68:71]
	v_mfma_f32_16x16x32_bf16 v[64:67], v[172:175], v[204:207], v[64:67]
	s_setprio 0
	s_barrier
	s_add_i32 s61, s61, s45
	v_lshl_add_u64 v[158:159], s[34:35], 0, v[208:209]
	s_mov_b32 m0, s61
	ds_read_b128 v[176:179], v163 offset:16384
	ds_read_b128 v[180:183], v163 offset:17408
	ds_read_b128 v[184:187], v163 offset:18432
	ds_read_b128 v[188:191], v163 offset:19456
	ds_read_b128 v[192:195], v163 offset:20480
	ds_read_b128 v[196:199], v163 offset:21504
	ds_read_b128 v[200:203], v163 offset:22528
	ds_read_b128 v[204:207], v163 offset:23552
	global_load_lds_dwordx4 v[158:159], off
	s_add_i32 m0, s61, 0x2000
	s_add_u32 s62, s34, 0x200000
	v_lshl_add_u64 v[210:211], s[34:35], 0, v[148:149]
	s_addc_u32 s63, s35, 0
	s_add_i32 s61, s33, s45
	global_load_lds_dwordx4 v[210:211], off
	v_lshl_add_u64 v[212:213], s[62:63], 0, v[208:209]
	s_mov_b32 m0, s61
	v_lshl_add_u64 v[214:215], s[36:37], 0, v[146:147]
	global_load_lds_dwordx4 v[212:213], off
	v_lshl_add_u64 v[212:213], s[62:63], 0, v[148:149]
	s_add_i32 m0, s61, 0x2000
	s_nop 0
	global_load_lds_dwordx4 v[212:213], off
	v_lshl_add_u64 v[212:213], s[36:37], 0, v[144:145]
	s_mov_b32 m0, s29
	s_nop 0
	global_load_lds_dwordx4 v[212:213], off
	s_mov_b32 m0, s46
	s_nop 0
	global_load_lds_dwordx4 v[214:215], off
	s_waitcnt vmcnt(8)
	s_waitcnt lgkmcnt(0)
	s_barrier
	s_setprio 1
	s_waitcnt lgkmcnt(0)
	v_mfma_f32_16x16x32_bf16 v[60:63], v[128:131], v[176:179], 0
	v_mfma_f32_16x16x32_bf16 v[56:59], v[136:139], v[176:179], 0
	v_mfma_f32_16x16x32_bf16 v[52:55], v[128:131], v[184:187], 0
	v_mfma_f32_16x16x32_bf16 v[48:51], v[136:139], v[184:187], 0
	v_mfma_f32_16x16x32_bf16 v[44:47], v[128:131], v[192:195], 0
	v_mfma_f32_16x16x32_bf16 v[36:39], v[136:139], v[192:195], 0
	v_mfma_f32_16x16x32_bf16 v[20:23], v[128:131], v[200:203], 0
	v_mfma_f32_16x16x32_bf16 v[8:11], v[136:139], v[200:203], 0
	v_mfma_f32_16x16x32_bf16 v[60:63], v[132:135], v[180:183], v[60:63]
	v_mfma_f32_16x16x32_bf16 v[56:59], v[140:143], v[180:183], v[56:59]
	v_mfma_f32_16x16x32_bf16 v[52:55], v[132:135], v[188:191], v[52:55]
	v_mfma_f32_16x16x32_bf16 v[48:51], v[140:143], v[188:191], v[48:51]
	v_mfma_f32_16x16x32_bf16 v[44:47], v[132:135], v[196:199], v[44:47]
	v_mfma_f32_16x16x32_bf16 v[36:39], v[140:143], v[196:199], v[36:39]
	v_mfma_f32_16x16x32_bf16 v[20:23], v[132:135], v[204:207], v[20:23]
	v_mfma_f32_16x16x32_bf16 v[8:11], v[140:143], v[204:207], v[8:11]
	s_setprio 0
	s_setprio 1
	v_mfma_f32_16x16x32_bf16 v[40:43], v[154:157], v[176:179], 0
	v_mfma_f32_16x16x32_bf16 v[32:35], v[168:171], v[176:179], 0
	v_mfma_f32_16x16x32_bf16 v[28:31], v[154:157], v[184:187], 0
	v_mfma_f32_16x16x32_bf16 v[24:27], v[168:171], v[184:187], 0
	v_mfma_f32_16x16x32_bf16 v[16:19], v[154:157], v[192:195], 0
	v_mfma_f32_16x16x32_bf16 v[12:15], v[168:171], v[192:195], 0
	v_mfma_f32_16x16x32_bf16 v[4:7], v[154:157], v[200:203], 0
	v_mfma_f32_16x16x32_bf16 v[0:3], v[168:171], v[200:203], 0
	v_mfma_f32_16x16x32_bf16 v[40:43], v[164:167], v[180:183], v[40:43]
	v_mfma_f32_16x16x32_bf16 v[32:35], v[172:175], v[180:183], v[32:35]
	v_mfma_f32_16x16x32_bf16 v[28:31], v[164:167], v[188:191], v[28:31]
	v_mfma_f32_16x16x32_bf16 v[24:27], v[172:175], v[188:191], v[24:27]
	v_mfma_f32_16x16x32_bf16 v[16:19], v[164:167], v[196:199], v[16:19]
	v_mfma_f32_16x16x32_bf16 v[12:15], v[172:175], v[196:199], v[12:15]
	v_mfma_f32_16x16x32_bf16 v[4:7], v[164:167], v[204:207], v[4:7]
	v_mfma_f32_16x16x32_bf16 v[0:3], v[172:175], v[204:207], v[0:3]
	s_setprio 0
	s_barrier
	s_branch .Lmy_mid_1604

; #define PG8_STAGE(bufoff, gbase, voff) do { _Pragma("unroll") for (int _i = 0; _i < 2; ++_i) \
;         __builtin_amdgcn_global_load_lds((const unsigned*)((const char*)(gbase) + (voff)[_i]), (PG8_LAS unsigned*)(lds + (bufoff) + ldsw + _i * 8192), 16, 0, 0); } while (0)
; #define PG8_LDA(dst, b, h) do { _Pragma("unroll") for (int m = 0; m < 4; ++m) _Pragma("unroll") for (int k = 0; k < 2; ++k) dst[m][k] = *(const PG8_LAS bf16x8*)(lds + PG8_SA(b, h) + aoff + m * 2048 + k * 1024); } while (0)
; #define PG8_LDB(dst, b, h) do { _Pragma("unroll") for (int n = 0; n < 2; ++n) _Pragma("unroll") for (int k = 0; k < 2; ++k) dst[n][k] = *(const PG8_LAS bf16x8*)(lds + PG8_SB(b, h) + boff + n * 2048 + k * 1024); } while (0)
; #define PG8_MMA(ai, bj, At, Bt) do { __builtin_amdgcn_s_setprio(1); _Pragma("unroll") for (int m = 0; m < 4; ++m) _Pragma("unroll") for (int n = 0; n < 2; ++n) _Pragma("unroll") for (int k = 0; k < 2; ++k) \
;         acc[ai][bj][m][n] = __builtin_amdgcn_mfma_f32_16x16x32_bf16(Bt[n][k], At[m][k], acc[ai][bj][m][n], 0, 0, 0); __builtin_amdgcn_s_setprio(0); } while (0)
; #define PG8_WAIT_V(n) asm volatile("s_waitcnt vmcnt(" #n ")" ::: "memory")
; #define PG8_WAIT_L(n) asm volatile("s_waitcnt lgkmcnt(" #n ")" ::: "memory")
; #define PG8_BAR __builtin_amdgcn_s_barrier()
; #define PG8_SCHED __builtin_amdgcn_sched_barrier(0)
; template <class Epi, class Sched, bool ALIGN_EPI = false, bool SP2 = false>
; __device__ __forceinline__ void gemm_phase(PG8_LAS unsigned char* lds, const Gemm g, const Sched& S, const Epi& E, const int tid) {
;     ...
;             PG8_LDB(B0, 1, 0); PG8_LDB(B1, 1, 1); PG8_SCHED; PG8_LDA(At, 1, 0); PG8_STAGE(PG8_SA(0, 1), a2 + hstep, voffA);
;             PG8_WAIT_V(8); PG8_WAIT_L(0); PG8_BAR; PG8_MMA(0, 0, At, B0); PG8_MMA(0, 1, At, B1); PG8_BAR; PG8_SCHED;
.Lmy_mid_1604:
	s_add_i32 s61, 0, 0x18000
	s_add_i32 s62, 0, 0x1c000
	v_add_u32_e32 v140, s61, v161
	v_add_u32_e32 v172, s62, v161
	ds_read_b128 v[128:131], v140
	ds_read_b128 v[132:135], v140 offset:1024
	ds_read_b128 v[136:139], v140 offset:2048
	ds_read_b128 v[140:143], v140 offset:3072
	ds_read_b128 v[154:157], v172
	ds_read_b128 v[164:167], v172 offset:1024
	ds_read_b128 v[168:171], v172 offset:2048
	ds_read_b128 v[172:175], v172 offset:3072
	s_add_u32 s36, s36, 0x200000
	s_addc_u32 s37, s37, 0
	s_mov_b32 m0, s47
	v_lshl_add_u64 v[216:217], s[36:37], 0, v[144:145]
	ds_read_b128 v[176:179], v163 offset:32768
	ds_read_b128 v[180:183], v163 offset:33792
	ds_read_b128 v[184:187], v163 offset:34816
	ds_read_b128 v[188:191], v163 offset:35840
	ds_read_b128 v[192:195], v163 offset:36864
	ds_read_b128 v[196:199], v163 offset:37888
	ds_read_b128 v[200:203], v163 offset:38912
	ds_read_b128 v[204:207], v163 offset:39936
	global_load_lds_dwordx4 v[216:217], off
	v_lshl_add_u64 v[216:217], s[36:37], 0, v[146:147]
	s_mov_b32 m0, s48
	s_nop 0
	global_load_lds_dwordx4 v[216:217], off
	s_waitcnt vmcnt(8)
	s_waitcnt lgkmcnt(0)
	s_barrier
	s_setprio 1
	s_waitcnt lgkmcnt(0)
	v_mfma_f32_16x16x32_bf16 v[124:127], v[128:131], v[176:179], v[124:127]
	v_mfma_f32_16x16x32_bf16 v[120:123], v[136:139], v[176:179], v[120:123]
	v_mfma_f32_16x16x32_bf16 v[116:119], v[128:131], v[184:187], v[116:119]
	v_mfma_f32_16x16x32_bf16 v[112:115], v[136:139], v[184:187], v[112:115]
	v_mfma_f32_16x16x32_bf16 v[108:111], v[128:131], v[192:195], v[108:111]
	v_mfma_f32_16x16x32_bf16 v[100:103], v[136:139], v[192:195], v[100:103]
	v_mfma_f32_16x16x32_bf16 v[92:95], v[128:131], v[200:203], v[92:95]
	v_mfma_f32_16x16x32_bf16 v[72:75], v[136:139], v[200:203], v[72:75]
	v_mfma_f32_16x16x32_bf16 v[124:127], v[132:135], v[180:183], v[124:127]
	v_mfma_f32_16x16x32_bf16 v[120:123], v[140:143], v[180:183], v[120:123]
	v_mfma_f32_16x16x32_bf16 v[116:119], v[132:135], v[188:191], v[116:119]
	v_mfma_f32_16x16x32_bf16 v[112:115], v[140:143], v[188:191], v[112:115]
	v_mfma_f32_16x16x32_bf16 v[108:111], v[132:135], v[196:199], v[108:111]
	v_mfma_f32_16x16x32_bf16 v[100:103], v[140:143], v[196:199], v[100:103]
	v_mfma_f32_16x16x32_bf16 v[92:95], v[132:135], v[204:207], v[92:95]
	v_mfma_f32_16x16x32_bf16 v[72:75], v[140:143], v[204:207], v[72:75]
	s_setprio 0
	s_setprio 1
	v_mfma_f32_16x16x32_bf16 v[104:107], v[154:157], v[176:179], v[104:107]
	v_mfma_f32_16x16x32_bf16 v[96:99], v[168:171], v[176:179], v[96:99]
	v_mfma_f32_16x16x32_bf16 v[88:91], v[154:157], v[184:187], v[88:91]
	v_mfma_f32_16x16x32_bf16 v[84:87], v[168:171], v[184:187], v[84:87]
	v_mfma_f32_16x16x32_bf16 v[80:83], v[154:157], v[192:195], v[80:83]
	v_mfma_f32_16x16x32_bf16 v[76:79], v[168:171], v[192:195], v[76:79]
	v_mfma_f32_16x16x32_bf16 v[68:71], v[154:157], v[200:203], v[68:71]
	v_mfma_f32_16x16x32_bf16 v[64:67], v[168:171], v[200:203], v[64:67]
	v_mfma_f32_16x16x32_bf16 v[104:107], v[164:167], v[180:183], v[104:107]
	v_mfma_f32_16x16x32_bf16 v[96:99], v[172:175], v[180:183], v[96:99]
	v_mfma_f32_16x16x32_bf16 v[88:91], v[164:167], v[188:191], v[88:91]
	v_mfma_f32_16x16x32_bf16 v[84:87], v[172:175], v[188:191], v[84:87]
	v_mfma_f32_16x16x32_bf16 v[80:83], v[164:167], v[196:199], v[80:83]
	v_mfma_f32_16x16x32_bf16 v[76:79], v[172:175], v[196:199], v[76:79]
	v_mfma_f32_16x16x32_bf16 v[68:71], v[164:167], v[204:207], v[68:71]
	v_mfma_f32_16x16x32_bf16 v[64:67], v[172:175], v[204:207], v[64:67]
	s_setprio 0
	s_barrier
; #define PG8_STAGE(bufoff, gbase, voff) do { _Pragma("unroll") for (int _i = 0; _i < 2; ++_i) \
;         __builtin_amdgcn_global_load_lds((const unsigned*)((const char*)(gbase) + (voff)[_i]), (PG8_LAS unsigned*)(lds + (bufoff) + ldsw + _i * 8192), 16, 0, 0); } while (0)
; #define PG8_LDA(dst, b, h) do { _Pragma("unroll") for (int m = 0; m < 4; ++m) _Pragma("unroll") for (int k = 0; k < 2; ++k) dst[m][k] = *(const PG8_LAS bf16x8*)(lds + PG8_SA(b, h) + aoff + m * 2048 + k * 1024); } while (0)
; #define PG8_BAR __builtin_amdgcn_s_barrier()
; template <class Epi, class Sched, bool ALIGN_EPI = false, bool SP2 = false>
; __device__ __forceinline__ void gemm_phase(PG8_LAS unsigned char* lds, const Gemm g, const Sched& S, const Epi& E, const int tid) {
;     ...
;             PG8_LDA(At, 1, 1); PG8_STAGE(PG8_SB(1, 0), b3, voffB); PG8_STAGE(PG8_SB(1, 1), b3 + hstep, voffB); PG8_STAGE(PG8_SA(1, 0), a3, voffA);
;             PG8_WAIT_V(8); PG8_WAIT_L(0); PG8_BAR; PG8_MMA(1, 0, At, B0); PG8_MMA(1, 1, At, B1); PG8_BAR; PG8_SCHED;
;             } else {
;             PG8_LDB(B0, 0, 0); PG8_SCHED; PG8_LDA(At, 0, 0); PG8_STAGE(PG8_SA(1, 1), a1 + hstep, voffA);
;             PG8_WAIT_L(8); PG8_BAR; PG8_WAIT_L(0); PG8_MMA(0, 0, At, B0); PG8_BAR; PG8_SCHED;
;             PG8_LDB(B1, 0, 1); PG8_STAGE(PG8_SB(0, 0), b2, voffB);
;             PG8_BAR; PG8_WAIT_L(0); PG8_MMA(0, 1, At, B1); PG8_BAR;
;             PG8_LDA(At, 0, 1); PG8_STAGE(PG8_SA(0, 0), a2, voffA);
;             PG8_BAR; PG8_WAIT_L(0); PG8_MMA(1, 0, At, B0); PG8_BAR; PG8_SCHED;
;             PG8_STAGE(PG8_SB(0, 1), b2 + hstep, voffB);
;             PG8_WAIT_V(6); PG8_BAR; PG8_MMA(1, 1, At, B1); PG8_BAR;
;             PG8_LDB(B0, 1, 0); PG8_SCHED; PG8_LDA(At, 1, 0); PG8_STAGE(PG8_SA(0, 1), a2 + hstep, voffA);
;             PG8_WAIT_L(8); PG8_BAR; PG8_WAIT_L(0); PG8_MMA(0, 0, At, B0); PG8_BAR; PG8_SCHED;
;             PG8_LDB(B1, 1, 1); PG8_STAGE(PG8_SB(1, 0), b3, voffB);
;             PG8_BAR; PG8_WAIT_L(0); PG8_MMA(0, 1, At, B1); PG8_BAR;
;             PG8_LDA(At, 1, 1); PG8_STAGE(PG8_SA(1, 0), a3, voffA);
;             PG8_BAR; PG8_WAIT_L(0); PG8_MMA(1, 0, At, B0); PG8_BAR; PG8_SCHED;
;             PG8_STAGE(PG8_SB(1, 1), b3 + hstep, voffB);
;             PG8_WAIT_V(6); PG8_BAR; PG8_MMA(1, 1, At, B1); PG8_BAR;
;             }
;         }
;         if constexpr (ALIGN_EPI) { if (wr == 0) PG8_BAR; }
	s_add_i32 s36, s61, s45
	v_lshl_add_u64 v[158:159], v[158:159], 0, s[2:3]
	s_mov_b32 m0, s36
	ds_read_b128 v[176:179], v163 offset:49152
	ds_read_b128 v[180:183], v163 offset:50176
	ds_read_b128 v[184:187], v163 offset:51200
	ds_read_b128 v[188:191], v163 offset:52224
	ds_read_b128 v[192:195], v163 offset:53248
	ds_read_b128 v[196:199], v163 offset:54272
	ds_read_b128 v[200:203], v163 offset:55296
	ds_read_b128 v[204:207], v163 offset:56320
	global_load_lds_dwordx4 v[158:159], off
	s_add_i32 m0, s36, 0x2000
	s_add_u32 s34, s34, 0x200080
	v_lshl_add_u64 v[158:159], v[210:211], 0, s[2:3]
	s_addc_u32 s35, s35, 0
	s_add_i32 s36, s62, s45
	global_load_lds_dwordx4 v[158:159], off
	v_lshl_add_u64 v[158:159], s[34:35], 0, v[208:209]
	s_mov_b32 m0, s36
	s_nop 0
	global_load_lds_dwordx4 v[158:159], off
	v_lshl_add_u64 v[158:159], s[34:35], 0, v[148:149]
	s_add_i32 m0, s36, 0x2000
	s_nop 0
	global_load_lds_dwordx4 v[158:159], off
	v_lshl_add_u64 v[158:159], v[212:213], 0, s[2:3]
	s_mov_b32 m0, s51
	s_nop 0
	global_load_lds_dwordx4 v[158:159], off
	v_lshl_add_u64 v[158:159], v[214:215], 0, s[2:3]
	s_mov_b32 m0, s52
	s_nop 0
	global_load_lds_dwordx4 v[158:159], off
	s_waitcnt vmcnt(8)
	s_waitcnt lgkmcnt(0)
	s_barrier
	s_setprio 1
	s_waitcnt lgkmcnt(0)
	v_mfma_f32_16x16x32_bf16 v[60:63], v[128:131], v[176:179], v[60:63]
	v_mfma_f32_16x16x32_bf16 v[56:59], v[136:139], v[176:179], v[56:59]
	v_mfma_f32_16x16x32_bf16 v[52:55], v[128:131], v[184:187], v[52:55]
	v_mfma_f32_16x16x32_bf16 v[48:51], v[136:139], v[184:187], v[48:51]
	v_mfma_f32_16x16x32_bf16 v[44:47], v[128:131], v[192:195], v[44:47]
	v_mfma_f32_16x16x32_bf16 v[36:39], v[136:139], v[192:195], v[36:39]
	v_mfma_f32_16x16x32_bf16 v[20:23], v[128:131], v[200:203], v[20:23]
	v_mfma_f32_16x16x32_bf16 v[8:11], v[136:139], v[200:203], v[8:11]
	v_mfma_f32_16x16x32_bf16 v[60:63], v[132:135], v[180:183], v[60:63]
	v_mfma_f32_16x16x32_bf16 v[56:59], v[140:143], v[180:183], v[56:59]
	v_mfma_f32_16x16x32_bf16 v[52:55], v[132:135], v[188:191], v[52:55]
	v_mfma_f32_16x16x32_bf16 v[48:51], v[140:143], v[188:191], v[48:51]
	v_mfma_f32_16x16x32_bf16 v[44:47], v[132:135], v[196:199], v[44:47]
	v_mfma_f32_16x16x32_bf16 v[36:39], v[140:143], v[196:199], v[36:39]
	v_mfma_f32_16x16x32_bf16 v[20:23], v[132:135], v[204:207], v[20:23]
	v_mfma_f32_16x16x32_bf16 v[8:11], v[140:143], v[204:207], v[8:11]
	s_setprio 0
	s_setprio 1
	v_mfma_f32_16x16x32_bf16 v[40:43], v[154:157], v[176:179], v[40:43]
	v_mfma_f32_16x16x32_bf16 v[32:35], v[168:171], v[176:179], v[32:35]
	v_mfma_f32_16x16x32_bf16 v[28:31], v[154:157], v[184:187], v[28:31]
	v_mfma_f32_16x16x32_bf16 v[24:27], v[168:171], v[184:187], v[24:27]
	v_mfma_f32_16x16x32_bf16 v[16:19], v[154:157], v[192:195], v[16:19]
	v_mfma_f32_16x16x32_bf16 v[12:15], v[168:171], v[192:195], v[12:15]
	v_mfma_f32_16x16x32_bf16 v[4:7], v[154:157], v[200:203], v[4:7]
	v_mfma_f32_16x16x32_bf16 v[0:3], v[168:171], v[200:203], v[0:3]
	v_mfma_f32_16x16x32_bf16 v[40:43], v[164:167], v[180:183], v[40:43]
	v_mfma_f32_16x16x32_bf16 v[32:35], v[172:175], v[180:183], v[32:35]
	v_mfma_f32_16x16x32_bf16 v[28:31], v[164:167], v[188:191], v[28:31]
	v_mfma_f32_16x16x32_bf16 v[24:27], v[172:175], v[188:191], v[24:27]
	v_mfma_f32_16x16x32_bf16 v[16:19], v[164:167], v[196:199], v[16:19]
	v_mfma_f32_16x16x32_bf16 v[12:15], v[172:175], v[196:199], v[12:15]
	v_mfma_f32_16x16x32_bf16 v[4:7], v[164:167], v[204:207], v[4:7]
	v_mfma_f32_16x16x32_bf16 v[0:3], v[172:175], v[204:207], v[0:3]
	s_setprio 0
	s_barrier
	s_add_i32 s60, s60, 2
	s_add_u32 s30, s30, 0x100
	s_addc_u32 s31, s31, 0
	s_add_u32 s58, s58, 0x100
	s_addc_u32 s59, s59, 0
	s_cmpk_gt_u32 s60, 0x7d
	s_cbranch_scc0 .LBB0_1604
	s_and_b64 vcc, exec, s[8:9]
	s_cbranch_vccz .LBB0_1607
	s_barrier
